# MFMAs of each K-substep (2 B-fragments x 4 A-fragments) issued in snake order so only one operand changes per instruction
# speedup vs baseline: 1.0021x; 1.0021x over previous
.Lm4ap_31:
	s_waitcnt lgkmcnt(0)
	s_barrier
	s_nop 0
	v_mfma_f32_16x16x32_bf16 v[124:127], v[128:131], v[162:165], 0
	v_mfma_f32_16x16x32_bf16 v[108:111], v[128:131], v[170:173], 0
	v_mfma_f32_16x16x32_bf16 v[96:99], v[128:131], v[178:181], 0
	v_mfma_f32_16x16x32_bf16 v[84:87], v[128:131], v[194:197], 0
	v_mfma_f32_16x16x32_bf16 v[80:83], v[136:139], v[194:197], 0
	v_mfma_f32_16x16x32_bf16 v[88:91], v[136:139], v[178:181], 0
	v_mfma_f32_16x16x32_bf16 v[104:107], v[136:139], v[170:173], 0
	v_mfma_f32_16x16x32_bf16 v[120:123], v[136:139], v[162:165], 0
	v_mfma_f32_16x16x32_bf16 v[124:127], v[132:135], v[166:169], v[124:127]
	v_mfma_f32_16x16x32_bf16 v[108:111], v[132:135], v[174:177], v[108:111]
	v_mfma_f32_16x16x32_bf16 v[96:99], v[132:135], v[182:185], v[96:99]
	v_mfma_f32_16x16x32_bf16 v[84:87], v[132:135], v[210:213], v[84:87]
	v_mfma_f32_16x16x32_bf16 v[80:83], v[146:149], v[210:213], v[80:83]
	v_mfma_f32_16x16x32_bf16 v[88:91], v[146:149], v[182:185], v[88:91]
	v_mfma_f32_16x16x32_bf16 v[104:107], v[146:149], v[174:177], v[104:107]
	v_mfma_f32_16x16x32_bf16 v[120:123], v[146:149], v[166:169], v[120:123]
	v_mfma_f32_16x16x32_bf16 v[116:119], v[214:217], v[162:165], 0
	v_mfma_f32_16x16x32_bf16 v[100:103], v[214:217], v[170:173], 0
	v_mfma_f32_16x16x32_bf16 v[76:79], v[214:217], v[178:181], 0
	v_mfma_f32_16x16x32_bf16 v[68:71], v[214:217], v[194:197], 0
	v_mfma_f32_16x16x32_bf16 v[64:67], v[222:225], v[194:197], 0
	v_mfma_f32_16x16x32_bf16 v[72:75], v[222:225], v[178:181], 0
	v_mfma_f32_16x16x32_bf16 v[92:95], v[222:225], v[170:173], 0
	v_mfma_f32_16x16x32_bf16 v[112:115], v[222:225], v[162:165], 0
	v_mfma_f32_16x16x32_bf16 v[116:119], v[218:221], v[166:169], v[116:119]
	v_mfma_f32_16x16x32_bf16 v[100:103], v[218:221], v[174:177], v[100:103]
	v_mfma_f32_16x16x32_bf16 v[76:79], v[218:221], v[182:185], v[76:79]
	v_mfma_f32_16x16x32_bf16 v[68:71], v[218:221], v[210:213], v[68:71]
	v_mfma_f32_16x16x32_bf16 v[64:67], v[226:229], v[210:213], v[64:67]
	v_mfma_f32_16x16x32_bf16 v[72:75], v[226:229], v[182:185], v[72:75]
	v_mfma_f32_16x16x32_bf16 v[92:95], v[226:229], v[174:177], v[92:95]
	v_mfma_f32_16x16x32_bf16 v[112:115], v[226:229], v[166:169], v[112:115]
	s_barrier
	s_add_i32 s6, s6, s57
	v_lshl_add_u64 v[230:231], s[48:49], 0, v[140:141]
	s_mov_b32 m0, s6
	s_nop 0
	global_load_lds_dwordx4 v[230:231], off
	v_lshl_add_u64 v[232:233], s[48:49], 0, v[150:151]
	s_add_i32 m0, s6, 0x2000
	s_nop 0
	global_load_lds_dwordx4 v[232:233], off
	s_mov_b32 m0, s58
	v_lshl_add_u64 v[234:235], s[52:53], 0, v[154:155]
	ds_read_b128 v[162:165], v208 offset:16384
	ds_read_b128 v[166:169], v208 offset:17408
	ds_read_b128 v[170:173], v208 offset:18432
	ds_read_b128 v[174:177], v208 offset:19456
	ds_read_b128 v[178:181], v208 offset:20480
	ds_read_b128 v[182:185], v208 offset:21504
	ds_read_b128 v[194:197], v208 offset:22528
	ds_read_b128 v[210:213], v208 offset:23552
	global_load_lds_dwordx4 v[234:235], off
	v_lshl_add_u64 v[236:237], s[52:53], 0, v[152:153]
	s_mov_b32 m0, s59
	s_nop 0
	global_load_lds_dwordx4 v[236:237], off
	s_add_u32 s50, s48, 0xb0000
	s_addc_u32 s51, s49, 0
	s_add_i32 s6, s19, s57
	v_lshl_add_u64 v[250:251], s[50:51], 0, v[140:141]
	s_mov_b32 m0, s6
	s_nop 0
	global_load_lds_dwordx4 v[250:251], off
	v_lshl_add_u64 v[250:251], s[50:51], 0, v[150:151]
	s_add_i32 m0, s6, 0x2000
	s_nop 0
	global_load_lds_dwordx4 v[250:251], off
	s_waitcnt vmcnt(40)
	s_cmp_lg_u32 s100, 0
	s_cbranch_scc1 .Lm4bp_31
	s_waitcnt vmcnt(8)
.Lm4bp_31:
	s_waitcnt lgkmcnt(0)
	s_mov_b32 s100, 0
	s_barrier
	v_mfma_f32_16x16x32_bf16 v[60:63], v[128:131], v[162:165], 0
	v_mfma_f32_16x16x32_bf16 v[48:51], v[128:131], v[170:173], 0
	v_mfma_f32_16x16x32_bf16 v[32:35], v[128:131], v[178:181], 0
	v_mfma_f32_16x16x32_bf16 v[16:19], v[128:131], v[194:197], 0
	v_mfma_f32_16x16x32_bf16 v[8:11], v[136:139], v[194:197], 0
	v_mfma_f32_16x16x32_bf16 v[24:27], v[136:139], v[178:181], 0
	v_mfma_f32_16x16x32_bf16 v[40:43], v[136:139], v[170:173], 0
	v_mfma_f32_16x16x32_bf16 v[56:59], v[136:139], v[162:165], 0
	v_mfma_f32_16x16x32_bf16 v[60:63], v[132:135], v[166:169], v[60:63]
	v_mfma_f32_16x16x32_bf16 v[48:51], v[132:135], v[174:177], v[48:51]
	v_mfma_f32_16x16x32_bf16 v[32:35], v[132:135], v[182:185], v[32:35]
	v_mfma_f32_16x16x32_bf16 v[16:19], v[132:135], v[210:213], v[16:19]
	v_mfma_f32_16x16x32_bf16 v[8:11], v[146:149], v[210:213], v[8:11]
	v_mfma_f32_16x16x32_bf16 v[24:27], v[146:149], v[182:185], v[24:27]
	v_mfma_f32_16x16x32_bf16 v[40:43], v[146:149], v[174:177], v[40:43]
	v_mfma_f32_16x16x32_bf16 v[56:59], v[146:149], v[166:169], v[56:59]
	v_mfma_f32_16x16x32_bf16 v[52:55], v[214:217], v[162:165], 0
	v_mfma_f32_16x16x32_bf16 v[36:39], v[214:217], v[170:173], 0
	v_mfma_f32_16x16x32_bf16 v[20:23], v[214:217], v[178:181], 0
	v_mfma_f32_16x16x32_bf16 v[4:7], v[214:217], v[194:197], 0
	v_mfma_f32_16x16x32_bf16 v[0:3], v[222:225], v[194:197], 0
	v_mfma_f32_16x16x32_bf16 v[12:15], v[222:225], v[178:181], 0
	v_mfma_f32_16x16x32_bf16 v[28:31], v[222:225], v[170:173], 0
	v_mfma_f32_16x16x32_bf16 v[44:47], v[222:225], v[162:165], 0
	v_mfma_f32_16x16x32_bf16 v[52:55], v[218:221], v[166:169], v[52:55]
	v_mfma_f32_16x16x32_bf16 v[36:39], v[218:221], v[174:177], v[36:39]
	v_mfma_f32_16x16x32_bf16 v[20:23], v[218:221], v[182:185], v[20:23]
	v_mfma_f32_16x16x32_bf16 v[4:7], v[218:221], v[210:213], v[4:7]
	v_mfma_f32_16x16x32_bf16 v[0:3], v[226:229], v[210:213], v[0:3]
	v_mfma_f32_16x16x32_bf16 v[12:15], v[226:229], v[182:185], v[12:15]
	v_mfma_f32_16x16x32_bf16 v[28:31], v[226:229], v[174:177], v[28:31]
	v_mfma_f32_16x16x32_bf16 v[44:47], v[226:229], v[166:169], v[44:47]
	s_barrier
	s_add_i32 s6, 0, 0x18000
	v_add_u32_e32 v146, s6, v206
	ds_read_b128 v[128:131], v146
	ds_read_b128 v[132:135], v146 offset:1024
	ds_read_b128 v[136:139], v146 offset:2048
	ds_read_b128 v[146:149], v146 offset:3072
	s_add_u32 s50, s52, 0xb0000
	s_addc_u32 s51, s53, 0
	s_mov_b32 m0, s68
	v_lshl_add_u64 v[214:215], s[50:51], 0, v[154:155]
	ds_read_b128 v[162:165], v208 offset:32768
	ds_read_b128 v[166:169], v208 offset:33792
	ds_read_b128 v[170:173], v208 offset:34816
	ds_read_b128 v[174:177], v208 offset:35840
	ds_read_b128 v[178:181], v208 offset:36864
	ds_read_b128 v[182:185], v208 offset:37888
	ds_read_b128 v[194:197], v208 offset:38912
	ds_read_b128 v[210:213], v208 offset:39936
	global_load_lds_dwordx4 v[214:215], off
	v_lshl_add_u64 v[214:215], s[50:51], 0, v[152:153]
	s_mov_b32 m0, s69
	s_nop 0
	global_load_lds_dwordx4 v[214:215], off
	s_add_i32 s19, 0, 0x1c000
	v_add_u32_e32 v192, s19, v206
	ds_read_b128 v[214:217], v192
	ds_read_b128 v[218:221], v192 offset:1024
	ds_read_b128 v[222:225], v192 offset:2048
	ds_read_b128 v[226:229], v192 offset:3072
	s_waitcnt vmcnt(8)
	s_waitcnt lgkmcnt(0)
	s_barrier
	v_mfma_f32_16x16x32_bf16 v[124:127], v[128:131], v[162:165], v[124:127]
	v_mfma_f32_16x16x32_bf16 v[108:111], v[128:131], v[170:173], v[108:111]
	v_mfma_f32_16x16x32_bf16 v[96:99], v[128:131], v[178:181], v[96:99]
	v_mfma_f32_16x16x32_bf16 v[84:87], v[128:131], v[194:197], v[84:87]
	v_mfma_f32_16x16x32_bf16 v[80:83], v[136:139], v[194:197], v[80:83]
	v_mfma_f32_16x16x32_bf16 v[88:91], v[136:139], v[178:181], v[88:91]
	v_mfma_f32_16x16x32_bf16 v[104:107], v[136:139], v[170:173], v[104:107]
	v_mfma_f32_16x16x32_bf16 v[120:123], v[136:139], v[162:165], v[120:123]
	v_mfma_f32_16x16x32_bf16 v[124:127], v[132:135], v[166:169], v[124:127]
	v_mfma_f32_16x16x32_bf16 v[108:111], v[132:135], v[174:177], v[108:111]
	v_mfma_f32_16x16x32_bf16 v[96:99], v[132:135], v[182:185], v[96:99]
	v_mfma_f32_16x16x32_bf16 v[84:87], v[132:135], v[210:213], v[84:87]
	v_mfma_f32_16x16x32_bf16 v[80:83], v[146:149], v[210:213], v[80:83]
	v_mfma_f32_16x16x32_bf16 v[88:91], v[146:149], v[182:185], v[88:91]
	v_mfma_f32_16x16x32_bf16 v[104:107], v[146:149], v[174:177], v[104:107]
	v_mfma_f32_16x16x32_bf16 v[120:123], v[146:149], v[166:169], v[120:123]
	v_mfma_f32_16x16x32_bf16 v[116:119], v[214:217], v[162:165], v[116:119]
	v_mfma_f32_16x16x32_bf16 v[100:103], v[214:217], v[170:173], v[100:103]
	v_mfma_f32_16x16x32_bf16 v[76:79], v[214:217], v[178:181], v[76:79]
	v_mfma_f32_16x16x32_bf16 v[68:71], v[214:217], v[194:197], v[68:71]
	v_mfma_f32_16x16x32_bf16 v[64:67], v[222:225], v[194:197], v[64:67]
	v_mfma_f32_16x16x32_bf16 v[72:75], v[222:225], v[178:181], v[72:75]
	v_mfma_f32_16x16x32_bf16 v[92:95], v[222:225], v[170:173], v[92:95]
	v_mfma_f32_16x16x32_bf16 v[112:115], v[222:225], v[162:165], v[112:115]
	v_mfma_f32_16x16x32_bf16 v[116:119], v[218:221], v[166:169], v[116:119]
	v_mfma_f32_16x16x32_bf16 v[100:103], v[218:221], v[174:177], v[100:103]
	v_mfma_f32_16x16x32_bf16 v[76:79], v[218:221], v[182:185], v[76:79]
	v_mfma_f32_16x16x32_bf16 v[68:71], v[218:221], v[210:213], v[68:71]
	v_mfma_f32_16x16x32_bf16 v[64:67], v[226:229], v[210:213], v[64:67]
	v_mfma_f32_16x16x32_bf16 v[72:75], v[226:229], v[182:185], v[72:75]
	v_mfma_f32_16x16x32_bf16 v[92:95], v[226:229], v[174:177], v[92:95]
	v_mfma_f32_16x16x32_bf16 v[112:115], v[226:229], v[166:169], v[112:115]
	s_barrier
	s_add_i32 s6, s6, s57
	v_lshl_add_u64 v[230:231], v[230:231], 0, s[36:37]
	s_mov_b32 m0, s6
	s_nop 0
	global_load_lds_dwordx4 v[230:231], off
	v_lshl_add_u64 v[230:231], v[232:233], 0, s[36:37]
	s_add_i32 m0, s6, 0x2000
	s_nop 0
	global_load_lds_dwordx4 v[230:231], off
	s_mov_b32 m0, s70
	v_lshl_add_u64 v[230:231], v[234:235], 0, s[36:37]
	ds_read_b128 v[162:165], v208 offset:49152
	ds_read_b128 v[166:169], v208 offset:50176
	ds_read_b128 v[170:173], v208 offset:51200
	ds_read_b128 v[174:177], v208 offset:52224
	ds_read_b128 v[178:181], v208 offset:53248
	ds_read_b128 v[182:185], v208 offset:54272
	ds_read_b128 v[194:197], v208 offset:55296
	ds_read_b128 v[210:213], v208 offset:56320
	global_load_lds_dwordx4 v[230:231], off
	v_lshl_add_u64 v[230:231], v[236:237], 0, s[36:37]
	s_mov_b32 m0, s71
	s_nop 0
	global_load_lds_dwordx4 v[230:231], off
	s_add_u32 s48, s48, 0xb0080
	s_addc_u32 s49, s49, 0
	s_add_i32 s6, s19, s57
	v_lshl_add_u64 v[250:251], s[48:49], 0, v[140:141]
	s_mov_b32 m0, s6
	s_nop 0
	global_load_lds_dwordx4 v[250:251], off
	v_lshl_add_u64 v[250:251], s[48:49], 0, v[150:151]
	s_add_i32 m0, s6, 0x2000
	s_nop 0
	global_load_lds_dwordx4 v[250:251], off
	s_waitcnt vmcnt(8)
	s_waitcnt lgkmcnt(0)
	s_barrier
	v_mfma_f32_16x16x32_bf16 v[60:63], v[128:131], v[162:165], v[60:63]
	v_mfma_f32_16x16x32_bf16 v[48:51], v[128:131], v[170:173], v[48:51]
	v_mfma_f32_16x16x32_bf16 v[32:35], v[128:131], v[178:181], v[32:35]
	v_mfma_f32_16x16x32_bf16 v[16:19], v[128:131], v[194:197], v[16:19]
	v_mfma_f32_16x16x32_bf16 v[8:11], v[136:139], v[194:197], v[8:11]
	v_mfma_f32_16x16x32_bf16 v[24:27], v[136:139], v[178:181], v[24:27]
	v_mfma_f32_16x16x32_bf16 v[40:43], v[136:139], v[170:173], v[40:43]
	v_mfma_f32_16x16x32_bf16 v[56:59], v[136:139], v[162:165], v[56:59]
	v_mfma_f32_16x16x32_bf16 v[60:63], v[132:135], v[166:169], v[60:63]
	v_mfma_f32_16x16x32_bf16 v[48:51], v[132:135], v[174:177], v[48:51]
	v_mfma_f32_16x16x32_bf16 v[32:35], v[132:135], v[182:185], v[32:35]
	v_mfma_f32_16x16x32_bf16 v[16:19], v[132:135], v[210:213], v[16:19]
	v_mfma_f32_16x16x32_bf16 v[8:11], v[146:149], v[210:213], v[8:11]
	v_mfma_f32_16x16x32_bf16 v[24:27], v[146:149], v[182:185], v[24:27]
	v_mfma_f32_16x16x32_bf16 v[40:43], v[146:149], v[174:177], v[40:43]
	v_mfma_f32_16x16x32_bf16 v[56:59], v[146:149], v[166:169], v[56:59]
	v_mfma_f32_16x16x32_bf16 v[52:55], v[214:217], v[162:165], v[52:55]
	v_mfma_f32_16x16x32_bf16 v[36:39], v[214:217], v[170:173], v[36:39]
	v_mfma_f32_16x16x32_bf16 v[20:23], v[214:217], v[178:181], v[20:23]
	v_mfma_f32_16x16x32_bf16 v[4:7], v[214:217], v[194:197], v[4:7]
	v_mfma_f32_16x16x32_bf16 v[0:3], v[222:225], v[194:197], v[0:3]
	v_mfma_f32_16x16x32_bf16 v[12:15], v[222:225], v[178:181], v[12:15]
	v_mfma_f32_16x16x32_bf16 v[28:31], v[222:225], v[170:173], v[28:31]
	v_mfma_f32_16x16x32_bf16 v[44:47], v[222:225], v[162:165], v[44:47]
	v_mfma_f32_16x16x32_bf16 v[52:55], v[218:221], v[166:169], v[52:55]
	v_mfma_f32_16x16x32_bf16 v[36:39], v[218:221], v[174:177], v[36:39]
	v_mfma_f32_16x16x32_bf16 v[20:23], v[218:221], v[182:185], v[20:23]
	v_mfma_f32_16x16x32_bf16 v[4:7], v[218:221], v[210:213], v[4:7]
	v_mfma_f32_16x16x32_bf16 v[0:3], v[226:229], v[210:213], v[0:3]
	v_mfma_f32_16x16x32_bf16 v[12:15], v[226:229], v[182:185], v[12:15]
	v_mfma_f32_16x16x32_bf16 v[28:31], v[226:229], v[174:177], v[28:31]
	v_mfma_f32_16x16x32_bf16 v[44:47], v[226:229], v[166:169], v[44:47]
	s_add_i32 s12, s12, 2
	s_add_u32 s10, s10, 0x100
	s_addc_u32 s11, s11, 0
	s_cmp_gt_u32 s12, 41
	s_mov_b64 s[50:51], s[46:47]
	s_barrier
.LBB0_31:
	s_add_u32 s46, s50, 0x100
	s_addc_u32 s47, s51, 0
	s_add_i32 s6, 0, 0x10000
	v_add_u32_e32 v146, s6, v206
	ds_read_b128 v[128:131], v146
	ds_read_b128 v[132:135], v146 offset:1024
	ds_read_b128 v[136:139], v146 offset:2048
	ds_read_b128 v[146:149], v146 offset:3072
	s_cmp_eq_u32 s12, 40
	s_cselect_b32 s53, s31, s47
	s_cselect_b32 s52, s30, s46
	s_cselect_b32 s49, s35, s11
	s_cselect_b32 s48, s34, s10
	v_lshl_add_u64 v[214:215], s[50:51], 0, v[158:159]
	s_add_i32 m0, s58, 0xc000
	ds_read_b128 v[162:165], v208
	ds_read_b128 v[166:169], v208 offset:1024
	ds_read_b128 v[170:173], v208 offset:2048
	ds_read_b128 v[174:177], v208 offset:3072
	ds_read_b128 v[178:181], v208 offset:4096
	ds_read_b128 v[182:185], v208 offset:5120
	ds_read_b128 v[194:197], v208 offset:6144
	ds_read_b128 v[210:213], v208 offset:7168
	global_load_lds_dwordx4 v[214:215], off
	v_lshl_add_u64 v[214:215], s[50:51], 0, v[160:161]
	s_add_i32 m0, s58, 0xe000
	s_nop 0
	global_load_lds_dwordx4 v[214:215], off
	s_add_i32 s19, 0, 0x14000
	v_add_u32_e32 v192, s19, v206
	ds_read_b128 v[214:217], v192
	ds_read_b128 v[218:221], v192 offset:1024
	ds_read_b128 v[222:225], v192 offset:2048
	ds_read_b128 v[226:229], v192 offset:3072
	s_nop 0
	s_waitcnt vmcnt(8)
	s_waitcnt lgkmcnt(0)
	s_barrier
	v_mfma_f32_16x16x32_bf16 v[124:127], v[128:131], v[162:165], v[124:127]
	v_mfma_f32_16x16x32_bf16 v[108:111], v[128:131], v[170:173], v[108:111]
	v_mfma_f32_16x16x32_bf16 v[96:99], v[128:131], v[178:181], v[96:99]
	v_mfma_f32_16x16x32_bf16 v[84:87], v[128:131], v[194:197], v[84:87]
	v_mfma_f32_16x16x32_bf16 v[80:83], v[136:139], v[194:197], v[80:83]
	v_mfma_f32_16x16x32_bf16 v[88:91], v[136:139], v[178:181], v[88:91]
	v_mfma_f32_16x16x32_bf16 v[104:107], v[136:139], v[170:173], v[104:107]
	v_mfma_f32_16x16x32_bf16 v[120:123], v[136:139], v[162:165], v[120:123]
	v_mfma_f32_16x16x32_bf16 v[124:127], v[132:135], v[166:169], v[124:127]
	v_mfma_f32_16x16x32_bf16 v[108:111], v[132:135], v[174:177], v[108:111]
	v_mfma_f32_16x16x32_bf16 v[96:99], v[132:135], v[182:185], v[96:99]
	v_mfma_f32_16x16x32_bf16 v[84:87], v[132:135], v[210:213], v[84:87]
	v_mfma_f32_16x16x32_bf16 v[80:83], v[146:149], v[210:213], v[80:83]
	v_mfma_f32_16x16x32_bf16 v[88:91], v[146:149], v[182:185], v[88:91]
	v_mfma_f32_16x16x32_bf16 v[104:107], v[146:149], v[174:177], v[104:107]
	v_mfma_f32_16x16x32_bf16 v[120:123], v[146:149], v[166:169], v[120:123]
	v_mfma_f32_16x16x32_bf16 v[116:119], v[214:217], v[162:165], v[116:119]
	v_mfma_f32_16x16x32_bf16 v[100:103], v[214:217], v[170:173], v[100:103]
	v_mfma_f32_16x16x32_bf16 v[76:79], v[214:217], v[178:181], v[76:79]
	v_mfma_f32_16x16x32_bf16 v[68:71], v[214:217], v[194:197], v[68:71]
	v_mfma_f32_16x16x32_bf16 v[64:67], v[222:225], v[194:197], v[64:67]
	v_mfma_f32_16x16x32_bf16 v[72:75], v[222:225], v[178:181], v[72:75]
	v_mfma_f32_16x16x32_bf16 v[92:95], v[222:225], v[170:173], v[92:95]
	v_mfma_f32_16x16x32_bf16 v[112:115], v[222:225], v[162:165], v[112:115]
	v_mfma_f32_16x16x32_bf16 v[116:119], v[218:221], v[166:169], v[116:119]
	v_mfma_f32_16x16x32_bf16 v[100:103], v[218:221], v[174:177], v[100:103]
	v_mfma_f32_16x16x32_bf16 v[76:79], v[218:221], v[182:185], v[76:79]
	v_mfma_f32_16x16x32_bf16 v[68:71], v[218:221], v[210:213], v[68:71]
	v_mfma_f32_16x16x32_bf16 v[64:67], v[226:229], v[210:213], v[64:67]
	v_mfma_f32_16x16x32_bf16 v[72:75], v[226:229], v[182:185], v[72:75]
	v_mfma_f32_16x16x32_bf16 v[92:95], v[226:229], v[174:177], v[92:95]
	v_mfma_f32_16x16x32_bf16 v[112:115], v[226:229], v[166:169], v[112:115]
	s_barrier
	s_add_i32 s6, s6, s57
	v_lshl_add_u64 v[230:231], s[48:49], 0, v[140:141]
	s_mov_b32 m0, s6
	s_nop 0
	global_load_lds_dwordx4 v[230:231], off
	v_lshl_add_u64 v[232:233], s[48:49], 0, v[150:151]
	s_add_i32 m0, s6, 0x2000
	s_nop 0
	global_load_lds_dwordx4 v[232:233], off
	s_mov_b32 m0, s58
	v_lshl_add_u64 v[234:235], s[52:53], 0, v[154:155]
	ds_read_b128 v[162:165], v208 offset:16384
	ds_read_b128 v[166:169], v208 offset:17408
	ds_read_b128 v[170:173], v208 offset:18432
	ds_read_b128 v[174:177], v208 offset:19456
	ds_read_b128 v[178:181], v208 offset:20480
	ds_read_b128 v[182:185], v208 offset:21504
	ds_read_b128 v[194:197], v208 offset:22528
	ds_read_b128 v[210:213], v208 offset:23552
	global_load_lds_dwordx4 v[234:235], off
	v_lshl_add_u64 v[236:237], s[52:53], 0, v[152:153]
	s_mov_b32 m0, s59
	s_nop 0
	global_load_lds_dwordx4 v[236:237], off
	s_add_u32 s50, s48, 0xb0000
	s_addc_u32 s51, s49, 0
	s_add_i32 s6, s19, s57
	v_lshl_add_u64 v[250:251], s[50:51], 0, v[140:141]
	s_mov_b32 m0, s6
	s_nop 0
	global_load_lds_dwordx4 v[250:251], off
	v_lshl_add_u64 v[250:251], s[50:51], 0, v[150:151]
	s_add_i32 m0, s6, 0x2000
	s_nop 0
	global_load_lds_dwordx4 v[250:251], off
	s_waitcnt vmcnt(8)
	s_waitcnt lgkmcnt(0)
	s_barrier
	v_mfma_f32_16x16x32_bf16 v[60:63], v[128:131], v[162:165], v[60:63]
	v_mfma_f32_16x16x32_bf16 v[48:51], v[128:131], v[170:173], v[48:51]
	v_mfma_f32_16x16x32_bf16 v[32:35], v[128:131], v[178:181], v[32:35]
	v_mfma_f32_16x16x32_bf16 v[16:19], v[128:131], v[194:197], v[16:19]
	v_mfma_f32_16x16x32_bf16 v[8:11], v[136:139], v[194:197], v[8:11]
	v_mfma_f32_16x16x32_bf16 v[24:27], v[136:139], v[178:181], v[24:27]
	v_mfma_f32_16x16x32_bf16 v[40:43], v[136:139], v[170:173], v[40:43]
	v_mfma_f32_16x16x32_bf16 v[56:59], v[136:139], v[162:165], v[56:59]
	v_mfma_f32_16x16x32_bf16 v[60:63], v[132:135], v[166:169], v[60:63]
	v_mfma_f32_16x16x32_bf16 v[48:51], v[132:135], v[174:177], v[48:51]
	v_mfma_f32_16x16x32_bf16 v[32:35], v[132:135], v[182:185], v[32:35]
	v_mfma_f32_16x16x32_bf16 v[16:19], v[132:135], v[210:213], v[16:19]
	v_mfma_f32_16x16x32_bf16 v[8:11], v[146:149], v[210:213], v[8:11]
	v_mfma_f32_16x16x32_bf16 v[24:27], v[146:149], v[182:185], v[24:27]
	v_mfma_f32_16x16x32_bf16 v[40:43], v[146:149], v[174:177], v[40:43]
	v_mfma_f32_16x16x32_bf16 v[56:59], v[146:149], v[166:169], v[56:59]
	v_mfma_f32_16x16x32_bf16 v[52:55], v[214:217], v[162:165], v[52:55]
	v_mfma_f32_16x16x32_bf16 v[36:39], v[214:217], v[170:173], v[36:39]
	v_mfma_f32_16x16x32_bf16 v[20:23], v[214:217], v[178:181], v[20:23]
	v_mfma_f32_16x16x32_bf16 v[4:7], v[214:217], v[194:197], v[4:7]
	v_mfma_f32_16x16x32_bf16 v[0:3], v[222:225], v[194:197], v[0:3]
	v_mfma_f32_16x16x32_bf16 v[12:15], v[222:225], v[178:181], v[12:15]
	v_mfma_f32_16x16x32_bf16 v[28:31], v[222:225], v[170:173], v[28:31]
	v_mfma_f32_16x16x32_bf16 v[44:47], v[222:225], v[162:165], v[44:47]
	v_mfma_f32_16x16x32_bf16 v[52:55], v[218:221], v[166:169], v[52:55]
	v_mfma_f32_16x16x32_bf16 v[36:39], v[218:221], v[174:177], v[36:39]
	v_mfma_f32_16x16x32_bf16 v[20:23], v[218:221], v[182:185], v[20:23]
	v_mfma_f32_16x16x32_bf16 v[4:7], v[218:221], v[210:213], v[4:7]
	v_mfma_f32_16x16x32_bf16 v[0:3], v[226:229], v[210:213], v[0:3]
	v_mfma_f32_16x16x32_bf16 v[12:15], v[226:229], v[182:185], v[12:15]
	v_mfma_f32_16x16x32_bf16 v[28:31], v[226:229], v[174:177], v[28:31]
	v_mfma_f32_16x16x32_bf16 v[44:47], v[226:229], v[166:169], v[44:47]
	s_barrier
	s_add_i32 s6, 0, 0x18000
	v_add_u32_e32 v146, s6, v206
	ds_read_b128 v[128:131], v146
	ds_read_b128 v[132:135], v146 offset:1024
	ds_read_b128 v[136:139], v146 offset:2048
	ds_read_b128 v[146:149], v146 offset:3072
	s_add_u32 s50, s52, 0xb0000
	s_addc_u32 s51, s53, 0
	s_mov_b32 m0, s68
	v_lshl_add_u64 v[214:215], s[50:51], 0, v[154:155]
	ds_read_b128 v[162:165], v208 offset:32768
	ds_read_b128 v[166:169], v208 offset:33792
	ds_read_b128 v[170:173], v208 offset:34816
	ds_read_b128 v[174:177], v208 offset:35840
	ds_read_b128 v[178:181], v208 offset:36864
	ds_read_b128 v[182:185], v208 offset:37888
	ds_read_b128 v[194:197], v208 offset:38912
	ds_read_b128 v[210:213], v208 offset:39936
	global_load_lds_dwordx4 v[214:215], off
	v_lshl_add_u64 v[214:215], s[50:51], 0, v[152:153]
	s_mov_b32 m0, s69
	s_nop 0
	global_load_lds_dwordx4 v[214:215], off
	s_add_i32 s19, 0, 0x1c000
	v_add_u32_e32 v192, s19, v206
	ds_read_b128 v[214:217], v192
	ds_read_b128 v[218:221], v192 offset:1024
	ds_read_b128 v[222:225], v192 offset:2048
	ds_read_b128 v[226:229], v192 offset:3072
	s_waitcnt vmcnt(8)
	s_waitcnt lgkmcnt(0)
	s_barrier
	v_mfma_f32_16x16x32_bf16 v[124:127], v[128:131], v[162:165], v[124:127]
	v_mfma_f32_16x16x32_bf16 v[108:111], v[128:131], v[170:173], v[108:111]
	v_mfma_f32_16x16x32_bf16 v[96:99], v[128:131], v[178:181], v[96:99]
	v_mfma_f32_16x16x32_bf16 v[84:87], v[128:131], v[194:197], v[84:87]
	v_mfma_f32_16x16x32_bf16 v[80:83], v[136:139], v[194:197], v[80:83]
	v_mfma_f32_16x16x32_bf16 v[88:91], v[136:139], v[178:181], v[88:91]
	v_mfma_f32_16x16x32_bf16 v[104:107], v[136:139], v[170:173], v[104:107]
	v_mfma_f32_16x16x32_bf16 v[120:123], v[136:139], v[162:165], v[120:123]
	v_mfma_f32_16x16x32_bf16 v[124:127], v[132:135], v[166:169], v[124:127]
	v_mfma_f32_16x16x32_bf16 v[108:111], v[132:135], v[174:177], v[108:111]
	v_mfma_f32_16x16x32_bf16 v[96:99], v[132:135], v[182:185], v[96:99]
	v_mfma_f32_16x16x32_bf16 v[84:87], v[132:135], v[210:213], v[84:87]
	v_mfma_f32_16x16x32_bf16 v[80:83], v[146:149], v[210:213], v[80:83]
	v_mfma_f32_16x16x32_bf16 v[88:91], v[146:149], v[182:185], v[88:91]
	v_mfma_f32_16x16x32_bf16 v[104:107], v[146:149], v[174:177], v[104:107]
	v_mfma_f32_16x16x32_bf16 v[120:123], v[146:149], v[166:169], v[120:123]
	v_mfma_f32_16x16x32_bf16 v[116:119], v[214:217], v[162:165], v[116:119]
	v_mfma_f32_16x16x32_bf16 v[100:103], v[214:217], v[170:173], v[100:103]
	v_mfma_f32_16x16x32_bf16 v[76:79], v[214:217], v[178:181], v[76:79]
	v_mfma_f32_16x16x32_bf16 v[68:71], v[214:217], v[194:197], v[68:71]
	v_mfma_f32_16x16x32_bf16 v[64:67], v[222:225], v[194:197], v[64:67]
	v_mfma_f32_16x16x32_bf16 v[72:75], v[222:225], v[178:181], v[72:75]
	v_mfma_f32_16x16x32_bf16 v[92:95], v[222:225], v[170:173], v[92:95]
	v_mfma_f32_16x16x32_bf16 v[112:115], v[222:225], v[162:165], v[112:115]
	v_mfma_f32_16x16x32_bf16 v[116:119], v[218:221], v[166:169], v[116:119]
	v_mfma_f32_16x16x32_bf16 v[100:103], v[218:221], v[174:177], v[100:103]
	v_mfma_f32_16x16x32_bf16 v[76:79], v[218:221], v[182:185], v[76:79]
	v_mfma_f32_16x16x32_bf16 v[68:71], v[218:221], v[210:213], v[68:71]
	v_mfma_f32_16x16x32_bf16 v[64:67], v[226:229], v[210:213], v[64:67]
	v_mfma_f32_16x16x32_bf16 v[72:75], v[226:229], v[182:185], v[72:75]
	v_mfma_f32_16x16x32_bf16 v[92:95], v[226:229], v[174:177], v[92:95]
	v_mfma_f32_16x16x32_bf16 v[112:115], v[226:229], v[166:169], v[112:115]
	s_barrier
	s_add_i32 s6, s6, s57
	v_lshl_add_u64 v[230:231], v[230:231], 0, s[36:37]
	s_mov_b32 m0, s6
	s_nop 0
	global_load_lds_dwordx4 v[230:231], off
	v_lshl_add_u64 v[230:231], v[232:233], 0, s[36:37]
	s_add_i32 m0, s6, 0x2000
	s_nop 0
	global_load_lds_dwordx4 v[230:231], off
	s_mov_b32 m0, s70
	v_lshl_add_u64 v[230:231], v[234:235], 0, s[36:37]
	ds_read_b128 v[162:165], v208 offset:49152
	ds_read_b128 v[166:169], v208 offset:50176
	ds_read_b128 v[170:173], v208 offset:51200
	ds_read_b128 v[174:177], v208 offset:52224
	ds_read_b128 v[178:181], v208 offset:53248
	ds_read_b128 v[182:185], v208 offset:54272
	ds_read_b128 v[194:197], v208 offset:55296
	ds_read_b128 v[210:213], v208 offset:56320
	global_load_lds_dwordx4 v[230:231], off
	v_lshl_add_u64 v[230:231], v[236:237], 0, s[36:37]
	s_mov_b32 m0, s71
	s_nop 0
	global_load_lds_dwordx4 v[230:231], off
	s_add_u32 s48, s48, 0xb0080
	s_addc_u32 s49, s49, 0
	s_add_i32 s6, s19, s57
	v_lshl_add_u64 v[250:251], s[48:49], 0, v[140:141]
	s_mov_b32 m0, s6
	s_nop 0
	global_load_lds_dwordx4 v[250:251], off
	v_lshl_add_u64 v[250:251], s[48:49], 0, v[150:151]
	s_add_i32 m0, s6, 0x2000
	s_nop 0
	global_load_lds_dwordx4 v[250:251], off
	s_waitcnt vmcnt(8)
	s_waitcnt lgkmcnt(0)
	s_barrier
	v_mfma_f32_16x16x32_bf16 v[60:63], v[128:131], v[162:165], v[60:63]
	v_mfma_f32_16x16x32_bf16 v[48:51], v[128:131], v[170:173], v[48:51]
	v_mfma_f32_16x16x32_bf16 v[32:35], v[128:131], v[178:181], v[32:35]
	v_mfma_f32_16x16x32_bf16 v[16:19], v[128:131], v[194:197], v[16:19]
	v_mfma_f32_16x16x32_bf16 v[8:11], v[136:139], v[194:197], v[8:11]
	v_mfma_f32_16x16x32_bf16 v[24:27], v[136:139], v[178:181], v[24:27]
	v_mfma_f32_16x16x32_bf16 v[40:43], v[136:139], v[170:173], v[40:43]
	v_mfma_f32_16x16x32_bf16 v[56:59], v[136:139], v[162:165], v[56:59]
	v_mfma_f32_16x16x32_bf16 v[60:63], v[132:135], v[166:169], v[60:63]
	v_mfma_f32_16x16x32_bf16 v[48:51], v[132:135], v[174:177], v[48:51]
	v_mfma_f32_16x16x32_bf16 v[32:35], v[132:135], v[182:185], v[32:35]
	v_mfma_f32_16x16x32_bf16 v[16:19], v[132:135], v[210:213], v[16:19]
	v_mfma_f32_16x16x32_bf16 v[8:11], v[146:149], v[210:213], v[8:11]
	v_mfma_f32_16x16x32_bf16 v[24:27], v[146:149], v[182:185], v[24:27]
	v_mfma_f32_16x16x32_bf16 v[40:43], v[146:149], v[174:177], v[40:43]
	v_mfma_f32_16x16x32_bf16 v[56:59], v[146:149], v[166:169], v[56:59]
	v_mfma_f32_16x16x32_bf16 v[52:55], v[214:217], v[162:165], v[52:55]
	v_mfma_f32_16x16x32_bf16 v[36:39], v[214:217], v[170:173], v[36:39]
	v_mfma_f32_16x16x32_bf16 v[20:23], v[214:217], v[178:181], v[20:23]
	v_mfma_f32_16x16x32_bf16 v[4:7], v[214:217], v[194:197], v[4:7]
	v_mfma_f32_16x16x32_bf16 v[0:3], v[222:225], v[194:197], v[0:3]
	v_mfma_f32_16x16x32_bf16 v[12:15], v[222:225], v[178:181], v[12:15]
	v_mfma_f32_16x16x32_bf16 v[28:31], v[222:225], v[170:173], v[28:31]
	v_mfma_f32_16x16x32_bf16 v[44:47], v[222:225], v[162:165], v[44:47]
	v_mfma_f32_16x16x32_bf16 v[52:55], v[218:221], v[166:169], v[52:55]
	v_mfma_f32_16x16x32_bf16 v[36:39], v[218:221], v[174:177], v[36:39]
	v_mfma_f32_16x16x32_bf16 v[20:23], v[218:221], v[182:185], v[20:23]
	v_mfma_f32_16x16x32_bf16 v[4:7], v[218:221], v[210:213], v[4:7]
	v_mfma_f32_16x16x32_bf16 v[0:3], v[226:229], v[210:213], v[0:3]
	v_mfma_f32_16x16x32_bf16 v[12:15], v[226:229], v[182:185], v[12:15]
	v_mfma_f32_16x16x32_bf16 v[28:31], v[226:229], v[174:177], v[28:31]
	v_mfma_f32_16x16x32_bf16 v[44:47], v[226:229], v[166:169], v[44:47]
	s_add_i32 s12, s12, 2
	s_add_u32 s10, s10, 0x100
	s_addc_u32 s11, s11, 0
	s_cmp_gt_u32 s12, 41
	s_mov_b64 s[50:51], s[46:47]
	s_barrier
	s_cbranch_scc0 .LBB0_31
	s_mov_b32 s100, 1
	s_ashr_i32 s39, s38, 31
	v_lshl_or_b32 v128, s81, 8, v207
	s_lshl_b64 s[10:11], s[38:39], 8
	v_ashrrev_i32_e32 v129, 31, v128
	v_lshl_add_u64 v[168:169], s[10:11], 0, v[156:157]
	v_lshlrev_b64 v[170:171], 1, v[128:129]
	v_lshl_add_u64 v[174:175], s[4:5], 0, v[170:171]
	v_lshlrev_b64 v[172:173], 11, v[168:169]
	v_lshl_add_u64 v[128:129], v[174:175], 0, v[172:173]
	global_load_dwordx4 v[146:149], v[128:129], off
	global_load_dwordx4 v[182:185], v[128:129], off offset:256
	v_or_b32_e32 v166, 16, v168
	v_mov_b32_e32 v167, v169
	v_lshlrev_b64 v[176:177], 11, v[166:167]
	v_lshl_add_u64 v[128:129], v[174:175], 0, v[176:177]
	global_load_dwordx4 v[194:197], v[128:129], off
	global_load_dwordx4 v[210:213], v[128:129], off offset:256
	v_or_b32_e32 v164, 32, v168
	v_mov_b32_e32 v165, v169
	v_or_b32_e32 v162, 48, v168
	v_mov_b32_e32 v163, v169
	v_lshlrev_b64 v[180:181], 11, v[164:165]
	v_lshlrev_b64 v[178:179], 11, v[162:163]
	v_lshl_add_u64 v[128:129], v[174:175], 0, v[180:181]
	v_lshl_add_u64 v[130:131], v[174:175], 0, v[178:179]
	global_load_dwordx4 v[214:217], v[128:129], off
	global_load_dwordx4 v[136:139], v[128:129], off offset:256
	global_load_dwordx4 v[132:135], v[130:131], off
	s_nop 0
	global_load_dwordx4 v[128:131], v[130:131], off offset:256
	s_mov_b64 s[10:11], 0x90
	v_lshl_add_u64 v[172:173], s[28:29], 0, v[172:173]
	v_lshl_add_u64 v[172:173], v[172:173], 0, v[170:171]
	s_waitcnt vmcnt(0)
	v_lshlrev_b32_e32 v218, 16, v146
	v_and_b32_e32 v219, 0xffff0000, v146
	v_lshlrev_b32_e32 v220, 16, v148
	v_and_b32_e32 v221, 0xffff0000, v148
	v_lshlrev_b32_e32 v146, 16, v147
	v_and_b32_e32 v147, 0xffff0000, v147
	v_lshlrev_b32_e32 v222, 16, v182
	v_and_b32_e32 v223, 0xffff0000, v182
	v_lshlrev_b32_e32 v224, 16, v184
	v_and_b32_e32 v225, 0xffff0000, v184
	v_lshlrev_b32_e32 v182, 16, v183
	v_and_b32_e32 v183, 0xffff0000, v183
	v_pk_fma_f32 v[124:125], v[124:125], 0.5, v[218:219] op_sel_hi:[1,0,1]
	v_pk_fma_f32 v[120:121], v[120:121], 0.5, v[220:221] op_sel_hi:[1,0,1]
	v_pk_fma_f32 v[126:127], v[126:127], 0.5, v[146:147] op_sel_hi:[1,0,1]
	v_pk_fma_f32 v[116:117], v[116:117], 0.5, v[222:223] op_sel_hi:[1,0,1]
	v_pk_fma_f32 v[146:147], v[112:113], 0.5, v[224:225] op_sel_hi:[1,0,1]
	v_pk_fma_f32 v[118:119], v[118:119], 0.5, v[182:183] op_sel_hi:[1,0,1]
	v_pk_mul_f32 v[220:221], v[124:125], v[124:125]
	v_pk_mul_f32 v[222:223], v[126:127], v[126:127]
	v_cvt_pk_bf16_f32 v112, v124, v125
	v_cvt_pk_bf16_f32 v113, v126, v127
	v_pk_mul_f32 v[124:125], v[116:117], v[116:117]
	v_pk_mul_f32 v[126:127], v[118:119], v[118:119]
	v_pk_mul_f32 v[228:229], v[146:147], v[146:147]
	v_cvt_pk_bf16_f32 v116, v116, v117
	v_cvt_pk_bf16_f32 v117, v118, v119
	v_cvt_pk_bf16_f32 v118, v146, v147
	v_add_f32_e32 v146, v220, v221
	v_add_f32_e32 v146, v222, v146
	v_lshlrev_b32_e32 v148, 16, v149
	v_and_b32_e32 v149, 0xffff0000, v149
	v_pk_mul_f32 v[224:225], v[120:121], v[120:121]
	v_add_f32_e32 v146, v223, v146
	v_pk_fma_f32 v[122:123], v[122:123], 0.5, v[148:149] op_sel_hi:[1,0,1]
	v_add_f32_e32 v146, v224, v146
	v_pk_mul_f32 v[226:227], v[122:123], v[122:123]
	v_add_f32_e32 v146, v225, v146
	v_add_f32_e32 v146, v226, v146
	v_add_f32_e32 v146, v227, v146
	v_add_f32_e32 v124, v124, v146
	v_add_f32_e32 v124, v125, v124
	v_add_f32_e32 v124, v126, v124
	v_lshlrev_b32_e32 v184, 16, v185
	v_and_b32_e32 v185, 0xffff0000, v185
	v_add_f32_e32 v124, v127, v124
	v_pk_fma_f32 v[148:149], v[114:115], 0.5, v[184:185] op_sel_hi:[1,0,1]
	v_add_f32_e32 v124, v228, v124
	v_pk_mul_f32 v[230:231], v[148:149], v[148:149]
	v_add_f32_e32 v124, v229, v124
	v_add_f32_e32 v124, v230, v124
	v_add_f32_e32 v209, v231, v124
	v_lshlrev_b32_e32 v124, 16, v212
	v_and_b32_e32 v125, 0xffff0000, v212
	v_pk_fma_f32 v[124:125], v[92:93], 0.5, v[124:125] op_sel_hi:[1,0,1]
	v_lshlrev_b32_e32 v92, 16, v211
	v_and_b32_e32 v93, 0xffff0000, v211
	v_pk_fma_f32 v[102:103], v[102:103], 0.5, v[92:93] op_sel_hi:[1,0,1]
	v_lshlrev_b32_e32 v92, 16, v213
	v_and_b32_e32 v93, 0xffff0000, v213
	v_pk_fma_f32 v[126:127], v[94:95], 0.5, v[92:93] op_sel_hi:[1,0,1]
	v_lshlrev_b32_e32 v92, 16, v214
	v_and_b32_e32 v93, 0xffff0000, v214
	v_pk_fma_f32 v[92:93], v[96:97], 0.5, v[92:93] op_sel_hi:[1,0,1]
	v_lshlrev_b32_e32 v96, 16, v217
	v_and_b32_e32 v97, 0xffff0000, v217
	v_lshlrev_b32_e32 v94, 16, v216
	v_and_b32_e32 v95, 0xffff0000, v216
	v_pk_fma_f32 v[90:91], v[90:91], 0.5, v[96:97] op_sel_hi:[1,0,1]
	v_lshlrev_b32_e32 v96, 16, v136
	v_and_b32_e32 v97, 0xffff0000, v136
	v_lshlrev_b32_e32 v182, 16, v194
	v_and_b32_e32 v183, 0xffff0000, v194
	v_pk_fma_f32 v[88:89], v[88:89], 0.5, v[94:95] op_sel_hi:[1,0,1]
	v_lshlrev_b32_e32 v94, 16, v215
	v_and_b32_e32 v95, 0xffff0000, v215
	v_pk_fma_f32 v[96:97], v[76:77], 0.5, v[96:97] op_sel_hi:[1,0,1]
	v_lshl_add_u64 v[76:77], v[168:169], 0, s[36:37]
	v_lshlrev_b32_e32 v184, 16, v196
	v_and_b32_e32 v185, 0xffff0000, v196
	v_cvt_pk_bf16_f32 v114, v120, v121
	v_pk_fma_f32 v[120:121], v[108:109], 0.5, v[182:183] op_sel_hi:[1,0,1]
	v_pk_fma_f32 v[94:95], v[98:99], 0.5, v[94:95] op_sel_hi:[1,0,1]
	v_lshlrev_b64 v[182:183], 11, v[76:77]
	v_lshlrev_b32_e32 v98, 16, v138
	v_and_b32_e32 v99, 0xffff0000, v138
	v_pk_fma_f32 v[108:109], v[104:105], 0.5, v[184:185] op_sel_hi:[1,0,1]
	v_lshl_add_u64 v[184:185], v[174:175], 0, v[182:183]
	v_pk_fma_f32 v[98:99], v[72:73], 0.5, v[98:99] op_sel_hi:[1,0,1]
	v_lshlrev_b32_e32 v72, 16, v137
	v_and_b32_e32 v73, 0xffff0000, v137
	v_lshlrev_b32_e32 v218, 16, v210
	v_and_b32_e32 v219, 0xffff0000, v210
	global_load_dwordx4 v[210:213], v[184:185], off
	v_pk_fma_f32 v[136:137], v[78:79], 0.5, v[72:73] op_sel_hi:[1,0,1]
	v_lshlrev_b32_e32 v72, 16, v139
	v_and_b32_e32 v73, 0xffff0000, v139
	v_pk_fma_f32 v[138:139], v[74:75], 0.5, v[72:73] op_sel_hi:[1,0,1]
	v_lshlrev_b32_e32 v72, 16, v132
	v_and_b32_e32 v73, 0xffff0000, v132
	v_pk_fma_f32 v[74:75], v[84:85], 0.5, v[72:73] op_sel_hi:[1,0,1]
	v_lshlrev_b32_e32 v72, 16, v134
	v_and_b32_e32 v73, 0xffff0000, v134
	v_pk_fma_f32 v[78:79], v[80:81], 0.5, v[72:73] op_sel_hi:[1,0,1]
	v_lshlrev_b32_e32 v72, 16, v133
	v_and_b32_e32 v73, 0xffff0000, v133
	v_pk_fma_f32 v[100:101], v[100:101], 0.5, v[218:219] op_sel_hi:[1,0,1]
	global_load_dwordx4 v[218:221], v[184:185], off offset:256
	v_pk_fma_f32 v[80:81], v[86:87], 0.5, v[72:73] op_sel_hi:[1,0,1]
	v_lshlrev_b32_e32 v72, 16, v135
	v_and_b32_e32 v73, 0xffff0000, v135
	v_pk_fma_f32 v[82:83], v[82:83], 0.5, v[72:73] op_sel_hi:[1,0,1]
	v_lshl_add_u64 v[72:73], v[168:169], 0, s[10:11]
	v_lshlrev_b64 v[132:133], 11, v[72:73]
	v_lshl_add_u64 v[134:135], v[174:175], 0, v[132:133]
	v_lshlrev_b32_e32 v84, 16, v128
	v_and_b32_e32 v85, 0xffff0000, v128
	global_load_dwordx4 v[226:229], v[134:135], off
	global_load_dwordx4 v[234:237], v[134:135], off offset:256
	v_pk_fma_f32 v[84:85], v[68:69], 0.5, v[84:85] op_sel_hi:[1,0,1]
	v_lshlrev_b32_e32 v68, 16, v130
	v_and_b32_e32 v69, 0xffff0000, v130
	v_pk_fma_f32 v[86:87], v[64:65], 0.5, v[68:69] op_sel_hi:[1,0,1]
	v_lshlrev_b32_e32 v64, 16, v129
	v_and_b32_e32 v65, 0xffff0000, v129
	s_mov_b64 s[10:11], 0xa0
	v_pk_fma_f32 v[128:129], v[70:71], 0.5, v[64:65] op_sel_hi:[1,0,1]
	v_lshl_add_u64 v[70:71], v[168:169], 0, s[10:11]
	s_mov_b64 s[10:11], 0xb0
	v_lshlrev_b32_e32 v64, 16, v131
	v_and_b32_e32 v65, 0xffff0000, v131
	v_lshlrev_b64 v[134:135], 11, v[70:71]
	v_lshl_add_u64 v[68:69], v[168:169], 0, s[10:11]
	v_pk_fma_f32 v[130:131], v[66:67], 0.5, v[64:65] op_sel_hi:[1,0,1]
	v_lshl_add_u64 v[64:65], v[174:175], 0, v[134:135]
	v_lshlrev_b64 v[184:185], 11, v[68:69]
	global_load_dwordx4 v[238:241], v[64:65], off
	global_load_dwordx4 v[242:245], v[64:65], off offset:256
	v_lshl_add_u64 v[64:65], v[174:175], 0, v[184:185]
	global_load_dwordx4 v[246:249], v[64:65], off
	s_nop 0
	global_load_dwordx4 v[64:67], v[64:65], off offset:256
	v_lshlrev_b32_e32 v194, 16, v195
	v_and_b32_e32 v195, 0xffff0000, v195
	v_lshlrev_b32_e32 v196, 16, v197
	v_and_b32_e32 v197, 0xffff0000, v197
	v_cvt_pk_bf16_f32 v115, v122, v123
	v_cvt_pk_bf16_f32 v119, v148, v149
	v_pk_fma_f32 v[122:123], v[110:111], 0.5, v[194:195] op_sel_hi:[1,0,1]
	v_pk_fma_f32 v[110:111], v[106:107], 0.5, v[196:197] op_sel_hi:[1,0,1]
	global_store_dwordx4 v[172:173], v[112:115], off
	global_store_dwordx4 v[172:173], v[116:119], off offset:256
	v_cvt_pk_bf16_f32 v104, v120, v121
	v_lshl_add_u64 v[112:113], s[28:29], 0, v[176:177]
	v_cvt_pk_bf16_f32 v105, v122, v123
	v_cvt_pk_bf16_f32 v106, v108, v109
	v_cvt_pk_bf16_f32 v107, v110, v111
	v_lshl_add_u64 v[112:113], v[112:113], 0, v[170:171]
	v_cvt_pk_bf16_f32 v146, v100, v101
	v_cvt_pk_bf16_f32 v147, v102, v103
	v_cvt_pk_bf16_f32 v148, v124, v125
	v_cvt_pk_bf16_f32 v149, v126, v127
	global_store_dwordx4 v[112:113], v[104:107], off
	global_store_dwordx4 v[112:113], v[146:149], off offset:256
	v_cvt_pk_bf16_f32 v194, v92, v93
	v_lshl_add_u64 v[104:105], s[28:29], 0, v[180:181]
	v_cvt_pk_bf16_f32 v195, v94, v95
	v_cvt_pk_bf16_f32 v196, v88, v89
	v_cvt_pk_bf16_f32 v197, v90, v91
	v_lshl_add_u64 v[104:105], v[104:105], 0, v[170:171]
	v_cvt_pk_bf16_f32 v214, v96, v97
	v_cvt_pk_bf16_f32 v215, v136, v137
	v_cvt_pk_bf16_f32 v216, v98, v99
	v_cvt_pk_bf16_f32 v217, v138, v139
	global_store_dwordx4 v[104:105], v[194:197], off
	global_store_dwordx4 v[104:105], v[214:217], off offset:256
	v_lshl_add_u64 v[104:105], s[28:29], 0, v[178:179]
	v_cvt_pk_bf16_f32 v222, v74, v75
	v_cvt_pk_bf16_f32 v223, v80, v81
	v_cvt_pk_bf16_f32 v224, v78, v79
	v_cvt_pk_bf16_f32 v225, v82, v83
	v_lshl_add_u64 v[104:105], v[104:105], 0, v[170:171]
	v_cvt_pk_bf16_f32 v230, v84, v85
	v_cvt_pk_bf16_f32 v231, v128, v129
	v_cvt_pk_bf16_f32 v232, v86, v87
	v_cvt_pk_bf16_f32 v233, v130, v131
	global_store_dwordx4 v[104:105], v[222:225], off
	global_store_dwordx4 v[104:105], v[230:233], off offset:256
	s_waitcnt vmcnt(0)
	v_lshlrev_b32_e32 v104, 16, v210
	v_and_b32_e32 v105, 0xffff0000, v210
	v_pk_fma_f32 v[60:61], v[60:61], 0.5, v[104:105] op_sel_hi:[1,0,1]
	v_lshlrev_b32_e32 v104, 16, v212
	v_and_b32_e32 v105, 0xffff0000, v212
	v_pk_fma_f32 v[56:57], v[56:57], 0.5, v[104:105] op_sel_hi:[1,0,1]
	v_lshlrev_b32_e32 v104, 16, v211
	v_and_b32_e32 v105, 0xffff0000, v211
	v_pk_fma_f32 v[62:63], v[62:63], 0.5, v[104:105] op_sel_hi:[1,0,1]
	v_lshlrev_b32_e32 v104, 16, v213
	v_and_b32_e32 v105, 0xffff0000, v213
	v_pk_fma_f32 v[58:59], v[58:59], 0.5, v[104:105] op_sel_hi:[1,0,1]
	v_lshlrev_b32_e32 v104, 16, v218
	v_and_b32_e32 v105, 0xffff0000, v218
	v_pk_fma_f32 v[52:53], v[52:53], 0.5, v[104:105] op_sel_hi:[1,0,1]
	v_lshlrev_b32_e32 v104, 16, v220
	v_and_b32_e32 v105, 0xffff0000, v220
	v_pk_fma_f32 v[104:105], v[44:45], 0.5, v[104:105] op_sel_hi:[1,0,1]
	v_lshlrev_b32_e32 v44, 16, v219
	v_and_b32_e32 v45, 0xffff0000, v219
	v_pk_fma_f32 v[54:55], v[54:55], 0.5, v[44:45] op_sel_hi:[1,0,1]
	v_lshlrev_b32_e32 v44, 16, v221
	v_and_b32_e32 v45, 0xffff0000, v221
	v_pk_fma_f32 v[106:107], v[46:47], 0.5, v[44:45] op_sel_hi:[1,0,1]
	v_lshlrev_b32_e32 v44, 16, v226
	v_and_b32_e32 v45, 0xffff0000, v226
	v_pk_fma_f32 v[44:45], v[48:49], 0.5, v[44:45] op_sel_hi:[1,0,1]
	v_lshlrev_b32_e32 v48, 16, v229
	v_and_b32_e32 v49, 0xffff0000, v229
	v_pk_fma_f32 v[42:43], v[42:43], 0.5, v[48:49] op_sel_hi:[1,0,1]
	v_lshlrev_b32_e32 v48, 16, v234
	v_and_b32_e32 v49, 0xffff0000, v234
	v_pk_fma_f32 v[36:37], v[36:37], 0.5, v[48:49] op_sel_hi:[1,0,1]
	v_lshlrev_b32_e32 v48, 16, v236
	v_and_b32_e32 v49, 0xffff0000, v236
	v_lshlrev_b32_e32 v46, 16, v228
	v_and_b32_e32 v47, 0xffff0000, v228
	v_pk_fma_f32 v[48:49], v[28:29], 0.5, v[48:49] op_sel_hi:[1,0,1]
	v_lshlrev_b32_e32 v28, 16, v235
	v_and_b32_e32 v29, 0xffff0000, v235
	v_pk_fma_f32 v[40:41], v[40:41], 0.5, v[46:47] op_sel_hi:[1,0,1]
	v_lshlrev_b32_e32 v46, 16, v227
	v_and_b32_e32 v47, 0xffff0000, v227
	v_pk_fma_f32 v[38:39], v[38:39], 0.5, v[28:29] op_sel_hi:[1,0,1]
	v_lshlrev_b32_e32 v28, 16, v237
	v_and_b32_e32 v29, 0xffff0000, v237
	v_pk_fma_f32 v[46:47], v[50:51], 0.5, v[46:47] op_sel_hi:[1,0,1]
	v_pk_fma_f32 v[50:51], v[30:31], 0.5, v[28:29] op_sel_hi:[1,0,1]
	v_lshlrev_b32_e32 v28, 16, v238
	v_and_b32_e32 v29, 0xffff0000, v238
	v_lshlrev_b32_e32 v180, 16, v64
	v_and_b32_e32 v181, 0xffff0000, v64
	v_pk_fma_f32 v[28:29], v[32:33], 0.5, v[28:29] op_sel_hi:[1,0,1]
	v_lshlrev_b32_e32 v32, 16, v241
	v_and_b32_e32 v33, 0xffff0000, v241
	v_pk_fma_f32 v[4:5], v[4:5], 0.5, v[180:181] op_sel_hi:[1,0,1]
	v_lshlrev_b32_e32 v180, 16, v66
	v_and_b32_e32 v181, 0xffff0000, v66
	v_pk_fma_f32 v[26:27], v[26:27], 0.5, v[32:33] op_sel_hi:[1,0,1]
	v_lshlrev_b32_e32 v32, 16, v242
	v_and_b32_e32 v33, 0xffff0000, v242
	v_pk_fma_f32 v[0:1], v[0:1], 0.5, v[180:181] op_sel_hi:[1,0,1]
	v_lshl_add_u64 v[180:181], s[28:29], 0, v[182:183]
	v_cvt_pk_bf16_f32 v112, v60, v61
	v_cvt_pk_bf16_f32 v113, v62, v63
	v_cvt_pk_bf16_f32 v114, v56, v57
	v_cvt_pk_bf16_f32 v115, v58, v59
	v_pk_fma_f32 v[20:21], v[20:21], 0.5, v[32:33] op_sel_hi:[1,0,1]
	v_lshlrev_b32_e32 v32, 16, v244
	v_and_b32_e32 v33, 0xffff0000, v244
	v_lshl_add_u64 v[180:181], v[180:181], 0, v[170:171]
	v_cvt_pk_bf16_f32 v116, v52, v53
	v_cvt_pk_bf16_f32 v117, v54, v55
	v_cvt_pk_bf16_f32 v118, v104, v105
	v_cvt_pk_bf16_f32 v119, v106, v107
	v_lshlrev_b32_e32 v30, 16, v240
	v_and_b32_e32 v31, 0xffff0000, v240
	v_pk_fma_f32 v[32:33], v[12:13], 0.5, v[32:33] op_sel_hi:[1,0,1]
	v_lshlrev_b32_e32 v12, 16, v243
	v_and_b32_e32 v13, 0xffff0000, v243
	global_store_dwordx4 v[180:181], v[112:115], off
	global_store_dwordx4 v[180:181], v[116:119], off offset:256
	v_cvt_pk_bf16_f32 v146, v44, v45
	v_lshl_add_u64 v[112:113], s[28:29], 0, v[132:133]
	v_cvt_pk_bf16_f32 v147, v46, v47
	v_cvt_pk_bf16_f32 v148, v40, v41
	v_cvt_pk_bf16_f32 v149, v42, v43
	v_pk_fma_f32 v[24:25], v[24:25], 0.5, v[30:31] op_sel_hi:[1,0,1]
	v_lshlrev_b32_e32 v30, 16, v239
	v_and_b32_e32 v31, 0xffff0000, v239
	v_pk_fma_f32 v[22:23], v[22:23], 0.5, v[12:13] op_sel_hi:[1,0,1]
	v_lshlrev_b32_e32 v12, 16, v245
	v_and_b32_e32 v13, 0xffff0000, v245
	v_lshl_add_u64 v[112:113], v[112:113], 0, v[170:171]
	v_cvt_pk_bf16_f32 v172, v36, v37
	v_cvt_pk_bf16_f32 v173, v38, v39
	v_cvt_pk_bf16_f32 v174, v48, v49
	v_cvt_pk_bf16_f32 v175, v50, v51
	v_pk_fma_f32 v[30:31], v[34:35], 0.5, v[30:31] op_sel_hi:[1,0,1]
	v_pk_fma_f32 v[34:35], v[14:15], 0.5, v[12:13] op_sel_hi:[1,0,1]
	v_lshlrev_b32_e32 v12, 16, v246
	v_and_b32_e32 v13, 0xffff0000, v246
	v_lshlrev_b32_e32 v14, 16, v248
	v_and_b32_e32 v15, 0xffff0000, v248
	global_store_dwordx4 v[112:113], v[146:149], off
	global_store_dwordx4 v[112:113], v[172:175], off offset:256
	v_lshl_add_u64 v[112:113], s[28:29], 0, v[134:135]
	v_cvt_pk_bf16_f32 v176, v28, v29
	v_cvt_pk_bf16_f32 v177, v30, v31
	v_cvt_pk_bf16_f32 v178, v24, v25
	v_cvt_pk_bf16_f32 v179, v26, v27
	v_pk_fma_f32 v[12:13], v[16:17], 0.5, v[12:13] op_sel_hi:[1,0,1]
	v_pk_fma_f32 v[8:9], v[8:9], 0.5, v[14:15] op_sel_hi:[1,0,1]
	v_lshlrev_b32_e32 v14, 16, v247
	v_and_b32_e32 v15, 0xffff0000, v247
	v_lshlrev_b32_e32 v16, 16, v249
	v_and_b32_e32 v17, 0xffff0000, v249
	v_lshlrev_b32_e32 v64, 16, v65
	v_and_b32_e32 v65, 0xffff0000, v65
	v_lshl_add_u64 v[112:113], v[112:113], 0, v[170:171]
	v_cvt_pk_bf16_f32 v194, v20, v21
	v_cvt_pk_bf16_f32 v195, v22, v23
	v_cvt_pk_bf16_f32 v196, v32, v33
	v_cvt_pk_bf16_f32 v197, v34, v35
	v_pk_fma_f32 v[14:15], v[18:19], 0.5, v[14:15] op_sel_hi:[1,0,1]
	v_pk_fma_f32 v[10:11], v[10:11], 0.5, v[16:17] op_sel_hi:[1,0,1]
	v_pk_fma_f32 v[6:7], v[6:7], 0.5, v[64:65] op_sel_hi:[1,0,1]
	v_lshlrev_b32_e32 v64, 16, v67
	v_and_b32_e32 v65, 0xffff0000, v67
	global_store_dwordx4 v[112:113], v[176:179], off
	global_store_dwordx4 v[112:113], v[194:197], off offset:256
	v_lshl_add_u64 v[112:113], s[28:29], 0, v[184:185]
	v_cvt_pk_bf16_f32 v16, v12, v13
	v_cvt_pk_bf16_f32 v17, v14, v15
	v_cvt_pk_bf16_f32 v18, v8, v9
	v_cvt_pk_bf16_f32 v19, v10, v11
	v_pk_fma_f32 v[2:3], v[2:3], 0.5, v[64:65] op_sel_hi:[1,0,1]
	v_lshl_add_u64 v[112:113], v[112:113], 0, v[170:171]
	v_cvt_pk_bf16_f32 v64, v4, v5
	v_cvt_pk_bf16_f32 v65, v6, v7
	v_cvt_pk_bf16_f32 v66, v0, v1
	v_cvt_pk_bf16_f32 v67, v2, v3
	global_store_dwordx4 v[112:113], v[16:19], off
	global_store_dwordx4 v[112:113], v[64:67], off offset:256
	s_lshl_b32 s10, s81, 2
	v_and_b32_e32 v17, 64, v188
	v_xor_b32_e32 v16, 16, v188
	v_add_u32_e32 v17, 64, v17
	v_cmp_lt_i32_e32 vcc, v16, v17
	v_xor_b32_e32 v18, 32, v188
	s_ashr_i32 s11, s10, 31
	v_cndmask_b32_e32 v16, v188, v16, vcc
	v_lshlrev_b32_e32 v16, 2, v16
	ds_bpermute_b32 v19, v16, v209
	v_cmp_lt_i32_e32 vcc, v18, v17
	s_lshl_b64 s[10:11], s[10:11], 2
	s_add_u32 s38, s73, s10
	v_cndmask_b32_e32 v17, v188, v18, vcc
	v_lshlrev_b32_e32 v17, 2, v17
	s_waitcnt lgkmcnt(0)
	v_add_f32_e32 v18, v209, v19
	ds_bpermute_b32 v19, v17, v18
	s_addc_u32 s39, s74, s11
	s_and_saveexec_b64 s[46:47], s[42:43]
	s_cbranch_execz .LBB0_34
	s_waitcnt lgkmcnt(0)
	v_add_f32_e32 v64, v18, v19
	v_lshlrev_b64 v[18:19], 6, v[168:169]
	v_lshl_add_u64 v[18:19], s[38:39], 0, v[18:19]
	global_store_dword v[18:19], v64, off

.Lm4ap_77:
	s_waitcnt lgkmcnt(0)
	s_barrier
	s_nop 0
	v_mfma_f32_16x16x32_bf16 v[124:127], v[158:161], v[174:177], 0
	v_mfma_f32_16x16x32_bf16 v[116:119], v[158:161], v[182:185], 0
	v_mfma_f32_16x16x32_bf16 v[108:111], v[158:161], v[210:213], 0
	v_mfma_f32_16x16x32_bf16 v[100:103], v[158:161], v[218:221], 0
	v_mfma_f32_16x16x32_bf16 v[96:99], v[166:169], v[218:221], 0
	v_mfma_f32_16x16x32_bf16 v[104:107], v[166:169], v[210:213], 0
	v_mfma_f32_16x16x32_bf16 v[112:115], v[166:169], v[182:185], 0
	v_mfma_f32_16x16x32_bf16 v[120:123], v[166:169], v[174:177], 0
	v_mfma_f32_16x16x32_bf16 v[124:127], v[162:165], v[178:181], v[124:127]
	v_mfma_f32_16x16x32_bf16 v[116:119], v[162:165], v[206:209], v[116:119]
	v_mfma_f32_16x16x32_bf16 v[108:111], v[162:165], v[214:217], v[108:111]
	v_mfma_f32_16x16x32_bf16 v[100:103], v[162:165], v[222:225], v[100:103]
	v_mfma_f32_16x16x32_bf16 v[96:99], v[170:173], v[222:225], v[96:99]
	v_mfma_f32_16x16x32_bf16 v[104:107], v[170:173], v[214:217], v[104:107]
	v_mfma_f32_16x16x32_bf16 v[112:115], v[170:173], v[206:209], v[112:115]
	v_mfma_f32_16x16x32_bf16 v[120:123], v[170:173], v[178:181], v[120:123]
	v_mfma_f32_16x16x32_bf16 v[92:95], v[226:229], v[174:177], 0
	v_mfma_f32_16x16x32_bf16 v[84:87], v[226:229], v[182:185], 0
	v_mfma_f32_16x16x32_bf16 v[76:79], v[226:229], v[210:213], 0
	v_mfma_f32_16x16x32_bf16 v[68:71], v[226:229], v[218:221], 0
	v_mfma_f32_16x16x32_bf16 v[64:67], v[234:237], v[218:221], 0
	v_mfma_f32_16x16x32_bf16 v[72:75], v[234:237], v[210:213], 0
	v_mfma_f32_16x16x32_bf16 v[80:83], v[234:237], v[182:185], 0
	v_mfma_f32_16x16x32_bf16 v[88:91], v[234:237], v[174:177], 0
	v_mfma_f32_16x16x32_bf16 v[92:95], v[230:233], v[178:181], v[92:95]
	v_mfma_f32_16x16x32_bf16 v[84:87], v[230:233], v[206:209], v[84:87]
	v_mfma_f32_16x16x32_bf16 v[76:79], v[230:233], v[214:217], v[76:79]
	v_mfma_f32_16x16x32_bf16 v[68:71], v[230:233], v[222:225], v[68:71]
	v_mfma_f32_16x16x32_bf16 v[64:67], v[238:241], v[222:225], v[64:67]
	v_mfma_f32_16x16x32_bf16 v[72:75], v[238:241], v[214:217], v[72:75]
	v_mfma_f32_16x16x32_bf16 v[80:83], v[238:241], v[206:209], v[80:83]
	v_mfma_f32_16x16x32_bf16 v[88:91], v[238:241], v[178:181], v[88:91]
	s_barrier
	s_add_i32 s19, s82, s59
	v_lshl_add_u64 v[146:147], s[52:53], 0, v[140:141]
	s_mov_b32 m0, s19
	v_lshl_add_u64 v[148:149], s[52:53], 0, v[132:133]
	global_load_lds_dwordx4 v[146:147], off
	s_add_i32 m0, s19, 0x2000
	s_nop 0
	global_load_lds_dwordx4 v[148:149], off
	s_mov_b32 m0, s68
	v_lshl_add_u64 v[194:195], s[54:55], 0, v[128:129]
	ds_read_b128 v[174:177], v157 offset:16384
	ds_read_b128 v[178:181], v157 offset:17408
	ds_read_b128 v[182:185], v157 offset:18432
	ds_read_b128 v[206:209], v157 offset:19456
	ds_read_b128 v[210:213], v157 offset:20480
	ds_read_b128 v[214:217], v157 offset:21504
	ds_read_b128 v[218:221], v157 offset:22528
	ds_read_b128 v[222:225], v157 offset:23552
	global_load_lds_dwordx4 v[194:195], off
	v_lshl_add_u64 v[196:197], s[54:55], 0, v[130:131]
	s_mov_b32 m0, s69
	s_nop 0
	global_load_lds_dwordx4 v[196:197], off
	s_add_u32 s82, s52, 0x40000
	s_addc_u32 s83, s53, 0
	s_add_i32 s6, s6, s59
	v_lshl_add_u64 v[250:251], s[82:83], 0, v[140:141]
	s_mov_b32 m0, s6
	s_nop 0
	global_load_lds_dwordx4 v[250:251], off
	v_lshl_add_u64 v[250:251], s[82:83], 0, v[132:133]
	s_add_i32 m0, s6, 0x2000
	s_nop 0
	global_load_lds_dwordx4 v[250:251], off
	s_waitcnt vmcnt(16)
	s_cmp_lg_u32 s100, 0
	s_cbranch_scc1 .Lm4bp_77
	s_waitcnt vmcnt(8)
.Lm4bp_77:
	s_waitcnt lgkmcnt(0)
	s_mov_b32 s100, 0
	s_barrier
	s_nop 0
	v_mfma_f32_16x16x32_bf16 v[60:63], v[158:161], v[174:177], 0
	v_mfma_f32_16x16x32_bf16 v[52:55], v[158:161], v[182:185], 0
	v_mfma_f32_16x16x32_bf16 v[44:47], v[158:161], v[210:213], 0
	v_mfma_f32_16x16x32_bf16 v[36:39], v[158:161], v[218:221], 0
	v_mfma_f32_16x16x32_bf16 v[32:35], v[166:169], v[218:221], 0
	v_mfma_f32_16x16x32_bf16 v[40:43], v[166:169], v[210:213], 0
	v_mfma_f32_16x16x32_bf16 v[48:51], v[166:169], v[182:185], 0
	v_mfma_f32_16x16x32_bf16 v[56:59], v[166:169], v[174:177], 0
	v_mfma_f32_16x16x32_bf16 v[60:63], v[162:165], v[178:181], v[60:63]
	v_mfma_f32_16x16x32_bf16 v[52:55], v[162:165], v[206:209], v[52:55]
	v_mfma_f32_16x16x32_bf16 v[44:47], v[162:165], v[214:217], v[44:47]
	v_mfma_f32_16x16x32_bf16 v[36:39], v[162:165], v[222:225], v[36:39]
	v_mfma_f32_16x16x32_bf16 v[32:35], v[170:173], v[222:225], v[32:35]
	v_mfma_f32_16x16x32_bf16 v[40:43], v[170:173], v[214:217], v[40:43]
	v_mfma_f32_16x16x32_bf16 v[48:51], v[170:173], v[206:209], v[48:51]
	v_mfma_f32_16x16x32_bf16 v[56:59], v[170:173], v[178:181], v[56:59]
	v_mfma_f32_16x16x32_bf16 v[28:31], v[226:229], v[174:177], 0
	v_mfma_f32_16x16x32_bf16 v[20:23], v[226:229], v[182:185], 0
	v_mfma_f32_16x16x32_bf16 v[12:15], v[226:229], v[210:213], 0
	v_mfma_f32_16x16x32_bf16 v[4:7], v[226:229], v[218:221], 0
	v_mfma_f32_16x16x32_bf16 v[0:3], v[234:237], v[218:221], 0
	v_mfma_f32_16x16x32_bf16 v[8:11], v[234:237], v[210:213], 0
	v_mfma_f32_16x16x32_bf16 v[16:19], v[234:237], v[182:185], 0
	v_mfma_f32_16x16x32_bf16 v[24:27], v[234:237], v[174:177], 0
	v_mfma_f32_16x16x32_bf16 v[28:31], v[230:233], v[178:181], v[28:31]
	v_mfma_f32_16x16x32_bf16 v[20:23], v[230:233], v[206:209], v[20:23]
	v_mfma_f32_16x16x32_bf16 v[12:15], v[230:233], v[214:217], v[12:15]
	v_mfma_f32_16x16x32_bf16 v[4:7], v[230:233], v[222:225], v[4:7]
	v_mfma_f32_16x16x32_bf16 v[0:3], v[238:241], v[222:225], v[0:3]
	v_mfma_f32_16x16x32_bf16 v[8:11], v[238:241], v[214:217], v[8:11]
	v_mfma_f32_16x16x32_bf16 v[16:19], v[238:241], v[206:209], v[16:19]
	v_mfma_f32_16x16x32_bf16 v[24:27], v[238:241], v[178:181], v[24:27]
	s_barrier
	s_add_i32 s6, 0, 0x18000
	v_add_u32_e32 v170, s6, v154
	ds_read_b128 v[158:161], v170
	ds_read_b128 v[162:165], v170 offset:1024
	ds_read_b128 v[166:169], v170 offset:2048
	ds_read_b128 v[170:173], v170 offset:3072
	s_add_u32 s54, s54, 0x40000
	s_addc_u32 s55, s55, 0
	s_mov_b32 m0, s70
	v_lshl_add_u64 v[226:227], s[54:55], 0, v[128:129]
	ds_read_b128 v[174:177], v157 offset:32768
	ds_read_b128 v[178:181], v157 offset:33792
	ds_read_b128 v[182:185], v157 offset:34816
	ds_read_b128 v[206:209], v157 offset:35840
	ds_read_b128 v[210:213], v157 offset:36864
	ds_read_b128 v[214:217], v157 offset:37888
	ds_read_b128 v[218:221], v157 offset:38912
	ds_read_b128 v[222:225], v157 offset:39936
	global_load_lds_dwordx4 v[226:227], off
	v_lshl_add_u64 v[226:227], s[54:55], 0, v[130:131]
	s_mov_b32 m0, s71
	s_nop 0
	global_load_lds_dwordx4 v[226:227], off
	s_add_i32 s19, 0, 0x1c000
	v_add_u32_e32 v192, s19, v154
	ds_read_b128 v[226:229], v192
	ds_read_b128 v[230:233], v192 offset:1024
	ds_read_b128 v[234:237], v192 offset:2048
	ds_read_b128 v[238:241], v192 offset:3072
	s_waitcnt vmcnt(8)
	s_waitcnt lgkmcnt(0)
	s_barrier
	v_mfma_f32_16x16x32_bf16 v[124:127], v[158:161], v[174:177], v[124:127]
	v_mfma_f32_16x16x32_bf16 v[116:119], v[158:161], v[182:185], v[116:119]
	v_mfma_f32_16x16x32_bf16 v[108:111], v[158:161], v[210:213], v[108:111]
	v_mfma_f32_16x16x32_bf16 v[100:103], v[158:161], v[218:221], v[100:103]
	v_mfma_f32_16x16x32_bf16 v[96:99], v[166:169], v[218:221], v[96:99]
	v_mfma_f32_16x16x32_bf16 v[104:107], v[166:169], v[210:213], v[104:107]
	v_mfma_f32_16x16x32_bf16 v[112:115], v[166:169], v[182:185], v[112:115]
	v_mfma_f32_16x16x32_bf16 v[120:123], v[166:169], v[174:177], v[120:123]
	v_mfma_f32_16x16x32_bf16 v[124:127], v[162:165], v[178:181], v[124:127]
	v_mfma_f32_16x16x32_bf16 v[116:119], v[162:165], v[206:209], v[116:119]
	v_mfma_f32_16x16x32_bf16 v[108:111], v[162:165], v[214:217], v[108:111]
	v_mfma_f32_16x16x32_bf16 v[100:103], v[162:165], v[222:225], v[100:103]
	v_mfma_f32_16x16x32_bf16 v[96:99], v[170:173], v[222:225], v[96:99]
	v_mfma_f32_16x16x32_bf16 v[104:107], v[170:173], v[214:217], v[104:107]
	v_mfma_f32_16x16x32_bf16 v[112:115], v[170:173], v[206:209], v[112:115]
	v_mfma_f32_16x16x32_bf16 v[120:123], v[170:173], v[178:181], v[120:123]
	v_mfma_f32_16x16x32_bf16 v[92:95], v[226:229], v[174:177], v[92:95]
	v_mfma_f32_16x16x32_bf16 v[84:87], v[226:229], v[182:185], v[84:87]
	v_mfma_f32_16x16x32_bf16 v[76:79], v[226:229], v[210:213], v[76:79]
	v_mfma_f32_16x16x32_bf16 v[68:71], v[226:229], v[218:221], v[68:71]
	v_mfma_f32_16x16x32_bf16 v[64:67], v[234:237], v[218:221], v[64:67]
	v_mfma_f32_16x16x32_bf16 v[72:75], v[234:237], v[210:213], v[72:75]
	v_mfma_f32_16x16x32_bf16 v[80:83], v[234:237], v[182:185], v[80:83]
	v_mfma_f32_16x16x32_bf16 v[88:91], v[234:237], v[174:177], v[88:91]
	v_mfma_f32_16x16x32_bf16 v[92:95], v[230:233], v[178:181], v[92:95]
	v_mfma_f32_16x16x32_bf16 v[84:87], v[230:233], v[206:209], v[84:87]
	v_mfma_f32_16x16x32_bf16 v[76:79], v[230:233], v[214:217], v[76:79]
	v_mfma_f32_16x16x32_bf16 v[68:71], v[230:233], v[222:225], v[68:71]
	v_mfma_f32_16x16x32_bf16 v[64:67], v[238:241], v[222:225], v[64:67]
	v_mfma_f32_16x16x32_bf16 v[72:75], v[238:241], v[214:217], v[72:75]
	v_mfma_f32_16x16x32_bf16 v[80:83], v[238:241], v[206:209], v[80:83]
	v_mfma_f32_16x16x32_bf16 v[88:91], v[238:241], v[178:181], v[88:91]
	s_barrier
	s_add_i32 s6, s6, s59
	v_lshl_add_u64 v[146:147], v[146:147], 0, s[36:37]
	s_mov_b32 m0, s6
	s_nop 0
	global_load_lds_dwordx4 v[146:147], off
	v_lshl_add_u64 v[146:147], v[148:149], 0, s[36:37]
	s_add_i32 m0, s6, 0x2000
	s_nop 0
	global_load_lds_dwordx4 v[146:147], off
	s_mov_b32 m0, s72
	v_lshl_add_u64 v[146:147], v[194:195], 0, s[36:37]
	ds_read_b128 v[174:177], v157 offset:49152
	ds_read_b128 v[178:181], v157 offset:50176
	ds_read_b128 v[182:185], v157 offset:51200
	ds_read_b128 v[206:209], v157 offset:52224
	ds_read_b128 v[210:213], v157 offset:53248
	ds_read_b128 v[214:217], v157 offset:54272
	ds_read_b128 v[218:221], v157 offset:55296
	ds_read_b128 v[222:225], v157 offset:56320
	global_load_lds_dwordx4 v[146:147], off
	v_lshl_add_u64 v[146:147], v[196:197], 0, s[36:37]
	s_mov_b32 m0, s73
	s_nop 0
	global_load_lds_dwordx4 v[146:147], off
	s_add_u32 s52, s52, 0x40080
	s_addc_u32 s53, s53, 0
	s_add_i32 s6, s19, s59
	v_lshl_add_u64 v[146:147], s[52:53], 0, v[140:141]
	s_mov_b32 m0, s6
	s_nop 0
	global_load_lds_dwordx4 v[146:147], off
	v_lshl_add_u64 v[146:147], s[52:53], 0, v[132:133]
	s_add_i32 m0, s6, 0x2000
	s_nop 0
	global_load_lds_dwordx4 v[146:147], off
	s_waitcnt vmcnt(8)
	s_waitcnt lgkmcnt(0)
	s_barrier
	v_mfma_f32_16x16x32_bf16 v[60:63], v[158:161], v[174:177], v[60:63]
	v_mfma_f32_16x16x32_bf16 v[52:55], v[158:161], v[182:185], v[52:55]
	v_mfma_f32_16x16x32_bf16 v[44:47], v[158:161], v[210:213], v[44:47]
	v_mfma_f32_16x16x32_bf16 v[36:39], v[158:161], v[218:221], v[36:39]
	v_mfma_f32_16x16x32_bf16 v[32:35], v[166:169], v[218:221], v[32:35]
	v_mfma_f32_16x16x32_bf16 v[40:43], v[166:169], v[210:213], v[40:43]
	v_mfma_f32_16x16x32_bf16 v[48:51], v[166:169], v[182:185], v[48:51]
	v_mfma_f32_16x16x32_bf16 v[56:59], v[166:169], v[174:177], v[56:59]
	v_mfma_f32_16x16x32_bf16 v[60:63], v[162:165], v[178:181], v[60:63]
	v_mfma_f32_16x16x32_bf16 v[52:55], v[162:165], v[206:209], v[52:55]
	v_mfma_f32_16x16x32_bf16 v[44:47], v[162:165], v[214:217], v[44:47]
	v_mfma_f32_16x16x32_bf16 v[36:39], v[162:165], v[222:225], v[36:39]
	v_mfma_f32_16x16x32_bf16 v[32:35], v[170:173], v[222:225], v[32:35]
	v_mfma_f32_16x16x32_bf16 v[40:43], v[170:173], v[214:217], v[40:43]
	v_mfma_f32_16x16x32_bf16 v[48:51], v[170:173], v[206:209], v[48:51]
	v_mfma_f32_16x16x32_bf16 v[56:59], v[170:173], v[178:181], v[56:59]
	v_mfma_f32_16x16x32_bf16 v[28:31], v[226:229], v[174:177], v[28:31]
	v_mfma_f32_16x16x32_bf16 v[20:23], v[226:229], v[182:185], v[20:23]
	v_mfma_f32_16x16x32_bf16 v[12:15], v[226:229], v[210:213], v[12:15]
	v_mfma_f32_16x16x32_bf16 v[4:7], v[226:229], v[218:221], v[4:7]
	v_mfma_f32_16x16x32_bf16 v[0:3], v[234:237], v[218:221], v[0:3]
	v_mfma_f32_16x16x32_bf16 v[8:11], v[234:237], v[210:213], v[8:11]
	v_mfma_f32_16x16x32_bf16 v[16:19], v[234:237], v[182:185], v[16:19]
	v_mfma_f32_16x16x32_bf16 v[24:27], v[234:237], v[174:177], v[24:27]
	v_mfma_f32_16x16x32_bf16 v[28:31], v[230:233], v[178:181], v[28:31]
	v_mfma_f32_16x16x32_bf16 v[20:23], v[230:233], v[206:209], v[20:23]
	v_mfma_f32_16x16x32_bf16 v[12:15], v[230:233], v[214:217], v[12:15]
	v_mfma_f32_16x16x32_bf16 v[4:7], v[230:233], v[222:225], v[4:7]
	v_mfma_f32_16x16x32_bf16 v[0:3], v[238:241], v[222:225], v[0:3]
	v_mfma_f32_16x16x32_bf16 v[8:11], v[238:241], v[214:217], v[8:11]
	v_mfma_f32_16x16x32_bf16 v[16:19], v[238:241], v[206:209], v[16:19]
	v_mfma_f32_16x16x32_bf16 v[24:27], v[238:241], v[178:181], v[24:27]
	s_add_i32 s81, s81, 2
	s_add_u32 s50, s50, 0x100
	s_addc_u32 s51, s51, 0
	s_cmp_gt_u32 s81, 13
	s_barrier
.LBB0_77:
	s_add_u32 s6, s26, s50
	s_addc_u32 s19, s27, s51
	s_add_u32 s6, s6, 0x100
	s_addc_u32 s19, s19, 0
	s_add_u32 s23, s10, s50
	s_addc_u32 s52, s11, s51
	s_add_i32 s82, 0, 0x10000
	v_add_u32_e32 v146, s82, v154
	ds_read_b128 v[158:161], v146
	ds_read_b128 v[162:165], v146 offset:1024
	ds_read_b128 v[166:169], v146 offset:2048
	ds_read_b128 v[170:173], v146 offset:3072
	s_cmpk_eq_i32 s50, 0x700
	s_cselect_b32 s55, s12, s19
	s_cselect_b32 s54, s31, s6
	s_cselect_b32 s53, s35, s52
	s_cselect_b32 s52, s39, s23
	v_lshl_add_u64 v[146:147], v[150:151], 0, s[50:51]
	s_add_i32 m0, s68, 0xc000
	ds_read_b128 v[174:177], v157
	ds_read_b128 v[178:181], v157 offset:1024
	ds_read_b128 v[182:185], v157 offset:2048
	ds_read_b128 v[206:209], v157 offset:3072
	ds_read_b128 v[210:213], v157 offset:4096
	ds_read_b128 v[214:217], v157 offset:5120
	ds_read_b128 v[218:221], v157 offset:6144
	ds_read_b128 v[222:225], v157 offset:7168
	global_load_lds_dwordx4 v[146:147], off
	v_lshl_add_u64 v[146:147], v[152:153], 0, s[50:51]
	s_add_i32 m0, s68, 0xe000
	s_nop 0
	global_load_lds_dwordx4 v[146:147], off
	s_add_i32 s6, 0, 0x14000
	v_add_u32_e32 v146, s6, v154
	ds_read_b128 v[226:229], v146
	ds_read_b128 v[230:233], v146 offset:1024
	ds_read_b128 v[234:237], v146 offset:2048
	ds_read_b128 v[238:241], v146 offset:3072
	s_waitcnt vmcnt(8)
	s_waitcnt lgkmcnt(0)
	s_barrier
	v_mfma_f32_16x16x32_bf16 v[124:127], v[158:161], v[174:177], v[124:127]
	v_mfma_f32_16x16x32_bf16 v[116:119], v[158:161], v[182:185], v[116:119]
	v_mfma_f32_16x16x32_bf16 v[108:111], v[158:161], v[210:213], v[108:111]
	v_mfma_f32_16x16x32_bf16 v[100:103], v[158:161], v[218:221], v[100:103]
	v_mfma_f32_16x16x32_bf16 v[96:99], v[166:169], v[218:221], v[96:99]
	v_mfma_f32_16x16x32_bf16 v[104:107], v[166:169], v[210:213], v[104:107]
	v_mfma_f32_16x16x32_bf16 v[112:115], v[166:169], v[182:185], v[112:115]
	v_mfma_f32_16x16x32_bf16 v[120:123], v[166:169], v[174:177], v[120:123]
	v_mfma_f32_16x16x32_bf16 v[124:127], v[162:165], v[178:181], v[124:127]
	v_mfma_f32_16x16x32_bf16 v[116:119], v[162:165], v[206:209], v[116:119]
	v_mfma_f32_16x16x32_bf16 v[108:111], v[162:165], v[214:217], v[108:111]
	v_mfma_f32_16x16x32_bf16 v[100:103], v[162:165], v[222:225], v[100:103]
	v_mfma_f32_16x16x32_bf16 v[96:99], v[170:173], v[222:225], v[96:99]
	v_mfma_f32_16x16x32_bf16 v[104:107], v[170:173], v[214:217], v[104:107]
	v_mfma_f32_16x16x32_bf16 v[112:115], v[170:173], v[206:209], v[112:115]
	v_mfma_f32_16x16x32_bf16 v[120:123], v[170:173], v[178:181], v[120:123]
	v_mfma_f32_16x16x32_bf16 v[92:95], v[226:229], v[174:177], v[92:95]
	v_mfma_f32_16x16x32_bf16 v[84:87], v[226:229], v[182:185], v[84:87]
	v_mfma_f32_16x16x32_bf16 v[76:79], v[226:229], v[210:213], v[76:79]
	v_mfma_f32_16x16x32_bf16 v[68:71], v[226:229], v[218:221], v[68:71]
	v_mfma_f32_16x16x32_bf16 v[64:67], v[234:237], v[218:221], v[64:67]
	v_mfma_f32_16x16x32_bf16 v[72:75], v[234:237], v[210:213], v[72:75]
	v_mfma_f32_16x16x32_bf16 v[80:83], v[234:237], v[182:185], v[80:83]
	v_mfma_f32_16x16x32_bf16 v[88:91], v[234:237], v[174:177], v[88:91]
	v_mfma_f32_16x16x32_bf16 v[92:95], v[230:233], v[178:181], v[92:95]
	v_mfma_f32_16x16x32_bf16 v[84:87], v[230:233], v[206:209], v[84:87]
	v_mfma_f32_16x16x32_bf16 v[76:79], v[230:233], v[214:217], v[76:79]
	v_mfma_f32_16x16x32_bf16 v[68:71], v[230:233], v[222:225], v[68:71]
	v_mfma_f32_16x16x32_bf16 v[64:67], v[238:241], v[222:225], v[64:67]
	v_mfma_f32_16x16x32_bf16 v[72:75], v[238:241], v[214:217], v[72:75]
	v_mfma_f32_16x16x32_bf16 v[80:83], v[238:241], v[206:209], v[80:83]
	v_mfma_f32_16x16x32_bf16 v[88:91], v[238:241], v[178:181], v[88:91]
	s_barrier
	s_add_i32 s19, s82, s59
	v_lshl_add_u64 v[146:147], s[52:53], 0, v[140:141]
	s_mov_b32 m0, s19
	v_lshl_add_u64 v[148:149], s[52:53], 0, v[132:133]
	global_load_lds_dwordx4 v[146:147], off
	s_add_i32 m0, s19, 0x2000
	s_nop 0
	global_load_lds_dwordx4 v[148:149], off
	s_mov_b32 m0, s68
	v_lshl_add_u64 v[194:195], s[54:55], 0, v[128:129]
	ds_read_b128 v[174:177], v157 offset:16384
	ds_read_b128 v[178:181], v157 offset:17408
	ds_read_b128 v[182:185], v157 offset:18432
	ds_read_b128 v[206:209], v157 offset:19456
	ds_read_b128 v[210:213], v157 offset:20480
	ds_read_b128 v[214:217], v157 offset:21504
	ds_read_b128 v[218:221], v157 offset:22528
	ds_read_b128 v[222:225], v157 offset:23552
	global_load_lds_dwordx4 v[194:195], off
	v_lshl_add_u64 v[196:197], s[54:55], 0, v[130:131]
	s_mov_b32 m0, s69
	s_nop 0
	global_load_lds_dwordx4 v[196:197], off
	s_add_u32 s82, s52, 0x40000
	s_addc_u32 s83, s53, 0
	s_add_i32 s6, s6, s59
	v_lshl_add_u64 v[250:251], s[82:83], 0, v[140:141]
	s_mov_b32 m0, s6
	s_nop 0
	global_load_lds_dwordx4 v[250:251], off
	v_lshl_add_u64 v[250:251], s[82:83], 0, v[132:133]
	s_add_i32 m0, s6, 0x2000
	s_nop 0
	global_load_lds_dwordx4 v[250:251], off
	s_nop 0
	s_waitcnt vmcnt(8)
	s_waitcnt lgkmcnt(0)
	s_barrier
	v_mfma_f32_16x16x32_bf16 v[60:63], v[158:161], v[174:177], v[60:63]
	v_mfma_f32_16x16x32_bf16 v[52:55], v[158:161], v[182:185], v[52:55]
	v_mfma_f32_16x16x32_bf16 v[44:47], v[158:161], v[210:213], v[44:47]
	v_mfma_f32_16x16x32_bf16 v[36:39], v[158:161], v[218:221], v[36:39]
	v_mfma_f32_16x16x32_bf16 v[32:35], v[166:169], v[218:221], v[32:35]
	v_mfma_f32_16x16x32_bf16 v[40:43], v[166:169], v[210:213], v[40:43]
	v_mfma_f32_16x16x32_bf16 v[48:51], v[166:169], v[182:185], v[48:51]
	v_mfma_f32_16x16x32_bf16 v[56:59], v[166:169], v[174:177], v[56:59]
	v_mfma_f32_16x16x32_bf16 v[60:63], v[162:165], v[178:181], v[60:63]
	v_mfma_f32_16x16x32_bf16 v[52:55], v[162:165], v[206:209], v[52:55]
	v_mfma_f32_16x16x32_bf16 v[44:47], v[162:165], v[214:217], v[44:47]
	v_mfma_f32_16x16x32_bf16 v[36:39], v[162:165], v[222:225], v[36:39]
	v_mfma_f32_16x16x32_bf16 v[32:35], v[170:173], v[222:225], v[32:35]
	v_mfma_f32_16x16x32_bf16 v[40:43], v[170:173], v[214:217], v[40:43]
	v_mfma_f32_16x16x32_bf16 v[48:51], v[170:173], v[206:209], v[48:51]
	v_mfma_f32_16x16x32_bf16 v[56:59], v[170:173], v[178:181], v[56:59]
	v_mfma_f32_16x16x32_bf16 v[28:31], v[226:229], v[174:177], v[28:31]
	v_mfma_f32_16x16x32_bf16 v[20:23], v[226:229], v[182:185], v[20:23]
	v_mfma_f32_16x16x32_bf16 v[12:15], v[226:229], v[210:213], v[12:15]
	v_mfma_f32_16x16x32_bf16 v[4:7], v[226:229], v[218:221], v[4:7]
	v_mfma_f32_16x16x32_bf16 v[0:3], v[234:237], v[218:221], v[0:3]
	v_mfma_f32_16x16x32_bf16 v[8:11], v[234:237], v[210:213], v[8:11]
	v_mfma_f32_16x16x32_bf16 v[16:19], v[234:237], v[182:185], v[16:19]
	v_mfma_f32_16x16x32_bf16 v[24:27], v[234:237], v[174:177], v[24:27]
	v_mfma_f32_16x16x32_bf16 v[28:31], v[230:233], v[178:181], v[28:31]
	v_mfma_f32_16x16x32_bf16 v[20:23], v[230:233], v[206:209], v[20:23]
	v_mfma_f32_16x16x32_bf16 v[12:15], v[230:233], v[214:217], v[12:15]
	v_mfma_f32_16x16x32_bf16 v[4:7], v[230:233], v[222:225], v[4:7]
	v_mfma_f32_16x16x32_bf16 v[0:3], v[238:241], v[222:225], v[0:3]
	v_mfma_f32_16x16x32_bf16 v[8:11], v[238:241], v[214:217], v[8:11]
	v_mfma_f32_16x16x32_bf16 v[16:19], v[238:241], v[206:209], v[16:19]
	v_mfma_f32_16x16x32_bf16 v[24:27], v[238:241], v[178:181], v[24:27]
	s_barrier
	s_add_i32 s6, 0, 0x18000
	v_add_u32_e32 v170, s6, v154
	ds_read_b128 v[158:161], v170
	ds_read_b128 v[162:165], v170 offset:1024
	ds_read_b128 v[166:169], v170 offset:2048
	ds_read_b128 v[170:173], v170 offset:3072
	s_add_u32 s54, s54, 0x40000
	s_addc_u32 s55, s55, 0
	s_mov_b32 m0, s70
	v_lshl_add_u64 v[226:227], s[54:55], 0, v[128:129]
	ds_read_b128 v[174:177], v157 offset:32768
	ds_read_b128 v[178:181], v157 offset:33792
	ds_read_b128 v[182:185], v157 offset:34816
	ds_read_b128 v[206:209], v157 offset:35840
	ds_read_b128 v[210:213], v157 offset:36864
	ds_read_b128 v[214:217], v157 offset:37888
	ds_read_b128 v[218:221], v157 offset:38912
	ds_read_b128 v[222:225], v157 offset:39936
	global_load_lds_dwordx4 v[226:227], off
	v_lshl_add_u64 v[226:227], s[54:55], 0, v[130:131]
	s_mov_b32 m0, s71
	s_nop 0
	global_load_lds_dwordx4 v[226:227], off
	s_add_i32 s19, 0, 0x1c000
	v_add_u32_e32 v192, s19, v154
	ds_read_b128 v[226:229], v192
	ds_read_b128 v[230:233], v192 offset:1024
	ds_read_b128 v[234:237], v192 offset:2048
	ds_read_b128 v[238:241], v192 offset:3072
	s_waitcnt vmcnt(8)
	s_waitcnt lgkmcnt(0)
	s_barrier
	v_mfma_f32_16x16x32_bf16 v[124:127], v[158:161], v[174:177], v[124:127]
	v_mfma_f32_16x16x32_bf16 v[116:119], v[158:161], v[182:185], v[116:119]
	v_mfma_f32_16x16x32_bf16 v[108:111], v[158:161], v[210:213], v[108:111]
	v_mfma_f32_16x16x32_bf16 v[100:103], v[158:161], v[218:221], v[100:103]
	v_mfma_f32_16x16x32_bf16 v[96:99], v[166:169], v[218:221], v[96:99]
	v_mfma_f32_16x16x32_bf16 v[104:107], v[166:169], v[210:213], v[104:107]
	v_mfma_f32_16x16x32_bf16 v[112:115], v[166:169], v[182:185], v[112:115]
	v_mfma_f32_16x16x32_bf16 v[120:123], v[166:169], v[174:177], v[120:123]
	v_mfma_f32_16x16x32_bf16 v[124:127], v[162:165], v[178:181], v[124:127]
	v_mfma_f32_16x16x32_bf16 v[116:119], v[162:165], v[206:209], v[116:119]
	v_mfma_f32_16x16x32_bf16 v[108:111], v[162:165], v[214:217], v[108:111]
	v_mfma_f32_16x16x32_bf16 v[100:103], v[162:165], v[222:225], v[100:103]
	v_mfma_f32_16x16x32_bf16 v[96:99], v[170:173], v[222:225], v[96:99]
	v_mfma_f32_16x16x32_bf16 v[104:107], v[170:173], v[214:217], v[104:107]
	v_mfma_f32_16x16x32_bf16 v[112:115], v[170:173], v[206:209], v[112:115]
	v_mfma_f32_16x16x32_bf16 v[120:123], v[170:173], v[178:181], v[120:123]
	v_mfma_f32_16x16x32_bf16 v[92:95], v[226:229], v[174:177], v[92:95]
	v_mfma_f32_16x16x32_bf16 v[84:87], v[226:229], v[182:185], v[84:87]
	v_mfma_f32_16x16x32_bf16 v[76:79], v[226:229], v[210:213], v[76:79]
	v_mfma_f32_16x16x32_bf16 v[68:71], v[226:229], v[218:221], v[68:71]
	v_mfma_f32_16x16x32_bf16 v[64:67], v[234:237], v[218:221], v[64:67]
	v_mfma_f32_16x16x32_bf16 v[72:75], v[234:237], v[210:213], v[72:75]
	v_mfma_f32_16x16x32_bf16 v[80:83], v[234:237], v[182:185], v[80:83]
	v_mfma_f32_16x16x32_bf16 v[88:91], v[234:237], v[174:177], v[88:91]
	v_mfma_f32_16x16x32_bf16 v[92:95], v[230:233], v[178:181], v[92:95]
	v_mfma_f32_16x16x32_bf16 v[84:87], v[230:233], v[206:209], v[84:87]
	v_mfma_f32_16x16x32_bf16 v[76:79], v[230:233], v[214:217], v[76:79]
	v_mfma_f32_16x16x32_bf16 v[68:71], v[230:233], v[222:225], v[68:71]
	v_mfma_f32_16x16x32_bf16 v[64:67], v[238:241], v[222:225], v[64:67]
	v_mfma_f32_16x16x32_bf16 v[72:75], v[238:241], v[214:217], v[72:75]
	v_mfma_f32_16x16x32_bf16 v[80:83], v[238:241], v[206:209], v[80:83]
	v_mfma_f32_16x16x32_bf16 v[88:91], v[238:241], v[178:181], v[88:91]
	s_barrier
	s_add_i32 s6, s6, s59
	v_lshl_add_u64 v[146:147], v[146:147], 0, s[36:37]
	s_mov_b32 m0, s6
	s_nop 0
	global_load_lds_dwordx4 v[146:147], off
	v_lshl_add_u64 v[146:147], v[148:149], 0, s[36:37]
	s_add_i32 m0, s6, 0x2000
	s_nop 0
	global_load_lds_dwordx4 v[146:147], off
	s_mov_b32 m0, s72
	v_lshl_add_u64 v[146:147], v[194:195], 0, s[36:37]
	ds_read_b128 v[174:177], v157 offset:49152
	ds_read_b128 v[178:181], v157 offset:50176
	ds_read_b128 v[182:185], v157 offset:51200
	ds_read_b128 v[206:209], v157 offset:52224
	ds_read_b128 v[210:213], v157 offset:53248
	ds_read_b128 v[214:217], v157 offset:54272
	ds_read_b128 v[218:221], v157 offset:55296
	ds_read_b128 v[222:225], v157 offset:56320
	global_load_lds_dwordx4 v[146:147], off
	v_lshl_add_u64 v[146:147], v[196:197], 0, s[36:37]
	s_mov_b32 m0, s73
	s_nop 0
	global_load_lds_dwordx4 v[146:147], off
	s_add_u32 s52, s52, 0x40080
	s_addc_u32 s53, s53, 0
	s_add_i32 s6, s19, s59
	v_lshl_add_u64 v[146:147], s[52:53], 0, v[140:141]
	s_mov_b32 m0, s6
	s_nop 0
	global_load_lds_dwordx4 v[146:147], off
	v_lshl_add_u64 v[146:147], s[52:53], 0, v[132:133]
	s_add_i32 m0, s6, 0x2000
	s_nop 0
	global_load_lds_dwordx4 v[146:147], off
	s_waitcnt vmcnt(8)
	s_waitcnt lgkmcnt(0)
	s_barrier
	v_mfma_f32_16x16x32_bf16 v[60:63], v[158:161], v[174:177], v[60:63]
	v_mfma_f32_16x16x32_bf16 v[52:55], v[158:161], v[182:185], v[52:55]
	v_mfma_f32_16x16x32_bf16 v[44:47], v[158:161], v[210:213], v[44:47]
	v_mfma_f32_16x16x32_bf16 v[36:39], v[158:161], v[218:221], v[36:39]
	v_mfma_f32_16x16x32_bf16 v[32:35], v[166:169], v[218:221], v[32:35]
	v_mfma_f32_16x16x32_bf16 v[40:43], v[166:169], v[210:213], v[40:43]
	v_mfma_f32_16x16x32_bf16 v[48:51], v[166:169], v[182:185], v[48:51]
	v_mfma_f32_16x16x32_bf16 v[56:59], v[166:169], v[174:177], v[56:59]
	v_mfma_f32_16x16x32_bf16 v[60:63], v[162:165], v[178:181], v[60:63]
	v_mfma_f32_16x16x32_bf16 v[52:55], v[162:165], v[206:209], v[52:55]
	v_mfma_f32_16x16x32_bf16 v[44:47], v[162:165], v[214:217], v[44:47]
	v_mfma_f32_16x16x32_bf16 v[36:39], v[162:165], v[222:225], v[36:39]
	v_mfma_f32_16x16x32_bf16 v[32:35], v[170:173], v[222:225], v[32:35]
	v_mfma_f32_16x16x32_bf16 v[40:43], v[170:173], v[214:217], v[40:43]
	v_mfma_f32_16x16x32_bf16 v[48:51], v[170:173], v[206:209], v[48:51]
	v_mfma_f32_16x16x32_bf16 v[56:59], v[170:173], v[178:181], v[56:59]
	v_mfma_f32_16x16x32_bf16 v[28:31], v[226:229], v[174:177], v[28:31]
	v_mfma_f32_16x16x32_bf16 v[20:23], v[226:229], v[182:185], v[20:23]
	v_mfma_f32_16x16x32_bf16 v[12:15], v[226:229], v[210:213], v[12:15]
	v_mfma_f32_16x16x32_bf16 v[4:7], v[226:229], v[218:221], v[4:7]
	v_mfma_f32_16x16x32_bf16 v[0:3], v[234:237], v[218:221], v[0:3]
	v_mfma_f32_16x16x32_bf16 v[8:11], v[234:237], v[210:213], v[8:11]
	v_mfma_f32_16x16x32_bf16 v[16:19], v[234:237], v[182:185], v[16:19]
	v_mfma_f32_16x16x32_bf16 v[24:27], v[234:237], v[174:177], v[24:27]
	v_mfma_f32_16x16x32_bf16 v[28:31], v[230:233], v[178:181], v[28:31]
	v_mfma_f32_16x16x32_bf16 v[20:23], v[230:233], v[206:209], v[20:23]
	v_mfma_f32_16x16x32_bf16 v[12:15], v[230:233], v[214:217], v[12:15]
	v_mfma_f32_16x16x32_bf16 v[4:7], v[230:233], v[222:225], v[4:7]
	v_mfma_f32_16x16x32_bf16 v[0:3], v[238:241], v[222:225], v[0:3]
	v_mfma_f32_16x16x32_bf16 v[8:11], v[238:241], v[214:217], v[8:11]
	v_mfma_f32_16x16x32_bf16 v[16:19], v[238:241], v[206:209], v[16:19]
	v_mfma_f32_16x16x32_bf16 v[24:27], v[238:241], v[178:181], v[24:27]
	s_add_i32 s81, s81, 2
	s_add_u32 s50, s50, 0x100
	s_addc_u32 s51, s51, 0
	s_cmp_gt_u32 s81, 13
	s_barrier
	s_cbranch_scc0 .LBB0_77
	s_mov_b32 s100, 1
	v_lshl_add_u32 v158, s75, 10, v155
	ds_read2_b32 v[146:147], v158 offset1:16
	s_add_u32 s50, s10, 0xffffff00
	s_addc_u32 s51, s11, -1
	s_ashr_i32 s31, s30, 31
	s_lshl_b64 s[10:11], s[30:31], 8
	s_waitcnt lgkmcnt(0)
	v_mul_f32_e32 v184, 0xbfb8aa3b, v146
	v_mul_f32_e32 v206, v146, v146
	v_pk_mul_f32 v[168:169], v[124:125], v[184:185] op_sel_hi:[1,0]
	v_pk_mul_f32 v[170:171], v[126:127], v[184:185] op_sel_hi:[1,0]
	v_pk_mul_f32 v[172:173], v[120:121], v[184:185] op_sel_hi:[1,0]
	v_pk_mul_f32 v[174:175], v[122:123], v[184:185] op_sel_hi:[1,0]
	v_exp_f32_e32 v168, v168
	v_exp_f32_e32 v169, v169
	v_exp_f32_e32 v170, v170
	v_exp_f32_e32 v171, v171
	v_exp_f32_e32 v172, v172
	v_exp_f32_e32 v173, v173
	v_exp_f32_e32 v174, v174
	v_exp_f32_e32 v175, v175
	v_pk_mul_f32 v[176:177], v[124:125], v[92:93]
	v_pk_mul_f32 v[178:179], v[126:127], v[94:95]
	v_pk_mul_f32 v[180:181], v[120:121], v[88:89]
	v_pk_mul_f32 v[182:183], v[122:123], v[90:91]
	v_pk_add_f32 v[168:169], v[168:169], 1.0 op_sel_hi:[1,0]
	v_pk_add_f32 v[170:171], v[170:171], 1.0 op_sel_hi:[1,0]
	v_pk_add_f32 v[172:173], v[172:173], 1.0 op_sel_hi:[1,0]
	v_pk_add_f32 v[174:175], v[174:175], 1.0 op_sel_hi:[1,0]
	v_rcp_f32_e32 v168, v168
	v_rcp_f32_e32 v169, v169
	v_rcp_f32_e32 v170, v170
	v_rcp_f32_e32 v171, v171
	v_rcp_f32_e32 v172, v172
	v_rcp_f32_e32 v173, v173
	v_rcp_f32_e32 v174, v174
	v_rcp_f32_e32 v175, v175
	v_pk_mul_f32 v[176:177], v[176:177], v[206:207] op_sel_hi:[1,0]
	v_pk_mul_f32 v[178:179], v[178:179], v[206:207] op_sel_hi:[1,0]
	v_pk_mul_f32 v[180:181], v[180:181], v[206:207] op_sel_hi:[1,0]
	v_pk_mul_f32 v[182:183], v[182:183], v[206:207] op_sel_hi:[1,0]
	v_pk_mul_f32 v[176:177], v[176:177], v[168:169]
	v_pk_mul_f32 v[178:179], v[178:179], v[170:171]
	v_pk_mul_f32 v[180:181], v[180:181], v[172:173]
	v_pk_mul_f32 v[182:183], v[182:183], v[174:175]
	v_cvt_pk_bf16_f32 v160, v176, v177
	v_cvt_pk_bf16_f32 v161, v178, v179
	v_cvt_pk_bf16_f32 v162, v180, v181
	v_cvt_pk_bf16_f32 v163, v182, v183
	v_lshl_add_u64 v[152:153], v[134:135], 0, s[10:11]
	s_movk_i32 s6, 0x1600
	v_lshl_or_b32 v150, s74, 7, v156
	v_ashrrev_i32_e32 v151, 31, v150
	s_nop 1
	v_mov_b64_e32 v[148:149], s[28:29]
	v_mad_u64_u32 v[148:149], s[10:11], v152, s6, v[148:149]
	v_mov_b32_e32 v146, v149
	v_mad_u64_u32 v[152:153], s[10:11], v153, s6, v[146:147]
	v_mov_b32_e32 v149, v152
	v_mov_b32_e32 v146, v147
	v_lshl_add_u64 v[150:151], v[150:151], 1, v[148:149]
	global_store_dwordx4 v[150:151], v[160:163], off
	v_mul_f32_e32 v184, 0xbfb8aa3b, v146
	v_mul_f32_e32 v206, v146, v146
	v_pk_mul_f32 v[168:169], v[116:117], v[184:185] op_sel_hi:[1,0]
	v_pk_mul_f32 v[170:171], v[118:119], v[184:185] op_sel_hi:[1,0]
	v_pk_mul_f32 v[172:173], v[112:113], v[184:185] op_sel_hi:[1,0]
	v_pk_mul_f32 v[174:175], v[114:115], v[184:185] op_sel_hi:[1,0]
	v_exp_f32_e32 v168, v168
	v_exp_f32_e32 v169, v169
	v_exp_f32_e32 v170, v170
	v_exp_f32_e32 v171, v171
	v_exp_f32_e32 v172, v172
	v_exp_f32_e32 v173, v173
	v_exp_f32_e32 v174, v174
	v_exp_f32_e32 v175, v175
	v_pk_mul_f32 v[176:177], v[116:117], v[84:85]
	v_pk_mul_f32 v[178:179], v[118:119], v[86:87]
	v_pk_mul_f32 v[180:181], v[112:113], v[80:81]
	v_pk_mul_f32 v[182:183], v[114:115], v[82:83]
	v_pk_add_f32 v[168:169], v[168:169], 1.0 op_sel_hi:[1,0]
	v_pk_add_f32 v[170:171], v[170:171], 1.0 op_sel_hi:[1,0]
	v_pk_add_f32 v[172:173], v[172:173], 1.0 op_sel_hi:[1,0]
	v_pk_add_f32 v[174:175], v[174:175], 1.0 op_sel_hi:[1,0]
	v_rcp_f32_e32 v168, v168
	v_rcp_f32_e32 v169, v169
	v_rcp_f32_e32 v170, v170
	v_rcp_f32_e32 v171, v171
	v_rcp_f32_e32 v172, v172
	v_rcp_f32_e32 v173, v173
	v_rcp_f32_e32 v174, v174
	v_rcp_f32_e32 v175, v175
	v_pk_mul_f32 v[176:177], v[176:177], v[206:207] op_sel_hi:[1,0]
	v_pk_mul_f32 v[178:179], v[178:179], v[206:207] op_sel_hi:[1,0]
	v_pk_mul_f32 v[180:181], v[180:181], v[206:207] op_sel_hi:[1,0]
	v_pk_mul_f32 v[182:183], v[182:183], v[206:207] op_sel_hi:[1,0]
	v_pk_mul_f32 v[176:177], v[176:177], v[168:169]
	v_pk_mul_f32 v[178:179], v[178:179], v[170:171]
	v_pk_mul_f32 v[180:181], v[180:181], v[172:173]
	v_pk_mul_f32 v[182:183], v[182:183], v[174:175]
	v_cvt_pk_bf16_f32 v160, v176, v177
	v_cvt_pk_bf16_f32 v161, v178, v179
	v_cvt_pk_bf16_f32 v162, v180, v181
	v_cvt_pk_bf16_f32 v163, v182, v183
	s_mov_b32 s6, 0x16000
	s_nop 1
	v_add_co_u32_e32 v146, vcc, s6, v150
	s_nop 0
	v_addc_co_u32_e32 v147, vcc, 0, v151, vcc
	global_store_dwordx4 v[146:147], v[160:163], off
	ds_read2_b32 v[146:147], v158 offset0:32 offset1:48
	s_mov_b32 s6, 0x2c000
	s_waitcnt lgkmcnt(0)
	v_mul_f32_e32 v184, 0xbfb8aa3b, v146
	v_mul_f32_e32 v206, v146, v146
	v_pk_mul_f32 v[168:169], v[108:109], v[184:185] op_sel_hi:[1,0]
	v_pk_mul_f32 v[170:171], v[110:111], v[184:185] op_sel_hi:[1,0]
	v_pk_mul_f32 v[172:173], v[104:105], v[184:185] op_sel_hi:[1,0]
	v_pk_mul_f32 v[174:175], v[106:107], v[184:185] op_sel_hi:[1,0]
	v_exp_f32_e32 v168, v168
	v_exp_f32_e32 v169, v169
	v_exp_f32_e32 v170, v170
	v_exp_f32_e32 v171, v171
	v_exp_f32_e32 v172, v172
	v_exp_f32_e32 v173, v173
	v_exp_f32_e32 v174, v174
	v_exp_f32_e32 v175, v175
	v_pk_mul_f32 v[176:177], v[108:109], v[76:77]
	v_pk_mul_f32 v[178:179], v[110:111], v[78:79]
	v_pk_mul_f32 v[180:181], v[104:105], v[72:73]
	v_pk_mul_f32 v[182:183], v[106:107], v[74:75]
	v_pk_add_f32 v[168:169], v[168:169], 1.0 op_sel_hi:[1,0]
	v_pk_add_f32 v[170:171], v[170:171], 1.0 op_sel_hi:[1,0]
	v_pk_add_f32 v[172:173], v[172:173], 1.0 op_sel_hi:[1,0]
	v_pk_add_f32 v[174:175], v[174:175], 1.0 op_sel_hi:[1,0]
	v_rcp_f32_e32 v168, v168
	v_rcp_f32_e32 v169, v169
	v_rcp_f32_e32 v170, v170
	v_rcp_f32_e32 v171, v171
	v_rcp_f32_e32 v172, v172
	v_rcp_f32_e32 v173, v173
	v_rcp_f32_e32 v174, v174
	v_rcp_f32_e32 v175, v175
	v_pk_mul_f32 v[176:177], v[176:177], v[206:207] op_sel_hi:[1,0]
	v_pk_mul_f32 v[178:179], v[178:179], v[206:207] op_sel_hi:[1,0]
	v_pk_mul_f32 v[180:181], v[180:181], v[206:207] op_sel_hi:[1,0]
	v_pk_mul_f32 v[182:183], v[182:183], v[206:207] op_sel_hi:[1,0]
	v_pk_mul_f32 v[176:177], v[176:177], v[168:169]
	v_pk_mul_f32 v[178:179], v[178:179], v[170:171]
	v_pk_mul_f32 v[180:181], v[180:181], v[172:173]
	v_pk_mul_f32 v[182:183], v[182:183], v[174:175]
	v_cvt_pk_bf16_f32 v160, v176, v177
	v_cvt_pk_bf16_f32 v161, v178, v179
	v_cvt_pk_bf16_f32 v162, v180, v181
	v_cvt_pk_bf16_f32 v163, v182, v183
	s_nop 1
	v_mov_b32_e32 v146, v147
	v_add_co_u32_e32 v148, vcc, s6, v150
	v_addc_co_u32_e32 v149, vcc, 0, v151, vcc
	global_store_dwordx4 v[148:149], v[160:163], off
	v_mul_f32_e32 v184, 0xbfb8aa3b, v146
	v_mul_f32_e32 v206, v146, v146
	v_pk_mul_f32 v[168:169], v[100:101], v[184:185] op_sel_hi:[1,0]
	v_pk_mul_f32 v[170:171], v[102:103], v[184:185] op_sel_hi:[1,0]
	v_pk_mul_f32 v[172:173], v[96:97], v[184:185] op_sel_hi:[1,0]
	v_pk_mul_f32 v[174:175], v[98:99], v[184:185] op_sel_hi:[1,0]
	v_exp_f32_e32 v168, v168
	v_exp_f32_e32 v169, v169
	v_exp_f32_e32 v170, v170
	v_exp_f32_e32 v171, v171
	v_exp_f32_e32 v172, v172
	v_exp_f32_e32 v173, v173
	v_exp_f32_e32 v174, v174
	v_exp_f32_e32 v175, v175
	v_pk_mul_f32 v[176:177], v[100:101], v[68:69]
	v_pk_mul_f32 v[178:179], v[102:103], v[70:71]
	v_pk_mul_f32 v[180:181], v[96:97], v[64:65]
	v_pk_mul_f32 v[182:183], v[98:99], v[66:67]
	v_pk_add_f32 v[168:169], v[168:169], 1.0 op_sel_hi:[1,0]
	v_pk_add_f32 v[170:171], v[170:171], 1.0 op_sel_hi:[1,0]
	v_pk_add_f32 v[172:173], v[172:173], 1.0 op_sel_hi:[1,0]
	v_pk_add_f32 v[174:175], v[174:175], 1.0 op_sel_hi:[1,0]
	v_rcp_f32_e32 v168, v168
	v_rcp_f32_e32 v169, v169
	v_rcp_f32_e32 v170, v170
	v_rcp_f32_e32 v171, v171
	v_rcp_f32_e32 v172, v172
	v_rcp_f32_e32 v173, v173
	v_rcp_f32_e32 v174, v174
	v_rcp_f32_e32 v175, v175
	v_pk_mul_f32 v[176:177], v[176:177], v[206:207] op_sel_hi:[1,0]
	v_pk_mul_f32 v[178:179], v[178:179], v[206:207] op_sel_hi:[1,0]
	v_pk_mul_f32 v[180:181], v[180:181], v[206:207] op_sel_hi:[1,0]
	v_pk_mul_f32 v[182:183], v[182:183], v[206:207] op_sel_hi:[1,0]
	v_pk_mul_f32 v[176:177], v[176:177], v[168:169]
	v_pk_mul_f32 v[178:179], v[178:179], v[170:171]
	v_pk_mul_f32 v[180:181], v[180:181], v[172:173]
	v_pk_mul_f32 v[182:183], v[182:183], v[174:175]
	v_cvt_pk_bf16_f32 v160, v176, v177
	v_cvt_pk_bf16_f32 v161, v178, v179
	v_cvt_pk_bf16_f32 v162, v180, v181
	v_cvt_pk_bf16_f32 v163, v182, v183
	s_mov_b32 s6, 0x42000
	s_nop 1
	v_add_co_u32_e32 v146, vcc, s6, v150
	s_nop 0
	v_addc_co_u32_e32 v147, vcc, 0, v151, vcc
	global_store_dwordx4 v[146:147], v[160:163], off
	ds_read2_b32 v[146:147], v158 offset0:128 offset1:144
	s_mov_b32 s6, 0xb0000
	s_waitcnt lgkmcnt(0)
	v_mul_f32_e32 v184, 0xbfb8aa3b, v146
	v_mul_f32_e32 v206, v146, v146
	v_pk_mul_f32 v[168:169], v[60:61], v[184:185] op_sel_hi:[1,0]
	v_pk_mul_f32 v[170:171], v[62:63], v[184:185] op_sel_hi:[1,0]
	v_pk_mul_f32 v[172:173], v[56:57], v[184:185] op_sel_hi:[1,0]
	v_pk_mul_f32 v[174:175], v[58:59], v[184:185] op_sel_hi:[1,0]
	v_exp_f32_e32 v168, v168
	v_exp_f32_e32 v169, v169
	v_exp_f32_e32 v170, v170
	v_exp_f32_e32 v171, v171
	v_exp_f32_e32 v172, v172
	v_exp_f32_e32 v173, v173
	v_exp_f32_e32 v174, v174
	v_exp_f32_e32 v175, v175
	v_pk_mul_f32 v[176:177], v[60:61], v[28:29]
	v_pk_mul_f32 v[178:179], v[62:63], v[30:31]
	v_pk_mul_f32 v[180:181], v[56:57], v[24:25]
	v_pk_mul_f32 v[182:183], v[58:59], v[26:27]
	v_pk_add_f32 v[168:169], v[168:169], 1.0 op_sel_hi:[1,0]
	v_pk_add_f32 v[170:171], v[170:171], 1.0 op_sel_hi:[1,0]
	v_pk_add_f32 v[172:173], v[172:173], 1.0 op_sel_hi:[1,0]
	v_pk_add_f32 v[174:175], v[174:175], 1.0 op_sel_hi:[1,0]
	v_rcp_f32_e32 v168, v168
	v_rcp_f32_e32 v169, v169
	v_rcp_f32_e32 v170, v170
	v_rcp_f32_e32 v171, v171
	v_rcp_f32_e32 v172, v172
	v_rcp_f32_e32 v173, v173
	v_rcp_f32_e32 v174, v174
	v_rcp_f32_e32 v175, v175
	v_pk_mul_f32 v[176:177], v[176:177], v[206:207] op_sel_hi:[1,0]
	v_pk_mul_f32 v[178:179], v[178:179], v[206:207] op_sel_hi:[1,0]
	v_pk_mul_f32 v[180:181], v[180:181], v[206:207] op_sel_hi:[1,0]
	v_pk_mul_f32 v[182:183], v[182:183], v[206:207] op_sel_hi:[1,0]
	v_pk_mul_f32 v[176:177], v[176:177], v[168:169]
	v_pk_mul_f32 v[178:179], v[178:179], v[170:171]
	v_pk_mul_f32 v[180:181], v[180:181], v[172:173]
	v_pk_mul_f32 v[182:183], v[182:183], v[174:175]
	v_cvt_pk_bf16_f32 v160, v176, v177
	v_cvt_pk_bf16_f32 v161, v178, v179
	v_cvt_pk_bf16_f32 v162, v180, v181
	v_cvt_pk_bf16_f32 v163, v182, v183
	s_nop 1
	v_mov_b32_e32 v146, v147
	v_add_co_u32_e32 v148, vcc, s6, v150
	v_addc_co_u32_e32 v149, vcc, 0, v151, vcc
	global_store_dwordx4 v[148:149], v[160:163], off
	v_mul_f32_e32 v184, 0xbfb8aa3b, v146
	v_mul_f32_e32 v206, v146, v146
	v_pk_mul_f32 v[168:169], v[52:53], v[184:185] op_sel_hi:[1,0]
	v_pk_mul_f32 v[170:171], v[54:55], v[184:185] op_sel_hi:[1,0]
	v_pk_mul_f32 v[172:173], v[48:49], v[184:185] op_sel_hi:[1,0]
	v_pk_mul_f32 v[174:175], v[50:51], v[184:185] op_sel_hi:[1,0]
	v_exp_f32_e32 v168, v168
	v_exp_f32_e32 v169, v169
	v_exp_f32_e32 v170, v170
	v_exp_f32_e32 v171, v171
	v_exp_f32_e32 v172, v172
	v_exp_f32_e32 v173, v173
	v_exp_f32_e32 v174, v174
	v_exp_f32_e32 v175, v175
	v_pk_mul_f32 v[176:177], v[52:53], v[20:21]
	v_pk_mul_f32 v[178:179], v[54:55], v[22:23]
	v_pk_mul_f32 v[180:181], v[48:49], v[16:17]
	v_pk_mul_f32 v[182:183], v[50:51], v[18:19]
	v_pk_add_f32 v[168:169], v[168:169], 1.0 op_sel_hi:[1,0]
	v_pk_add_f32 v[170:171], v[170:171], 1.0 op_sel_hi:[1,0]
	v_pk_add_f32 v[172:173], v[172:173], 1.0 op_sel_hi:[1,0]
	v_pk_add_f32 v[174:175], v[174:175], 1.0 op_sel_hi:[1,0]
	v_rcp_f32_e32 v168, v168
	v_rcp_f32_e32 v169, v169
	v_rcp_f32_e32 v170, v170
	v_rcp_f32_e32 v171, v171
	v_rcp_f32_e32 v172, v172
	v_rcp_f32_e32 v173, v173
	v_rcp_f32_e32 v174, v174
	v_rcp_f32_e32 v175, v175
	v_pk_mul_f32 v[176:177], v[176:177], v[206:207] op_sel_hi:[1,0]
	v_pk_mul_f32 v[178:179], v[178:179], v[206:207] op_sel_hi:[1,0]
	v_pk_mul_f32 v[180:181], v[180:181], v[206:207] op_sel_hi:[1,0]
	v_pk_mul_f32 v[182:183], v[182:183], v[206:207] op_sel_hi:[1,0]
	v_pk_mul_f32 v[176:177], v[176:177], v[168:169]
	v_pk_mul_f32 v[178:179], v[178:179], v[170:171]
	v_pk_mul_f32 v[180:181], v[180:181], v[172:173]
	v_pk_mul_f32 v[182:183], v[182:183], v[174:175]
	v_cvt_pk_bf16_f32 v160, v176, v177
	v_cvt_pk_bf16_f32 v161, v178, v179
	v_cvt_pk_bf16_f32 v162, v180, v181
	v_cvt_pk_bf16_f32 v163, v182, v183
	s_mov_b32 s6, 0xc6000
	s_nop 1
	v_add_co_u32_e32 v146, vcc, s6, v150
	s_nop 0
	v_addc_co_u32_e32 v147, vcc, 0, v151, vcc
	global_store_dwordx4 v[146:147], v[160:163], off
	ds_read2_b32 v[146:147], v158 offset0:160 offset1:176
	s_mov_b32 s6, 0xdc000
	s_waitcnt lgkmcnt(0)
	v_mul_f32_e32 v184, 0xbfb8aa3b, v146
	v_mul_f32_e32 v206, v146, v146
	v_pk_mul_f32 v[168:169], v[44:45], v[184:185] op_sel_hi:[1,0]
	v_pk_mul_f32 v[170:171], v[46:47], v[184:185] op_sel_hi:[1,0]
	v_pk_mul_f32 v[172:173], v[40:41], v[184:185] op_sel_hi:[1,0]
	v_pk_mul_f32 v[174:175], v[42:43], v[184:185] op_sel_hi:[1,0]
	v_exp_f32_e32 v168, v168
	v_exp_f32_e32 v169, v169
	v_exp_f32_e32 v170, v170
	v_exp_f32_e32 v171, v171
	v_exp_f32_e32 v172, v172
	v_exp_f32_e32 v173, v173
	v_exp_f32_e32 v174, v174
	v_exp_f32_e32 v175, v175
	v_pk_mul_f32 v[176:177], v[44:45], v[12:13]
	v_pk_mul_f32 v[178:179], v[46:47], v[14:15]
	v_pk_mul_f32 v[180:181], v[40:41], v[8:9]
	v_pk_mul_f32 v[182:183], v[42:43], v[10:11]
	v_pk_add_f32 v[168:169], v[168:169], 1.0 op_sel_hi:[1,0]
	v_pk_add_f32 v[170:171], v[170:171], 1.0 op_sel_hi:[1,0]
	v_pk_add_f32 v[172:173], v[172:173], 1.0 op_sel_hi:[1,0]
	v_pk_add_f32 v[174:175], v[174:175], 1.0 op_sel_hi:[1,0]
	v_rcp_f32_e32 v168, v168
	v_rcp_f32_e32 v169, v169
	v_rcp_f32_e32 v170, v170
	v_rcp_f32_e32 v171, v171
	v_rcp_f32_e32 v172, v172
	v_rcp_f32_e32 v173, v173
	v_rcp_f32_e32 v174, v174
	v_rcp_f32_e32 v175, v175
	v_pk_mul_f32 v[176:177], v[176:177], v[206:207] op_sel_hi:[1,0]
	v_pk_mul_f32 v[178:179], v[178:179], v[206:207] op_sel_hi:[1,0]
	v_pk_mul_f32 v[180:181], v[180:181], v[206:207] op_sel_hi:[1,0]
	v_pk_mul_f32 v[182:183], v[182:183], v[206:207] op_sel_hi:[1,0]
	v_pk_mul_f32 v[176:177], v[176:177], v[168:169]
	v_pk_mul_f32 v[178:179], v[178:179], v[170:171]
	v_pk_mul_f32 v[180:181], v[180:181], v[172:173]
	v_pk_mul_f32 v[182:183], v[182:183], v[174:175]
	v_cvt_pk_bf16_f32 v158, v176, v177
	v_cvt_pk_bf16_f32 v159, v178, v179
	v_cvt_pk_bf16_f32 v160, v180, v181
	v_cvt_pk_bf16_f32 v161, v182, v183
	s_nop 1
	v_mov_b32_e32 v146, v147
	v_add_co_u32_e32 v148, vcc, s6, v150
	v_addc_co_u32_e32 v149, vcc, 0, v151, vcc
	global_store_dwordx4 v[148:149], v[158:161], off
	v_mul_f32_e32 v184, 0xbfb8aa3b, v146
	v_mul_f32_e32 v206, v146, v146
	v_pk_mul_f32 v[168:169], v[36:37], v[184:185] op_sel_hi:[1,0]
	v_pk_mul_f32 v[170:171], v[38:39], v[184:185] op_sel_hi:[1,0]
	v_pk_mul_f32 v[172:173], v[32:33], v[184:185] op_sel_hi:[1,0]
	v_pk_mul_f32 v[174:175], v[34:35], v[184:185] op_sel_hi:[1,0]
	v_exp_f32_e32 v168, v168
	v_exp_f32_e32 v169, v169
	v_exp_f32_e32 v170, v170
	v_exp_f32_e32 v171, v171
	v_exp_f32_e32 v172, v172
	v_exp_f32_e32 v173, v173
	v_exp_f32_e32 v174, v174
	v_exp_f32_e32 v175, v175
	v_pk_mul_f32 v[176:177], v[36:37], v[4:5]
	v_pk_mul_f32 v[178:179], v[38:39], v[6:7]
	v_pk_mul_f32 v[180:181], v[32:33], v[0:1]
	v_pk_mul_f32 v[182:183], v[34:35], v[2:3]
	v_pk_add_f32 v[168:169], v[168:169], 1.0 op_sel_hi:[1,0]
	v_pk_add_f32 v[170:171], v[170:171], 1.0 op_sel_hi:[1,0]
	v_pk_add_f32 v[172:173], v[172:173], 1.0 op_sel_hi:[1,0]
	v_pk_add_f32 v[174:175], v[174:175], 1.0 op_sel_hi:[1,0]
	v_rcp_f32_e32 v168, v168
	v_rcp_f32_e32 v169, v169
	v_rcp_f32_e32 v170, v170
	v_rcp_f32_e32 v171, v171
	v_rcp_f32_e32 v172, v172
	v_rcp_f32_e32 v173, v173
	v_rcp_f32_e32 v174, v174
	v_rcp_f32_e32 v175, v175
	v_pk_mul_f32 v[176:177], v[176:177], v[206:207] op_sel_hi:[1,0]
	v_pk_mul_f32 v[178:179], v[178:179], v[206:207] op_sel_hi:[1,0]
	v_pk_mul_f32 v[180:181], v[180:181], v[206:207] op_sel_hi:[1,0]
	v_pk_mul_f32 v[182:183], v[182:183], v[206:207] op_sel_hi:[1,0]
	v_pk_mul_f32 v[176:177], v[176:177], v[168:169]
	v_pk_mul_f32 v[178:179], v[178:179], v[170:171]
	v_pk_mul_f32 v[180:181], v[180:181], v[172:173]
	v_pk_mul_f32 v[182:183], v[182:183], v[174:175]
	v_cvt_pk_bf16_f32 v158, v176, v177
	v_cvt_pk_bf16_f32 v159, v178, v179
	v_cvt_pk_bf16_f32 v160, v180, v181
	v_cvt_pk_bf16_f32 v161, v182, v183
	s_nop 1
	v_add_co_u32_e32 v146, vcc, 0xf2000, v150
	s_nop 0
	v_addc_co_u32_e32 v147, vcc, 0, v151, vcc
	s_andn2_b64 vcc, exec, s[44:45]
	global_store_dwordx4 v[146:147], v[158:161], off
	s_cbranch_vccz .LBB0_73
	s_mov_b64 s[46:47], s[50:51]
	s_andn2_b64 vcc, exec, s[42:43]
	s_mov_b64 s[50:51], s[46:47]
	s_cbranch_vccnz .LBB0_74

.Lm4ap_103:
	s_waitcnt lgkmcnt(0)
	s_barrier
	s_nop 0
	v_mfma_f32_16x16x32_bf16 v[124:127], v[128:131], v[162:165], 0
	v_mfma_f32_16x16x32_bf16 v[108:111], v[128:131], v[170:173], 0
	v_mfma_f32_16x16x32_bf16 v[96:99], v[128:131], v[178:181], 0
	v_mfma_f32_16x16x32_bf16 v[84:87], v[128:131], v[194:197], 0
	v_mfma_f32_16x16x32_bf16 v[80:83], v[136:139], v[194:197], 0
	v_mfma_f32_16x16x32_bf16 v[88:91], v[136:139], v[178:181], 0
	v_mfma_f32_16x16x32_bf16 v[104:107], v[136:139], v[170:173], 0
	v_mfma_f32_16x16x32_bf16 v[120:123], v[136:139], v[162:165], 0
	v_mfma_f32_16x16x32_bf16 v[124:127], v[132:135], v[166:169], v[124:127]
	v_mfma_f32_16x16x32_bf16 v[108:111], v[132:135], v[174:177], v[108:111]
	v_mfma_f32_16x16x32_bf16 v[96:99], v[132:135], v[182:185], v[96:99]
	v_mfma_f32_16x16x32_bf16 v[84:87], v[132:135], v[210:213], v[84:87]
	v_mfma_f32_16x16x32_bf16 v[80:83], v[146:149], v[210:213], v[80:83]
	v_mfma_f32_16x16x32_bf16 v[88:91], v[146:149], v[182:185], v[88:91]
	v_mfma_f32_16x16x32_bf16 v[104:107], v[146:149], v[174:177], v[104:107]
	v_mfma_f32_16x16x32_bf16 v[120:123], v[146:149], v[166:169], v[120:123]
	v_mfma_f32_16x16x32_bf16 v[116:119], v[214:217], v[162:165], 0
	v_mfma_f32_16x16x32_bf16 v[100:103], v[214:217], v[170:173], 0
	v_mfma_f32_16x16x32_bf16 v[76:79], v[214:217], v[178:181], 0
	v_mfma_f32_16x16x32_bf16 v[68:71], v[214:217], v[194:197], 0
	v_mfma_f32_16x16x32_bf16 v[64:67], v[222:225], v[194:197], 0
	v_mfma_f32_16x16x32_bf16 v[72:75], v[222:225], v[178:181], 0
	v_mfma_f32_16x16x32_bf16 v[92:95], v[222:225], v[170:173], 0
	v_mfma_f32_16x16x32_bf16 v[112:115], v[222:225], v[162:165], 0
	v_mfma_f32_16x16x32_bf16 v[116:119], v[218:221], v[166:169], v[116:119]
	v_mfma_f32_16x16x32_bf16 v[100:103], v[218:221], v[174:177], v[100:103]
	v_mfma_f32_16x16x32_bf16 v[76:79], v[218:221], v[182:185], v[76:79]
	v_mfma_f32_16x16x32_bf16 v[68:71], v[218:221], v[210:213], v[68:71]
	v_mfma_f32_16x16x32_bf16 v[64:67], v[226:229], v[210:213], v[64:67]
	v_mfma_f32_16x16x32_bf16 v[72:75], v[226:229], v[182:185], v[72:75]
	v_mfma_f32_16x16x32_bf16 v[92:95], v[226:229], v[174:177], v[92:95]
	v_mfma_f32_16x16x32_bf16 v[112:115], v[226:229], v[166:169], v[112:115]
	s_barrier
	s_add_i32 s19, s23, s71
	v_lshl_add_u64 v[192:193], s[58:59], 0, v[140:141]
	s_mov_b32 m0, s19
	v_lshl_add_u64 v[230:231], s[58:59], 0, v[150:151]
	global_load_lds_dwordx4 v[192:193], off
	s_add_i32 m0, s19, 0x2000
	s_nop 0
	global_load_lds_dwordx4 v[230:231], off
	s_mov_b32 m0, s72
	v_lshl_add_u64 v[232:233], s[68:69], 0, v[154:155]
	ds_read_b128 v[162:165], v208 offset:16384
	ds_read_b128 v[166:169], v208 offset:17408
	ds_read_b128 v[170:173], v208 offset:18432
	ds_read_b128 v[174:177], v208 offset:19456
	ds_read_b128 v[178:181], v208 offset:20480
	ds_read_b128 v[182:185], v208 offset:21504
	ds_read_b128 v[194:197], v208 offset:22528
	ds_read_b128 v[210:213], v208 offset:23552
	global_load_lds_dwordx4 v[232:233], off
	v_lshl_add_u64 v[234:235], s[68:69], 0, v[152:153]
	s_mov_b32 m0, s73
	s_nop 0
	global_load_lds_dwordx4 v[234:235], off
	s_add_u32 s86, s58, 0x40000
	s_addc_u32 s87, s59, 0
	s_add_i32 s6, s6, s71
	v_lshl_add_u64 v[250:251], s[86:87], 0, v[140:141]
	s_mov_b32 m0, s6
	s_nop 0
	global_load_lds_dwordx4 v[250:251], off
	v_lshl_add_u64 v[250:251], s[86:87], 0, v[150:151]
	s_add_i32 m0, s6, 0x2000
	s_nop 0
	global_load_lds_dwordx4 v[250:251], off
	s_waitcnt vmcnt(40)
	s_cmp_lg_u32 s100, 0
	s_cbranch_scc1 .Lm4bp_103
	s_waitcnt vmcnt(8)
.Lm4bp_103:
	s_waitcnt lgkmcnt(0)
	s_mov_b32 s100, 0
	s_barrier
	s_nop 0
	v_mfma_f32_16x16x32_bf16 v[60:63], v[128:131], v[162:165], 0
	v_mfma_f32_16x16x32_bf16 v[48:51], v[128:131], v[170:173], 0
	v_mfma_f32_16x16x32_bf16 v[32:35], v[128:131], v[178:181], 0
	v_mfma_f32_16x16x32_bf16 v[16:19], v[128:131], v[194:197], 0
	v_mfma_f32_16x16x32_bf16 v[8:11], v[136:139], v[194:197], 0
	v_mfma_f32_16x16x32_bf16 v[24:27], v[136:139], v[178:181], 0
	v_mfma_f32_16x16x32_bf16 v[40:43], v[136:139], v[170:173], 0
	v_mfma_f32_16x16x32_bf16 v[56:59], v[136:139], v[162:165], 0
	v_mfma_f32_16x16x32_bf16 v[60:63], v[132:135], v[166:169], v[60:63]
	v_mfma_f32_16x16x32_bf16 v[48:51], v[132:135], v[174:177], v[48:51]
	v_mfma_f32_16x16x32_bf16 v[32:35], v[132:135], v[182:185], v[32:35]
	v_mfma_f32_16x16x32_bf16 v[16:19], v[132:135], v[210:213], v[16:19]
	v_mfma_f32_16x16x32_bf16 v[8:11], v[146:149], v[210:213], v[8:11]
	v_mfma_f32_16x16x32_bf16 v[24:27], v[146:149], v[182:185], v[24:27]
	v_mfma_f32_16x16x32_bf16 v[40:43], v[146:149], v[174:177], v[40:43]
	v_mfma_f32_16x16x32_bf16 v[56:59], v[146:149], v[166:169], v[56:59]
	v_mfma_f32_16x16x32_bf16 v[52:55], v[214:217], v[162:165], 0
	v_mfma_f32_16x16x32_bf16 v[36:39], v[214:217], v[170:173], 0
	v_mfma_f32_16x16x32_bf16 v[20:23], v[214:217], v[178:181], 0
	v_mfma_f32_16x16x32_bf16 v[4:7], v[214:217], v[194:197], 0
	v_mfma_f32_16x16x32_bf16 v[0:3], v[222:225], v[194:197], 0
	v_mfma_f32_16x16x32_bf16 v[12:15], v[222:225], v[178:181], 0
	v_mfma_f32_16x16x32_bf16 v[28:31], v[222:225], v[170:173], 0
	v_mfma_f32_16x16x32_bf16 v[44:47], v[222:225], v[162:165], 0
	v_mfma_f32_16x16x32_bf16 v[52:55], v[218:221], v[166:169], v[52:55]
	v_mfma_f32_16x16x32_bf16 v[36:39], v[218:221], v[174:177], v[36:39]
	v_mfma_f32_16x16x32_bf16 v[20:23], v[218:221], v[182:185], v[20:23]
	v_mfma_f32_16x16x32_bf16 v[4:7], v[218:221], v[210:213], v[4:7]
	v_mfma_f32_16x16x32_bf16 v[0:3], v[226:229], v[210:213], v[0:3]
	v_mfma_f32_16x16x32_bf16 v[12:15], v[226:229], v[182:185], v[12:15]
	v_mfma_f32_16x16x32_bf16 v[28:31], v[226:229], v[174:177], v[28:31]
	v_mfma_f32_16x16x32_bf16 v[44:47], v[226:229], v[166:169], v[44:47]
	s_barrier
	s_add_i32 s6, 0, 0x18000
	v_add_u32_e32 v146, s6, v206
	ds_read_b128 v[128:131], v146
	ds_read_b128 v[132:135], v146 offset:1024
	ds_read_b128 v[136:139], v146 offset:2048
	ds_read_b128 v[146:149], v146 offset:3072
	s_add_u32 s68, s68, 0x40000
	s_addc_u32 s69, s69, 0
	s_mov_b32 m0, s74
	v_lshl_add_u64 v[214:215], s[68:69], 0, v[154:155]
	ds_read_b128 v[162:165], v208 offset:32768
	ds_read_b128 v[166:169], v208 offset:33792
	ds_read_b128 v[170:173], v208 offset:34816
	ds_read_b128 v[174:177], v208 offset:35840
	ds_read_b128 v[178:181], v208 offset:36864
	ds_read_b128 v[182:185], v208 offset:37888
	ds_read_b128 v[194:197], v208 offset:38912
	ds_read_b128 v[210:213], v208 offset:39936
	global_load_lds_dwordx4 v[214:215], off
	v_lshl_add_u64 v[214:215], s[68:69], 0, v[152:153]
	s_mov_b32 m0, s75
	s_nop 0
	global_load_lds_dwordx4 v[214:215], off
	s_add_i32 s19, 0, 0x1c000
	v_add_u32_e32 v209, s19, v206
	ds_read_b128 v[214:217], v209
	ds_read_b128 v[218:221], v209 offset:1024
	ds_read_b128 v[222:225], v209 offset:2048
	ds_read_b128 v[226:229], v209 offset:3072
	s_waitcnt vmcnt(8)
	s_waitcnt lgkmcnt(0)
	s_barrier
	v_mfma_f32_16x16x32_bf16 v[124:127], v[128:131], v[162:165], v[124:127]
	v_mfma_f32_16x16x32_bf16 v[108:111], v[128:131], v[170:173], v[108:111]
	v_mfma_f32_16x16x32_bf16 v[96:99], v[128:131], v[178:181], v[96:99]
	v_mfma_f32_16x16x32_bf16 v[84:87], v[128:131], v[194:197], v[84:87]
	v_mfma_f32_16x16x32_bf16 v[80:83], v[136:139], v[194:197], v[80:83]
	v_mfma_f32_16x16x32_bf16 v[88:91], v[136:139], v[178:181], v[88:91]
	v_mfma_f32_16x16x32_bf16 v[104:107], v[136:139], v[170:173], v[104:107]
	v_mfma_f32_16x16x32_bf16 v[120:123], v[136:139], v[162:165], v[120:123]
	v_mfma_f32_16x16x32_bf16 v[124:127], v[132:135], v[166:169], v[124:127]
	v_mfma_f32_16x16x32_bf16 v[108:111], v[132:135], v[174:177], v[108:111]
	v_mfma_f32_16x16x32_bf16 v[96:99], v[132:135], v[182:185], v[96:99]
	v_mfma_f32_16x16x32_bf16 v[84:87], v[132:135], v[210:213], v[84:87]
	v_mfma_f32_16x16x32_bf16 v[80:83], v[146:149], v[210:213], v[80:83]
	v_mfma_f32_16x16x32_bf16 v[88:91], v[146:149], v[182:185], v[88:91]
	v_mfma_f32_16x16x32_bf16 v[104:107], v[146:149], v[174:177], v[104:107]
	v_mfma_f32_16x16x32_bf16 v[120:123], v[146:149], v[166:169], v[120:123]
	v_mfma_f32_16x16x32_bf16 v[116:119], v[214:217], v[162:165], v[116:119]
	v_mfma_f32_16x16x32_bf16 v[100:103], v[214:217], v[170:173], v[100:103]
	v_mfma_f32_16x16x32_bf16 v[76:79], v[214:217], v[178:181], v[76:79]
	v_mfma_f32_16x16x32_bf16 v[68:71], v[214:217], v[194:197], v[68:71]
	v_mfma_f32_16x16x32_bf16 v[64:67], v[222:225], v[194:197], v[64:67]
	v_mfma_f32_16x16x32_bf16 v[72:75], v[222:225], v[178:181], v[72:75]
	v_mfma_f32_16x16x32_bf16 v[92:95], v[222:225], v[170:173], v[92:95]
	v_mfma_f32_16x16x32_bf16 v[112:115], v[222:225], v[162:165], v[112:115]
	v_mfma_f32_16x16x32_bf16 v[116:119], v[218:221], v[166:169], v[116:119]
	v_mfma_f32_16x16x32_bf16 v[100:103], v[218:221], v[174:177], v[100:103]
	v_mfma_f32_16x16x32_bf16 v[76:79], v[218:221], v[182:185], v[76:79]
	v_mfma_f32_16x16x32_bf16 v[68:71], v[218:221], v[210:213], v[68:71]
	v_mfma_f32_16x16x32_bf16 v[64:67], v[226:229], v[210:213], v[64:67]
	v_mfma_f32_16x16x32_bf16 v[72:75], v[226:229], v[182:185], v[72:75]
	v_mfma_f32_16x16x32_bf16 v[92:95], v[226:229], v[174:177], v[92:95]
	v_mfma_f32_16x16x32_bf16 v[112:115], v[226:229], v[166:169], v[112:115]
	s_barrier
	s_add_i32 s6, s6, s71
	v_lshl_add_u64 v[192:193], v[192:193], 0, s[36:37]
	s_mov_b32 m0, s6
	s_nop 0
	global_load_lds_dwordx4 v[192:193], off
	v_lshl_add_u64 v[192:193], v[230:231], 0, s[36:37]
	s_add_i32 m0, s6, 0x2000
	s_nop 0
	global_load_lds_dwordx4 v[192:193], off
	s_mov_b32 m0, s80
	v_lshl_add_u64 v[192:193], v[232:233], 0, s[36:37]
	ds_read_b128 v[162:165], v208 offset:49152
	ds_read_b128 v[166:169], v208 offset:50176
	ds_read_b128 v[170:173], v208 offset:51200
	ds_read_b128 v[174:177], v208 offset:52224
	ds_read_b128 v[178:181], v208 offset:53248
	ds_read_b128 v[182:185], v208 offset:54272
	ds_read_b128 v[194:197], v208 offset:55296
	ds_read_b128 v[210:213], v208 offset:56320
	global_load_lds_dwordx4 v[192:193], off
	v_lshl_add_u64 v[192:193], v[234:235], 0, s[36:37]
	s_mov_b32 m0, s81
	s_nop 0
	global_load_lds_dwordx4 v[192:193], off
	s_add_u32 s58, s58, 0x40080
	s_addc_u32 s59, s59, 0
	s_add_i32 s6, s19, s71
	v_lshl_add_u64 v[250:251], s[58:59], 0, v[140:141]
	s_mov_b32 m0, s6
	s_nop 0
	global_load_lds_dwordx4 v[250:251], off
	v_lshl_add_u64 v[250:251], s[58:59], 0, v[150:151]
	s_add_i32 m0, s6, 0x2000
	s_nop 0
	global_load_lds_dwordx4 v[250:251], off
	s_waitcnt vmcnt(8)
	s_waitcnt lgkmcnt(0)
	s_barrier
	v_mfma_f32_16x16x32_bf16 v[60:63], v[128:131], v[162:165], v[60:63]
	v_mfma_f32_16x16x32_bf16 v[48:51], v[128:131], v[170:173], v[48:51]
	v_mfma_f32_16x16x32_bf16 v[32:35], v[128:131], v[178:181], v[32:35]
	v_mfma_f32_16x16x32_bf16 v[16:19], v[128:131], v[194:197], v[16:19]
	v_mfma_f32_16x16x32_bf16 v[8:11], v[136:139], v[194:197], v[8:11]
	v_mfma_f32_16x16x32_bf16 v[24:27], v[136:139], v[178:181], v[24:27]
	v_mfma_f32_16x16x32_bf16 v[40:43], v[136:139], v[170:173], v[40:43]
	v_mfma_f32_16x16x32_bf16 v[56:59], v[136:139], v[162:165], v[56:59]
	v_mfma_f32_16x16x32_bf16 v[60:63], v[132:135], v[166:169], v[60:63]
	v_mfma_f32_16x16x32_bf16 v[48:51], v[132:135], v[174:177], v[48:51]
	v_mfma_f32_16x16x32_bf16 v[32:35], v[132:135], v[182:185], v[32:35]
	v_mfma_f32_16x16x32_bf16 v[16:19], v[132:135], v[210:213], v[16:19]
	v_mfma_f32_16x16x32_bf16 v[8:11], v[146:149], v[210:213], v[8:11]
	v_mfma_f32_16x16x32_bf16 v[24:27], v[146:149], v[182:185], v[24:27]
	v_mfma_f32_16x16x32_bf16 v[40:43], v[146:149], v[174:177], v[40:43]
	v_mfma_f32_16x16x32_bf16 v[56:59], v[146:149], v[166:169], v[56:59]
	v_mfma_f32_16x16x32_bf16 v[52:55], v[214:217], v[162:165], v[52:55]
	v_mfma_f32_16x16x32_bf16 v[36:39], v[214:217], v[170:173], v[36:39]
	v_mfma_f32_16x16x32_bf16 v[20:23], v[214:217], v[178:181], v[20:23]
	v_mfma_f32_16x16x32_bf16 v[4:7], v[214:217], v[194:197], v[4:7]
	v_mfma_f32_16x16x32_bf16 v[0:3], v[222:225], v[194:197], v[0:3]
	v_mfma_f32_16x16x32_bf16 v[12:15], v[222:225], v[178:181], v[12:15]
	v_mfma_f32_16x16x32_bf16 v[28:31], v[222:225], v[170:173], v[28:31]
	v_mfma_f32_16x16x32_bf16 v[44:47], v[222:225], v[162:165], v[44:47]
	v_mfma_f32_16x16x32_bf16 v[52:55], v[218:221], v[166:169], v[52:55]
	v_mfma_f32_16x16x32_bf16 v[36:39], v[218:221], v[174:177], v[36:39]
	v_mfma_f32_16x16x32_bf16 v[20:23], v[218:221], v[182:185], v[20:23]
	v_mfma_f32_16x16x32_bf16 v[4:7], v[218:221], v[210:213], v[4:7]
	v_mfma_f32_16x16x32_bf16 v[0:3], v[226:229], v[210:213], v[0:3]
	v_mfma_f32_16x16x32_bf16 v[12:15], v[226:229], v[182:185], v[12:15]
	v_mfma_f32_16x16x32_bf16 v[28:31], v[226:229], v[174:177], v[28:31]
	v_mfma_f32_16x16x32_bf16 v[44:47], v[226:229], v[166:169], v[44:47]
	s_add_i32 s12, s12, 2
	s_add_u32 s54, s54, 0x100
	s_addc_u32 s55, s55, 0
	s_add_u32 s10, s10, 0x100
	s_addc_u32 s11, s11, 0
	s_cmp_gt_u32 s12, 13
	s_barrier
.LBB0_103:
	s_add_u32 s6, s54, 0xfffc0080
	s_addc_u32 s19, s55, -1
	s_add_i32 s23, 0, 0x10000
	v_add_u32_e32 v146, s23, v206
	ds_read_b128 v[128:131], v146
	ds_read_b128 v[132:135], v146 offset:1024
	ds_read_b128 v[136:139], v146 offset:2048
	ds_read_b128 v[146:149], v146 offset:3072
	s_cmp_eq_u32 s12, 12
	s_cselect_b32 s69, s47, s19
	s_cselect_b32 s68, s46, s6
	s_cselect_b32 s59, s49, s11
	s_cselect_b32 s58, s48, s10
	v_lshl_add_u64 v[192:193], s[54:55], 0, v[158:159]
	s_add_i32 m0, s72, 0xc000
	ds_read_b128 v[162:165], v208
	ds_read_b128 v[166:169], v208 offset:1024
	ds_read_b128 v[170:173], v208 offset:2048
	ds_read_b128 v[174:177], v208 offset:3072
	ds_read_b128 v[178:181], v208 offset:4096
	ds_read_b128 v[182:185], v208 offset:5120
	ds_read_b128 v[194:197], v208 offset:6144
	ds_read_b128 v[210:213], v208 offset:7168
	global_load_lds_dwordx4 v[192:193], off
	v_lshl_add_u64 v[192:193], s[54:55], 0, v[160:161]
	s_add_i32 m0, s72, 0xe000
	s_nop 0
	global_load_lds_dwordx4 v[192:193], off
	s_add_i32 s6, 0, 0x14000
	v_add_u32_e32 v192, s6, v206
	ds_read_b128 v[214:217], v192
	ds_read_b128 v[218:221], v192 offset:1024
	ds_read_b128 v[222:225], v192 offset:2048
	ds_read_b128 v[226:229], v192 offset:3072
	s_nop 0
	s_waitcnt vmcnt(8)
	s_waitcnt lgkmcnt(0)
	s_barrier
	v_mfma_f32_16x16x32_bf16 v[124:127], v[128:131], v[162:165], v[124:127]
	v_mfma_f32_16x16x32_bf16 v[108:111], v[128:131], v[170:173], v[108:111]
	v_mfma_f32_16x16x32_bf16 v[96:99], v[128:131], v[178:181], v[96:99]
	v_mfma_f32_16x16x32_bf16 v[84:87], v[128:131], v[194:197], v[84:87]
	v_mfma_f32_16x16x32_bf16 v[80:83], v[136:139], v[194:197], v[80:83]
	v_mfma_f32_16x16x32_bf16 v[88:91], v[136:139], v[178:181], v[88:91]
	v_mfma_f32_16x16x32_bf16 v[104:107], v[136:139], v[170:173], v[104:107]
	v_mfma_f32_16x16x32_bf16 v[120:123], v[136:139], v[162:165], v[120:123]
	v_mfma_f32_16x16x32_bf16 v[124:127], v[132:135], v[166:169], v[124:127]
	v_mfma_f32_16x16x32_bf16 v[108:111], v[132:135], v[174:177], v[108:111]
	v_mfma_f32_16x16x32_bf16 v[96:99], v[132:135], v[182:185], v[96:99]
	v_mfma_f32_16x16x32_bf16 v[84:87], v[132:135], v[210:213], v[84:87]
	v_mfma_f32_16x16x32_bf16 v[80:83], v[146:149], v[210:213], v[80:83]
	v_mfma_f32_16x16x32_bf16 v[88:91], v[146:149], v[182:185], v[88:91]
	v_mfma_f32_16x16x32_bf16 v[104:107], v[146:149], v[174:177], v[104:107]
	v_mfma_f32_16x16x32_bf16 v[120:123], v[146:149], v[166:169], v[120:123]
	v_mfma_f32_16x16x32_bf16 v[116:119], v[214:217], v[162:165], v[116:119]
	v_mfma_f32_16x16x32_bf16 v[100:103], v[214:217], v[170:173], v[100:103]
	v_mfma_f32_16x16x32_bf16 v[76:79], v[214:217], v[178:181], v[76:79]
	v_mfma_f32_16x16x32_bf16 v[68:71], v[214:217], v[194:197], v[68:71]
	v_mfma_f32_16x16x32_bf16 v[64:67], v[222:225], v[194:197], v[64:67]
	v_mfma_f32_16x16x32_bf16 v[72:75], v[222:225], v[178:181], v[72:75]
	v_mfma_f32_16x16x32_bf16 v[92:95], v[222:225], v[170:173], v[92:95]
	v_mfma_f32_16x16x32_bf16 v[112:115], v[222:225], v[162:165], v[112:115]
	v_mfma_f32_16x16x32_bf16 v[116:119], v[218:221], v[166:169], v[116:119]
	v_mfma_f32_16x16x32_bf16 v[100:103], v[218:221], v[174:177], v[100:103]
	v_mfma_f32_16x16x32_bf16 v[76:79], v[218:221], v[182:185], v[76:79]
	v_mfma_f32_16x16x32_bf16 v[68:71], v[218:221], v[210:213], v[68:71]
	v_mfma_f32_16x16x32_bf16 v[64:67], v[226:229], v[210:213], v[64:67]
	v_mfma_f32_16x16x32_bf16 v[72:75], v[226:229], v[182:185], v[72:75]
	v_mfma_f32_16x16x32_bf16 v[92:95], v[226:229], v[174:177], v[92:95]
	v_mfma_f32_16x16x32_bf16 v[112:115], v[226:229], v[166:169], v[112:115]
	s_barrier
	s_add_i32 s19, s23, s71
	v_lshl_add_u64 v[192:193], s[58:59], 0, v[140:141]
	s_mov_b32 m0, s19
	v_lshl_add_u64 v[230:231], s[58:59], 0, v[150:151]
	global_load_lds_dwordx4 v[192:193], off
	s_add_i32 m0, s19, 0x2000
	s_nop 0
	global_load_lds_dwordx4 v[230:231], off
	s_mov_b32 m0, s72
	v_lshl_add_u64 v[232:233], s[68:69], 0, v[154:155]
	ds_read_b128 v[162:165], v208 offset:16384
	ds_read_b128 v[166:169], v208 offset:17408
	ds_read_b128 v[170:173], v208 offset:18432
	ds_read_b128 v[174:177], v208 offset:19456
	ds_read_b128 v[178:181], v208 offset:20480
	ds_read_b128 v[182:185], v208 offset:21504
	ds_read_b128 v[194:197], v208 offset:22528
	ds_read_b128 v[210:213], v208 offset:23552
	global_load_lds_dwordx4 v[232:233], off
	v_lshl_add_u64 v[234:235], s[68:69], 0, v[152:153]
	s_mov_b32 m0, s73
	s_nop 0
	global_load_lds_dwordx4 v[234:235], off
	s_add_u32 s86, s58, 0x40000
	s_addc_u32 s87, s59, 0
	s_add_i32 s6, s6, s71
	v_lshl_add_u64 v[250:251], s[86:87], 0, v[140:141]
	s_mov_b32 m0, s6
	s_nop 0
	global_load_lds_dwordx4 v[250:251], off
	v_lshl_add_u64 v[250:251], s[86:87], 0, v[150:151]
	s_add_i32 m0, s6, 0x2000
	s_nop 0
	global_load_lds_dwordx4 v[250:251], off
	s_nop 0
	s_waitcnt vmcnt(8)
	s_waitcnt lgkmcnt(0)
	s_barrier
	v_mfma_f32_16x16x32_bf16 v[60:63], v[128:131], v[162:165], v[60:63]
	v_mfma_f32_16x16x32_bf16 v[48:51], v[128:131], v[170:173], v[48:51]
	v_mfma_f32_16x16x32_bf16 v[32:35], v[128:131], v[178:181], v[32:35]
	v_mfma_f32_16x16x32_bf16 v[16:19], v[128:131], v[194:197], v[16:19]
	v_mfma_f32_16x16x32_bf16 v[8:11], v[136:139], v[194:197], v[8:11]
	v_mfma_f32_16x16x32_bf16 v[24:27], v[136:139], v[178:181], v[24:27]
	v_mfma_f32_16x16x32_bf16 v[40:43], v[136:139], v[170:173], v[40:43]
	v_mfma_f32_16x16x32_bf16 v[56:59], v[136:139], v[162:165], v[56:59]
	v_mfma_f32_16x16x32_bf16 v[60:63], v[132:135], v[166:169], v[60:63]
	v_mfma_f32_16x16x32_bf16 v[48:51], v[132:135], v[174:177], v[48:51]
	v_mfma_f32_16x16x32_bf16 v[32:35], v[132:135], v[182:185], v[32:35]
	v_mfma_f32_16x16x32_bf16 v[16:19], v[132:135], v[210:213], v[16:19]
	v_mfma_f32_16x16x32_bf16 v[8:11], v[146:149], v[210:213], v[8:11]
	v_mfma_f32_16x16x32_bf16 v[24:27], v[146:149], v[182:185], v[24:27]
	v_mfma_f32_16x16x32_bf16 v[40:43], v[146:149], v[174:177], v[40:43]
	v_mfma_f32_16x16x32_bf16 v[56:59], v[146:149], v[166:169], v[56:59]
	v_mfma_f32_16x16x32_bf16 v[52:55], v[214:217], v[162:165], v[52:55]
	v_mfma_f32_16x16x32_bf16 v[36:39], v[214:217], v[170:173], v[36:39]
	v_mfma_f32_16x16x32_bf16 v[20:23], v[214:217], v[178:181], v[20:23]
	v_mfma_f32_16x16x32_bf16 v[4:7], v[214:217], v[194:197], v[4:7]
	v_mfma_f32_16x16x32_bf16 v[0:3], v[222:225], v[194:197], v[0:3]
	v_mfma_f32_16x16x32_bf16 v[12:15], v[222:225], v[178:181], v[12:15]
	v_mfma_f32_16x16x32_bf16 v[28:31], v[222:225], v[170:173], v[28:31]
	v_mfma_f32_16x16x32_bf16 v[44:47], v[222:225], v[162:165], v[44:47]
	v_mfma_f32_16x16x32_bf16 v[52:55], v[218:221], v[166:169], v[52:55]
	v_mfma_f32_16x16x32_bf16 v[36:39], v[218:221], v[174:177], v[36:39]
	v_mfma_f32_16x16x32_bf16 v[20:23], v[218:221], v[182:185], v[20:23]
	v_mfma_f32_16x16x32_bf16 v[4:7], v[218:221], v[210:213], v[4:7]
	v_mfma_f32_16x16x32_bf16 v[0:3], v[226:229], v[210:213], v[0:3]
	v_mfma_f32_16x16x32_bf16 v[12:15], v[226:229], v[182:185], v[12:15]
	v_mfma_f32_16x16x32_bf16 v[28:31], v[226:229], v[174:177], v[28:31]
	v_mfma_f32_16x16x32_bf16 v[44:47], v[226:229], v[166:169], v[44:47]
	s_barrier
	s_add_i32 s6, 0, 0x18000
	v_add_u32_e32 v146, s6, v206
	ds_read_b128 v[128:131], v146
	ds_read_b128 v[132:135], v146 offset:1024
	ds_read_b128 v[136:139], v146 offset:2048
	ds_read_b128 v[146:149], v146 offset:3072
	s_add_u32 s68, s68, 0x40000
	s_addc_u32 s69, s69, 0
	s_mov_b32 m0, s74
	v_lshl_add_u64 v[214:215], s[68:69], 0, v[154:155]
	ds_read_b128 v[162:165], v208 offset:32768
	ds_read_b128 v[166:169], v208 offset:33792
	ds_read_b128 v[170:173], v208 offset:34816
	ds_read_b128 v[174:177], v208 offset:35840
	ds_read_b128 v[178:181], v208 offset:36864
	ds_read_b128 v[182:185], v208 offset:37888
	ds_read_b128 v[194:197], v208 offset:38912
	ds_read_b128 v[210:213], v208 offset:39936
	global_load_lds_dwordx4 v[214:215], off
	v_lshl_add_u64 v[214:215], s[68:69], 0, v[152:153]
	s_mov_b32 m0, s75
	s_nop 0
	global_load_lds_dwordx4 v[214:215], off
	s_add_i32 s19, 0, 0x1c000
	v_add_u32_e32 v209, s19, v206
	ds_read_b128 v[214:217], v209
	ds_read_b128 v[218:221], v209 offset:1024
	ds_read_b128 v[222:225], v209 offset:2048
	ds_read_b128 v[226:229], v209 offset:3072
	s_waitcnt vmcnt(8)
	s_waitcnt lgkmcnt(0)
	s_barrier
	v_mfma_f32_16x16x32_bf16 v[124:127], v[128:131], v[162:165], v[124:127]
	v_mfma_f32_16x16x32_bf16 v[108:111], v[128:131], v[170:173], v[108:111]
	v_mfma_f32_16x16x32_bf16 v[96:99], v[128:131], v[178:181], v[96:99]
	v_mfma_f32_16x16x32_bf16 v[84:87], v[128:131], v[194:197], v[84:87]
	v_mfma_f32_16x16x32_bf16 v[80:83], v[136:139], v[194:197], v[80:83]
	v_mfma_f32_16x16x32_bf16 v[88:91], v[136:139], v[178:181], v[88:91]
	v_mfma_f32_16x16x32_bf16 v[104:107], v[136:139], v[170:173], v[104:107]
	v_mfma_f32_16x16x32_bf16 v[120:123], v[136:139], v[162:165], v[120:123]
	v_mfma_f32_16x16x32_bf16 v[124:127], v[132:135], v[166:169], v[124:127]
	v_mfma_f32_16x16x32_bf16 v[108:111], v[132:135], v[174:177], v[108:111]
	v_mfma_f32_16x16x32_bf16 v[96:99], v[132:135], v[182:185], v[96:99]
	v_mfma_f32_16x16x32_bf16 v[84:87], v[132:135], v[210:213], v[84:87]
	v_mfma_f32_16x16x32_bf16 v[80:83], v[146:149], v[210:213], v[80:83]
	v_mfma_f32_16x16x32_bf16 v[88:91], v[146:149], v[182:185], v[88:91]
	v_mfma_f32_16x16x32_bf16 v[104:107], v[146:149], v[174:177], v[104:107]
	v_mfma_f32_16x16x32_bf16 v[120:123], v[146:149], v[166:169], v[120:123]
	v_mfma_f32_16x16x32_bf16 v[116:119], v[214:217], v[162:165], v[116:119]
	v_mfma_f32_16x16x32_bf16 v[100:103], v[214:217], v[170:173], v[100:103]
	v_mfma_f32_16x16x32_bf16 v[76:79], v[214:217], v[178:181], v[76:79]
	v_mfma_f32_16x16x32_bf16 v[68:71], v[214:217], v[194:197], v[68:71]
	v_mfma_f32_16x16x32_bf16 v[64:67], v[222:225], v[194:197], v[64:67]
	v_mfma_f32_16x16x32_bf16 v[72:75], v[222:225], v[178:181], v[72:75]
	v_mfma_f32_16x16x32_bf16 v[92:95], v[222:225], v[170:173], v[92:95]
	v_mfma_f32_16x16x32_bf16 v[112:115], v[222:225], v[162:165], v[112:115]
	v_mfma_f32_16x16x32_bf16 v[116:119], v[218:221], v[166:169], v[116:119]
	v_mfma_f32_16x16x32_bf16 v[100:103], v[218:221], v[174:177], v[100:103]
	v_mfma_f32_16x16x32_bf16 v[76:79], v[218:221], v[182:185], v[76:79]
	v_mfma_f32_16x16x32_bf16 v[68:71], v[218:221], v[210:213], v[68:71]
	v_mfma_f32_16x16x32_bf16 v[64:67], v[226:229], v[210:213], v[64:67]
	v_mfma_f32_16x16x32_bf16 v[72:75], v[226:229], v[182:185], v[72:75]
	v_mfma_f32_16x16x32_bf16 v[92:95], v[226:229], v[174:177], v[92:95]
	v_mfma_f32_16x16x32_bf16 v[112:115], v[226:229], v[166:169], v[112:115]
	s_barrier
	s_add_i32 s6, s6, s71
	v_lshl_add_u64 v[192:193], v[192:193], 0, s[36:37]
	s_mov_b32 m0, s6
	s_nop 0
	global_load_lds_dwordx4 v[192:193], off
	v_lshl_add_u64 v[192:193], v[230:231], 0, s[36:37]
	s_add_i32 m0, s6, 0x2000
	s_nop 0
	global_load_lds_dwordx4 v[192:193], off
	s_mov_b32 m0, s80
	v_lshl_add_u64 v[192:193], v[232:233], 0, s[36:37]
	ds_read_b128 v[162:165], v208 offset:49152
	ds_read_b128 v[166:169], v208 offset:50176
	ds_read_b128 v[170:173], v208 offset:51200
	ds_read_b128 v[174:177], v208 offset:52224
	ds_read_b128 v[178:181], v208 offset:53248
	ds_read_b128 v[182:185], v208 offset:54272
	ds_read_b128 v[194:197], v208 offset:55296
	ds_read_b128 v[210:213], v208 offset:56320
	global_load_lds_dwordx4 v[192:193], off
	v_lshl_add_u64 v[192:193], v[234:235], 0, s[36:37]
	s_mov_b32 m0, s81
	s_nop 0
	global_load_lds_dwordx4 v[192:193], off
	s_add_u32 s58, s58, 0x40080
	s_addc_u32 s59, s59, 0
	s_add_i32 s6, s19, s71
	v_lshl_add_u64 v[250:251], s[58:59], 0, v[140:141]
	s_mov_b32 m0, s6
	s_nop 0
	global_load_lds_dwordx4 v[250:251], off
	v_lshl_add_u64 v[250:251], s[58:59], 0, v[150:151]
	s_add_i32 m0, s6, 0x2000
	s_nop 0
	global_load_lds_dwordx4 v[250:251], off
	s_waitcnt vmcnt(8)
	s_waitcnt lgkmcnt(0)
	s_barrier
	v_mfma_f32_16x16x32_bf16 v[60:63], v[128:131], v[162:165], v[60:63]
	v_mfma_f32_16x16x32_bf16 v[48:51], v[128:131], v[170:173], v[48:51]
	v_mfma_f32_16x16x32_bf16 v[32:35], v[128:131], v[178:181], v[32:35]
	v_mfma_f32_16x16x32_bf16 v[16:19], v[128:131], v[194:197], v[16:19]
	v_mfma_f32_16x16x32_bf16 v[8:11], v[136:139], v[194:197], v[8:11]
	v_mfma_f32_16x16x32_bf16 v[24:27], v[136:139], v[178:181], v[24:27]
	v_mfma_f32_16x16x32_bf16 v[40:43], v[136:139], v[170:173], v[40:43]
	v_mfma_f32_16x16x32_bf16 v[56:59], v[136:139], v[162:165], v[56:59]
	v_mfma_f32_16x16x32_bf16 v[60:63], v[132:135], v[166:169], v[60:63]
	v_mfma_f32_16x16x32_bf16 v[48:51], v[132:135], v[174:177], v[48:51]
	v_mfma_f32_16x16x32_bf16 v[32:35], v[132:135], v[182:185], v[32:35]
	v_mfma_f32_16x16x32_bf16 v[16:19], v[132:135], v[210:213], v[16:19]
	v_mfma_f32_16x16x32_bf16 v[8:11], v[146:149], v[210:213], v[8:11]
	v_mfma_f32_16x16x32_bf16 v[24:27], v[146:149], v[182:185], v[24:27]
	v_mfma_f32_16x16x32_bf16 v[40:43], v[146:149], v[174:177], v[40:43]
	v_mfma_f32_16x16x32_bf16 v[56:59], v[146:149], v[166:169], v[56:59]
	v_mfma_f32_16x16x32_bf16 v[52:55], v[214:217], v[162:165], v[52:55]
	v_mfma_f32_16x16x32_bf16 v[36:39], v[214:217], v[170:173], v[36:39]
	v_mfma_f32_16x16x32_bf16 v[20:23], v[214:217], v[178:181], v[20:23]
	v_mfma_f32_16x16x32_bf16 v[4:7], v[214:217], v[194:197], v[4:7]
	v_mfma_f32_16x16x32_bf16 v[0:3], v[222:225], v[194:197], v[0:3]
	v_mfma_f32_16x16x32_bf16 v[12:15], v[222:225], v[178:181], v[12:15]
	v_mfma_f32_16x16x32_bf16 v[28:31], v[222:225], v[170:173], v[28:31]
	v_mfma_f32_16x16x32_bf16 v[44:47], v[222:225], v[162:165], v[44:47]
	v_mfma_f32_16x16x32_bf16 v[52:55], v[218:221], v[166:169], v[52:55]
	v_mfma_f32_16x16x32_bf16 v[36:39], v[218:221], v[174:177], v[36:39]
	v_mfma_f32_16x16x32_bf16 v[20:23], v[218:221], v[182:185], v[20:23]
	v_mfma_f32_16x16x32_bf16 v[4:7], v[218:221], v[210:213], v[4:7]
	v_mfma_f32_16x16x32_bf16 v[0:3], v[226:229], v[210:213], v[0:3]
	v_mfma_f32_16x16x32_bf16 v[12:15], v[226:229], v[182:185], v[12:15]
	v_mfma_f32_16x16x32_bf16 v[28:31], v[226:229], v[174:177], v[28:31]
	v_mfma_f32_16x16x32_bf16 v[44:47], v[226:229], v[166:169], v[44:47]
	s_add_i32 s12, s12, 2
	s_add_u32 s54, s54, 0x100
	s_addc_u32 s55, s55, 0
	s_add_u32 s10, s10, 0x100
	s_addc_u32 s11, s11, 0
	s_cmp_gt_u32 s12, 13
	s_barrier
	s_cbranch_scc0 .LBB0_103
	s_mov_b32 s100, 1
	s_ashr_i32 s51, s50, 31
	s_ashr_i32 s53, s52, 31
	s_lshl_b64 s[10:11], s[50:51], 13
	s_lshl_b64 s[50:51], s[52:53], 8
	s_add_u32 s10, s50, s10
	v_lshl_or_b32 v128, s85, 8, v207
	s_addc_u32 s11, s51, s11
	v_ashrrev_i32_e32 v129, 31, v128
	v_lshl_add_u64 v[168:169], s[10:11], 0, v[156:157]
	v_lshlrev_b64 v[170:171], 1, v[128:129]
	v_lshl_add_u64 v[174:175], s[26:27], 0, v[170:171]
	v_lshlrev_b64 v[172:173], 11, v[168:169]
	v_or_b32_e32 v166, 16, v168
	v_mov_b32_e32 v167, v169
	v_lshl_add_u64 v[128:129], v[174:175], 0, v[172:173]
	v_lshlrev_b64 v[176:177], 11, v[166:167]
	global_load_dwordx4 v[146:149], v[128:129], off
	global_load_dwordx4 v[182:185], v[128:129], off offset:256
	v_lshl_add_u64 v[128:129], v[174:175], 0, v[176:177]
	global_load_dwordx4 v[194:197], v[128:129], off
	global_load_dwordx4 v[210:213], v[128:129], off offset:256
	v_or_b32_e32 v164, 32, v168
	v_mov_b32_e32 v165, v169
	v_or_b32_e32 v162, 48, v168
	v_mov_b32_e32 v163, v169
	v_lshlrev_b64 v[180:181], 11, v[164:165]
	v_lshlrev_b64 v[178:179], 11, v[162:163]
	v_lshl_add_u64 v[128:129], v[174:175], 0, v[180:181]
	v_lshl_add_u64 v[130:131], v[174:175], 0, v[178:179]
	global_load_dwordx4 v[214:217], v[128:129], off
	global_load_dwordx4 v[136:139], v[128:129], off offset:256
	global_load_dwordx4 v[132:135], v[130:131], off
	s_nop 0
	global_load_dwordx4 v[128:131], v[130:131], off offset:256
	s_mov_b64 s[10:11], 0x90
	v_lshl_add_u64 v[172:173], s[28:29], 0, v[172:173]
	v_lshl_add_u64 v[172:173], v[172:173], 0, v[170:171]
	s_waitcnt vmcnt(0)
	v_lshlrev_b32_e32 v192, 16, v146
	v_and_b32_e32 v193, 0xffff0000, v146
	v_lshlrev_b32_e32 v218, 16, v148
	v_and_b32_e32 v219, 0xffff0000, v148
	v_lshlrev_b32_e32 v146, 16, v147
	v_and_b32_e32 v147, 0xffff0000, v147
	v_lshlrev_b32_e32 v148, 16, v149
	v_and_b32_e32 v149, 0xffff0000, v149
	v_lshlrev_b32_e32 v220, 16, v182
	v_and_b32_e32 v221, 0xffff0000, v182
	v_lshlrev_b32_e32 v222, 16, v184
	v_and_b32_e32 v223, 0xffff0000, v184
	v_lshlrev_b32_e32 v182, 16, v183
	v_and_b32_e32 v183, 0xffff0000, v183
	v_lshlrev_b32_e32 v184, 16, v185
	v_and_b32_e32 v185, 0xffff0000, v185
	v_pk_add_f32 v[124:125], v[124:125], v[192:193]
	v_pk_add_f32 v[126:127], v[126:127], v[146:147]
	v_pk_add_f32 v[122:123], v[122:123], v[148:149]
	v_pk_add_f32 v[116:117], v[116:117], v[220:221]
	v_pk_add_f32 v[146:147], v[112:113], v[222:223]
	v_pk_add_f32 v[118:119], v[118:119], v[182:183]
	v_pk_add_f32 v[148:149], v[114:115], v[184:185]
	v_lshlrev_b32_e32 v182, 16, v194
	v_and_b32_e32 v183, 0xffff0000, v194
	v_lshlrev_b32_e32 v184, 16, v196
	v_and_b32_e32 v185, 0xffff0000, v196
	v_lshlrev_b32_e32 v192, 16, v195
	v_and_b32_e32 v193, 0xffff0000, v195
	v_lshlrev_b32_e32 v194, 16, v197
	v_and_b32_e32 v195, 0xffff0000, v197
	v_pk_mul_f32 v[196:197], v[124:125], v[124:125]
	v_pk_add_f32 v[120:121], v[120:121], v[218:219]
	v_pk_mul_f32 v[218:219], v[126:127], v[126:127]
	v_cvt_pk_bf16_f32 v112, v124, v125
	v_cvt_pk_bf16_f32 v113, v126, v127
	v_pk_mul_f32 v[124:125], v[116:117], v[116:117]
	v_pk_mul_f32 v[126:127], v[118:119], v[118:119]
	v_pk_mul_f32 v[224:225], v[146:147], v[146:147]
	v_cvt_pk_bf16_f32 v116, v116, v117
	v_cvt_pk_bf16_f32 v117, v118, v119
	v_cvt_pk_bf16_f32 v118, v146, v147
	v_add_f32_e32 v146, v196, v197
	v_add_f32_e32 v146, v218, v146
	v_pk_mul_f32 v[220:221], v[120:121], v[120:121]
	v_add_f32_e32 v146, v219, v146
	v_add_f32_e32 v146, v220, v146
	v_pk_mul_f32 v[222:223], v[122:123], v[122:123]
	v_add_f32_e32 v146, v221, v146
	v_add_f32_e32 v146, v222, v146
	v_add_f32_e32 v146, v223, v146
	v_add_f32_e32 v124, v124, v146
	v_add_f32_e32 v124, v125, v124
	v_add_f32_e32 v124, v126, v124
	v_add_f32_e32 v124, v127, v124
	v_add_f32_e32 v124, v224, v124
	v_pk_mul_f32 v[226:227], v[148:149], v[148:149]
	v_add_f32_e32 v124, v225, v124
	v_add_f32_e32 v124, v226, v124
	v_add_f32_e32 v209, v227, v124
	v_lshlrev_b32_e32 v124, 16, v210
	v_and_b32_e32 v125, 0xffff0000, v210
	v_pk_add_f32 v[100:101], v[100:101], v[124:125]
	v_lshlrev_b32_e32 v124, 16, v212
	v_and_b32_e32 v125, 0xffff0000, v212
	v_pk_add_f32 v[124:125], v[92:93], v[124:125]
	v_lshlrev_b32_e32 v92, 16, v211
	v_and_b32_e32 v93, 0xffff0000, v211
	v_pk_add_f32 v[102:103], v[102:103], v[92:93]
	v_lshlrev_b32_e32 v92, 16, v213
	v_and_b32_e32 v93, 0xffff0000, v213
	v_pk_add_f32 v[126:127], v[94:95], v[92:93]
	v_lshlrev_b32_e32 v92, 16, v214
	v_and_b32_e32 v93, 0xffff0000, v214
	v_pk_add_f32 v[92:93], v[96:97], v[92:93]
	v_lshlrev_b32_e32 v96, 16, v217
	v_and_b32_e32 v97, 0xffff0000, v217
	v_lshlrev_b32_e32 v94, 16, v216
	v_and_b32_e32 v95, 0xffff0000, v216
	v_pk_add_f32 v[90:91], v[90:91], v[96:97]
	v_lshlrev_b32_e32 v96, 16, v136
	v_and_b32_e32 v97, 0xffff0000, v136
	v_pk_add_f32 v[88:89], v[88:89], v[94:95]
	v_lshlrev_b32_e32 v94, 16, v215
	v_and_b32_e32 v95, 0xffff0000, v215
	v_pk_add_f32 v[96:97], v[76:77], v[96:97]
	v_lshl_add_u64 v[76:77], v[168:169], 0, s[36:37]
	v_cvt_pk_bf16_f32 v114, v120, v121
	v_pk_add_f32 v[120:121], v[108:109], v[182:183]
	v_pk_add_f32 v[94:95], v[98:99], v[94:95]
	v_lshlrev_b64 v[182:183], 11, v[76:77]
	v_lshlrev_b32_e32 v98, 16, v138
	v_and_b32_e32 v99, 0xffff0000, v138
	v_pk_add_f32 v[108:109], v[104:105], v[184:185]
	v_lshl_add_u64 v[184:185], v[174:175], 0, v[182:183]
	v_pk_add_f32 v[98:99], v[72:73], v[98:99]
	v_lshlrev_b32_e32 v72, 16, v137
	v_and_b32_e32 v73, 0xffff0000, v137
	global_load_dwordx4 v[210:213], v[184:185], off
	global_load_dwordx4 v[218:221], v[184:185], off offset:256
	v_pk_add_f32 v[136:137], v[78:79], v[72:73]
	v_lshlrev_b32_e32 v72, 16, v139
	v_and_b32_e32 v73, 0xffff0000, v139
	v_pk_add_f32 v[138:139], v[74:75], v[72:73]
	v_lshlrev_b32_e32 v72, 16, v132
	v_and_b32_e32 v73, 0xffff0000, v132
	v_pk_add_f32 v[74:75], v[84:85], v[72:73]
	v_lshlrev_b32_e32 v72, 16, v134
	v_and_b32_e32 v73, 0xffff0000, v134
	v_pk_add_f32 v[78:79], v[80:81], v[72:73]
	v_lshlrev_b32_e32 v72, 16, v133
	v_and_b32_e32 v73, 0xffff0000, v133
	v_pk_add_f32 v[80:81], v[86:87], v[72:73]
	v_lshlrev_b32_e32 v72, 16, v135
	v_and_b32_e32 v73, 0xffff0000, v135
	v_pk_add_f32 v[82:83], v[82:83], v[72:73]
	v_lshl_add_u64 v[72:73], v[168:169], 0, s[10:11]
	v_lshlrev_b64 v[132:133], 11, v[72:73]
	v_lshl_add_u64 v[134:135], v[174:175], 0, v[132:133]
	v_lshlrev_b32_e32 v84, 16, v128
	v_and_b32_e32 v85, 0xffff0000, v128
	global_load_dwordx4 v[226:229], v[134:135], off
	global_load_dwordx4 v[234:237], v[134:135], off offset:256
	v_pk_add_f32 v[84:85], v[68:69], v[84:85]
	v_lshlrev_b32_e32 v68, 16, v130
	v_and_b32_e32 v69, 0xffff0000, v130
	v_pk_add_f32 v[86:87], v[64:65], v[68:69]
	v_lshlrev_b32_e32 v64, 16, v129
	v_and_b32_e32 v65, 0xffff0000, v129
	s_mov_b64 s[10:11], 0xa0
	v_pk_add_f32 v[128:129], v[70:71], v[64:65]
	v_lshl_add_u64 v[70:71], v[168:169], 0, s[10:11]
	s_mov_b64 s[10:11], 0xb0
	v_lshlrev_b32_e32 v64, 16, v131
	v_and_b32_e32 v65, 0xffff0000, v131
	v_lshlrev_b64 v[134:135], 11, v[70:71]
	v_lshl_add_u64 v[68:69], v[168:169], 0, s[10:11]
	v_pk_add_f32 v[130:131], v[66:67], v[64:65]
	v_lshl_add_u64 v[64:65], v[174:175], 0, v[134:135]
	v_lshlrev_b64 v[184:185], 11, v[68:69]
	global_load_dwordx4 v[238:241], v[64:65], off
	global_load_dwordx4 v[242:245], v[64:65], off offset:256
	v_lshl_add_u64 v[64:65], v[174:175], 0, v[184:185]
	global_load_dwordx4 v[246:249], v[64:65], off
	s_nop 0
	global_load_dwordx4 v[64:67], v[64:65], off offset:256
	v_cvt_pk_bf16_f32 v115, v122, v123
	v_cvt_pk_bf16_f32 v119, v148, v149
	v_pk_add_f32 v[110:111], v[110:111], v[192:193]
	v_pk_add_f32 v[122:123], v[106:107], v[194:195]
	global_store_dwordx4 v[172:173], v[112:115], off
	global_store_dwordx4 v[172:173], v[116:119], off offset:256
	v_cvt_pk_bf16_f32 v104, v120, v121
	v_lshl_add_u64 v[112:113], s[28:29], 0, v[176:177]
	v_cvt_pk_bf16_f32 v105, v110, v111
	v_cvt_pk_bf16_f32 v106, v108, v109
	v_cvt_pk_bf16_f32 v107, v122, v123
	v_lshl_add_u64 v[112:113], v[112:113], 0, v[170:171]
	v_cvt_pk_bf16_f32 v146, v100, v101
	v_cvt_pk_bf16_f32 v147, v102, v103
	v_cvt_pk_bf16_f32 v148, v124, v125
	v_cvt_pk_bf16_f32 v149, v126, v127
	global_store_dwordx4 v[112:113], v[104:107], off
	global_store_dwordx4 v[112:113], v[146:149], off offset:256
	v_cvt_pk_bf16_f32 v194, v92, v93
	v_lshl_add_u64 v[104:105], s[28:29], 0, v[180:181]
	v_cvt_pk_bf16_f32 v195, v94, v95
	v_cvt_pk_bf16_f32 v196, v88, v89
	v_cvt_pk_bf16_f32 v197, v90, v91
	v_lshl_add_u64 v[104:105], v[104:105], 0, v[170:171]
	v_cvt_pk_bf16_f32 v214, v96, v97
	v_cvt_pk_bf16_f32 v215, v136, v137
	v_cvt_pk_bf16_f32 v216, v98, v99
	v_cvt_pk_bf16_f32 v217, v138, v139
	global_store_dwordx4 v[104:105], v[194:197], off
	global_store_dwordx4 v[104:105], v[214:217], off offset:256
	v_lshl_add_u64 v[104:105], s[28:29], 0, v[178:179]
	v_cvt_pk_bf16_f32 v222, v74, v75
	v_cvt_pk_bf16_f32 v223, v80, v81
	v_cvt_pk_bf16_f32 v224, v78, v79
	v_cvt_pk_bf16_f32 v225, v82, v83
	v_lshl_add_u64 v[104:105], v[104:105], 0, v[170:171]
	v_cvt_pk_bf16_f32 v230, v84, v85
	v_cvt_pk_bf16_f32 v231, v128, v129
	v_cvt_pk_bf16_f32 v232, v86, v87
	v_cvt_pk_bf16_f32 v233, v130, v131
	global_store_dwordx4 v[104:105], v[222:225], off
	global_store_dwordx4 v[104:105], v[230:233], off offset:256
	s_waitcnt vmcnt(0)
	v_lshlrev_b32_e32 v104, 16, v210
	v_and_b32_e32 v105, 0xffff0000, v210
	v_pk_add_f32 v[60:61], v[60:61], v[104:105]
	v_lshlrev_b32_e32 v104, 16, v212
	v_and_b32_e32 v105, 0xffff0000, v212
	v_pk_add_f32 v[56:57], v[56:57], v[104:105]
	v_lshlrev_b32_e32 v104, 16, v211
	v_and_b32_e32 v105, 0xffff0000, v211
	v_pk_add_f32 v[62:63], v[62:63], v[104:105]
	v_lshlrev_b32_e32 v104, 16, v213
	v_and_b32_e32 v105, 0xffff0000, v213
	v_pk_add_f32 v[58:59], v[58:59], v[104:105]
	v_lshlrev_b32_e32 v104, 16, v218
	v_and_b32_e32 v105, 0xffff0000, v218
	v_pk_add_f32 v[52:53], v[52:53], v[104:105]
	v_lshlrev_b32_e32 v104, 16, v220
	v_and_b32_e32 v105, 0xffff0000, v220
	v_pk_add_f32 v[104:105], v[44:45], v[104:105]
	v_lshlrev_b32_e32 v44, 16, v219
	v_and_b32_e32 v45, 0xffff0000, v219
	v_pk_add_f32 v[54:55], v[54:55], v[44:45]
	v_lshlrev_b32_e32 v44, 16, v221
	v_and_b32_e32 v45, 0xffff0000, v221
	v_pk_add_f32 v[106:107], v[46:47], v[44:45]
	v_lshlrev_b32_e32 v44, 16, v226
	v_and_b32_e32 v45, 0xffff0000, v226
	v_pk_add_f32 v[44:45], v[48:49], v[44:45]
	v_lshlrev_b32_e32 v48, 16, v229
	v_and_b32_e32 v49, 0xffff0000, v229
	v_pk_add_f32 v[42:43], v[42:43], v[48:49]
	v_lshlrev_b32_e32 v48, 16, v234
	v_and_b32_e32 v49, 0xffff0000, v234
	v_pk_add_f32 v[36:37], v[36:37], v[48:49]
	v_lshlrev_b32_e32 v48, 16, v236
	v_and_b32_e32 v49, 0xffff0000, v236
	v_lshlrev_b32_e32 v46, 16, v228
	v_and_b32_e32 v47, 0xffff0000, v228
	v_pk_add_f32 v[48:49], v[28:29], v[48:49]
	v_lshlrev_b32_e32 v28, 16, v235
	v_and_b32_e32 v29, 0xffff0000, v235
	v_pk_add_f32 v[40:41], v[40:41], v[46:47]
	v_lshlrev_b32_e32 v46, 16, v227
	v_and_b32_e32 v47, 0xffff0000, v227
	v_pk_add_f32 v[38:39], v[38:39], v[28:29]
	v_lshlrev_b32_e32 v28, 16, v237
	v_and_b32_e32 v29, 0xffff0000, v237
	v_pk_add_f32 v[46:47], v[50:51], v[46:47]
	v_pk_add_f32 v[50:51], v[30:31], v[28:29]
	v_lshlrev_b32_e32 v28, 16, v238
	v_and_b32_e32 v29, 0xffff0000, v238
	v_lshlrev_b32_e32 v180, 16, v64
	v_and_b32_e32 v181, 0xffff0000, v64
	v_pk_add_f32 v[28:29], v[32:33], v[28:29]
	v_lshlrev_b32_e32 v32, 16, v241
	v_and_b32_e32 v33, 0xffff0000, v241
	v_pk_add_f32 v[4:5], v[4:5], v[180:181]
	v_lshlrev_b32_e32 v180, 16, v66
	v_and_b32_e32 v181, 0xffff0000, v66
	v_pk_add_f32 v[26:27], v[26:27], v[32:33]
	v_lshlrev_b32_e32 v32, 16, v242
	v_and_b32_e32 v33, 0xffff0000, v242
	v_pk_add_f32 v[0:1], v[0:1], v[180:181]
	v_lshl_add_u64 v[180:181], s[28:29], 0, v[182:183]
	v_cvt_pk_bf16_f32 v112, v60, v61
	v_cvt_pk_bf16_f32 v113, v62, v63
	v_cvt_pk_bf16_f32 v114, v56, v57
	v_cvt_pk_bf16_f32 v115, v58, v59
	v_pk_add_f32 v[20:21], v[20:21], v[32:33]
	v_lshlrev_b32_e32 v32, 16, v244
	v_and_b32_e32 v33, 0xffff0000, v244
	v_lshl_add_u64 v[180:181], v[180:181], 0, v[170:171]
	v_cvt_pk_bf16_f32 v116, v52, v53
	v_cvt_pk_bf16_f32 v117, v54, v55
	v_cvt_pk_bf16_f32 v118, v104, v105
	v_cvt_pk_bf16_f32 v119, v106, v107
	v_lshlrev_b32_e32 v30, 16, v240
	v_and_b32_e32 v31, 0xffff0000, v240
	v_pk_add_f32 v[32:33], v[12:13], v[32:33]
	v_lshlrev_b32_e32 v12, 16, v243
	v_and_b32_e32 v13, 0xffff0000, v243
	global_store_dwordx4 v[180:181], v[112:115], off
	global_store_dwordx4 v[180:181], v[116:119], off offset:256
	v_cvt_pk_bf16_f32 v146, v44, v45
	v_lshl_add_u64 v[112:113], s[28:29], 0, v[132:133]
	v_cvt_pk_bf16_f32 v147, v46, v47
	v_cvt_pk_bf16_f32 v148, v40, v41
	v_cvt_pk_bf16_f32 v149, v42, v43
	v_pk_add_f32 v[24:25], v[24:25], v[30:31]
	v_lshlrev_b32_e32 v30, 16, v239
	v_and_b32_e32 v31, 0xffff0000, v239
	v_pk_add_f32 v[22:23], v[22:23], v[12:13]
	v_lshlrev_b32_e32 v12, 16, v245
	v_and_b32_e32 v13, 0xffff0000, v245
	v_lshl_add_u64 v[112:113], v[112:113], 0, v[170:171]
	v_cvt_pk_bf16_f32 v172, v36, v37
	v_cvt_pk_bf16_f32 v173, v38, v39
	v_cvt_pk_bf16_f32 v174, v48, v49
	v_cvt_pk_bf16_f32 v175, v50, v51
	v_pk_add_f32 v[30:31], v[34:35], v[30:31]
	v_pk_add_f32 v[34:35], v[14:15], v[12:13]
	v_lshlrev_b32_e32 v12, 16, v246
	v_and_b32_e32 v13, 0xffff0000, v246
	v_lshlrev_b32_e32 v14, 16, v248
	v_and_b32_e32 v15, 0xffff0000, v248
	global_store_dwordx4 v[112:113], v[146:149], off
	global_store_dwordx4 v[112:113], v[172:175], off offset:256
	v_lshl_add_u64 v[112:113], s[28:29], 0, v[134:135]
	v_cvt_pk_bf16_f32 v176, v28, v29
	v_cvt_pk_bf16_f32 v177, v30, v31
	v_cvt_pk_bf16_f32 v178, v24, v25
	v_cvt_pk_bf16_f32 v179, v26, v27
	v_pk_add_f32 v[12:13], v[16:17], v[12:13]
	v_pk_add_f32 v[8:9], v[8:9], v[14:15]
	v_lshlrev_b32_e32 v14, 16, v247
	v_and_b32_e32 v15, 0xffff0000, v247
	v_lshlrev_b32_e32 v16, 16, v249
	v_and_b32_e32 v17, 0xffff0000, v249
	v_lshlrev_b32_e32 v64, 16, v65
	v_and_b32_e32 v65, 0xffff0000, v65
	v_lshl_add_u64 v[112:113], v[112:113], 0, v[170:171]
	v_cvt_pk_bf16_f32 v194, v20, v21
	v_cvt_pk_bf16_f32 v195, v22, v23
	v_cvt_pk_bf16_f32 v196, v32, v33
	v_cvt_pk_bf16_f32 v197, v34, v35
	v_pk_add_f32 v[14:15], v[18:19], v[14:15]
	v_pk_add_f32 v[10:11], v[10:11], v[16:17]
	v_pk_add_f32 v[6:7], v[6:7], v[64:65]
	v_lshlrev_b32_e32 v64, 16, v67
	v_and_b32_e32 v65, 0xffff0000, v67
	global_store_dwordx4 v[112:113], v[176:179], off
	global_store_dwordx4 v[112:113], v[194:197], off offset:256
	v_lshl_add_u64 v[112:113], s[28:29], 0, v[184:185]
	v_cvt_pk_bf16_f32 v16, v12, v13
	v_cvt_pk_bf16_f32 v17, v14, v15
	v_cvt_pk_bf16_f32 v18, v8, v9
	v_cvt_pk_bf16_f32 v19, v10, v11
	v_pk_add_f32 v[2:3], v[2:3], v[64:65]
	v_lshl_add_u64 v[112:113], v[112:113], 0, v[170:171]
	v_cvt_pk_bf16_f32 v64, v4, v5
	v_cvt_pk_bf16_f32 v65, v6, v7
	v_cvt_pk_bf16_f32 v66, v0, v1
	v_cvt_pk_bf16_f32 v67, v2, v3
	global_store_dwordx4 v[112:113], v[16:19], off
	global_store_dwordx4 v[112:113], v[64:67], off offset:256
	s_lshl_b32 s10, s85, 2
	v_and_b32_e32 v17, 64, v188
	v_xor_b32_e32 v16, 16, v188
	v_add_u32_e32 v17, 64, v17
	v_cmp_lt_i32_e32 vcc, v16, v17
	v_xor_b32_e32 v18, 32, v188
	s_ashr_i32 s11, s10, 31
	v_cndmask_b32_e32 v16, v188, v16, vcc
	v_lshlrev_b32_e32 v16, 2, v16
	ds_bpermute_b32 v19, v16, v209
	v_cmp_lt_i32_e32 vcc, v18, v17
	s_lshl_b64 s[10:11], s[10:11], 2
	s_add_u32 s50, s83, s10
	v_cndmask_b32_e32 v17, v188, v18, vcc
	v_lshlrev_b32_e32 v17, 2, v17
	s_waitcnt lgkmcnt(0)
	v_add_f32_e32 v18, v209, v19
	ds_bpermute_b32 v19, v17, v18
	s_addc_u32 s51, s84, s11
	s_and_saveexec_b64 s[52:53], s[42:43]
	s_cbranch_execz .LBB0_106
	s_waitcnt lgkmcnt(0)
	v_add_f32_e32 v64, v18, v19
	v_lshlrev_b64 v[18:19], 6, v[168:169]
	v_lshl_add_u64 v[18:19], s[50:51], 0, v[18:19]
	global_store_dword v[18:19], v64, off

.LBB0_192:
	s_add_u32 s6, s26, s54
	s_addc_u32 s11, s27, s55
	s_add_u32 s6, s6, 0x100
	s_addc_u32 s11, s11, 0
	s_add_u32 s12, s29, s54
	s_addc_u32 s19, s31, s55
	s_add_i32 s23, 0, 0x10000
	v_add_u32_e32 v169, s23, v156
	ds_read_b128 v[146:149], v169
	ds_read_b128 v[170:173], v169 offset:1024
	ds_read_b128 v[174:177], v169 offset:2048
	ds_read_b128 v[178:181], v169 offset:3072
	s_cmpk_eq_i32 s54, 0x700
	s_cselect_b32 s69, s53, s11
	s_cselect_b32 s68, s52, s6
	s_cselect_b32 s59, s49, s19
	s_cselect_b32 s58, s48, s12
	v_lshl_add_u64 v[230:231], v[152:153], 0, s[54:55]
	s_add_i32 m0, s72, 0xc000
	ds_read_b128 v[182:185], v168
	ds_read_b128 v[194:197], v168 offset:1024
	ds_read_b128 v[206:209], v168 offset:2048
	ds_read_b128 v[210:213], v168 offset:3072
	ds_read_b128 v[214:217], v168 offset:4096
	ds_read_b128 v[218:221], v168 offset:5120
	ds_read_b128 v[222:225], v168 offset:6144
	ds_read_b128 v[226:229], v168 offset:7168
	global_load_lds_dwordx4 v[230:231], off
	v_lshl_add_u64 v[230:231], v[154:155], 0, s[54:55]
	s_add_i32 m0, s72, 0xe000
	s_nop 0
	global_load_lds_dwordx4 v[230:231], off
	s_waitcnt lgkmcnt(8)
	s_barrier
	s_setprio 1
	s_waitcnt lgkmcnt(7)
	v_mfma_f32_16x16x32_bf16 v[16:19], v[146:149], v[182:185], v[16:19]
	v_mfma_f32_16x16x32_bf16 v[20:23], v[174:177], v[182:185], v[20:23]
	s_waitcnt lgkmcnt(5)
	v_mfma_f32_16x16x32_bf16 v[40:43], v[146:149], v[206:209], v[40:43]
	v_mfma_f32_16x16x32_bf16 v[32:35], v[174:177], v[206:209], v[32:35]
	s_waitcnt lgkmcnt(3)
	v_mfma_f32_16x16x32_bf16 v[64:67], v[146:149], v[214:217], v[64:67]
	v_mfma_f32_16x16x32_bf16 v[56:59], v[174:177], v[214:217], v[56:59]
	s_waitcnt lgkmcnt(1)
	v_mfma_f32_16x16x32_bf16 v[88:91], v[146:149], v[222:225], v[88:91]
	v_mfma_f32_16x16x32_bf16 v[80:83], v[174:177], v[222:225], v[80:83]
	v_mfma_f32_16x16x32_bf16 v[16:19], v[170:173], v[194:197], v[16:19]
	v_mfma_f32_16x16x32_bf16 v[20:23], v[178:181], v[194:197], v[20:23]
	v_mfma_f32_16x16x32_bf16 v[40:43], v[170:173], v[210:213], v[40:43]
	v_mfma_f32_16x16x32_bf16 v[32:35], v[178:181], v[210:213], v[32:35]
	v_mfma_f32_16x16x32_bf16 v[64:67], v[170:173], v[218:221], v[64:67]
	v_mfma_f32_16x16x32_bf16 v[56:59], v[178:181], v[218:221], v[56:59]
	s_waitcnt lgkmcnt(0)
	v_mfma_f32_16x16x32_bf16 v[88:91], v[170:173], v[226:229], v[88:91]
	v_mfma_f32_16x16x32_bf16 v[80:83], v[178:181], v[226:229], v[80:83]
	s_setprio 0
	s_barrier
	s_add_i32 s6, 0, 0x14000
	s_add_i32 s11, s23, s71
	v_add_u32_e32 v169, s6, v156
	v_lshl_add_u64 v[246:247], s[58:59], 0, v[130:131]
	s_mov_b32 m0, s11
	ds_read_b128 v[230:233], v169
	ds_read_b128 v[234:237], v169 offset:1024
	ds_read_b128 v[238:241], v169 offset:2048
	ds_read_b128 v[242:245], v169 offset:3072
	global_load_lds_dwordx4 v[246:247], off
	v_lshl_add_u64 v[248:249], s[58:59], 0, v[134:135]
	s_add_i32 m0, s11, 0x2000
	s_nop 0
	global_load_lds_dwordx4 v[248:249], off
	s_barrier
	s_setprio 1
	s_waitcnt lgkmcnt(3)
	v_mfma_f32_16x16x32_bf16 v[0:3], v[230:233], v[182:185], v[0:3]
	s_waitcnt lgkmcnt(1)
	v_mfma_f32_16x16x32_bf16 v[4:7], v[238:241], v[182:185], v[4:7]
	v_mfma_f32_16x16x32_bf16 v[8:11], v[230:233], v[206:209], v[8:11]
	v_mfma_f32_16x16x32_bf16 v[12:15], v[238:241], v[206:209], v[12:15]
	v_mfma_f32_16x16x32_bf16 v[24:27], v[230:233], v[214:217], v[24:27]
	v_mfma_f32_16x16x32_bf16 v[28:31], v[238:241], v[214:217], v[28:31]
	v_mfma_f32_16x16x32_bf16 v[48:51], v[230:233], v[222:225], v[48:51]
	v_mfma_f32_16x16x32_bf16 v[52:55], v[238:241], v[222:225], v[52:55]
	v_mfma_f32_16x16x32_bf16 v[0:3], v[234:237], v[194:197], v[0:3]
	s_waitcnt lgkmcnt(0)
	v_mfma_f32_16x16x32_bf16 v[4:7], v[242:245], v[194:197], v[4:7]
	v_mfma_f32_16x16x32_bf16 v[8:11], v[234:237], v[210:213], v[8:11]
	v_mfma_f32_16x16x32_bf16 v[12:15], v[242:245], v[210:213], v[12:15]
	v_mfma_f32_16x16x32_bf16 v[24:27], v[234:237], v[218:221], v[24:27]
	v_mfma_f32_16x16x32_bf16 v[28:31], v[242:245], v[218:221], v[28:31]
	v_mfma_f32_16x16x32_bf16 v[48:51], v[234:237], v[226:229], v[48:51]
	v_mfma_f32_16x16x32_bf16 v[52:55], v[242:245], v[226:229], v[52:55]
	s_setprio 0
	s_mov_b32 m0, s72
	v_lshl_add_u64 v[250:251], s[68:69], 0, v[128:129]
	s_barrier
	ds_read_b128 v[182:185], v168 offset:16384
	ds_read_b128 v[194:197], v168 offset:17408
	ds_read_b128 v[206:209], v168 offset:18432
	ds_read_b128 v[210:213], v168 offset:19456
	ds_read_b128 v[214:217], v168 offset:20480
	ds_read_b128 v[218:221], v168 offset:21504
	ds_read_b128 v[222:225], v168 offset:22528
	ds_read_b128 v[226:229], v168 offset:23552
	global_load_lds_dwordx4 v[250:251], off
	v_lshl_add_u64 v[192:193], s[68:69], 0, v[132:133]
	s_mov_b32 m0, s73
	s_nop 0
	global_load_lds_dwordx4 v[192:193], off
	s_barrier
	s_setprio 1
	s_waitcnt lgkmcnt(7)
	v_mfma_f32_16x16x32_bf16 v[76:79], v[146:149], v[182:185], v[76:79]
	v_mfma_f32_16x16x32_bf16 v[72:75], v[174:177], v[182:185], v[72:75]
	s_waitcnt lgkmcnt(5)
	v_mfma_f32_16x16x32_bf16 v[100:103], v[146:149], v[206:209], v[100:103]
	v_mfma_f32_16x16x32_bf16 v[96:99], v[174:177], v[206:209], v[96:99]
	s_waitcnt lgkmcnt(3)
	v_mfma_f32_16x16x32_bf16 v[116:119], v[146:149], v[214:217], v[116:119]
	v_mfma_f32_16x16x32_bf16 v[112:115], v[174:177], v[214:217], v[112:115]
	s_waitcnt lgkmcnt(1)
	v_mfma_f32_16x16x32_bf16 v[124:127], v[146:149], v[222:225], v[124:127]
	v_mfma_f32_16x16x32_bf16 v[120:123], v[174:177], v[222:225], v[120:123]
	v_mfma_f32_16x16x32_bf16 v[76:79], v[170:173], v[194:197], v[76:79]
	v_mfma_f32_16x16x32_bf16 v[72:75], v[178:181], v[194:197], v[72:75]
	v_mfma_f32_16x16x32_bf16 v[100:103], v[170:173], v[210:213], v[100:103]
	v_mfma_f32_16x16x32_bf16 v[96:99], v[178:181], v[210:213], v[96:99]
	v_mfma_f32_16x16x32_bf16 v[116:119], v[170:173], v[218:221], v[116:119]
	v_mfma_f32_16x16x32_bf16 v[112:115], v[178:181], v[218:221], v[112:115]
	s_waitcnt lgkmcnt(0)
	v_mfma_f32_16x16x32_bf16 v[124:127], v[170:173], v[226:229], v[124:127]
	v_mfma_f32_16x16x32_bf16 v[120:123], v[178:181], v[226:229], v[120:123]
	s_setprio 0
	s_barrier
	s_add_u32 s88, s58, 0x40000
	s_addc_u32 s89, s59, 0
	s_add_i32 s6, s6, s71
	v_lshl_add_u64 v[146:147], s[88:89], 0, v[130:131]
	s_mov_b32 m0, s6
	s_nop 0
	global_load_lds_dwordx4 v[146:147], off
	v_lshl_add_u64 v[146:147], s[88:89], 0, v[134:135]
	s_add_i32 m0, s6, 0x2000
	s_nop 0
	global_load_lds_dwordx4 v[146:147], off
	s_waitcnt vmcnt(6)
	s_barrier
	s_setprio 1
	v_mfma_f32_16x16x32_bf16 v[36:39], v[230:233], v[182:185], v[36:39]
	v_mfma_f32_16x16x32_bf16 v[60:63], v[230:233], v[206:209], v[60:63]
	v_mfma_f32_16x16x32_bf16 v[84:87], v[230:233], v[214:217], v[84:87]
	v_mfma_f32_16x16x32_bf16 v[108:111], v[230:233], v[222:225], v[108:111]
	v_mfma_f32_16x16x32_bf16 v[104:107], v[238:241], v[222:225], v[104:107]
	v_mfma_f32_16x16x32_bf16 v[92:95], v[238:241], v[214:217], v[92:95]
	v_mfma_f32_16x16x32_bf16 v[68:71], v[238:241], v[206:209], v[68:71]
	v_mfma_f32_16x16x32_bf16 v[44:47], v[238:241], v[182:185], v[44:47]
	v_mfma_f32_16x16x32_bf16 v[36:39], v[234:237], v[194:197], v[36:39]
	v_mfma_f32_16x16x32_bf16 v[60:63], v[234:237], v[210:213], v[60:63]
	v_mfma_f32_16x16x32_bf16 v[84:87], v[234:237], v[218:221], v[84:87]
	v_mfma_f32_16x16x32_bf16 v[108:111], v[234:237], v[226:229], v[108:111]
	v_mfma_f32_16x16x32_bf16 v[104:107], v[242:245], v[226:229], v[104:107]
	v_mfma_f32_16x16x32_bf16 v[92:95], v[242:245], v[218:221], v[92:95]
	v_mfma_f32_16x16x32_bf16 v[68:71], v[242:245], v[210:213], v[68:71]
	v_mfma_f32_16x16x32_bf16 v[44:47], v[242:245], v[194:197], v[44:47]
	s_setprio 0
	s_add_i32 s6, 0, 0x18000
	v_add_u32_e32 v169, s6, v156
	s_barrier
	ds_read_b128 v[146:149], v169
	ds_read_b128 v[170:173], v169 offset:1024
	ds_read_b128 v[174:177], v169 offset:2048
	ds_read_b128 v[178:181], v169 offset:3072
	s_add_u32 s68, s68, 0x40000
	s_addc_u32 s69, s69, 0
	s_mov_b32 m0, s74
	v_lshl_add_u64 v[230:231], s[68:69], 0, v[128:129]
	ds_read_b128 v[182:185], v168 offset:32768
	ds_read_b128 v[194:197], v168 offset:33792
	ds_read_b128 v[206:209], v168 offset:34816
	ds_read_b128 v[210:213], v168 offset:35840
	ds_read_b128 v[214:217], v168 offset:36864
	ds_read_b128 v[218:221], v168 offset:37888
	ds_read_b128 v[222:225], v168 offset:38912
	ds_read_b128 v[226:229], v168 offset:39936
	global_load_lds_dwordx4 v[230:231], off
	v_lshl_add_u64 v[230:231], s[68:69], 0, v[132:133]
	s_mov_b32 m0, s75
	s_nop 0
	global_load_lds_dwordx4 v[230:231], off
	s_waitcnt lgkmcnt(8)
	s_barrier
	s_setprio 1
	s_waitcnt lgkmcnt(7)
	v_mfma_f32_16x16x32_bf16 v[16:19], v[146:149], v[182:185], v[16:19]
	v_mfma_f32_16x16x32_bf16 v[20:23], v[174:177], v[182:185], v[20:23]
	s_waitcnt lgkmcnt(5)
	v_mfma_f32_16x16x32_bf16 v[40:43], v[146:149], v[206:209], v[40:43]
	v_mfma_f32_16x16x32_bf16 v[32:35], v[174:177], v[206:209], v[32:35]
	s_waitcnt lgkmcnt(3)
	v_mfma_f32_16x16x32_bf16 v[64:67], v[146:149], v[214:217], v[64:67]
	v_mfma_f32_16x16x32_bf16 v[56:59], v[174:177], v[214:217], v[56:59]
	s_waitcnt lgkmcnt(1)
	v_mfma_f32_16x16x32_bf16 v[88:91], v[146:149], v[222:225], v[88:91]
	v_mfma_f32_16x16x32_bf16 v[80:83], v[174:177], v[222:225], v[80:83]
	v_mfma_f32_16x16x32_bf16 v[16:19], v[170:173], v[194:197], v[16:19]
	v_mfma_f32_16x16x32_bf16 v[20:23], v[178:181], v[194:197], v[20:23]
	v_mfma_f32_16x16x32_bf16 v[40:43], v[170:173], v[210:213], v[40:43]
	v_mfma_f32_16x16x32_bf16 v[32:35], v[178:181], v[210:213], v[32:35]
	v_mfma_f32_16x16x32_bf16 v[64:67], v[170:173], v[218:221], v[64:67]
	v_mfma_f32_16x16x32_bf16 v[56:59], v[178:181], v[218:221], v[56:59]
	s_waitcnt lgkmcnt(0)
	v_mfma_f32_16x16x32_bf16 v[88:91], v[170:173], v[226:229], v[88:91]
	v_mfma_f32_16x16x32_bf16 v[80:83], v[178:181], v[226:229], v[80:83]
	s_setprio 0
	s_barrier
	s_add_i32 s11, 0, 0x1c000
	s_add_i32 s6, s6, s71
	v_add_u32_e32 v169, s11, v156
	v_lshl_add_u64 v[246:247], v[246:247], 0, s[36:37]
	s_mov_b32 m0, s6
	ds_read_b128 v[230:233], v169
	ds_read_b128 v[234:237], v169 offset:1024
	ds_read_b128 v[238:241], v169 offset:2048
	ds_read_b128 v[242:245], v169 offset:3072
	global_load_lds_dwordx4 v[246:247], off
	v_lshl_add_u64 v[246:247], v[248:249], 0, s[36:37]
	s_add_i32 m0, s6, 0x2000
	s_nop 0
	global_load_lds_dwordx4 v[246:247], off
	s_barrier
	s_setprio 1
	s_waitcnt lgkmcnt(3)
	v_mfma_f32_16x16x32_bf16 v[0:3], v[230:233], v[182:185], v[0:3]
	s_waitcnt lgkmcnt(1)
	v_mfma_f32_16x16x32_bf16 v[4:7], v[238:241], v[182:185], v[4:7]
	v_mfma_f32_16x16x32_bf16 v[8:11], v[230:233], v[206:209], v[8:11]
	v_mfma_f32_16x16x32_bf16 v[12:15], v[238:241], v[206:209], v[12:15]
	v_mfma_f32_16x16x32_bf16 v[24:27], v[230:233], v[214:217], v[24:27]
	v_mfma_f32_16x16x32_bf16 v[28:31], v[238:241], v[214:217], v[28:31]
	v_mfma_f32_16x16x32_bf16 v[48:51], v[230:233], v[222:225], v[48:51]
	v_mfma_f32_16x16x32_bf16 v[52:55], v[238:241], v[222:225], v[52:55]
	v_mfma_f32_16x16x32_bf16 v[0:3], v[234:237], v[194:197], v[0:3]
	s_waitcnt lgkmcnt(0)
	v_mfma_f32_16x16x32_bf16 v[4:7], v[242:245], v[194:197], v[4:7]
	v_mfma_f32_16x16x32_bf16 v[8:11], v[234:237], v[210:213], v[8:11]
	v_mfma_f32_16x16x32_bf16 v[12:15], v[242:245], v[210:213], v[12:15]
	v_mfma_f32_16x16x32_bf16 v[24:27], v[234:237], v[218:221], v[24:27]
	v_mfma_f32_16x16x32_bf16 v[28:31], v[242:245], v[218:221], v[28:31]
	v_mfma_f32_16x16x32_bf16 v[48:51], v[234:237], v[226:229], v[48:51]
	v_mfma_f32_16x16x32_bf16 v[52:55], v[242:245], v[226:229], v[52:55]
	s_setprio 0
	s_mov_b32 m0, s82
	v_lshl_add_u64 v[246:247], v[250:251], 0, s[36:37]
	s_barrier
	ds_read_b128 v[182:185], v168 offset:49152
	ds_read_b128 v[194:197], v168 offset:50176
	ds_read_b128 v[206:209], v168 offset:51200
	ds_read_b128 v[210:213], v168 offset:52224
	ds_read_b128 v[214:217], v168 offset:53248
	ds_read_b128 v[218:221], v168 offset:54272
	ds_read_b128 v[222:225], v168 offset:55296
	ds_read_b128 v[226:229], v168 offset:56320
	global_load_lds_dwordx4 v[246:247], off
	v_lshl_add_u64 v[192:193], v[192:193], 0, s[36:37]
	s_mov_b32 m0, s83
	s_nop 0
	global_load_lds_dwordx4 v[192:193], off
	s_barrier
	s_setprio 1
	s_waitcnt lgkmcnt(7)
	v_mfma_f32_16x16x32_bf16 v[76:79], v[146:149], v[182:185], v[76:79]
	v_mfma_f32_16x16x32_bf16 v[72:75], v[174:177], v[182:185], v[72:75]
	s_waitcnt lgkmcnt(5)
	v_mfma_f32_16x16x32_bf16 v[100:103], v[146:149], v[206:209], v[100:103]
	v_mfma_f32_16x16x32_bf16 v[96:99], v[174:177], v[206:209], v[96:99]
	s_waitcnt lgkmcnt(3)
	v_mfma_f32_16x16x32_bf16 v[116:119], v[146:149], v[214:217], v[116:119]
	v_mfma_f32_16x16x32_bf16 v[112:115], v[174:177], v[214:217], v[112:115]
	s_waitcnt lgkmcnt(1)
	v_mfma_f32_16x16x32_bf16 v[124:127], v[146:149], v[222:225], v[124:127]
	v_mfma_f32_16x16x32_bf16 v[120:123], v[174:177], v[222:225], v[120:123]
	v_mfma_f32_16x16x32_bf16 v[76:79], v[170:173], v[194:197], v[76:79]
	v_mfma_f32_16x16x32_bf16 v[72:75], v[178:181], v[194:197], v[72:75]
	v_mfma_f32_16x16x32_bf16 v[100:103], v[170:173], v[210:213], v[100:103]
	v_mfma_f32_16x16x32_bf16 v[96:99], v[178:181], v[210:213], v[96:99]
	v_mfma_f32_16x16x32_bf16 v[116:119], v[170:173], v[218:221], v[116:119]
	v_mfma_f32_16x16x32_bf16 v[112:115], v[178:181], v[218:221], v[112:115]
	s_waitcnt lgkmcnt(0)
	v_mfma_f32_16x16x32_bf16 v[124:127], v[170:173], v[226:229], v[124:127]
	v_mfma_f32_16x16x32_bf16 v[120:123], v[178:181], v[226:229], v[120:123]
	s_setprio 0
	s_barrier
	s_add_u32 s58, s58, 0x40080
	s_addc_u32 s59, s59, 0
	s_add_i32 s6, s11, s71
	v_lshl_add_u64 v[146:147], s[58:59], 0, v[130:131]
	s_mov_b32 m0, s6
	s_nop 0
	global_load_lds_dwordx4 v[146:147], off
	v_lshl_add_u64 v[146:147], s[58:59], 0, v[134:135]
	s_add_i32 m0, s6, 0x2000
	s_nop 0
	global_load_lds_dwordx4 v[146:147], off
	s_waitcnt vmcnt(6)
	s_barrier
	s_setprio 1
	v_mfma_f32_16x16x32_bf16 v[36:39], v[230:233], v[182:185], v[36:39]
	v_mfma_f32_16x16x32_bf16 v[60:63], v[230:233], v[206:209], v[60:63]
	v_mfma_f32_16x16x32_bf16 v[84:87], v[230:233], v[214:217], v[84:87]
	v_mfma_f32_16x16x32_bf16 v[108:111], v[230:233], v[222:225], v[108:111]
	v_mfma_f32_16x16x32_bf16 v[104:107], v[238:241], v[222:225], v[104:107]
	v_mfma_f32_16x16x32_bf16 v[92:95], v[238:241], v[214:217], v[92:95]
	v_mfma_f32_16x16x32_bf16 v[68:71], v[238:241], v[206:209], v[68:71]
	v_mfma_f32_16x16x32_bf16 v[44:47], v[238:241], v[182:185], v[44:47]
	v_mfma_f32_16x16x32_bf16 v[36:39], v[234:237], v[194:197], v[36:39]
	v_mfma_f32_16x16x32_bf16 v[60:63], v[234:237], v[210:213], v[60:63]
	v_mfma_f32_16x16x32_bf16 v[84:87], v[234:237], v[218:221], v[84:87]
	v_mfma_f32_16x16x32_bf16 v[108:111], v[234:237], v[226:229], v[108:111]
	v_mfma_f32_16x16x32_bf16 v[104:107], v[242:245], v[226:229], v[104:107]
	v_mfma_f32_16x16x32_bf16 v[92:95], v[242:245], v[218:221], v[92:95]
	v_mfma_f32_16x16x32_bf16 v[68:71], v[242:245], v[210:213], v[68:71]
	v_mfma_f32_16x16x32_bf16 v[44:47], v[242:245], v[194:197], v[44:47]
	s_setprio 0
	s_add_i32 s10, s10, 2
	s_add_u32 s54, s54, 0x100
	s_addc_u32 s55, s55, 0
	s_cmp_gt_u32 s10, 13
	s_barrier
	s_cbranch_scc0 .LBB0_192
	s_lshl_b32 s6, s84, 10
	v_add_u32_e32 v154, s6, v167
	ds_read_b32 v148, v154
	s_mov_b32 s6, 0xff61b1e6
	v_and_b32_e32 v147, 64, v188
	v_xor_b32_e32 v146, 16, v188
	v_add_u32_e32 v147, 64, v147
	s_waitcnt lgkmcnt(0)
	v_mul_f32_e32 v174, v16, v148
	v_mul_f32_e32 v16, v17, v148
	v_max3_f32 v17, v174, s6, v16
	v_mul_f32_e32 v18, v18, v148
	v_mul_f32_e32 v19, v19, v148
	v_max3_f32 v17, v17, v18, v19
	v_mul_f32_e32 v20, v20, v148
	v_mul_f32_e32 v21, v21, v148
	v_max3_f32 v17, v17, v20, v21
	v_mul_f32_e32 v22, v22, v148
	v_mul_f32_e32 v23, v23, v148
	v_max3_f32 v17, v17, v22, v23
	v_mul_f32_e32 v0, v0, v148
	v_mul_f32_e32 v1, v1, v148
	v_max3_f32 v17, v17, v0, v1
	v_mul_f32_e32 v2, v2, v148
	v_mul_f32_e32 v3, v3, v148
	v_cmp_lt_i32_e32 vcc, v146, v147
	v_max3_f32 v17, v17, v2, v3
	v_mul_f32_e32 v4, v4, v148
	v_mul_f32_e32 v5, v5, v148
	v_cndmask_b32_e32 v146, v188, v146, vcc
	v_max3_f32 v17, v17, v4, v5
	v_mul_f32_e32 v6, v6, v148
	v_mul_f32_e32 v7, v7, v148
	v_lshlrev_b32_e32 v152, 2, v146
	v_max3_f32 v17, v17, v6, v7
	ds_bpermute_b32 v146, v152, v17
	v_xor_b32_e32 v148, 32, v188
	v_cmp_lt_i32_e32 vcc, v148, v147
	s_waitcnt lgkmcnt(0)
	v_max_f32_e32 v146, v146, v146
	v_cndmask_b32_e32 v147, v188, v148, vcc
	v_lshlrev_b32_e32 v153, 2, v147
	v_max_f32_e32 v17, v17, v146
	ds_bpermute_b32 v155, v153, v17
	s_and_saveexec_b64 s[54:55], s[42:43]
	s_cbranch_execz .LBB0_195
	s_waitcnt lgkmcnt(0)
	v_max_f32_e32 v146, v155, v155
	v_max_f32_e32 v17, v17, v17
	v_max_f32_e32 v17, v17, v146
	v_add_u32_e32 v146, s85, v157
	ds_write_b32 v146, v17

.Lm4ap_248:
	s_waitcnt lgkmcnt(0)
	s_barrier
	v_mfma_f32_16x16x32_bf16 v[124:127], v[128:131], v[162:165], 0
	v_mfma_f32_16x16x32_bf16 v[108:111], v[128:131], v[170:173], 0
	v_mfma_f32_16x16x32_bf16 v[96:99], v[128:131], v[178:181], 0
	v_mfma_f32_16x16x32_bf16 v[84:87], v[128:131], v[194:197], 0
	v_mfma_f32_16x16x32_bf16 v[80:83], v[136:139], v[194:197], 0
	v_mfma_f32_16x16x32_bf16 v[88:91], v[136:139], v[178:181], 0
	v_mfma_f32_16x16x32_bf16 v[104:107], v[136:139], v[170:173], 0
	v_mfma_f32_16x16x32_bf16 v[120:123], v[136:139], v[162:165], 0
	v_mfma_f32_16x16x32_bf16 v[124:127], v[132:135], v[166:169], v[124:127]
	v_mfma_f32_16x16x32_bf16 v[108:111], v[132:135], v[174:177], v[108:111]
	v_mfma_f32_16x16x32_bf16 v[96:99], v[132:135], v[182:185], v[96:99]
	v_mfma_f32_16x16x32_bf16 v[84:87], v[132:135], v[210:213], v[84:87]
	v_mfma_f32_16x16x32_bf16 v[80:83], v[146:149], v[210:213], v[80:83]
	v_mfma_f32_16x16x32_bf16 v[88:91], v[146:149], v[182:185], v[88:91]
	v_mfma_f32_16x16x32_bf16 v[104:107], v[146:149], v[174:177], v[104:107]
	v_mfma_f32_16x16x32_bf16 v[120:123], v[146:149], v[166:169], v[120:123]
	v_mfma_f32_16x16x32_bf16 v[116:119], v[214:217], v[162:165], 0
	v_mfma_f32_16x16x32_bf16 v[100:103], v[214:217], v[170:173], 0
	v_mfma_f32_16x16x32_bf16 v[76:79], v[214:217], v[178:181], 0
	v_mfma_f32_16x16x32_bf16 v[68:71], v[214:217], v[194:197], 0
	v_mfma_f32_16x16x32_bf16 v[64:67], v[222:225], v[194:197], 0
	v_mfma_f32_16x16x32_bf16 v[72:75], v[222:225], v[178:181], 0
	v_mfma_f32_16x16x32_bf16 v[92:95], v[222:225], v[170:173], 0
	v_mfma_f32_16x16x32_bf16 v[112:115], v[222:225], v[162:165], 0
	v_mfma_f32_16x16x32_bf16 v[116:119], v[218:221], v[166:169], v[116:119]
	v_mfma_f32_16x16x32_bf16 v[100:103], v[218:221], v[174:177], v[100:103]
	v_mfma_f32_16x16x32_bf16 v[76:79], v[218:221], v[182:185], v[76:79]
	v_mfma_f32_16x16x32_bf16 v[68:71], v[218:221], v[210:213], v[68:71]
	v_mfma_f32_16x16x32_bf16 v[64:67], v[226:229], v[210:213], v[64:67]
	v_mfma_f32_16x16x32_bf16 v[72:75], v[226:229], v[182:185], v[72:75]
	v_mfma_f32_16x16x32_bf16 v[92:95], v[226:229], v[174:177], v[92:95]
	v_mfma_f32_16x16x32_bf16 v[112:115], v[226:229], v[166:169], v[112:115]
	s_barrier
	s_add_i32 s19, s23, s57
	v_lshl_add_u64 v[230:231], s[54:55], 0, v[140:141]
	s_mov_b32 m0, s19
	s_nop 0
	global_load_lds_dwordx4 v[230:231], off
	v_lshl_add_u64 v[232:233], s[54:55], 0, v[150:151]
	s_add_i32 m0, s19, 0x2000
	s_nop 0
	global_load_lds_dwordx4 v[232:233], off
	s_mov_b32 m0, s68
	v_lshl_add_u64 v[234:235], s[58:59], 0, v[154:155]
	ds_read_b128 v[162:165], v208 offset:16384
	ds_read_b128 v[166:169], v208 offset:17408
	ds_read_b128 v[170:173], v208 offset:18432
	ds_read_b128 v[174:177], v208 offset:19456
	ds_read_b128 v[178:181], v208 offset:20480
	ds_read_b128 v[182:185], v208 offset:21504
	ds_read_b128 v[194:197], v208 offset:22528
	ds_read_b128 v[210:213], v208 offset:23552
	global_load_lds_dwordx4 v[234:235], off
	v_lshl_add_u64 v[236:237], s[58:59], 0, v[152:153]
	s_mov_b32 m0, s69
	s_nop 0
	global_load_lds_dwordx4 v[236:237], off
	s_add_u32 s84, s54, 0x40000
	s_addc_u32 s85, s55, 0
	s_add_i32 s6, s6, s57
	v_lshl_add_u64 v[250:251], s[84:85], 0, v[140:141]
	s_mov_b32 m0, s6
	s_nop 0
	global_load_lds_dwordx4 v[250:251], off
	v_lshl_add_u64 v[250:251], s[84:85], 0, v[150:151]
	s_add_i32 m0, s6, 0x2000
	s_nop 0
	global_load_lds_dwordx4 v[250:251], off
	s_waitcnt vmcnt(40)
	s_cmp_lg_u32 s100, 0
	s_cbranch_scc1 .Lm4bp_248
	s_waitcnt vmcnt(8)
.Lm4bp_248:
	s_waitcnt lgkmcnt(0)
	s_mov_b32 s100, 0
	s_barrier
	v_mfma_f32_16x16x32_bf16 v[60:63], v[128:131], v[162:165], 0
	v_mfma_f32_16x16x32_bf16 v[48:51], v[128:131], v[170:173], 0
	v_mfma_f32_16x16x32_bf16 v[32:35], v[128:131], v[178:181], 0
	v_mfma_f32_16x16x32_bf16 v[16:19], v[128:131], v[194:197], 0
	v_mfma_f32_16x16x32_bf16 v[8:11], v[136:139], v[194:197], 0
	v_mfma_f32_16x16x32_bf16 v[24:27], v[136:139], v[178:181], 0
	v_mfma_f32_16x16x32_bf16 v[40:43], v[136:139], v[170:173], 0
	v_mfma_f32_16x16x32_bf16 v[56:59], v[136:139], v[162:165], 0
	v_mfma_f32_16x16x32_bf16 v[60:63], v[132:135], v[166:169], v[60:63]
	v_mfma_f32_16x16x32_bf16 v[48:51], v[132:135], v[174:177], v[48:51]
	v_mfma_f32_16x16x32_bf16 v[32:35], v[132:135], v[182:185], v[32:35]
	v_mfma_f32_16x16x32_bf16 v[16:19], v[132:135], v[210:213], v[16:19]
	v_mfma_f32_16x16x32_bf16 v[8:11], v[146:149], v[210:213], v[8:11]
	v_mfma_f32_16x16x32_bf16 v[24:27], v[146:149], v[182:185], v[24:27]
	v_mfma_f32_16x16x32_bf16 v[40:43], v[146:149], v[174:177], v[40:43]
	v_mfma_f32_16x16x32_bf16 v[56:59], v[146:149], v[166:169], v[56:59]
	v_mfma_f32_16x16x32_bf16 v[52:55], v[214:217], v[162:165], 0
	v_mfma_f32_16x16x32_bf16 v[36:39], v[214:217], v[170:173], 0
	v_mfma_f32_16x16x32_bf16 v[20:23], v[214:217], v[178:181], 0
	v_mfma_f32_16x16x32_bf16 v[4:7], v[214:217], v[194:197], 0
	v_mfma_f32_16x16x32_bf16 v[0:3], v[222:225], v[194:197], 0
	v_mfma_f32_16x16x32_bf16 v[12:15], v[222:225], v[178:181], 0
	v_mfma_f32_16x16x32_bf16 v[28:31], v[222:225], v[170:173], 0
	v_mfma_f32_16x16x32_bf16 v[44:47], v[222:225], v[162:165], 0
	v_mfma_f32_16x16x32_bf16 v[52:55], v[218:221], v[166:169], v[52:55]
	v_mfma_f32_16x16x32_bf16 v[36:39], v[218:221], v[174:177], v[36:39]
	v_mfma_f32_16x16x32_bf16 v[20:23], v[218:221], v[182:185], v[20:23]
	v_mfma_f32_16x16x32_bf16 v[4:7], v[218:221], v[210:213], v[4:7]
	v_mfma_f32_16x16x32_bf16 v[0:3], v[226:229], v[210:213], v[0:3]
	v_mfma_f32_16x16x32_bf16 v[12:15], v[226:229], v[182:185], v[12:15]
	v_mfma_f32_16x16x32_bf16 v[28:31], v[226:229], v[174:177], v[28:31]
	v_mfma_f32_16x16x32_bf16 v[44:47], v[226:229], v[166:169], v[44:47]
	s_barrier
	s_add_i32 s6, 0, 0x18000
	v_add_u32_e32 v146, s6, v206
	ds_read_b128 v[128:131], v146
	ds_read_b128 v[132:135], v146 offset:1024
	ds_read_b128 v[136:139], v146 offset:2048
	ds_read_b128 v[146:149], v146 offset:3072
	s_add_u32 s58, s58, 0x40000
	s_addc_u32 s59, s59, 0
	s_mov_b32 m0, s70
	v_lshl_add_u64 v[214:215], s[58:59], 0, v[154:155]
	ds_read_b128 v[162:165], v208 offset:32768
	ds_read_b128 v[166:169], v208 offset:33792
	ds_read_b128 v[170:173], v208 offset:34816
	ds_read_b128 v[174:177], v208 offset:35840
	ds_read_b128 v[178:181], v208 offset:36864
	ds_read_b128 v[182:185], v208 offset:37888
	ds_read_b128 v[194:197], v208 offset:38912
	ds_read_b128 v[210:213], v208 offset:39936
	global_load_lds_dwordx4 v[214:215], off
	v_lshl_add_u64 v[214:215], s[58:59], 0, v[152:153]
	s_mov_b32 m0, s71
	s_nop 0
	global_load_lds_dwordx4 v[214:215], off
	s_add_i32 s19, 0, 0x1c000
	v_add_u32_e32 v192, s19, v206
	ds_read_b128 v[214:217], v192
	ds_read_b128 v[218:221], v192 offset:1024
	ds_read_b128 v[222:225], v192 offset:2048
	ds_read_b128 v[226:229], v192 offset:3072
	s_waitcnt vmcnt(8)
	s_waitcnt lgkmcnt(0)
	s_barrier
	v_mfma_f32_16x16x32_bf16 v[124:127], v[128:131], v[162:165], v[124:127]
	v_mfma_f32_16x16x32_bf16 v[108:111], v[128:131], v[170:173], v[108:111]
	v_mfma_f32_16x16x32_bf16 v[96:99], v[128:131], v[178:181], v[96:99]
	v_mfma_f32_16x16x32_bf16 v[84:87], v[128:131], v[194:197], v[84:87]
	v_mfma_f32_16x16x32_bf16 v[80:83], v[136:139], v[194:197], v[80:83]
	v_mfma_f32_16x16x32_bf16 v[88:91], v[136:139], v[178:181], v[88:91]
	v_mfma_f32_16x16x32_bf16 v[104:107], v[136:139], v[170:173], v[104:107]
	v_mfma_f32_16x16x32_bf16 v[120:123], v[136:139], v[162:165], v[120:123]
	v_mfma_f32_16x16x32_bf16 v[124:127], v[132:135], v[166:169], v[124:127]
	v_mfma_f32_16x16x32_bf16 v[108:111], v[132:135], v[174:177], v[108:111]
	v_mfma_f32_16x16x32_bf16 v[96:99], v[132:135], v[182:185], v[96:99]
	v_mfma_f32_16x16x32_bf16 v[84:87], v[132:135], v[210:213], v[84:87]
	v_mfma_f32_16x16x32_bf16 v[80:83], v[146:149], v[210:213], v[80:83]
	v_mfma_f32_16x16x32_bf16 v[88:91], v[146:149], v[182:185], v[88:91]
	v_mfma_f32_16x16x32_bf16 v[104:107], v[146:149], v[174:177], v[104:107]
	v_mfma_f32_16x16x32_bf16 v[120:123], v[146:149], v[166:169], v[120:123]
	v_mfma_f32_16x16x32_bf16 v[116:119], v[214:217], v[162:165], v[116:119]
	v_mfma_f32_16x16x32_bf16 v[100:103], v[214:217], v[170:173], v[100:103]
	v_mfma_f32_16x16x32_bf16 v[76:79], v[214:217], v[178:181], v[76:79]
	v_mfma_f32_16x16x32_bf16 v[68:71], v[214:217], v[194:197], v[68:71]
	v_mfma_f32_16x16x32_bf16 v[64:67], v[222:225], v[194:197], v[64:67]
	v_mfma_f32_16x16x32_bf16 v[72:75], v[222:225], v[178:181], v[72:75]
	v_mfma_f32_16x16x32_bf16 v[92:95], v[222:225], v[170:173], v[92:95]
	v_mfma_f32_16x16x32_bf16 v[112:115], v[222:225], v[162:165], v[112:115]
	v_mfma_f32_16x16x32_bf16 v[116:119], v[218:221], v[166:169], v[116:119]
	v_mfma_f32_16x16x32_bf16 v[100:103], v[218:221], v[174:177], v[100:103]
	v_mfma_f32_16x16x32_bf16 v[76:79], v[218:221], v[182:185], v[76:79]
	v_mfma_f32_16x16x32_bf16 v[68:71], v[218:221], v[210:213], v[68:71]
	v_mfma_f32_16x16x32_bf16 v[64:67], v[226:229], v[210:213], v[64:67]
	v_mfma_f32_16x16x32_bf16 v[72:75], v[226:229], v[182:185], v[72:75]
	v_mfma_f32_16x16x32_bf16 v[92:95], v[226:229], v[174:177], v[92:95]
	v_mfma_f32_16x16x32_bf16 v[112:115], v[226:229], v[166:169], v[112:115]
	s_barrier
	s_add_i32 s6, s6, s57
	v_lshl_add_u64 v[230:231], v[230:231], 0, s[36:37]
	s_mov_b32 m0, s6
	s_nop 0
	global_load_lds_dwordx4 v[230:231], off
	v_lshl_add_u64 v[230:231], v[232:233], 0, s[36:37]
	s_add_i32 m0, s6, 0x2000
	s_nop 0
	global_load_lds_dwordx4 v[230:231], off
	s_mov_b32 m0, s72
	v_lshl_add_u64 v[230:231], v[234:235], 0, s[36:37]
	ds_read_b128 v[162:165], v208 offset:49152
	ds_read_b128 v[166:169], v208 offset:50176
	ds_read_b128 v[170:173], v208 offset:51200
	ds_read_b128 v[174:177], v208 offset:52224
	ds_read_b128 v[178:181], v208 offset:53248
	ds_read_b128 v[182:185], v208 offset:54272
	ds_read_b128 v[194:197], v208 offset:55296
	ds_read_b128 v[210:213], v208 offset:56320
	global_load_lds_dwordx4 v[230:231], off
	v_lshl_add_u64 v[230:231], v[236:237], 0, s[36:37]
	s_mov_b32 m0, s73
	s_nop 0
	global_load_lds_dwordx4 v[230:231], off
	s_add_u32 s54, s54, 0x40080
	s_addc_u32 s55, s55, 0
	s_add_i32 s6, s19, s57
	v_lshl_add_u64 v[250:251], s[54:55], 0, v[140:141]
	s_mov_b32 m0, s6
	s_nop 0
	global_load_lds_dwordx4 v[250:251], off
	v_lshl_add_u64 v[250:251], s[54:55], 0, v[150:151]
	s_add_i32 m0, s6, 0x2000
	s_nop 0
	global_load_lds_dwordx4 v[250:251], off
	s_waitcnt vmcnt(8)
	s_waitcnt lgkmcnt(0)
	s_barrier
	v_mfma_f32_16x16x32_bf16 v[60:63], v[128:131], v[162:165], v[60:63]
	v_mfma_f32_16x16x32_bf16 v[48:51], v[128:131], v[170:173], v[48:51]
	v_mfma_f32_16x16x32_bf16 v[32:35], v[128:131], v[178:181], v[32:35]
	v_mfma_f32_16x16x32_bf16 v[16:19], v[128:131], v[194:197], v[16:19]
	v_mfma_f32_16x16x32_bf16 v[8:11], v[136:139], v[194:197], v[8:11]
	v_mfma_f32_16x16x32_bf16 v[24:27], v[136:139], v[178:181], v[24:27]
	v_mfma_f32_16x16x32_bf16 v[40:43], v[136:139], v[170:173], v[40:43]
	v_mfma_f32_16x16x32_bf16 v[56:59], v[136:139], v[162:165], v[56:59]
	v_mfma_f32_16x16x32_bf16 v[60:63], v[132:135], v[166:169], v[60:63]
	v_mfma_f32_16x16x32_bf16 v[48:51], v[132:135], v[174:177], v[48:51]
	v_mfma_f32_16x16x32_bf16 v[32:35], v[132:135], v[182:185], v[32:35]
	v_mfma_f32_16x16x32_bf16 v[16:19], v[132:135], v[210:213], v[16:19]
	v_mfma_f32_16x16x32_bf16 v[8:11], v[146:149], v[210:213], v[8:11]
	v_mfma_f32_16x16x32_bf16 v[24:27], v[146:149], v[182:185], v[24:27]
	v_mfma_f32_16x16x32_bf16 v[40:43], v[146:149], v[174:177], v[40:43]
	v_mfma_f32_16x16x32_bf16 v[56:59], v[146:149], v[166:169], v[56:59]
	v_mfma_f32_16x16x32_bf16 v[52:55], v[214:217], v[162:165], v[52:55]
	v_mfma_f32_16x16x32_bf16 v[36:39], v[214:217], v[170:173], v[36:39]
	v_mfma_f32_16x16x32_bf16 v[20:23], v[214:217], v[178:181], v[20:23]
	v_mfma_f32_16x16x32_bf16 v[4:7], v[214:217], v[194:197], v[4:7]
	v_mfma_f32_16x16x32_bf16 v[0:3], v[222:225], v[194:197], v[0:3]
	v_mfma_f32_16x16x32_bf16 v[12:15], v[222:225], v[178:181], v[12:15]
	v_mfma_f32_16x16x32_bf16 v[28:31], v[222:225], v[170:173], v[28:31]
	v_mfma_f32_16x16x32_bf16 v[44:47], v[222:225], v[162:165], v[44:47]
	v_mfma_f32_16x16x32_bf16 v[52:55], v[218:221], v[166:169], v[52:55]
	v_mfma_f32_16x16x32_bf16 v[36:39], v[218:221], v[174:177], v[36:39]
	v_mfma_f32_16x16x32_bf16 v[20:23], v[218:221], v[182:185], v[20:23]
	v_mfma_f32_16x16x32_bf16 v[4:7], v[218:221], v[210:213], v[4:7]
	v_mfma_f32_16x16x32_bf16 v[0:3], v[226:229], v[210:213], v[0:3]
	v_mfma_f32_16x16x32_bf16 v[12:15], v[226:229], v[182:185], v[12:15]
	v_mfma_f32_16x16x32_bf16 v[28:31], v[226:229], v[174:177], v[28:31]
	v_mfma_f32_16x16x32_bf16 v[44:47], v[226:229], v[166:169], v[44:47]
	s_add_i32 s82, s82, 2
	s_add_u32 s52, s52, 0x100
	s_addc_u32 s53, s53, 0
	s_add_u32 s39, s39, 0x100
	s_addc_u32 s51, s51, 0
	s_cmp_gt_u32 s82, 13
	s_barrier
.LBB0_248:
	s_add_u32 s6, s52, 0xfffc0080
	s_addc_u32 s19, s53, -1
	s_add_i32 s23, 0, 0x10000
	v_add_u32_e32 v146, s23, v206
	ds_read_b128 v[128:131], v146
	ds_read_b128 v[132:135], v146 offset:1024
	ds_read_b128 v[136:139], v146 offset:2048
	ds_read_b128 v[146:149], v146 offset:3072
	s_cmp_eq_u32 s82, 12
	s_cselect_b32 s59, s10, s19
	s_cselect_b32 s58, s11, s6
	s_cselect_b32 s55, s12, s51
	s_cselect_b32 s54, s35, s39
	v_lshl_add_u64 v[214:215], s[52:53], 0, v[158:159]
	s_add_i32 m0, s68, 0xc000
	ds_read_b128 v[162:165], v208
	ds_read_b128 v[166:169], v208 offset:1024
	ds_read_b128 v[170:173], v208 offset:2048
	ds_read_b128 v[174:177], v208 offset:3072
	ds_read_b128 v[178:181], v208 offset:4096
	ds_read_b128 v[182:185], v208 offset:5120
	ds_read_b128 v[194:197], v208 offset:6144
	ds_read_b128 v[210:213], v208 offset:7168
	global_load_lds_dwordx4 v[214:215], off
	v_lshl_add_u64 v[214:215], s[52:53], 0, v[160:161]
	s_add_i32 m0, s68, 0xe000
	s_nop 0
	global_load_lds_dwordx4 v[214:215], off
	s_add_i32 s6, 0, 0x14000
	v_add_u32_e32 v192, s6, v206
	ds_read_b128 v[214:217], v192
	ds_read_b128 v[218:221], v192 offset:1024
	ds_read_b128 v[222:225], v192 offset:2048
	ds_read_b128 v[226:229], v192 offset:3072
	s_nop 0
	s_waitcnt vmcnt(8)
	s_waitcnt lgkmcnt(0)
	s_barrier
	v_mfma_f32_16x16x32_bf16 v[124:127], v[128:131], v[162:165], v[124:127]
	v_mfma_f32_16x16x32_bf16 v[108:111], v[128:131], v[170:173], v[108:111]
	v_mfma_f32_16x16x32_bf16 v[96:99], v[128:131], v[178:181], v[96:99]
	v_mfma_f32_16x16x32_bf16 v[84:87], v[128:131], v[194:197], v[84:87]
	v_mfma_f32_16x16x32_bf16 v[80:83], v[136:139], v[194:197], v[80:83]
	v_mfma_f32_16x16x32_bf16 v[88:91], v[136:139], v[178:181], v[88:91]
	v_mfma_f32_16x16x32_bf16 v[104:107], v[136:139], v[170:173], v[104:107]
	v_mfma_f32_16x16x32_bf16 v[120:123], v[136:139], v[162:165], v[120:123]
	v_mfma_f32_16x16x32_bf16 v[124:127], v[132:135], v[166:169], v[124:127]
	v_mfma_f32_16x16x32_bf16 v[108:111], v[132:135], v[174:177], v[108:111]
	v_mfma_f32_16x16x32_bf16 v[96:99], v[132:135], v[182:185], v[96:99]
	v_mfma_f32_16x16x32_bf16 v[84:87], v[132:135], v[210:213], v[84:87]
	v_mfma_f32_16x16x32_bf16 v[80:83], v[146:149], v[210:213], v[80:83]
	v_mfma_f32_16x16x32_bf16 v[88:91], v[146:149], v[182:185], v[88:91]
	v_mfma_f32_16x16x32_bf16 v[104:107], v[146:149], v[174:177], v[104:107]
	v_mfma_f32_16x16x32_bf16 v[120:123], v[146:149], v[166:169], v[120:123]
	v_mfma_f32_16x16x32_bf16 v[116:119], v[214:217], v[162:165], v[116:119]
	v_mfma_f32_16x16x32_bf16 v[100:103], v[214:217], v[170:173], v[100:103]
	v_mfma_f32_16x16x32_bf16 v[76:79], v[214:217], v[178:181], v[76:79]
	v_mfma_f32_16x16x32_bf16 v[68:71], v[214:217], v[194:197], v[68:71]
	v_mfma_f32_16x16x32_bf16 v[64:67], v[222:225], v[194:197], v[64:67]
	v_mfma_f32_16x16x32_bf16 v[72:75], v[222:225], v[178:181], v[72:75]
	v_mfma_f32_16x16x32_bf16 v[92:95], v[222:225], v[170:173], v[92:95]
	v_mfma_f32_16x16x32_bf16 v[112:115], v[222:225], v[162:165], v[112:115]
	v_mfma_f32_16x16x32_bf16 v[116:119], v[218:221], v[166:169], v[116:119]
	v_mfma_f32_16x16x32_bf16 v[100:103], v[218:221], v[174:177], v[100:103]
	v_mfma_f32_16x16x32_bf16 v[76:79], v[218:221], v[182:185], v[76:79]
	v_mfma_f32_16x16x32_bf16 v[68:71], v[218:221], v[210:213], v[68:71]
	v_mfma_f32_16x16x32_bf16 v[64:67], v[226:229], v[210:213], v[64:67]
	v_mfma_f32_16x16x32_bf16 v[72:75], v[226:229], v[182:185], v[72:75]
	v_mfma_f32_16x16x32_bf16 v[92:95], v[226:229], v[174:177], v[92:95]
	v_mfma_f32_16x16x32_bf16 v[112:115], v[226:229], v[166:169], v[112:115]
	s_barrier
	s_add_i32 s19, s23, s57
	v_lshl_add_u64 v[230:231], s[54:55], 0, v[140:141]
	s_mov_b32 m0, s19
	s_nop 0
	global_load_lds_dwordx4 v[230:231], off
	v_lshl_add_u64 v[232:233], s[54:55], 0, v[150:151]
	s_add_i32 m0, s19, 0x2000
	s_nop 0
	global_load_lds_dwordx4 v[232:233], off
	s_mov_b32 m0, s68
	v_lshl_add_u64 v[234:235], s[58:59], 0, v[154:155]
	ds_read_b128 v[162:165], v208 offset:16384
	ds_read_b128 v[166:169], v208 offset:17408
	ds_read_b128 v[170:173], v208 offset:18432
	ds_read_b128 v[174:177], v208 offset:19456
	ds_read_b128 v[178:181], v208 offset:20480
	ds_read_b128 v[182:185], v208 offset:21504
	ds_read_b128 v[194:197], v208 offset:22528
	ds_read_b128 v[210:213], v208 offset:23552
	global_load_lds_dwordx4 v[234:235], off
	v_lshl_add_u64 v[236:237], s[58:59], 0, v[152:153]
	s_mov_b32 m0, s69
	s_nop 0
	global_load_lds_dwordx4 v[236:237], off
	s_add_u32 s84, s54, 0x40000
	s_addc_u32 s85, s55, 0
	s_add_i32 s6, s6, s57
	v_lshl_add_u64 v[250:251], s[84:85], 0, v[140:141]
	s_mov_b32 m0, s6
	s_nop 0
	global_load_lds_dwordx4 v[250:251], off
	v_lshl_add_u64 v[250:251], s[84:85], 0, v[150:151]
	s_add_i32 m0, s6, 0x2000
	s_nop 0
	global_load_lds_dwordx4 v[250:251], off
	s_waitcnt vmcnt(8)
	s_waitcnt lgkmcnt(0)
	s_barrier
	v_mfma_f32_16x16x32_bf16 v[60:63], v[128:131], v[162:165], v[60:63]
	v_mfma_f32_16x16x32_bf16 v[48:51], v[128:131], v[170:173], v[48:51]
	v_mfma_f32_16x16x32_bf16 v[32:35], v[128:131], v[178:181], v[32:35]
	v_mfma_f32_16x16x32_bf16 v[16:19], v[128:131], v[194:197], v[16:19]
	v_mfma_f32_16x16x32_bf16 v[8:11], v[136:139], v[194:197], v[8:11]
	v_mfma_f32_16x16x32_bf16 v[24:27], v[136:139], v[178:181], v[24:27]
	v_mfma_f32_16x16x32_bf16 v[40:43], v[136:139], v[170:173], v[40:43]
	v_mfma_f32_16x16x32_bf16 v[56:59], v[136:139], v[162:165], v[56:59]
	v_mfma_f32_16x16x32_bf16 v[60:63], v[132:135], v[166:169], v[60:63]
	v_mfma_f32_16x16x32_bf16 v[48:51], v[132:135], v[174:177], v[48:51]
	v_mfma_f32_16x16x32_bf16 v[32:35], v[132:135], v[182:185], v[32:35]
	v_mfma_f32_16x16x32_bf16 v[16:19], v[132:135], v[210:213], v[16:19]
	v_mfma_f32_16x16x32_bf16 v[8:11], v[146:149], v[210:213], v[8:11]
	v_mfma_f32_16x16x32_bf16 v[24:27], v[146:149], v[182:185], v[24:27]
	v_mfma_f32_16x16x32_bf16 v[40:43], v[146:149], v[174:177], v[40:43]
	v_mfma_f32_16x16x32_bf16 v[56:59], v[146:149], v[166:169], v[56:59]
	v_mfma_f32_16x16x32_bf16 v[52:55], v[214:217], v[162:165], v[52:55]
	v_mfma_f32_16x16x32_bf16 v[36:39], v[214:217], v[170:173], v[36:39]
	v_mfma_f32_16x16x32_bf16 v[20:23], v[214:217], v[178:181], v[20:23]
	v_mfma_f32_16x16x32_bf16 v[4:7], v[214:217], v[194:197], v[4:7]
	v_mfma_f32_16x16x32_bf16 v[0:3], v[222:225], v[194:197], v[0:3]
	v_mfma_f32_16x16x32_bf16 v[12:15], v[222:225], v[178:181], v[12:15]
	v_mfma_f32_16x16x32_bf16 v[28:31], v[222:225], v[170:173], v[28:31]
	v_mfma_f32_16x16x32_bf16 v[44:47], v[222:225], v[162:165], v[44:47]
	v_mfma_f32_16x16x32_bf16 v[52:55], v[218:221], v[166:169], v[52:55]
	v_mfma_f32_16x16x32_bf16 v[36:39], v[218:221], v[174:177], v[36:39]
	v_mfma_f32_16x16x32_bf16 v[20:23], v[218:221], v[182:185], v[20:23]
	v_mfma_f32_16x16x32_bf16 v[4:7], v[218:221], v[210:213], v[4:7]
	v_mfma_f32_16x16x32_bf16 v[0:3], v[226:229], v[210:213], v[0:3]
	v_mfma_f32_16x16x32_bf16 v[12:15], v[226:229], v[182:185], v[12:15]
	v_mfma_f32_16x16x32_bf16 v[28:31], v[226:229], v[174:177], v[28:31]
	v_mfma_f32_16x16x32_bf16 v[44:47], v[226:229], v[166:169], v[44:47]
	s_barrier
	s_add_i32 s6, 0, 0x18000
	v_add_u32_e32 v146, s6, v206
	ds_read_b128 v[128:131], v146
	ds_read_b128 v[132:135], v146 offset:1024
	ds_read_b128 v[136:139], v146 offset:2048
	ds_read_b128 v[146:149], v146 offset:3072
	s_add_u32 s58, s58, 0x40000
	s_addc_u32 s59, s59, 0
	s_mov_b32 m0, s70
	v_lshl_add_u64 v[214:215], s[58:59], 0, v[154:155]
	ds_read_b128 v[162:165], v208 offset:32768
	ds_read_b128 v[166:169], v208 offset:33792
	ds_read_b128 v[170:173], v208 offset:34816
	ds_read_b128 v[174:177], v208 offset:35840
	ds_read_b128 v[178:181], v208 offset:36864
	ds_read_b128 v[182:185], v208 offset:37888
	ds_read_b128 v[194:197], v208 offset:38912
	ds_read_b128 v[210:213], v208 offset:39936
	global_load_lds_dwordx4 v[214:215], off
	v_lshl_add_u64 v[214:215], s[58:59], 0, v[152:153]
	s_mov_b32 m0, s71
	s_nop 0
	global_load_lds_dwordx4 v[214:215], off
	s_add_i32 s19, 0, 0x1c000
	v_add_u32_e32 v192, s19, v206
	ds_read_b128 v[214:217], v192
	ds_read_b128 v[218:221], v192 offset:1024
	ds_read_b128 v[222:225], v192 offset:2048
	ds_read_b128 v[226:229], v192 offset:3072
	s_waitcnt vmcnt(8)
	s_waitcnt lgkmcnt(0)
	s_barrier
	v_mfma_f32_16x16x32_bf16 v[124:127], v[128:131], v[162:165], v[124:127]
	v_mfma_f32_16x16x32_bf16 v[108:111], v[128:131], v[170:173], v[108:111]
	v_mfma_f32_16x16x32_bf16 v[96:99], v[128:131], v[178:181], v[96:99]
	v_mfma_f32_16x16x32_bf16 v[84:87], v[128:131], v[194:197], v[84:87]
	v_mfma_f32_16x16x32_bf16 v[80:83], v[136:139], v[194:197], v[80:83]
	v_mfma_f32_16x16x32_bf16 v[88:91], v[136:139], v[178:181], v[88:91]
	v_mfma_f32_16x16x32_bf16 v[104:107], v[136:139], v[170:173], v[104:107]
	v_mfma_f32_16x16x32_bf16 v[120:123], v[136:139], v[162:165], v[120:123]
	v_mfma_f32_16x16x32_bf16 v[124:127], v[132:135], v[166:169], v[124:127]
	v_mfma_f32_16x16x32_bf16 v[108:111], v[132:135], v[174:177], v[108:111]
	v_mfma_f32_16x16x32_bf16 v[96:99], v[132:135], v[182:185], v[96:99]
	v_mfma_f32_16x16x32_bf16 v[84:87], v[132:135], v[210:213], v[84:87]
	v_mfma_f32_16x16x32_bf16 v[80:83], v[146:149], v[210:213], v[80:83]
	v_mfma_f32_16x16x32_bf16 v[88:91], v[146:149], v[182:185], v[88:91]
	v_mfma_f32_16x16x32_bf16 v[104:107], v[146:149], v[174:177], v[104:107]
	v_mfma_f32_16x16x32_bf16 v[120:123], v[146:149], v[166:169], v[120:123]
	v_mfma_f32_16x16x32_bf16 v[116:119], v[214:217], v[162:165], v[116:119]
	v_mfma_f32_16x16x32_bf16 v[100:103], v[214:217], v[170:173], v[100:103]
	v_mfma_f32_16x16x32_bf16 v[76:79], v[214:217], v[178:181], v[76:79]
	v_mfma_f32_16x16x32_bf16 v[68:71], v[214:217], v[194:197], v[68:71]
	v_mfma_f32_16x16x32_bf16 v[64:67], v[222:225], v[194:197], v[64:67]
	v_mfma_f32_16x16x32_bf16 v[72:75], v[222:225], v[178:181], v[72:75]
	v_mfma_f32_16x16x32_bf16 v[92:95], v[222:225], v[170:173], v[92:95]
	v_mfma_f32_16x16x32_bf16 v[112:115], v[222:225], v[162:165], v[112:115]
	v_mfma_f32_16x16x32_bf16 v[116:119], v[218:221], v[166:169], v[116:119]
	v_mfma_f32_16x16x32_bf16 v[100:103], v[218:221], v[174:177], v[100:103]
	v_mfma_f32_16x16x32_bf16 v[76:79], v[218:221], v[182:185], v[76:79]
	v_mfma_f32_16x16x32_bf16 v[68:71], v[218:221], v[210:213], v[68:71]
	v_mfma_f32_16x16x32_bf16 v[64:67], v[226:229], v[210:213], v[64:67]
	v_mfma_f32_16x16x32_bf16 v[72:75], v[226:229], v[182:185], v[72:75]
	v_mfma_f32_16x16x32_bf16 v[92:95], v[226:229], v[174:177], v[92:95]
	v_mfma_f32_16x16x32_bf16 v[112:115], v[226:229], v[166:169], v[112:115]
	s_barrier
	s_add_i32 s6, s6, s57
	v_lshl_add_u64 v[230:231], v[230:231], 0, s[36:37]
	s_mov_b32 m0, s6
	s_nop 0
	global_load_lds_dwordx4 v[230:231], off
	v_lshl_add_u64 v[230:231], v[232:233], 0, s[36:37]
	s_add_i32 m0, s6, 0x2000
	s_nop 0
	global_load_lds_dwordx4 v[230:231], off
	s_mov_b32 m0, s72
	v_lshl_add_u64 v[230:231], v[234:235], 0, s[36:37]
	ds_read_b128 v[162:165], v208 offset:49152
	ds_read_b128 v[166:169], v208 offset:50176
	ds_read_b128 v[170:173], v208 offset:51200
	ds_read_b128 v[174:177], v208 offset:52224
	ds_read_b128 v[178:181], v208 offset:53248
	ds_read_b128 v[182:185], v208 offset:54272
	ds_read_b128 v[194:197], v208 offset:55296
	ds_read_b128 v[210:213], v208 offset:56320
	global_load_lds_dwordx4 v[230:231], off
	v_lshl_add_u64 v[230:231], v[236:237], 0, s[36:37]
	s_mov_b32 m0, s73
	s_nop 0
	global_load_lds_dwordx4 v[230:231], off
	s_add_u32 s54, s54, 0x40080
	s_addc_u32 s55, s55, 0
	s_add_i32 s6, s19, s57
	v_lshl_add_u64 v[250:251], s[54:55], 0, v[140:141]
	s_mov_b32 m0, s6
	s_nop 0
	global_load_lds_dwordx4 v[250:251], off
	v_lshl_add_u64 v[250:251], s[54:55], 0, v[150:151]
	s_add_i32 m0, s6, 0x2000
	s_nop 0
	global_load_lds_dwordx4 v[250:251], off
	s_waitcnt vmcnt(8)
	s_waitcnt lgkmcnt(0)
	s_barrier
	v_mfma_f32_16x16x32_bf16 v[60:63], v[128:131], v[162:165], v[60:63]
	v_mfma_f32_16x16x32_bf16 v[48:51], v[128:131], v[170:173], v[48:51]
	v_mfma_f32_16x16x32_bf16 v[32:35], v[128:131], v[178:181], v[32:35]
	v_mfma_f32_16x16x32_bf16 v[16:19], v[128:131], v[194:197], v[16:19]
	v_mfma_f32_16x16x32_bf16 v[8:11], v[136:139], v[194:197], v[8:11]
	v_mfma_f32_16x16x32_bf16 v[24:27], v[136:139], v[178:181], v[24:27]
	v_mfma_f32_16x16x32_bf16 v[40:43], v[136:139], v[170:173], v[40:43]
	v_mfma_f32_16x16x32_bf16 v[56:59], v[136:139], v[162:165], v[56:59]
	v_mfma_f32_16x16x32_bf16 v[60:63], v[132:135], v[166:169], v[60:63]
	v_mfma_f32_16x16x32_bf16 v[48:51], v[132:135], v[174:177], v[48:51]
	v_mfma_f32_16x16x32_bf16 v[32:35], v[132:135], v[182:185], v[32:35]
	v_mfma_f32_16x16x32_bf16 v[16:19], v[132:135], v[210:213], v[16:19]
	v_mfma_f32_16x16x32_bf16 v[8:11], v[146:149], v[210:213], v[8:11]
	v_mfma_f32_16x16x32_bf16 v[24:27], v[146:149], v[182:185], v[24:27]
	v_mfma_f32_16x16x32_bf16 v[40:43], v[146:149], v[174:177], v[40:43]
	v_mfma_f32_16x16x32_bf16 v[56:59], v[146:149], v[166:169], v[56:59]
	v_mfma_f32_16x16x32_bf16 v[52:55], v[214:217], v[162:165], v[52:55]
	v_mfma_f32_16x16x32_bf16 v[36:39], v[214:217], v[170:173], v[36:39]
	v_mfma_f32_16x16x32_bf16 v[20:23], v[214:217], v[178:181], v[20:23]
	v_mfma_f32_16x16x32_bf16 v[4:7], v[214:217], v[194:197], v[4:7]
	v_mfma_f32_16x16x32_bf16 v[0:3], v[222:225], v[194:197], v[0:3]
	v_mfma_f32_16x16x32_bf16 v[12:15], v[222:225], v[178:181], v[12:15]
	v_mfma_f32_16x16x32_bf16 v[28:31], v[222:225], v[170:173], v[28:31]
	v_mfma_f32_16x16x32_bf16 v[44:47], v[222:225], v[162:165], v[44:47]
	v_mfma_f32_16x16x32_bf16 v[52:55], v[218:221], v[166:169], v[52:55]
	v_mfma_f32_16x16x32_bf16 v[36:39], v[218:221], v[174:177], v[36:39]
	v_mfma_f32_16x16x32_bf16 v[20:23], v[218:221], v[182:185], v[20:23]
	v_mfma_f32_16x16x32_bf16 v[4:7], v[218:221], v[210:213], v[4:7]
	v_mfma_f32_16x16x32_bf16 v[0:3], v[226:229], v[210:213], v[0:3]
	v_mfma_f32_16x16x32_bf16 v[12:15], v[226:229], v[182:185], v[12:15]
	v_mfma_f32_16x16x32_bf16 v[28:31], v[226:229], v[174:177], v[28:31]
	v_mfma_f32_16x16x32_bf16 v[44:47], v[226:229], v[166:169], v[44:47]
	s_add_i32 s82, s82, 2
	s_add_u32 s52, s52, 0x100
	s_addc_u32 s53, s53, 0
	s_add_u32 s39, s39, 0x100
	s_addc_u32 s51, s51, 0
	s_cmp_gt_u32 s82, 13
	s_barrier
	s_cbranch_scc0 .LBB0_248
	s_mov_b32 s100, 1
	s_ashr_i32 s51, s50, 31
	v_lshl_or_b32 v128, s81, 8, v207
	s_lshl_b64 s[10:11], s[50:51], 8
	v_ashrrev_i32_e32 v129, 31, v128
	v_lshl_add_u64 v[168:169], s[10:11], 0, v[156:157]
	v_lshlrev_b64 v[170:171], 1, v[128:129]
	v_lshl_add_u64 v[174:175], s[28:29], 0, v[170:171]
	v_lshlrev_b64 v[172:173], 11, v[168:169]
	v_lshl_add_u64 v[128:129], v[174:175], 0, v[172:173]
	global_load_dwordx4 v[146:149], v[128:129], off
	global_load_dwordx4 v[182:185], v[128:129], off offset:256
	v_or_b32_e32 v166, 16, v168
	v_mov_b32_e32 v167, v169
	v_lshlrev_b64 v[176:177], 11, v[166:167]
	v_lshl_add_u64 v[128:129], v[174:175], 0, v[176:177]
	global_load_dwordx4 v[194:197], v[128:129], off
	global_load_dwordx4 v[210:213], v[128:129], off offset:256
	v_or_b32_e32 v164, 32, v168
	v_mov_b32_e32 v165, v169
	v_or_b32_e32 v162, 48, v168
	v_mov_b32_e32 v163, v169
	v_lshlrev_b64 v[180:181], 11, v[164:165]
	v_lshlrev_b64 v[178:179], 11, v[162:163]
	v_lshl_add_u64 v[128:129], v[174:175], 0, v[180:181]
	v_lshl_add_u64 v[130:131], v[174:175], 0, v[178:179]
	global_load_dwordx4 v[214:217], v[128:129], off
	global_load_dwordx4 v[136:139], v[128:129], off offset:256
	global_load_dwordx4 v[132:135], v[130:131], off
	s_nop 0
	global_load_dwordx4 v[128:131], v[130:131], off offset:256
	s_mov_b64 s[10:11], 0x90
	v_lshl_add_u64 v[172:173], s[30:31], 0, v[172:173]
	v_lshl_add_u64 v[172:173], v[172:173], 0, v[170:171]
	s_waitcnt vmcnt(0)
	v_lshlrev_b32_e32 v218, 16, v146
	v_and_b32_e32 v219, 0xffff0000, v146
	v_lshlrev_b32_e32 v220, 16, v148
	v_and_b32_e32 v221, 0xffff0000, v148
	v_lshlrev_b32_e32 v146, 16, v147
	v_and_b32_e32 v147, 0xffff0000, v147
	v_lshlrev_b32_e32 v222, 16, v182
	v_and_b32_e32 v223, 0xffff0000, v182
	v_lshlrev_b32_e32 v224, 16, v184
	v_and_b32_e32 v225, 0xffff0000, v184
	v_lshlrev_b32_e32 v182, 16, v183
	v_and_b32_e32 v183, 0xffff0000, v183
	v_pk_add_f32 v[124:125], v[124:125], v[218:219]
	v_pk_add_f32 v[120:121], v[120:121], v[220:221]
	v_pk_add_f32 v[126:127], v[126:127], v[146:147]
	v_pk_add_f32 v[116:117], v[116:117], v[222:223]
	v_pk_add_f32 v[146:147], v[112:113], v[224:225]
	v_pk_add_f32 v[118:119], v[118:119], v[182:183]
	v_pk_mul_f32 v[220:221], v[124:125], v[124:125]
	v_pk_mul_f32 v[222:223], v[126:127], v[126:127]
	v_cvt_pk_bf16_f32 v112, v124, v125
	v_cvt_pk_bf16_f32 v113, v126, v127
	v_pk_mul_f32 v[124:125], v[116:117], v[116:117]
	v_pk_mul_f32 v[126:127], v[118:119], v[118:119]
	v_pk_mul_f32 v[228:229], v[146:147], v[146:147]
	v_cvt_pk_bf16_f32 v116, v116, v117
	v_cvt_pk_bf16_f32 v117, v118, v119
	v_cvt_pk_bf16_f32 v118, v146, v147
	v_add_f32_e32 v146, v220, v221
	v_add_f32_e32 v146, v222, v146
	v_lshlrev_b32_e32 v148, 16, v149
	v_and_b32_e32 v149, 0xffff0000, v149
	v_pk_mul_f32 v[224:225], v[120:121], v[120:121]
	v_add_f32_e32 v146, v223, v146
	v_pk_add_f32 v[122:123], v[122:123], v[148:149]
	v_add_f32_e32 v146, v224, v146
	v_pk_mul_f32 v[226:227], v[122:123], v[122:123]
	v_add_f32_e32 v146, v225, v146
	v_add_f32_e32 v146, v226, v146
	v_add_f32_e32 v146, v227, v146
	v_add_f32_e32 v124, v124, v146
	v_add_f32_e32 v124, v125, v124
	v_add_f32_e32 v124, v126, v124
	v_lshlrev_b32_e32 v184, 16, v185
	v_and_b32_e32 v185, 0xffff0000, v185
	v_add_f32_e32 v124, v127, v124
	v_pk_add_f32 v[148:149], v[114:115], v[184:185]
	v_add_f32_e32 v124, v228, v124
	v_pk_mul_f32 v[230:231], v[148:149], v[148:149]
	v_add_f32_e32 v124, v229, v124
	v_add_f32_e32 v124, v230, v124
	v_add_f32_e32 v209, v231, v124
	v_lshlrev_b32_e32 v124, 16, v212
	v_and_b32_e32 v125, 0xffff0000, v212
	v_pk_add_f32 v[124:125], v[92:93], v[124:125]
	v_lshlrev_b32_e32 v92, 16, v211
	v_and_b32_e32 v93, 0xffff0000, v211
	v_pk_add_f32 v[102:103], v[102:103], v[92:93]
	v_lshlrev_b32_e32 v92, 16, v213
	v_and_b32_e32 v93, 0xffff0000, v213
	v_pk_add_f32 v[126:127], v[94:95], v[92:93]
	v_lshlrev_b32_e32 v92, 16, v214
	v_and_b32_e32 v93, 0xffff0000, v214
	v_pk_add_f32 v[92:93], v[96:97], v[92:93]
	v_lshlrev_b32_e32 v96, 16, v217
	v_and_b32_e32 v97, 0xffff0000, v217
	v_lshlrev_b32_e32 v94, 16, v216
	v_and_b32_e32 v95, 0xffff0000, v216
	v_pk_add_f32 v[90:91], v[90:91], v[96:97]
	v_lshlrev_b32_e32 v96, 16, v136
	v_and_b32_e32 v97, 0xffff0000, v136
	v_lshlrev_b32_e32 v182, 16, v194
	v_and_b32_e32 v183, 0xffff0000, v194
	v_pk_add_f32 v[88:89], v[88:89], v[94:95]
	v_lshlrev_b32_e32 v94, 16, v215
	v_and_b32_e32 v95, 0xffff0000, v215
	v_pk_add_f32 v[96:97], v[76:77], v[96:97]
	v_lshl_add_u64 v[76:77], v[168:169], 0, s[36:37]
	v_lshlrev_b32_e32 v184, 16, v196
	v_and_b32_e32 v185, 0xffff0000, v196
	v_cvt_pk_bf16_f32 v114, v120, v121
	v_pk_add_f32 v[120:121], v[108:109], v[182:183]
	v_pk_add_f32 v[94:95], v[98:99], v[94:95]
	v_lshlrev_b64 v[182:183], 11, v[76:77]
	v_lshlrev_b32_e32 v98, 16, v138
	v_and_b32_e32 v99, 0xffff0000, v138
	v_pk_add_f32 v[108:109], v[104:105], v[184:185]
	v_lshl_add_u64 v[184:185], v[174:175], 0, v[182:183]
	v_pk_add_f32 v[98:99], v[72:73], v[98:99]
	v_lshlrev_b32_e32 v72, 16, v137
	v_and_b32_e32 v73, 0xffff0000, v137
	v_lshlrev_b32_e32 v218, 16, v210
	v_and_b32_e32 v219, 0xffff0000, v210
	global_load_dwordx4 v[210:213], v[184:185], off
	v_pk_add_f32 v[136:137], v[78:79], v[72:73]
	v_lshlrev_b32_e32 v72, 16, v139
	v_and_b32_e32 v73, 0xffff0000, v139
	v_pk_add_f32 v[138:139], v[74:75], v[72:73]
	v_lshlrev_b32_e32 v72, 16, v132
	v_and_b32_e32 v73, 0xffff0000, v132
	v_pk_add_f32 v[74:75], v[84:85], v[72:73]
	v_lshlrev_b32_e32 v72, 16, v134
	v_and_b32_e32 v73, 0xffff0000, v134
	v_pk_add_f32 v[78:79], v[80:81], v[72:73]
	v_lshlrev_b32_e32 v72, 16, v133
	v_and_b32_e32 v73, 0xffff0000, v133
	v_pk_add_f32 v[100:101], v[100:101], v[218:219]
	global_load_dwordx4 v[218:221], v[184:185], off offset:256
	v_pk_add_f32 v[80:81], v[86:87], v[72:73]
	v_lshlrev_b32_e32 v72, 16, v135
	v_and_b32_e32 v73, 0xffff0000, v135
	v_pk_add_f32 v[82:83], v[82:83], v[72:73]
	v_lshl_add_u64 v[72:73], v[168:169], 0, s[10:11]
	v_lshlrev_b64 v[132:133], 11, v[72:73]
	v_lshl_add_u64 v[134:135], v[174:175], 0, v[132:133]
	v_lshlrev_b32_e32 v84, 16, v128
	v_and_b32_e32 v85, 0xffff0000, v128
	global_load_dwordx4 v[226:229], v[134:135], off
	global_load_dwordx4 v[234:237], v[134:135], off offset:256
	v_pk_add_f32 v[84:85], v[68:69], v[84:85]
	v_lshlrev_b32_e32 v68, 16, v130
	v_and_b32_e32 v69, 0xffff0000, v130
	v_pk_add_f32 v[86:87], v[64:65], v[68:69]
	v_lshlrev_b32_e32 v64, 16, v129
	v_and_b32_e32 v65, 0xffff0000, v129
	s_mov_b64 s[10:11], 0xa0
	v_pk_add_f32 v[128:129], v[70:71], v[64:65]
	v_lshl_add_u64 v[70:71], v[168:169], 0, s[10:11]
	s_mov_b64 s[10:11], 0xb0
	v_lshlrev_b32_e32 v64, 16, v131
	v_and_b32_e32 v65, 0xffff0000, v131
	v_lshlrev_b64 v[134:135], 11, v[70:71]
	v_lshl_add_u64 v[68:69], v[168:169], 0, s[10:11]
	v_pk_add_f32 v[130:131], v[66:67], v[64:65]
	v_lshl_add_u64 v[64:65], v[174:175], 0, v[134:135]
	v_lshlrev_b64 v[184:185], 11, v[68:69]
	global_load_dwordx4 v[238:241], v[64:65], off
	global_load_dwordx4 v[242:245], v[64:65], off offset:256
	v_lshl_add_u64 v[64:65], v[174:175], 0, v[184:185]
	global_load_dwordx4 v[246:249], v[64:65], off
	s_nop 0
	global_load_dwordx4 v[64:67], v[64:65], off offset:256
	v_lshlrev_b32_e32 v194, 16, v195
	v_and_b32_e32 v195, 0xffff0000, v195
	v_lshlrev_b32_e32 v196, 16, v197
	v_and_b32_e32 v197, 0xffff0000, v197
	v_cvt_pk_bf16_f32 v115, v122, v123
	v_cvt_pk_bf16_f32 v119, v148, v149
	v_pk_add_f32 v[122:123], v[110:111], v[194:195]
	v_pk_add_f32 v[110:111], v[106:107], v[196:197]
	global_store_dwordx4 v[172:173], v[112:115], off
	global_store_dwordx4 v[172:173], v[116:119], off offset:256
	v_cvt_pk_bf16_f32 v104, v120, v121
	v_lshl_add_u64 v[112:113], s[30:31], 0, v[176:177]
	v_cvt_pk_bf16_f32 v105, v122, v123
	v_cvt_pk_bf16_f32 v106, v108, v109
	v_cvt_pk_bf16_f32 v107, v110, v111
	v_lshl_add_u64 v[112:113], v[112:113], 0, v[170:171]
	v_cvt_pk_bf16_f32 v146, v100, v101
	v_cvt_pk_bf16_f32 v147, v102, v103
	v_cvt_pk_bf16_f32 v148, v124, v125
	v_cvt_pk_bf16_f32 v149, v126, v127
	global_store_dwordx4 v[112:113], v[104:107], off
	global_store_dwordx4 v[112:113], v[146:149], off offset:256
	v_cvt_pk_bf16_f32 v194, v92, v93
	v_lshl_add_u64 v[104:105], s[30:31], 0, v[180:181]
	v_cvt_pk_bf16_f32 v195, v94, v95
	v_cvt_pk_bf16_f32 v196, v88, v89
	v_cvt_pk_bf16_f32 v197, v90, v91
	v_lshl_add_u64 v[104:105], v[104:105], 0, v[170:171]
	v_cvt_pk_bf16_f32 v214, v96, v97
	v_cvt_pk_bf16_f32 v215, v136, v137
	v_cvt_pk_bf16_f32 v216, v98, v99
	v_cvt_pk_bf16_f32 v217, v138, v139
	global_store_dwordx4 v[104:105], v[194:197], off
	global_store_dwordx4 v[104:105], v[214:217], off offset:256
	v_lshl_add_u64 v[104:105], s[30:31], 0, v[178:179]
	v_cvt_pk_bf16_f32 v222, v74, v75
	v_cvt_pk_bf16_f32 v223, v80, v81
	v_cvt_pk_bf16_f32 v224, v78, v79
	v_cvt_pk_bf16_f32 v225, v82, v83
	v_lshl_add_u64 v[104:105], v[104:105], 0, v[170:171]
	v_cvt_pk_bf16_f32 v230, v84, v85
	v_cvt_pk_bf16_f32 v231, v128, v129
	v_cvt_pk_bf16_f32 v232, v86, v87
	v_cvt_pk_bf16_f32 v233, v130, v131
	global_store_dwordx4 v[104:105], v[222:225], off
	global_store_dwordx4 v[104:105], v[230:233], off offset:256
	s_waitcnt vmcnt(0)
	v_lshlrev_b32_e32 v104, 16, v210
	v_and_b32_e32 v105, 0xffff0000, v210
	v_pk_add_f32 v[60:61], v[60:61], v[104:105]
	v_lshlrev_b32_e32 v104, 16, v212
	v_and_b32_e32 v105, 0xffff0000, v212
	v_pk_add_f32 v[56:57], v[56:57], v[104:105]
	v_lshlrev_b32_e32 v104, 16, v211
	v_and_b32_e32 v105, 0xffff0000, v211
	v_pk_add_f32 v[62:63], v[62:63], v[104:105]
	v_lshlrev_b32_e32 v104, 16, v213
	v_and_b32_e32 v105, 0xffff0000, v213
	v_pk_add_f32 v[58:59], v[58:59], v[104:105]
	v_lshlrev_b32_e32 v104, 16, v218
	v_and_b32_e32 v105, 0xffff0000, v218
	v_pk_add_f32 v[52:53], v[52:53], v[104:105]
	v_lshlrev_b32_e32 v104, 16, v220
	v_and_b32_e32 v105, 0xffff0000, v220
	v_pk_add_f32 v[104:105], v[44:45], v[104:105]
	v_lshlrev_b32_e32 v44, 16, v219
	v_and_b32_e32 v45, 0xffff0000, v219
	v_pk_add_f32 v[54:55], v[54:55], v[44:45]
	v_lshlrev_b32_e32 v44, 16, v221
	v_and_b32_e32 v45, 0xffff0000, v221
	v_pk_add_f32 v[106:107], v[46:47], v[44:45]
	v_lshlrev_b32_e32 v44, 16, v226
	v_and_b32_e32 v45, 0xffff0000, v226
	v_pk_add_f32 v[44:45], v[48:49], v[44:45]
	v_lshlrev_b32_e32 v48, 16, v229
	v_and_b32_e32 v49, 0xffff0000, v229
	v_pk_add_f32 v[42:43], v[42:43], v[48:49]
	v_lshlrev_b32_e32 v48, 16, v234
	v_and_b32_e32 v49, 0xffff0000, v234
	v_pk_add_f32 v[36:37], v[36:37], v[48:49]
	v_lshlrev_b32_e32 v48, 16, v236
	v_and_b32_e32 v49, 0xffff0000, v236
	v_lshlrev_b32_e32 v46, 16, v228
	v_and_b32_e32 v47, 0xffff0000, v228
	v_pk_add_f32 v[48:49], v[28:29], v[48:49]
	v_lshlrev_b32_e32 v28, 16, v235
	v_and_b32_e32 v29, 0xffff0000, v235
	v_pk_add_f32 v[40:41], v[40:41], v[46:47]
	v_lshlrev_b32_e32 v46, 16, v227
	v_and_b32_e32 v47, 0xffff0000, v227
	v_pk_add_f32 v[38:39], v[38:39], v[28:29]
	v_lshlrev_b32_e32 v28, 16, v237
	v_and_b32_e32 v29, 0xffff0000, v237
	v_pk_add_f32 v[46:47], v[50:51], v[46:47]
	v_pk_add_f32 v[50:51], v[30:31], v[28:29]
	v_lshlrev_b32_e32 v28, 16, v238
	v_and_b32_e32 v29, 0xffff0000, v238
	v_lshlrev_b32_e32 v180, 16, v64
	v_and_b32_e32 v181, 0xffff0000, v64
	v_pk_add_f32 v[28:29], v[32:33], v[28:29]
	v_lshlrev_b32_e32 v32, 16, v241
	v_and_b32_e32 v33, 0xffff0000, v241
	v_pk_add_f32 v[4:5], v[4:5], v[180:181]
	v_lshlrev_b32_e32 v180, 16, v66
	v_and_b32_e32 v181, 0xffff0000, v66
	v_pk_add_f32 v[26:27], v[26:27], v[32:33]
	v_lshlrev_b32_e32 v32, 16, v242
	v_and_b32_e32 v33, 0xffff0000, v242
	v_pk_add_f32 v[0:1], v[0:1], v[180:181]
	v_lshl_add_u64 v[180:181], s[30:31], 0, v[182:183]
	v_cvt_pk_bf16_f32 v112, v60, v61
	v_cvt_pk_bf16_f32 v113, v62, v63
	v_cvt_pk_bf16_f32 v114, v56, v57
	v_cvt_pk_bf16_f32 v115, v58, v59
	v_pk_add_f32 v[20:21], v[20:21], v[32:33]
	v_lshlrev_b32_e32 v32, 16, v244
	v_and_b32_e32 v33, 0xffff0000, v244
	v_lshl_add_u64 v[180:181], v[180:181], 0, v[170:171]
	v_cvt_pk_bf16_f32 v116, v52, v53
	v_cvt_pk_bf16_f32 v117, v54, v55
	v_cvt_pk_bf16_f32 v118, v104, v105
	v_cvt_pk_bf16_f32 v119, v106, v107
	v_lshlrev_b32_e32 v30, 16, v240
	v_and_b32_e32 v31, 0xffff0000, v240
	v_pk_add_f32 v[32:33], v[12:13], v[32:33]
	v_lshlrev_b32_e32 v12, 16, v243
	v_and_b32_e32 v13, 0xffff0000, v243
	global_store_dwordx4 v[180:181], v[112:115], off
	global_store_dwordx4 v[180:181], v[116:119], off offset:256
	v_cvt_pk_bf16_f32 v146, v44, v45
	v_lshl_add_u64 v[112:113], s[30:31], 0, v[132:133]
	v_cvt_pk_bf16_f32 v147, v46, v47
	v_cvt_pk_bf16_f32 v148, v40, v41
	v_cvt_pk_bf16_f32 v149, v42, v43
	v_pk_add_f32 v[24:25], v[24:25], v[30:31]
	v_lshlrev_b32_e32 v30, 16, v239
	v_and_b32_e32 v31, 0xffff0000, v239
	v_pk_add_f32 v[22:23], v[22:23], v[12:13]
	v_lshlrev_b32_e32 v12, 16, v245
	v_and_b32_e32 v13, 0xffff0000, v245
	v_lshl_add_u64 v[112:113], v[112:113], 0, v[170:171]
	v_cvt_pk_bf16_f32 v172, v36, v37
	v_cvt_pk_bf16_f32 v173, v38, v39
	v_cvt_pk_bf16_f32 v174, v48, v49
	v_cvt_pk_bf16_f32 v175, v50, v51
	v_pk_add_f32 v[30:31], v[34:35], v[30:31]
	v_pk_add_f32 v[34:35], v[14:15], v[12:13]
	v_lshlrev_b32_e32 v12, 16, v246
	v_and_b32_e32 v13, 0xffff0000, v246
	v_lshlrev_b32_e32 v14, 16, v248
	v_and_b32_e32 v15, 0xffff0000, v248
	global_store_dwordx4 v[112:113], v[146:149], off
	global_store_dwordx4 v[112:113], v[172:175], off offset:256
	v_lshl_add_u64 v[112:113], s[30:31], 0, v[134:135]
	v_cvt_pk_bf16_f32 v176, v28, v29
	v_cvt_pk_bf16_f32 v177, v30, v31
	v_cvt_pk_bf16_f32 v178, v24, v25
	v_cvt_pk_bf16_f32 v179, v26, v27
	v_pk_add_f32 v[12:13], v[16:17], v[12:13]
	v_pk_add_f32 v[8:9], v[8:9], v[14:15]
	v_lshlrev_b32_e32 v14, 16, v247
	v_and_b32_e32 v15, 0xffff0000, v247
	v_lshlrev_b32_e32 v16, 16, v249
	v_and_b32_e32 v17, 0xffff0000, v249
	v_lshlrev_b32_e32 v64, 16, v65
	v_and_b32_e32 v65, 0xffff0000, v65
	v_lshl_add_u64 v[112:113], v[112:113], 0, v[170:171]
	v_cvt_pk_bf16_f32 v194, v20, v21
	v_cvt_pk_bf16_f32 v195, v22, v23
	v_cvt_pk_bf16_f32 v196, v32, v33
	v_cvt_pk_bf16_f32 v197, v34, v35
	v_pk_add_f32 v[14:15], v[18:19], v[14:15]
	v_pk_add_f32 v[10:11], v[10:11], v[16:17]
	v_pk_add_f32 v[6:7], v[6:7], v[64:65]
	v_lshlrev_b32_e32 v64, 16, v67
	v_and_b32_e32 v65, 0xffff0000, v67
	global_store_dwordx4 v[112:113], v[176:179], off
	global_store_dwordx4 v[112:113], v[194:197], off offset:256
	v_lshl_add_u64 v[112:113], s[30:31], 0, v[184:185]
	v_cvt_pk_bf16_f32 v16, v12, v13
	v_cvt_pk_bf16_f32 v17, v14, v15
	v_cvt_pk_bf16_f32 v18, v8, v9
	v_cvt_pk_bf16_f32 v19, v10, v11
	v_pk_add_f32 v[2:3], v[2:3], v[64:65]
	v_lshl_add_u64 v[112:113], v[112:113], 0, v[170:171]
	v_cvt_pk_bf16_f32 v64, v4, v5
	v_cvt_pk_bf16_f32 v65, v6, v7
	v_cvt_pk_bf16_f32 v66, v0, v1
	v_cvt_pk_bf16_f32 v67, v2, v3
	global_store_dwordx4 v[112:113], v[16:19], off
	global_store_dwordx4 v[112:113], v[64:67], off offset:256
	s_lshl_b32 s10, s81, 2
	v_and_b32_e32 v17, 64, v188
	v_xor_b32_e32 v16, 16, v188
	v_add_u32_e32 v17, 64, v17
	v_cmp_lt_i32_e32 vcc, v16, v17
	v_xor_b32_e32 v18, 32, v188
	s_ashr_i32 s11, s10, 31
	v_cndmask_b32_e32 v16, v188, v16, vcc
	v_lshlrev_b32_e32 v16, 2, v16
	ds_bpermute_b32 v19, v16, v209
	v_cmp_lt_i32_e32 vcc, v18, v17
	s_lshl_b64 s[10:11], s[10:11], 2
	s_add_u32 s50, s75, s10
	v_cndmask_b32_e32 v17, v188, v18, vcc
	v_lshlrev_b32_e32 v17, 2, v17
	s_waitcnt lgkmcnt(0)
	v_add_f32_e32 v18, v209, v19
	ds_bpermute_b32 v19, v17, v18
	s_addc_u32 s51, s80, s11
	s_and_saveexec_b64 s[52:53], s[42:43]
	s_cbranch_execz .LBB0_251
	s_waitcnt lgkmcnt(0)
	v_add_f32_e32 v64, v18, v19
	v_lshlrev_b64 v[18:19], 6, v[168:169]
	v_lshl_add_u64 v[18:19], s[50:51], 0, v[18:19]
	global_store_dword v[18:19], v64, off

.Lm4ap_295:
	s_waitcnt lgkmcnt(0)
	s_barrier
	s_nop 0
	v_mfma_f32_16x16x32_bf16 v[124:127], v[146:149], v[170:173], 0
	v_mfma_f32_16x16x32_bf16 v[116:119], v[146:149], v[178:181], 0
	v_mfma_f32_16x16x32_bf16 v[108:111], v[146:149], v[194:197], 0
	v_mfma_f32_16x16x32_bf16 v[100:103], v[146:149], v[210:213], 0
	v_mfma_f32_16x16x32_bf16 v[96:99], v[162:165], v[210:213], 0
	v_mfma_f32_16x16x32_bf16 v[104:107], v[162:165], v[194:197], 0
	v_mfma_f32_16x16x32_bf16 v[112:115], v[162:165], v[178:181], 0
	v_mfma_f32_16x16x32_bf16 v[120:123], v[162:165], v[170:173], 0
	v_mfma_f32_16x16x32_bf16 v[124:127], v[158:161], v[174:177], v[124:127]
	v_mfma_f32_16x16x32_bf16 v[116:119], v[158:161], v[182:185], v[116:119]
	v_mfma_f32_16x16x32_bf16 v[108:111], v[158:161], v[206:209], v[108:111]
	v_mfma_f32_16x16x32_bf16 v[100:103], v[158:161], v[214:217], v[100:103]
	v_mfma_f32_16x16x32_bf16 v[96:99], v[166:169], v[214:217], v[96:99]
	v_mfma_f32_16x16x32_bf16 v[104:107], v[166:169], v[206:209], v[104:107]
	v_mfma_f32_16x16x32_bf16 v[112:115], v[166:169], v[182:185], v[112:115]
	v_mfma_f32_16x16x32_bf16 v[120:123], v[166:169], v[174:177], v[120:123]
	v_mfma_f32_16x16x32_bf16 v[92:95], v[218:221], v[170:173], 0
	v_mfma_f32_16x16x32_bf16 v[84:87], v[218:221], v[178:181], 0
	v_mfma_f32_16x16x32_bf16 v[76:79], v[218:221], v[194:197], 0
	v_mfma_f32_16x16x32_bf16 v[68:71], v[218:221], v[210:213], 0
	v_mfma_f32_16x16x32_bf16 v[64:67], v[226:229], v[210:213], 0
	v_mfma_f32_16x16x32_bf16 v[72:75], v[226:229], v[194:197], 0
	v_mfma_f32_16x16x32_bf16 v[80:83], v[226:229], v[178:181], 0
	v_mfma_f32_16x16x32_bf16 v[88:91], v[226:229], v[170:173], 0
	v_mfma_f32_16x16x32_bf16 v[92:95], v[222:225], v[174:177], v[92:95]
	v_mfma_f32_16x16x32_bf16 v[84:87], v[222:225], v[182:185], v[84:87]
	v_mfma_f32_16x16x32_bf16 v[76:79], v[222:225], v[206:209], v[76:79]
	v_mfma_f32_16x16x32_bf16 v[68:71], v[222:225], v[214:217], v[68:71]
	v_mfma_f32_16x16x32_bf16 v[64:67], v[230:233], v[214:217], v[64:67]
	v_mfma_f32_16x16x32_bf16 v[72:75], v[230:233], v[206:209], v[72:75]
	v_mfma_f32_16x16x32_bf16 v[80:83], v[230:233], v[182:185], v[80:83]
	v_mfma_f32_16x16x32_bf16 v[88:91], v[230:233], v[174:177], v[88:91]
	s_barrier
	s_add_i32 s19, s80, s57
	v_lshl_add_u64 v[234:235], s[50:51], 0, v[140:141]
	s_mov_b32 m0, s19
	s_nop 0
	global_load_lds_dwordx4 v[234:235], off
	v_lshl_add_u64 v[236:237], s[50:51], 0, v[132:133]
	s_add_i32 m0, s19, 0x2000
	s_nop 0
	global_load_lds_dwordx4 v[236:237], off
	s_mov_b32 m0, s58
	v_lshl_add_u64 v[238:239], s[52:53], 0, v[128:129]
	ds_read_b128 v[170:173], v157 offset:16384
	ds_read_b128 v[174:177], v157 offset:17408
	ds_read_b128 v[178:181], v157 offset:18432
	ds_read_b128 v[182:185], v157 offset:19456
	ds_read_b128 v[194:197], v157 offset:20480
	ds_read_b128 v[206:209], v157 offset:21504
	ds_read_b128 v[210:213], v157 offset:22528
	ds_read_b128 v[214:217], v157 offset:23552
	global_load_lds_dwordx4 v[238:239], off
	v_lshl_add_u64 v[240:241], s[52:53], 0, v[130:131]
	s_mov_b32 m0, s59
	s_nop 0
	global_load_lds_dwordx4 v[240:241], off
	s_add_u32 s80, s50, 0x40000
	s_addc_u32 s81, s51, 0
	s_add_i32 s6, s6, s57
	v_lshl_add_u64 v[250:251], s[80:81], 0, v[140:141]
	s_mov_b32 m0, s6
	s_nop 0
	global_load_lds_dwordx4 v[250:251], off
	v_lshl_add_u64 v[250:251], s[80:81], 0, v[132:133]
	s_add_i32 m0, s6, 0x2000
	s_nop 0
	global_load_lds_dwordx4 v[250:251], off
	s_waitcnt vmcnt(24)
	s_cmp_lg_u32 s100, 0
	s_cbranch_scc1 .Lm4bp_295
	s_waitcnt vmcnt(8)
.Lm4bp_295:
	s_waitcnt lgkmcnt(0)
	s_mov_b32 s100, 0
	s_barrier
	v_mfma_f32_16x16x32_bf16 v[60:63], v[146:149], v[170:173], 0
	v_mfma_f32_16x16x32_bf16 v[52:55], v[146:149], v[178:181], 0
	v_mfma_f32_16x16x32_bf16 v[44:47], v[146:149], v[194:197], 0
	v_mfma_f32_16x16x32_bf16 v[36:39], v[146:149], v[210:213], 0
	v_mfma_f32_16x16x32_bf16 v[32:35], v[162:165], v[210:213], 0
	v_mfma_f32_16x16x32_bf16 v[40:43], v[162:165], v[194:197], 0
	v_mfma_f32_16x16x32_bf16 v[48:51], v[162:165], v[178:181], 0
	v_mfma_f32_16x16x32_bf16 v[56:59], v[162:165], v[170:173], 0
	v_mfma_f32_16x16x32_bf16 v[60:63], v[158:161], v[174:177], v[60:63]
	v_mfma_f32_16x16x32_bf16 v[52:55], v[158:161], v[182:185], v[52:55]
	v_mfma_f32_16x16x32_bf16 v[44:47], v[158:161], v[206:209], v[44:47]
	v_mfma_f32_16x16x32_bf16 v[36:39], v[158:161], v[214:217], v[36:39]
	v_mfma_f32_16x16x32_bf16 v[32:35], v[166:169], v[214:217], v[32:35]
	v_mfma_f32_16x16x32_bf16 v[40:43], v[166:169], v[206:209], v[40:43]
	v_mfma_f32_16x16x32_bf16 v[48:51], v[166:169], v[182:185], v[48:51]
	v_mfma_f32_16x16x32_bf16 v[56:59], v[166:169], v[174:177], v[56:59]
	v_mfma_f32_16x16x32_bf16 v[28:31], v[218:221], v[170:173], 0
	v_mfma_f32_16x16x32_bf16 v[20:23], v[218:221], v[178:181], 0
	v_mfma_f32_16x16x32_bf16 v[12:15], v[218:221], v[194:197], 0
	v_mfma_f32_16x16x32_bf16 v[4:7], v[218:221], v[210:213], 0
	v_mfma_f32_16x16x32_bf16 v[0:3], v[226:229], v[210:213], 0
	v_mfma_f32_16x16x32_bf16 v[8:11], v[226:229], v[194:197], 0
	v_mfma_f32_16x16x32_bf16 v[16:19], v[226:229], v[178:181], 0
	v_mfma_f32_16x16x32_bf16 v[24:27], v[226:229], v[170:173], 0
	v_mfma_f32_16x16x32_bf16 v[28:31], v[222:225], v[174:177], v[28:31]
	v_mfma_f32_16x16x32_bf16 v[20:23], v[222:225], v[182:185], v[20:23]
	v_mfma_f32_16x16x32_bf16 v[12:15], v[222:225], v[206:209], v[12:15]
	v_mfma_f32_16x16x32_bf16 v[4:7], v[222:225], v[214:217], v[4:7]
	v_mfma_f32_16x16x32_bf16 v[0:3], v[230:233], v[214:217], v[0:3]
	v_mfma_f32_16x16x32_bf16 v[8:11], v[230:233], v[206:209], v[8:11]
	v_mfma_f32_16x16x32_bf16 v[16:19], v[230:233], v[182:185], v[16:19]
	v_mfma_f32_16x16x32_bf16 v[24:27], v[230:233], v[174:177], v[24:27]
	s_barrier
	s_add_i32 s6, 0, 0x18000
	v_add_u32_e32 v166, s6, v154
	ds_read_b128 v[146:149], v166
	ds_read_b128 v[158:161], v166 offset:1024
	ds_read_b128 v[162:165], v166 offset:2048
	ds_read_b128 v[166:169], v166 offset:3072
	s_add_u32 s52, s52, 0x40000
	s_addc_u32 s53, s53, 0
	s_mov_b32 m0, s68
	v_lshl_add_u64 v[218:219], s[52:53], 0, v[128:129]
	ds_read_b128 v[170:173], v157 offset:32768
	ds_read_b128 v[174:177], v157 offset:33792
	ds_read_b128 v[178:181], v157 offset:34816
	ds_read_b128 v[182:185], v157 offset:35840
	ds_read_b128 v[194:197], v157 offset:36864
	ds_read_b128 v[206:209], v157 offset:37888
	ds_read_b128 v[210:213], v157 offset:38912
	ds_read_b128 v[214:217], v157 offset:39936
	global_load_lds_dwordx4 v[218:219], off
	v_lshl_add_u64 v[218:219], s[52:53], 0, v[130:131]
	s_mov_b32 m0, s69
	s_nop 0
	global_load_lds_dwordx4 v[218:219], off
	s_add_i32 s19, 0, 0x1c000
	v_add_u32_e32 v192, s19, v154
	ds_read_b128 v[218:221], v192
	ds_read_b128 v[222:225], v192 offset:1024
	ds_read_b128 v[226:229], v192 offset:2048
	ds_read_b128 v[230:233], v192 offset:3072
	s_waitcnt vmcnt(8)
	s_waitcnt lgkmcnt(0)
	s_barrier
	v_mfma_f32_16x16x32_bf16 v[124:127], v[146:149], v[170:173], v[124:127]
	v_mfma_f32_16x16x32_bf16 v[116:119], v[146:149], v[178:181], v[116:119]
	v_mfma_f32_16x16x32_bf16 v[108:111], v[146:149], v[194:197], v[108:111]
	v_mfma_f32_16x16x32_bf16 v[100:103], v[146:149], v[210:213], v[100:103]
	v_mfma_f32_16x16x32_bf16 v[96:99], v[162:165], v[210:213], v[96:99]
	v_mfma_f32_16x16x32_bf16 v[104:107], v[162:165], v[194:197], v[104:107]
	v_mfma_f32_16x16x32_bf16 v[112:115], v[162:165], v[178:181], v[112:115]
	v_mfma_f32_16x16x32_bf16 v[120:123], v[162:165], v[170:173], v[120:123]
	v_mfma_f32_16x16x32_bf16 v[124:127], v[158:161], v[174:177], v[124:127]
	v_mfma_f32_16x16x32_bf16 v[116:119], v[158:161], v[182:185], v[116:119]
	v_mfma_f32_16x16x32_bf16 v[108:111], v[158:161], v[206:209], v[108:111]
	v_mfma_f32_16x16x32_bf16 v[100:103], v[158:161], v[214:217], v[100:103]
	v_mfma_f32_16x16x32_bf16 v[96:99], v[166:169], v[214:217], v[96:99]
	v_mfma_f32_16x16x32_bf16 v[104:107], v[166:169], v[206:209], v[104:107]
	v_mfma_f32_16x16x32_bf16 v[112:115], v[166:169], v[182:185], v[112:115]
	v_mfma_f32_16x16x32_bf16 v[120:123], v[166:169], v[174:177], v[120:123]
	v_mfma_f32_16x16x32_bf16 v[92:95], v[218:221], v[170:173], v[92:95]
	v_mfma_f32_16x16x32_bf16 v[84:87], v[218:221], v[178:181], v[84:87]
	v_mfma_f32_16x16x32_bf16 v[76:79], v[218:221], v[194:197], v[76:79]
	v_mfma_f32_16x16x32_bf16 v[68:71], v[218:221], v[210:213], v[68:71]
	v_mfma_f32_16x16x32_bf16 v[64:67], v[226:229], v[210:213], v[64:67]
	v_mfma_f32_16x16x32_bf16 v[72:75], v[226:229], v[194:197], v[72:75]
	v_mfma_f32_16x16x32_bf16 v[80:83], v[226:229], v[178:181], v[80:83]
	v_mfma_f32_16x16x32_bf16 v[88:91], v[226:229], v[170:173], v[88:91]
	v_mfma_f32_16x16x32_bf16 v[92:95], v[222:225], v[174:177], v[92:95]
	v_mfma_f32_16x16x32_bf16 v[84:87], v[222:225], v[182:185], v[84:87]
	v_mfma_f32_16x16x32_bf16 v[76:79], v[222:225], v[206:209], v[76:79]
	v_mfma_f32_16x16x32_bf16 v[68:71], v[222:225], v[214:217], v[68:71]
	v_mfma_f32_16x16x32_bf16 v[64:67], v[230:233], v[214:217], v[64:67]
	v_mfma_f32_16x16x32_bf16 v[72:75], v[230:233], v[206:209], v[72:75]
	v_mfma_f32_16x16x32_bf16 v[80:83], v[230:233], v[182:185], v[80:83]
	v_mfma_f32_16x16x32_bf16 v[88:91], v[230:233], v[174:177], v[88:91]
	s_barrier
	s_add_i32 s6, s6, s57
	v_lshl_add_u64 v[234:235], v[234:235], 0, s[36:37]
	s_mov_b32 m0, s6
	s_nop 0
	global_load_lds_dwordx4 v[234:235], off
	v_lshl_add_u64 v[234:235], v[236:237], 0, s[36:37]
	s_add_i32 m0, s6, 0x2000
	s_nop 0
	global_load_lds_dwordx4 v[234:235], off
	s_mov_b32 m0, s70
	v_lshl_add_u64 v[234:235], v[238:239], 0, s[36:37]
	ds_read_b128 v[170:173], v157 offset:49152
	ds_read_b128 v[174:177], v157 offset:50176
	ds_read_b128 v[178:181], v157 offset:51200
	ds_read_b128 v[182:185], v157 offset:52224
	ds_read_b128 v[194:197], v157 offset:53248
	ds_read_b128 v[206:209], v157 offset:54272
	ds_read_b128 v[210:213], v157 offset:55296
	ds_read_b128 v[214:217], v157 offset:56320
	global_load_lds_dwordx4 v[234:235], off
	v_lshl_add_u64 v[234:235], v[240:241], 0, s[36:37]
	s_mov_b32 m0, s71
	s_nop 0
	global_load_lds_dwordx4 v[234:235], off
	s_add_u32 s50, s50, 0x40080
	s_addc_u32 s51, s51, 0
	s_add_i32 s6, s19, s57
	v_lshl_add_u64 v[250:251], s[50:51], 0, v[140:141]
	s_mov_b32 m0, s6
	s_nop 0
	global_load_lds_dwordx4 v[250:251], off
	v_lshl_add_u64 v[250:251], s[50:51], 0, v[132:133]
	s_add_i32 m0, s6, 0x2000
	s_nop 0
	global_load_lds_dwordx4 v[250:251], off
	s_waitcnt vmcnt(8)
	s_waitcnt lgkmcnt(0)
	s_barrier
	v_mfma_f32_16x16x32_bf16 v[60:63], v[146:149], v[170:173], v[60:63]
	v_mfma_f32_16x16x32_bf16 v[52:55], v[146:149], v[178:181], v[52:55]
	v_mfma_f32_16x16x32_bf16 v[44:47], v[146:149], v[194:197], v[44:47]
	v_mfma_f32_16x16x32_bf16 v[36:39], v[146:149], v[210:213], v[36:39]
	v_mfma_f32_16x16x32_bf16 v[32:35], v[162:165], v[210:213], v[32:35]
	v_mfma_f32_16x16x32_bf16 v[40:43], v[162:165], v[194:197], v[40:43]
	v_mfma_f32_16x16x32_bf16 v[48:51], v[162:165], v[178:181], v[48:51]
	v_mfma_f32_16x16x32_bf16 v[56:59], v[162:165], v[170:173], v[56:59]
	v_mfma_f32_16x16x32_bf16 v[60:63], v[158:161], v[174:177], v[60:63]
	v_mfma_f32_16x16x32_bf16 v[52:55], v[158:161], v[182:185], v[52:55]
	v_mfma_f32_16x16x32_bf16 v[44:47], v[158:161], v[206:209], v[44:47]
	v_mfma_f32_16x16x32_bf16 v[36:39], v[158:161], v[214:217], v[36:39]
	v_mfma_f32_16x16x32_bf16 v[32:35], v[166:169], v[214:217], v[32:35]
	v_mfma_f32_16x16x32_bf16 v[40:43], v[166:169], v[206:209], v[40:43]
	v_mfma_f32_16x16x32_bf16 v[48:51], v[166:169], v[182:185], v[48:51]
	v_mfma_f32_16x16x32_bf16 v[56:59], v[166:169], v[174:177], v[56:59]
	v_mfma_f32_16x16x32_bf16 v[28:31], v[218:221], v[170:173], v[28:31]
	v_mfma_f32_16x16x32_bf16 v[20:23], v[218:221], v[178:181], v[20:23]
	v_mfma_f32_16x16x32_bf16 v[12:15], v[218:221], v[194:197], v[12:15]
	v_mfma_f32_16x16x32_bf16 v[4:7], v[218:221], v[210:213], v[4:7]
	v_mfma_f32_16x16x32_bf16 v[0:3], v[226:229], v[210:213], v[0:3]
	v_mfma_f32_16x16x32_bf16 v[8:11], v[226:229], v[194:197], v[8:11]
	v_mfma_f32_16x16x32_bf16 v[16:19], v[226:229], v[178:181], v[16:19]
	v_mfma_f32_16x16x32_bf16 v[24:27], v[226:229], v[170:173], v[24:27]
	v_mfma_f32_16x16x32_bf16 v[28:31], v[222:225], v[174:177], v[28:31]
	v_mfma_f32_16x16x32_bf16 v[20:23], v[222:225], v[182:185], v[20:23]
	v_mfma_f32_16x16x32_bf16 v[12:15], v[222:225], v[206:209], v[12:15]
	v_mfma_f32_16x16x32_bf16 v[4:7], v[222:225], v[214:217], v[4:7]
	v_mfma_f32_16x16x32_bf16 v[0:3], v[230:233], v[214:217], v[0:3]
	v_mfma_f32_16x16x32_bf16 v[8:11], v[230:233], v[206:209], v[8:11]
	v_mfma_f32_16x16x32_bf16 v[16:19], v[230:233], v[182:185], v[16:19]
	v_mfma_f32_16x16x32_bf16 v[24:27], v[230:233], v[174:177], v[24:27]
	s_add_i32 s75, s75, 2
	s_add_u32 s48, s48, 0x100
	s_addc_u32 s49, s49, 0
	s_cmp_gt_u32 s75, 13
	s_barrier
.LBB0_295:
	s_add_u32 s6, s4, s48
	s_addc_u32 s19, s5, s49
	s_add_u32 s6, s6, 0x100
	s_addc_u32 s19, s19, 0
	s_add_u32 s23, s10, s48
	s_addc_u32 s50, s11, s49
	s_add_i32 s80, 0, 0x10000
	v_add_u32_e32 v166, s80, v154
	ds_read_b128 v[146:149], v166
	ds_read_b128 v[158:161], v166 offset:1024
	ds_read_b128 v[162:165], v166 offset:2048
	ds_read_b128 v[166:169], v166 offset:3072
	s_cmpk_eq_i32 s48, 0x700
	s_cselect_b32 s53, s12, s19
	s_cselect_b32 s52, s29, s6
	s_cselect_b32 s51, s31, s50
	s_cselect_b32 s50, s35, s23
	v_lshl_add_u64 v[218:219], v[150:151], 0, s[48:49]
	s_add_i32 m0, s58, 0xc000
	ds_read_b128 v[170:173], v157
	ds_read_b128 v[174:177], v157 offset:1024
	ds_read_b128 v[178:181], v157 offset:2048
	ds_read_b128 v[182:185], v157 offset:3072
	ds_read_b128 v[194:197], v157 offset:4096
	ds_read_b128 v[206:209], v157 offset:5120
	ds_read_b128 v[210:213], v157 offset:6144
	ds_read_b128 v[214:217], v157 offset:7168
	global_load_lds_dwordx4 v[218:219], off
	v_lshl_add_u64 v[218:219], v[152:153], 0, s[48:49]
	s_add_i32 m0, s58, 0xe000
	s_nop 0
	global_load_lds_dwordx4 v[218:219], off
	s_add_i32 s6, 0, 0x14000
	v_add_u32_e32 v192, s6, v154
	ds_read_b128 v[218:221], v192
	ds_read_b128 v[222:225], v192 offset:1024
	ds_read_b128 v[226:229], v192 offset:2048
	ds_read_b128 v[230:233], v192 offset:3072
	s_waitcnt vmcnt(8)
	s_waitcnt lgkmcnt(0)
	s_barrier
	v_mfma_f32_16x16x32_bf16 v[124:127], v[146:149], v[170:173], v[124:127]
	v_mfma_f32_16x16x32_bf16 v[116:119], v[146:149], v[178:181], v[116:119]
	v_mfma_f32_16x16x32_bf16 v[108:111], v[146:149], v[194:197], v[108:111]
	v_mfma_f32_16x16x32_bf16 v[100:103], v[146:149], v[210:213], v[100:103]
	v_mfma_f32_16x16x32_bf16 v[96:99], v[162:165], v[210:213], v[96:99]
	v_mfma_f32_16x16x32_bf16 v[104:107], v[162:165], v[194:197], v[104:107]
	v_mfma_f32_16x16x32_bf16 v[112:115], v[162:165], v[178:181], v[112:115]
	v_mfma_f32_16x16x32_bf16 v[120:123], v[162:165], v[170:173], v[120:123]
	v_mfma_f32_16x16x32_bf16 v[124:127], v[158:161], v[174:177], v[124:127]
	v_mfma_f32_16x16x32_bf16 v[116:119], v[158:161], v[182:185], v[116:119]
	v_mfma_f32_16x16x32_bf16 v[108:111], v[158:161], v[206:209], v[108:111]
	v_mfma_f32_16x16x32_bf16 v[100:103], v[158:161], v[214:217], v[100:103]
	v_mfma_f32_16x16x32_bf16 v[96:99], v[166:169], v[214:217], v[96:99]
	v_mfma_f32_16x16x32_bf16 v[104:107], v[166:169], v[206:209], v[104:107]
	v_mfma_f32_16x16x32_bf16 v[112:115], v[166:169], v[182:185], v[112:115]
	v_mfma_f32_16x16x32_bf16 v[120:123], v[166:169], v[174:177], v[120:123]
	v_mfma_f32_16x16x32_bf16 v[92:95], v[218:221], v[170:173], v[92:95]
	v_mfma_f32_16x16x32_bf16 v[84:87], v[218:221], v[178:181], v[84:87]
	v_mfma_f32_16x16x32_bf16 v[76:79], v[218:221], v[194:197], v[76:79]
	v_mfma_f32_16x16x32_bf16 v[68:71], v[218:221], v[210:213], v[68:71]
	v_mfma_f32_16x16x32_bf16 v[64:67], v[226:229], v[210:213], v[64:67]
	v_mfma_f32_16x16x32_bf16 v[72:75], v[226:229], v[194:197], v[72:75]
	v_mfma_f32_16x16x32_bf16 v[80:83], v[226:229], v[178:181], v[80:83]
	v_mfma_f32_16x16x32_bf16 v[88:91], v[226:229], v[170:173], v[88:91]
	v_mfma_f32_16x16x32_bf16 v[92:95], v[222:225], v[174:177], v[92:95]
	v_mfma_f32_16x16x32_bf16 v[84:87], v[222:225], v[182:185], v[84:87]
	v_mfma_f32_16x16x32_bf16 v[76:79], v[222:225], v[206:209], v[76:79]
	v_mfma_f32_16x16x32_bf16 v[68:71], v[222:225], v[214:217], v[68:71]
	v_mfma_f32_16x16x32_bf16 v[64:67], v[230:233], v[214:217], v[64:67]
	v_mfma_f32_16x16x32_bf16 v[72:75], v[230:233], v[206:209], v[72:75]
	v_mfma_f32_16x16x32_bf16 v[80:83], v[230:233], v[182:185], v[80:83]
	v_mfma_f32_16x16x32_bf16 v[88:91], v[230:233], v[174:177], v[88:91]
	s_barrier
	s_add_i32 s19, s80, s57
	v_lshl_add_u64 v[234:235], s[50:51], 0, v[140:141]
	s_mov_b32 m0, s19
	s_nop 0
	global_load_lds_dwordx4 v[234:235], off
	v_lshl_add_u64 v[236:237], s[50:51], 0, v[132:133]
	s_add_i32 m0, s19, 0x2000
	s_nop 0
	global_load_lds_dwordx4 v[236:237], off
	s_mov_b32 m0, s58
	v_lshl_add_u64 v[238:239], s[52:53], 0, v[128:129]
	ds_read_b128 v[170:173], v157 offset:16384
	ds_read_b128 v[174:177], v157 offset:17408
	ds_read_b128 v[178:181], v157 offset:18432
	ds_read_b128 v[182:185], v157 offset:19456
	ds_read_b128 v[194:197], v157 offset:20480
	ds_read_b128 v[206:209], v157 offset:21504
	ds_read_b128 v[210:213], v157 offset:22528
	ds_read_b128 v[214:217], v157 offset:23552
	global_load_lds_dwordx4 v[238:239], off
	v_lshl_add_u64 v[240:241], s[52:53], 0, v[130:131]
	s_mov_b32 m0, s59
	s_nop 0
	global_load_lds_dwordx4 v[240:241], off
	s_add_u32 s80, s50, 0x40000
	s_addc_u32 s81, s51, 0
	s_add_i32 s6, s6, s57
	v_lshl_add_u64 v[250:251], s[80:81], 0, v[140:141]
	s_mov_b32 m0, s6
	s_nop 0
	global_load_lds_dwordx4 v[250:251], off
	v_lshl_add_u64 v[250:251], s[80:81], 0, v[132:133]
	s_add_i32 m0, s6, 0x2000
	s_nop 0
	global_load_lds_dwordx4 v[250:251], off
	s_waitcnt vmcnt(8)
	s_waitcnt lgkmcnt(0)
	s_barrier
	v_mfma_f32_16x16x32_bf16 v[60:63], v[146:149], v[170:173], v[60:63]
	v_mfma_f32_16x16x32_bf16 v[52:55], v[146:149], v[178:181], v[52:55]
	v_mfma_f32_16x16x32_bf16 v[44:47], v[146:149], v[194:197], v[44:47]
	v_mfma_f32_16x16x32_bf16 v[36:39], v[146:149], v[210:213], v[36:39]
	v_mfma_f32_16x16x32_bf16 v[32:35], v[162:165], v[210:213], v[32:35]
	v_mfma_f32_16x16x32_bf16 v[40:43], v[162:165], v[194:197], v[40:43]
	v_mfma_f32_16x16x32_bf16 v[48:51], v[162:165], v[178:181], v[48:51]
	v_mfma_f32_16x16x32_bf16 v[56:59], v[162:165], v[170:173], v[56:59]
	v_mfma_f32_16x16x32_bf16 v[60:63], v[158:161], v[174:177], v[60:63]
	v_mfma_f32_16x16x32_bf16 v[52:55], v[158:161], v[182:185], v[52:55]
	v_mfma_f32_16x16x32_bf16 v[44:47], v[158:161], v[206:209], v[44:47]
	v_mfma_f32_16x16x32_bf16 v[36:39], v[158:161], v[214:217], v[36:39]
	v_mfma_f32_16x16x32_bf16 v[32:35], v[166:169], v[214:217], v[32:35]
	v_mfma_f32_16x16x32_bf16 v[40:43], v[166:169], v[206:209], v[40:43]
	v_mfma_f32_16x16x32_bf16 v[48:51], v[166:169], v[182:185], v[48:51]
	v_mfma_f32_16x16x32_bf16 v[56:59], v[166:169], v[174:177], v[56:59]
	v_mfma_f32_16x16x32_bf16 v[28:31], v[218:221], v[170:173], v[28:31]
	v_mfma_f32_16x16x32_bf16 v[20:23], v[218:221], v[178:181], v[20:23]
	v_mfma_f32_16x16x32_bf16 v[12:15], v[218:221], v[194:197], v[12:15]
	v_mfma_f32_16x16x32_bf16 v[4:7], v[218:221], v[210:213], v[4:7]
	v_mfma_f32_16x16x32_bf16 v[0:3], v[226:229], v[210:213], v[0:3]
	v_mfma_f32_16x16x32_bf16 v[8:11], v[226:229], v[194:197], v[8:11]
	v_mfma_f32_16x16x32_bf16 v[16:19], v[226:229], v[178:181], v[16:19]
	v_mfma_f32_16x16x32_bf16 v[24:27], v[226:229], v[170:173], v[24:27]
	v_mfma_f32_16x16x32_bf16 v[28:31], v[222:225], v[174:177], v[28:31]
	v_mfma_f32_16x16x32_bf16 v[20:23], v[222:225], v[182:185], v[20:23]
	v_mfma_f32_16x16x32_bf16 v[12:15], v[222:225], v[206:209], v[12:15]
	v_mfma_f32_16x16x32_bf16 v[4:7], v[222:225], v[214:217], v[4:7]
	v_mfma_f32_16x16x32_bf16 v[0:3], v[230:233], v[214:217], v[0:3]
	v_mfma_f32_16x16x32_bf16 v[8:11], v[230:233], v[206:209], v[8:11]
	v_mfma_f32_16x16x32_bf16 v[16:19], v[230:233], v[182:185], v[16:19]
	v_mfma_f32_16x16x32_bf16 v[24:27], v[230:233], v[174:177], v[24:27]
	s_barrier
	s_add_i32 s6, 0, 0x18000
	v_add_u32_e32 v166, s6, v154
	ds_read_b128 v[146:149], v166
	ds_read_b128 v[158:161], v166 offset:1024
	ds_read_b128 v[162:165], v166 offset:2048
	ds_read_b128 v[166:169], v166 offset:3072
	s_add_u32 s52, s52, 0x40000
	s_addc_u32 s53, s53, 0
	s_mov_b32 m0, s68
	v_lshl_add_u64 v[218:219], s[52:53], 0, v[128:129]
	ds_read_b128 v[170:173], v157 offset:32768
	ds_read_b128 v[174:177], v157 offset:33792
	ds_read_b128 v[178:181], v157 offset:34816
	ds_read_b128 v[182:185], v157 offset:35840
	ds_read_b128 v[194:197], v157 offset:36864
	ds_read_b128 v[206:209], v157 offset:37888
	ds_read_b128 v[210:213], v157 offset:38912
	ds_read_b128 v[214:217], v157 offset:39936
	global_load_lds_dwordx4 v[218:219], off
	v_lshl_add_u64 v[218:219], s[52:53], 0, v[130:131]
	s_mov_b32 m0, s69
	s_nop 0
	global_load_lds_dwordx4 v[218:219], off
	s_add_i32 s19, 0, 0x1c000
	v_add_u32_e32 v192, s19, v154
	ds_read_b128 v[218:221], v192
	ds_read_b128 v[222:225], v192 offset:1024
	ds_read_b128 v[226:229], v192 offset:2048
	ds_read_b128 v[230:233], v192 offset:3072
	s_waitcnt vmcnt(8)
	s_waitcnt lgkmcnt(0)
	s_barrier
	v_mfma_f32_16x16x32_bf16 v[124:127], v[146:149], v[170:173], v[124:127]
	v_mfma_f32_16x16x32_bf16 v[116:119], v[146:149], v[178:181], v[116:119]
	v_mfma_f32_16x16x32_bf16 v[108:111], v[146:149], v[194:197], v[108:111]
	v_mfma_f32_16x16x32_bf16 v[100:103], v[146:149], v[210:213], v[100:103]
	v_mfma_f32_16x16x32_bf16 v[96:99], v[162:165], v[210:213], v[96:99]
	v_mfma_f32_16x16x32_bf16 v[104:107], v[162:165], v[194:197], v[104:107]
	v_mfma_f32_16x16x32_bf16 v[112:115], v[162:165], v[178:181], v[112:115]
	v_mfma_f32_16x16x32_bf16 v[120:123], v[162:165], v[170:173], v[120:123]
	v_mfma_f32_16x16x32_bf16 v[124:127], v[158:161], v[174:177], v[124:127]
	v_mfma_f32_16x16x32_bf16 v[116:119], v[158:161], v[182:185], v[116:119]
	v_mfma_f32_16x16x32_bf16 v[108:111], v[158:161], v[206:209], v[108:111]
	v_mfma_f32_16x16x32_bf16 v[100:103], v[158:161], v[214:217], v[100:103]
	v_mfma_f32_16x16x32_bf16 v[96:99], v[166:169], v[214:217], v[96:99]
	v_mfma_f32_16x16x32_bf16 v[104:107], v[166:169], v[206:209], v[104:107]
	v_mfma_f32_16x16x32_bf16 v[112:115], v[166:169], v[182:185], v[112:115]
	v_mfma_f32_16x16x32_bf16 v[120:123], v[166:169], v[174:177], v[120:123]
	v_mfma_f32_16x16x32_bf16 v[92:95], v[218:221], v[170:173], v[92:95]
	v_mfma_f32_16x16x32_bf16 v[84:87], v[218:221], v[178:181], v[84:87]
	v_mfma_f32_16x16x32_bf16 v[76:79], v[218:221], v[194:197], v[76:79]
	v_mfma_f32_16x16x32_bf16 v[68:71], v[218:221], v[210:213], v[68:71]
	v_mfma_f32_16x16x32_bf16 v[64:67], v[226:229], v[210:213], v[64:67]
	v_mfma_f32_16x16x32_bf16 v[72:75], v[226:229], v[194:197], v[72:75]
	v_mfma_f32_16x16x32_bf16 v[80:83], v[226:229], v[178:181], v[80:83]
	v_mfma_f32_16x16x32_bf16 v[88:91], v[226:229], v[170:173], v[88:91]
	v_mfma_f32_16x16x32_bf16 v[92:95], v[222:225], v[174:177], v[92:95]
	v_mfma_f32_16x16x32_bf16 v[84:87], v[222:225], v[182:185], v[84:87]
	v_mfma_f32_16x16x32_bf16 v[76:79], v[222:225], v[206:209], v[76:79]
	v_mfma_f32_16x16x32_bf16 v[68:71], v[222:225], v[214:217], v[68:71]
	v_mfma_f32_16x16x32_bf16 v[64:67], v[230:233], v[214:217], v[64:67]
	v_mfma_f32_16x16x32_bf16 v[72:75], v[230:233], v[206:209], v[72:75]
	v_mfma_f32_16x16x32_bf16 v[80:83], v[230:233], v[182:185], v[80:83]
	v_mfma_f32_16x16x32_bf16 v[88:91], v[230:233], v[174:177], v[88:91]
	s_barrier
	s_add_i32 s6, s6, s57
	v_lshl_add_u64 v[234:235], v[234:235], 0, s[36:37]
	s_mov_b32 m0, s6
	s_nop 0
	global_load_lds_dwordx4 v[234:235], off
	v_lshl_add_u64 v[234:235], v[236:237], 0, s[36:37]
	s_add_i32 m0, s6, 0x2000
	s_nop 0
	global_load_lds_dwordx4 v[234:235], off
	s_mov_b32 m0, s70
	v_lshl_add_u64 v[234:235], v[238:239], 0, s[36:37]
	ds_read_b128 v[170:173], v157 offset:49152
	ds_read_b128 v[174:177], v157 offset:50176
	ds_read_b128 v[178:181], v157 offset:51200
	ds_read_b128 v[182:185], v157 offset:52224
	ds_read_b128 v[194:197], v157 offset:53248
	ds_read_b128 v[206:209], v157 offset:54272
	ds_read_b128 v[210:213], v157 offset:55296
	ds_read_b128 v[214:217], v157 offset:56320
	global_load_lds_dwordx4 v[234:235], off
	v_lshl_add_u64 v[234:235], v[240:241], 0, s[36:37]
	s_mov_b32 m0, s71
	s_nop 0
	global_load_lds_dwordx4 v[234:235], off
	s_add_u32 s50, s50, 0x40080
	s_addc_u32 s51, s51, 0
	s_add_i32 s6, s19, s57
	v_lshl_add_u64 v[250:251], s[50:51], 0, v[140:141]
	s_mov_b32 m0, s6
	s_nop 0
	global_load_lds_dwordx4 v[250:251], off
	v_lshl_add_u64 v[250:251], s[50:51], 0, v[132:133]
	s_add_i32 m0, s6, 0x2000
	s_nop 0
	global_load_lds_dwordx4 v[250:251], off
	s_waitcnt vmcnt(8)
	s_waitcnt lgkmcnt(0)
	s_barrier
	v_mfma_f32_16x16x32_bf16 v[60:63], v[146:149], v[170:173], v[60:63]
	v_mfma_f32_16x16x32_bf16 v[52:55], v[146:149], v[178:181], v[52:55]
	v_mfma_f32_16x16x32_bf16 v[44:47], v[146:149], v[194:197], v[44:47]
	v_mfma_f32_16x16x32_bf16 v[36:39], v[146:149], v[210:213], v[36:39]
	v_mfma_f32_16x16x32_bf16 v[32:35], v[162:165], v[210:213], v[32:35]
	v_mfma_f32_16x16x32_bf16 v[40:43], v[162:165], v[194:197], v[40:43]
	v_mfma_f32_16x16x32_bf16 v[48:51], v[162:165], v[178:181], v[48:51]
	v_mfma_f32_16x16x32_bf16 v[56:59], v[162:165], v[170:173], v[56:59]
	v_mfma_f32_16x16x32_bf16 v[60:63], v[158:161], v[174:177], v[60:63]
	v_mfma_f32_16x16x32_bf16 v[52:55], v[158:161], v[182:185], v[52:55]
	v_mfma_f32_16x16x32_bf16 v[44:47], v[158:161], v[206:209], v[44:47]
	v_mfma_f32_16x16x32_bf16 v[36:39], v[158:161], v[214:217], v[36:39]
	v_mfma_f32_16x16x32_bf16 v[32:35], v[166:169], v[214:217], v[32:35]
	v_mfma_f32_16x16x32_bf16 v[40:43], v[166:169], v[206:209], v[40:43]
	v_mfma_f32_16x16x32_bf16 v[48:51], v[166:169], v[182:185], v[48:51]
	v_mfma_f32_16x16x32_bf16 v[56:59], v[166:169], v[174:177], v[56:59]
	v_mfma_f32_16x16x32_bf16 v[28:31], v[218:221], v[170:173], v[28:31]
	v_mfma_f32_16x16x32_bf16 v[20:23], v[218:221], v[178:181], v[20:23]
	v_mfma_f32_16x16x32_bf16 v[12:15], v[218:221], v[194:197], v[12:15]
	v_mfma_f32_16x16x32_bf16 v[4:7], v[218:221], v[210:213], v[4:7]
	v_mfma_f32_16x16x32_bf16 v[0:3], v[226:229], v[210:213], v[0:3]
	v_mfma_f32_16x16x32_bf16 v[8:11], v[226:229], v[194:197], v[8:11]
	v_mfma_f32_16x16x32_bf16 v[16:19], v[226:229], v[178:181], v[16:19]
	v_mfma_f32_16x16x32_bf16 v[24:27], v[226:229], v[170:173], v[24:27]
	v_mfma_f32_16x16x32_bf16 v[28:31], v[222:225], v[174:177], v[28:31]
	v_mfma_f32_16x16x32_bf16 v[20:23], v[222:225], v[182:185], v[20:23]
	v_mfma_f32_16x16x32_bf16 v[12:15], v[222:225], v[206:209], v[12:15]
	v_mfma_f32_16x16x32_bf16 v[4:7], v[222:225], v[214:217], v[4:7]
	v_mfma_f32_16x16x32_bf16 v[0:3], v[230:233], v[214:217], v[0:3]
	v_mfma_f32_16x16x32_bf16 v[8:11], v[230:233], v[206:209], v[8:11]
	v_mfma_f32_16x16x32_bf16 v[16:19], v[230:233], v[182:185], v[16:19]
	v_mfma_f32_16x16x32_bf16 v[24:27], v[230:233], v[174:177], v[24:27]
	s_add_i32 s75, s75, 2
	s_add_u32 s48, s48, 0x100
	s_addc_u32 s49, s49, 0
	s_cmp_gt_u32 s75, 13
	s_barrier
	s_cbranch_scc0 .LBB0_295
	s_mov_b32 s100, 1
	s_add_u32 s48, s10, 0xffffff00
	v_lshl_add_u32 v166, s73, 10, v155
	s_addc_u32 s49, s11, -1
	s_ashr_i32 s29, s28, 31
	v_lshl_or_b32 v146, s72, 8, v156
	ds_read2_b32 v[158:159], v166 offset1:16
	s_lshl_b64 s[10:11], s[28:29], 8
	v_ashrrev_i32_e32 v147, 31, v146
	v_lshl_add_u64 v[148:149], s[10:11], 0, v[134:135]
	v_lshl_add_u64 v[146:147], v[146:147], 1, s[26:27]
	v_mad_u64_u32 v[150:151], s[10:11], v148, s13, v[146:147]
	v_mov_b32_e32 v146, v151
	v_mad_u64_u32 v[152:153], s[10:11], v149, s13, v[146:147]
	s_waitcnt lgkmcnt(0)
	v_pk_mul_f32 v[148:149], v[126:127], v[158:159] op_sel_hi:[1,0]
	v_pk_mul_f32 v[146:147], v[124:125], v[158:159] op_sel_hi:[1,0]
	v_pk_mul_f32 v[160:161], v[122:123], v[158:159] op_sel_hi:[1,0]
	v_pk_mul_f32 v[162:163], v[120:121], v[158:159] op_sel_hi:[1,0]
	v_mov_b32_e32 v151, v152
	v_cvt_pk_bf16_f32 v146, v146, v147
	v_cvt_pk_bf16_f32 v147, v148, v149
	v_cvt_pk_bf16_f32 v148, v162, v163
	v_cvt_pk_bf16_f32 v149, v160, v161
	global_store_dwordx4 v[150:151], v[146:149], off
	v_pk_mul_f32 v[160:161], v[90:91], v[158:159] op_sel_hi:[1,0]
	v_pk_mul_f32 v[162:163], v[88:89], v[158:159] op_sel_hi:[1,0]
	v_pk_mul_f32 v[148:149], v[94:95], v[158:159] op_sel_hi:[1,0]
	v_pk_mul_f32 v[146:147], v[92:93], v[158:159] op_sel_hi:[1,0]
	v_mov_b32_e32 v158, v159
	v_cvt_pk_bf16_f32 v146, v146, v147
	v_cvt_pk_bf16_f32 v147, v148, v149
	v_cvt_pk_bf16_f32 v148, v162, v163
	v_cvt_pk_bf16_f32 v149, v160, v161
	global_store_dwordx4 v[150:151], v[146:149], off offset:256
	v_pk_mul_f32 v[160:161], v[114:115], v[158:159] op_sel_hi:[1,0]
	s_mov_b32 s6, 0x1e000
	v_pk_mul_f32 v[148:149], v[118:119], v[158:159] op_sel_hi:[1,0]
	v_pk_mul_f32 v[146:147], v[116:117], v[158:159] op_sel_hi:[1,0]
	ds_read2_b32 v[164:165], v166 offset0:32 offset1:48
	v_pk_mul_f32 v[162:163], v[112:113], v[158:159] op_sel_hi:[1,0]
	v_cvt_pk_bf16_f32 v146, v146, v147
	v_cvt_pk_bf16_f32 v147, v148, v149
	v_cvt_pk_bf16_f32 v149, v160, v161
	v_add_co_u32_e32 v160, vcc, s6, v150
	v_cvt_pk_bf16_f32 v148, v162, v163
	s_nop 0
	v_addc_co_u32_e32 v161, vcc, 0, v152, vcc
	global_store_dwordx4 v[160:161], v[146:149], off
	v_pk_mul_f32 v[162:163], v[82:83], v[158:159] op_sel_hi:[1,0]
	s_mov_b32 s6, 0x3c000
	v_pk_mul_f32 v[148:149], v[86:87], v[158:159] op_sel_hi:[1,0]
	v_pk_mul_f32 v[146:147], v[84:85], v[158:159] op_sel_hi:[1,0]
	v_pk_mul_f32 v[158:159], v[80:81], v[158:159] op_sel_hi:[1,0]
	v_cvt_pk_bf16_f32 v146, v146, v147
	v_cvt_pk_bf16_f32 v147, v148, v149
	v_cvt_pk_bf16_f32 v148, v158, v159
	v_cvt_pk_bf16_f32 v149, v162, v163
	global_store_dwordx4 v[160:161], v[146:149], off offset:256
	s_waitcnt lgkmcnt(0)
	v_pk_mul_f32 v[158:159], v[106:107], v[164:165] op_sel_hi:[1,0]
	v_pk_mul_f32 v[160:161], v[104:105], v[164:165] op_sel_hi:[1,0]
	v_pk_mul_f32 v[148:149], v[110:111], v[164:165] op_sel_hi:[1,0]
	v_pk_mul_f32 v[146:147], v[108:109], v[164:165] op_sel_hi:[1,0]
	v_pk_mul_f32 v[162:163], v[72:73], v[164:165] op_sel_hi:[1,0]
	v_cvt_pk_bf16_f32 v146, v146, v147
	v_cvt_pk_bf16_f32 v147, v148, v149
	v_cvt_pk_bf16_f32 v149, v158, v159
	v_add_co_u32_e32 v158, vcc, s6, v150
	v_cvt_pk_bf16_f32 v148, v160, v161
	s_nop 0
	v_addc_co_u32_e32 v159, vcc, 0, v152, vcc
	global_store_dwordx4 v[158:159], v[146:149], off
	v_pk_mul_f32 v[160:161], v[74:75], v[164:165] op_sel_hi:[1,0]
	s_mov_b32 s6, 0x5a000
	v_pk_mul_f32 v[148:149], v[78:79], v[164:165] op_sel_hi:[1,0]
	v_pk_mul_f32 v[146:147], v[76:77], v[164:165] op_sel_hi:[1,0]
	s_nop 0
	v_cvt_pk_bf16_f32 v146, v146, v147
	v_cvt_pk_bf16_f32 v147, v148, v149
	v_cvt_pk_bf16_f32 v148, v162, v163
	v_cvt_pk_bf16_f32 v149, v160, v161
	global_store_dwordx4 v[158:159], v[146:149], off offset:256
	v_mov_b32_e32 v158, v165
	v_pk_mul_f32 v[160:161], v[98:99], v[158:159] op_sel_hi:[1,0]
	v_pk_mul_f32 v[148:149], v[102:103], v[158:159] op_sel_hi:[1,0]
	v_pk_mul_f32 v[146:147], v[100:101], v[158:159] op_sel_hi:[1,0]
	ds_read2_b32 v[164:165], v166 offset0:128 offset1:144
	v_pk_mul_f32 v[162:163], v[96:97], v[158:159] op_sel_hi:[1,0]
	v_cvt_pk_bf16_f32 v146, v146, v147
	v_cvt_pk_bf16_f32 v147, v148, v149
	v_cvt_pk_bf16_f32 v149, v160, v161
	v_add_co_u32_e32 v160, vcc, s6, v150
	v_cvt_pk_bf16_f32 v148, v162, v163
	s_nop 0
	v_addc_co_u32_e32 v161, vcc, 0, v152, vcc
	global_store_dwordx4 v[160:161], v[146:149], off
	v_pk_mul_f32 v[162:163], v[66:67], v[158:159] op_sel_hi:[1,0]
	s_mov_b32 s6, 0xf0000
	v_pk_mul_f32 v[148:149], v[70:71], v[158:159] op_sel_hi:[1,0]
	v_pk_mul_f32 v[146:147], v[68:69], v[158:159] op_sel_hi:[1,0]
	v_pk_mul_f32 v[158:159], v[64:65], v[158:159] op_sel_hi:[1,0]
	v_cvt_pk_bf16_f32 v146, v146, v147
	v_cvt_pk_bf16_f32 v147, v148, v149
	v_cvt_pk_bf16_f32 v148, v158, v159
	v_cvt_pk_bf16_f32 v149, v162, v163
	global_store_dwordx4 v[160:161], v[146:149], off offset:256
	s_waitcnt lgkmcnt(0)
	v_pk_mul_f32 v[158:159], v[58:59], v[164:165] op_sel_hi:[1,0]
	v_pk_mul_f32 v[160:161], v[56:57], v[164:165] op_sel_hi:[1,0]
	v_pk_mul_f32 v[148:149], v[62:63], v[164:165] op_sel_hi:[1,0]
	v_pk_mul_f32 v[146:147], v[60:61], v[164:165] op_sel_hi:[1,0]
	v_pk_mul_f32 v[162:163], v[24:25], v[164:165] op_sel_hi:[1,0]
	v_cvt_pk_bf16_f32 v146, v146, v147
	v_cvt_pk_bf16_f32 v147, v148, v149
	v_cvt_pk_bf16_f32 v149, v158, v159
	v_add_co_u32_e32 v158, vcc, s6, v150
	v_cvt_pk_bf16_f32 v148, v160, v161
	s_nop 0
	v_addc_co_u32_e32 v159, vcc, 0, v152, vcc
	global_store_dwordx4 v[158:159], v[146:149], off
	v_pk_mul_f32 v[160:161], v[26:27], v[164:165] op_sel_hi:[1,0]
	s_mov_b32 s6, 0x10e000
	v_pk_mul_f32 v[148:149], v[30:31], v[164:165] op_sel_hi:[1,0]
	v_pk_mul_f32 v[146:147], v[28:29], v[164:165] op_sel_hi:[1,0]
	s_nop 0
	v_cvt_pk_bf16_f32 v146, v146, v147
	v_cvt_pk_bf16_f32 v147, v148, v149
	v_cvt_pk_bf16_f32 v148, v162, v163
	v_cvt_pk_bf16_f32 v149, v160, v161
	global_store_dwordx4 v[158:159], v[146:149], off offset:256
	v_mov_b32_e32 v158, v165
	v_pk_mul_f32 v[160:161], v[50:51], v[158:159] op_sel_hi:[1,0]
	v_pk_mul_f32 v[148:149], v[54:55], v[158:159] op_sel_hi:[1,0]
	v_pk_mul_f32 v[146:147], v[52:53], v[158:159] op_sel_hi:[1,0]
	ds_read2_b32 v[164:165], v166 offset0:160 offset1:176
	v_pk_mul_f32 v[162:163], v[48:49], v[158:159] op_sel_hi:[1,0]
	v_cvt_pk_bf16_f32 v146, v146, v147
	v_cvt_pk_bf16_f32 v147, v148, v149
	v_cvt_pk_bf16_f32 v149, v160, v161
	v_add_co_u32_e32 v160, vcc, s6, v150
	v_cvt_pk_bf16_f32 v148, v162, v163
	s_nop 0
	v_addc_co_u32_e32 v161, vcc, 0, v152, vcc
	global_store_dwordx4 v[160:161], v[146:149], off
	v_pk_mul_f32 v[162:163], v[18:19], v[158:159] op_sel_hi:[1,0]
	s_mov_b32 s6, 0x12c000
	v_pk_mul_f32 v[148:149], v[22:23], v[158:159] op_sel_hi:[1,0]
	v_pk_mul_f32 v[146:147], v[20:21], v[158:159] op_sel_hi:[1,0]
	v_pk_mul_f32 v[158:159], v[16:17], v[158:159] op_sel_hi:[1,0]
	v_cvt_pk_bf16_f32 v146, v146, v147
	v_cvt_pk_bf16_f32 v147, v148, v149
	v_cvt_pk_bf16_f32 v148, v158, v159
	v_cvt_pk_bf16_f32 v149, v162, v163
	global_store_dwordx4 v[160:161], v[146:149], off offset:256
	s_waitcnt lgkmcnt(0)
	v_pk_mul_f32 v[158:159], v[42:43], v[164:165] op_sel_hi:[1,0]
	v_pk_mul_f32 v[160:161], v[40:41], v[164:165] op_sel_hi:[1,0]
	v_pk_mul_f32 v[148:149], v[46:47], v[164:165] op_sel_hi:[1,0]
	v_pk_mul_f32 v[146:147], v[44:45], v[164:165] op_sel_hi:[1,0]
	v_pk_mul_f32 v[162:163], v[8:9], v[164:165] op_sel_hi:[1,0]
	v_cvt_pk_bf16_f32 v146, v146, v147
	v_cvt_pk_bf16_f32 v147, v148, v149
	v_cvt_pk_bf16_f32 v149, v158, v159
	v_add_co_u32_e32 v158, vcc, s6, v150
	v_cvt_pk_bf16_f32 v148, v160, v161
	s_nop 0
	v_addc_co_u32_e32 v159, vcc, 0, v152, vcc
	global_store_dwordx4 v[158:159], v[146:149], off
	v_pk_mul_f32 v[160:161], v[10:11], v[164:165] op_sel_hi:[1,0]
	s_mov_b32 s6, 0x14a000
	v_pk_mul_f32 v[148:149], v[14:15], v[164:165] op_sel_hi:[1,0]
	v_pk_mul_f32 v[146:147], v[12:13], v[164:165] op_sel_hi:[1,0]
	v_add_co_u32_e32 v150, vcc, s6, v150
	v_cvt_pk_bf16_f32 v146, v146, v147
	v_cvt_pk_bf16_f32 v147, v148, v149
	v_cvt_pk_bf16_f32 v148, v162, v163
	v_cvt_pk_bf16_f32 v149, v160, v161
	global_store_dwordx4 v[158:159], v[146:149], off offset:256
	v_mov_b32_e32 v158, v165
	v_pk_mul_f32 v[160:161], v[34:35], v[158:159] op_sel_hi:[1,0]
	v_pk_mul_f32 v[148:149], v[38:39], v[158:159] op_sel_hi:[1,0]
	v_pk_mul_f32 v[146:147], v[36:37], v[158:159] op_sel_hi:[1,0]
	v_pk_mul_f32 v[162:163], v[32:33], v[158:159] op_sel_hi:[1,0]
	v_cvt_pk_bf16_f32 v146, v146, v147
	v_cvt_pk_bf16_f32 v147, v148, v149
	v_cvt_pk_bf16_f32 v148, v162, v163
	v_cvt_pk_bf16_f32 v149, v160, v161
	v_addc_co_u32_e32 v151, vcc, 0, v152, vcc
	global_store_dwordx4 v[150:151], v[146:149], off
	v_pk_mul_f32 v[152:153], v[2:3], v[158:159] op_sel_hi:[1,0]
	s_andn2_b64 vcc, exec, s[44:45]
	v_pk_mul_f32 v[148:149], v[6:7], v[158:159] op_sel_hi:[1,0]
	v_pk_mul_f32 v[146:147], v[4:5], v[158:159] op_sel_hi:[1,0]
	v_pk_mul_f32 v[158:159], v[0:1], v[158:159] op_sel_hi:[1,0]
	v_cvt_pk_bf16_f32 v146, v146, v147
	v_cvt_pk_bf16_f32 v147, v148, v149
	v_cvt_pk_bf16_f32 v148, v158, v159
	v_cvt_pk_bf16_f32 v149, v152, v153
	global_store_dwordx4 v[150:151], v[146:149], off offset:256
	s_cbranch_vccz .LBB0_291
	s_mov_b64 s[38:39], s[48:49]
	s_andn2_b64 vcc, exec, s[42:43]
	s_mov_b64 s[48:49], s[38:39]
	s_cbranch_vccnz .LBB0_292

.Lm4ap_315:
	s_waitcnt lgkmcnt(0)
	s_barrier
	v_mfma_f32_16x16x32_bf16 v[124:127], v[146:149], v[170:173], 0
	v_mfma_f32_16x16x32_bf16 v[116:119], v[146:149], v[178:181], 0
	v_mfma_f32_16x16x32_bf16 v[108:111], v[146:149], v[194:197], 0
	v_mfma_f32_16x16x32_bf16 v[100:103], v[146:149], v[210:213], 0
	v_mfma_f32_16x16x32_bf16 v[96:99], v[162:165], v[210:213], 0
	v_mfma_f32_16x16x32_bf16 v[104:107], v[162:165], v[194:197], 0
	v_mfma_f32_16x16x32_bf16 v[112:115], v[162:165], v[178:181], 0
	v_mfma_f32_16x16x32_bf16 v[120:123], v[162:165], v[170:173], 0
	v_mfma_f32_16x16x32_bf16 v[124:127], v[158:161], v[174:177], v[124:127]
	v_mfma_f32_16x16x32_bf16 v[116:119], v[158:161], v[182:185], v[116:119]
	v_mfma_f32_16x16x32_bf16 v[108:111], v[158:161], v[206:209], v[108:111]
	v_mfma_f32_16x16x32_bf16 v[100:103], v[158:161], v[214:217], v[100:103]
	v_mfma_f32_16x16x32_bf16 v[96:99], v[166:169], v[214:217], v[96:99]
	v_mfma_f32_16x16x32_bf16 v[104:107], v[166:169], v[206:209], v[104:107]
	v_mfma_f32_16x16x32_bf16 v[112:115], v[166:169], v[182:185], v[112:115]
	v_mfma_f32_16x16x32_bf16 v[120:123], v[166:169], v[174:177], v[120:123]
	v_mfma_f32_16x16x32_bf16 v[92:95], v[218:221], v[170:173], 0
	v_mfma_f32_16x16x32_bf16 v[84:87], v[218:221], v[178:181], 0
	v_mfma_f32_16x16x32_bf16 v[76:79], v[218:221], v[194:197], 0
	v_mfma_f32_16x16x32_bf16 v[68:71], v[218:221], v[210:213], 0
	v_mfma_f32_16x16x32_bf16 v[64:67], v[226:229], v[210:213], 0
	v_mfma_f32_16x16x32_bf16 v[72:75], v[226:229], v[194:197], 0
	v_mfma_f32_16x16x32_bf16 v[80:83], v[226:229], v[178:181], 0
	v_mfma_f32_16x16x32_bf16 v[88:91], v[226:229], v[170:173], 0
	v_mfma_f32_16x16x32_bf16 v[92:95], v[222:225], v[174:177], v[92:95]
	v_mfma_f32_16x16x32_bf16 v[84:87], v[222:225], v[182:185], v[84:87]
	v_mfma_f32_16x16x32_bf16 v[76:79], v[222:225], v[206:209], v[76:79]
	v_mfma_f32_16x16x32_bf16 v[68:71], v[222:225], v[214:217], v[68:71]
	v_mfma_f32_16x16x32_bf16 v[64:67], v[230:233], v[214:217], v[64:67]
	v_mfma_f32_16x16x32_bf16 v[72:75], v[230:233], v[206:209], v[72:75]
	v_mfma_f32_16x16x32_bf16 v[80:83], v[230:233], v[182:185], v[80:83]
	v_mfma_f32_16x16x32_bf16 v[88:91], v[230:233], v[174:177], v[88:91]
	s_barrier
	s_add_i32 s19, s80, s57
	v_lshl_add_u64 v[234:235], s[50:51], 0, v[140:141]
	s_mov_b32 m0, s19
	s_nop 0
	global_load_lds_dwordx4 v[234:235], off
	v_lshl_add_u64 v[236:237], s[50:51], 0, v[132:133]
	s_add_i32 m0, s19, 0x2000
	s_nop 0
	global_load_lds_dwordx4 v[236:237], off
	s_mov_b32 m0, s58
	v_lshl_add_u64 v[238:239], s[52:53], 0, v[128:129]
	ds_read_b128 v[170:173], v156 offset:16384
	ds_read_b128 v[174:177], v156 offset:17408
	ds_read_b128 v[178:181], v156 offset:18432
	ds_read_b128 v[182:185], v156 offset:19456
	ds_read_b128 v[194:197], v156 offset:20480
	ds_read_b128 v[206:209], v156 offset:21504
	ds_read_b128 v[210:213], v156 offset:22528
	ds_read_b128 v[214:217], v156 offset:23552
	global_load_lds_dwordx4 v[238:239], off
	v_lshl_add_u64 v[240:241], s[52:53], 0, v[130:131]
	s_mov_b32 m0, s59
	s_nop 0
	global_load_lds_dwordx4 v[240:241], off
	s_add_u32 s80, s50, 0x40000
	s_addc_u32 s81, s51, 0
	s_add_i32 s6, s6, s57
	v_lshl_add_u64 v[250:251], s[80:81], 0, v[140:141]
	s_mov_b32 m0, s6
	s_nop 0
	global_load_lds_dwordx4 v[250:251], off
	v_lshl_add_u64 v[250:251], s[80:81], 0, v[132:133]
	s_add_i32 m0, s6, 0x2000
	s_nop 0
	global_load_lds_dwordx4 v[250:251], off
	s_waitcnt vmcnt(24)
	s_cmp_lg_u32 s100, 0
	s_cbranch_scc1 .Lm4bp_315
	s_waitcnt vmcnt(8)
.Lm4bp_315:
	s_waitcnt lgkmcnt(0)
	s_mov_b32 s100, 0
	s_barrier
	v_mfma_f32_16x16x32_bf16 v[60:63], v[146:149], v[170:173], 0
	v_mfma_f32_16x16x32_bf16 v[52:55], v[146:149], v[178:181], 0
	v_mfma_f32_16x16x32_bf16 v[44:47], v[146:149], v[194:197], 0
	v_mfma_f32_16x16x32_bf16 v[36:39], v[146:149], v[210:213], 0
	v_mfma_f32_16x16x32_bf16 v[32:35], v[162:165], v[210:213], 0
	v_mfma_f32_16x16x32_bf16 v[40:43], v[162:165], v[194:197], 0
	v_mfma_f32_16x16x32_bf16 v[48:51], v[162:165], v[178:181], 0
	v_mfma_f32_16x16x32_bf16 v[56:59], v[162:165], v[170:173], 0
	v_mfma_f32_16x16x32_bf16 v[60:63], v[158:161], v[174:177], v[60:63]
	v_mfma_f32_16x16x32_bf16 v[52:55], v[158:161], v[182:185], v[52:55]
	v_mfma_f32_16x16x32_bf16 v[44:47], v[158:161], v[206:209], v[44:47]
	v_mfma_f32_16x16x32_bf16 v[36:39], v[158:161], v[214:217], v[36:39]
	v_mfma_f32_16x16x32_bf16 v[32:35], v[166:169], v[214:217], v[32:35]
	v_mfma_f32_16x16x32_bf16 v[40:43], v[166:169], v[206:209], v[40:43]
	v_mfma_f32_16x16x32_bf16 v[48:51], v[166:169], v[182:185], v[48:51]
	v_mfma_f32_16x16x32_bf16 v[56:59], v[166:169], v[174:177], v[56:59]
	v_mfma_f32_16x16x32_bf16 v[28:31], v[218:221], v[170:173], 0
	v_mfma_f32_16x16x32_bf16 v[20:23], v[218:221], v[178:181], 0
	v_mfma_f32_16x16x32_bf16 v[12:15], v[218:221], v[194:197], 0
	v_mfma_f32_16x16x32_bf16 v[4:7], v[218:221], v[210:213], 0
	v_mfma_f32_16x16x32_bf16 v[0:3], v[226:229], v[210:213], 0
	v_mfma_f32_16x16x32_bf16 v[8:11], v[226:229], v[194:197], 0
	v_mfma_f32_16x16x32_bf16 v[16:19], v[226:229], v[178:181], 0
	v_mfma_f32_16x16x32_bf16 v[24:27], v[226:229], v[170:173], 0
	v_mfma_f32_16x16x32_bf16 v[28:31], v[222:225], v[174:177], v[28:31]
	v_mfma_f32_16x16x32_bf16 v[20:23], v[222:225], v[182:185], v[20:23]
	v_mfma_f32_16x16x32_bf16 v[12:15], v[222:225], v[206:209], v[12:15]
	v_mfma_f32_16x16x32_bf16 v[4:7], v[222:225], v[214:217], v[4:7]
	v_mfma_f32_16x16x32_bf16 v[0:3], v[230:233], v[214:217], v[0:3]
	v_mfma_f32_16x16x32_bf16 v[8:11], v[230:233], v[206:209], v[8:11]
	v_mfma_f32_16x16x32_bf16 v[16:19], v[230:233], v[182:185], v[16:19]
	v_mfma_f32_16x16x32_bf16 v[24:27], v[230:233], v[174:177], v[24:27]
	s_barrier
	s_add_i32 s6, 0, 0x18000
	v_add_u32_e32 v157, s6, v154
	ds_read_b128 v[146:149], v157
	ds_read_b128 v[158:161], v157 offset:1024
	ds_read_b128 v[162:165], v157 offset:2048
	ds_read_b128 v[166:169], v157 offset:3072
	s_add_u32 s52, s52, 0x40000
	s_addc_u32 s53, s53, 0
	s_mov_b32 m0, s68
	v_lshl_add_u64 v[218:219], s[52:53], 0, v[128:129]
	ds_read_b128 v[170:173], v156 offset:32768
	ds_read_b128 v[174:177], v156 offset:33792
	ds_read_b128 v[178:181], v156 offset:34816
	ds_read_b128 v[182:185], v156 offset:35840
	ds_read_b128 v[194:197], v156 offset:36864
	ds_read_b128 v[206:209], v156 offset:37888
	ds_read_b128 v[210:213], v156 offset:38912
	ds_read_b128 v[214:217], v156 offset:39936
	global_load_lds_dwordx4 v[218:219], off
	v_lshl_add_u64 v[218:219], s[52:53], 0, v[130:131]
	s_mov_b32 m0, s69
	s_nop 0
	global_load_lds_dwordx4 v[218:219], off
	s_add_i32 s19, 0, 0x1c000
	v_add_u32_e32 v157, s19, v154
	ds_read_b128 v[218:221], v157
	ds_read_b128 v[222:225], v157 offset:1024
	ds_read_b128 v[226:229], v157 offset:2048
	ds_read_b128 v[230:233], v157 offset:3072
	s_waitcnt vmcnt(8)
	s_waitcnt lgkmcnt(0)
	s_barrier
	v_mfma_f32_16x16x32_bf16 v[124:127], v[146:149], v[170:173], v[124:127]
	v_mfma_f32_16x16x32_bf16 v[116:119], v[146:149], v[178:181], v[116:119]
	v_mfma_f32_16x16x32_bf16 v[108:111], v[146:149], v[194:197], v[108:111]
	v_mfma_f32_16x16x32_bf16 v[100:103], v[146:149], v[210:213], v[100:103]
	v_mfma_f32_16x16x32_bf16 v[96:99], v[162:165], v[210:213], v[96:99]
	v_mfma_f32_16x16x32_bf16 v[104:107], v[162:165], v[194:197], v[104:107]
	v_mfma_f32_16x16x32_bf16 v[112:115], v[162:165], v[178:181], v[112:115]
	v_mfma_f32_16x16x32_bf16 v[120:123], v[162:165], v[170:173], v[120:123]
	v_mfma_f32_16x16x32_bf16 v[124:127], v[158:161], v[174:177], v[124:127]
	v_mfma_f32_16x16x32_bf16 v[116:119], v[158:161], v[182:185], v[116:119]
	v_mfma_f32_16x16x32_bf16 v[108:111], v[158:161], v[206:209], v[108:111]
	v_mfma_f32_16x16x32_bf16 v[100:103], v[158:161], v[214:217], v[100:103]
	v_mfma_f32_16x16x32_bf16 v[96:99], v[166:169], v[214:217], v[96:99]
	v_mfma_f32_16x16x32_bf16 v[104:107], v[166:169], v[206:209], v[104:107]
	v_mfma_f32_16x16x32_bf16 v[112:115], v[166:169], v[182:185], v[112:115]
	v_mfma_f32_16x16x32_bf16 v[120:123], v[166:169], v[174:177], v[120:123]
	v_mfma_f32_16x16x32_bf16 v[92:95], v[218:221], v[170:173], v[92:95]
	v_mfma_f32_16x16x32_bf16 v[84:87], v[218:221], v[178:181], v[84:87]
	v_mfma_f32_16x16x32_bf16 v[76:79], v[218:221], v[194:197], v[76:79]
	v_mfma_f32_16x16x32_bf16 v[68:71], v[218:221], v[210:213], v[68:71]
	v_mfma_f32_16x16x32_bf16 v[64:67], v[226:229], v[210:213], v[64:67]
	v_mfma_f32_16x16x32_bf16 v[72:75], v[226:229], v[194:197], v[72:75]
	v_mfma_f32_16x16x32_bf16 v[80:83], v[226:229], v[178:181], v[80:83]
	v_mfma_f32_16x16x32_bf16 v[88:91], v[226:229], v[170:173], v[88:91]
	v_mfma_f32_16x16x32_bf16 v[92:95], v[222:225], v[174:177], v[92:95]
	v_mfma_f32_16x16x32_bf16 v[84:87], v[222:225], v[182:185], v[84:87]
	v_mfma_f32_16x16x32_bf16 v[76:79], v[222:225], v[206:209], v[76:79]
	v_mfma_f32_16x16x32_bf16 v[68:71], v[222:225], v[214:217], v[68:71]
	v_mfma_f32_16x16x32_bf16 v[64:67], v[230:233], v[214:217], v[64:67]
	v_mfma_f32_16x16x32_bf16 v[72:75], v[230:233], v[206:209], v[72:75]
	v_mfma_f32_16x16x32_bf16 v[80:83], v[230:233], v[182:185], v[80:83]
	v_mfma_f32_16x16x32_bf16 v[88:91], v[230:233], v[174:177], v[88:91]
	s_barrier
	s_add_i32 s6, s6, s57
	v_lshl_add_u64 v[234:235], v[234:235], 0, s[36:37]
	s_mov_b32 m0, s6
	s_nop 0
	global_load_lds_dwordx4 v[234:235], off
	v_lshl_add_u64 v[234:235], v[236:237], 0, s[36:37]
	s_add_i32 m0, s6, 0x2000
	s_nop 0
	global_load_lds_dwordx4 v[234:235], off
	s_mov_b32 m0, s71
	v_lshl_add_u64 v[234:235], v[238:239], 0, s[36:37]
	ds_read_b128 v[170:173], v156 offset:49152
	ds_read_b128 v[174:177], v156 offset:50176
	ds_read_b128 v[178:181], v156 offset:51200
	ds_read_b128 v[182:185], v156 offset:52224
	ds_read_b128 v[194:197], v156 offset:53248
	ds_read_b128 v[206:209], v156 offset:54272
	ds_read_b128 v[210:213], v156 offset:55296
	ds_read_b128 v[214:217], v156 offset:56320
	global_load_lds_dwordx4 v[234:235], off
	v_lshl_add_u64 v[234:235], v[240:241], 0, s[36:37]
	s_mov_b32 m0, s72
	s_nop 0
	global_load_lds_dwordx4 v[234:235], off
	s_add_u32 s50, s50, 0x40080
	s_addc_u32 s51, s51, 0
	s_add_i32 s6, s19, s57
	v_lshl_add_u64 v[250:251], s[50:51], 0, v[140:141]
	s_mov_b32 m0, s6
	s_nop 0
	global_load_lds_dwordx4 v[250:251], off
	v_lshl_add_u64 v[250:251], s[50:51], 0, v[132:133]
	s_add_i32 m0, s6, 0x2000
	s_nop 0
	global_load_lds_dwordx4 v[250:251], off
	s_waitcnt vmcnt(8)
	s_waitcnt lgkmcnt(0)
	s_barrier
	v_mfma_f32_16x16x32_bf16 v[60:63], v[146:149], v[170:173], v[60:63]
	v_mfma_f32_16x16x32_bf16 v[52:55], v[146:149], v[178:181], v[52:55]
	v_mfma_f32_16x16x32_bf16 v[44:47], v[146:149], v[194:197], v[44:47]
	v_mfma_f32_16x16x32_bf16 v[36:39], v[146:149], v[210:213], v[36:39]
	v_mfma_f32_16x16x32_bf16 v[32:35], v[162:165], v[210:213], v[32:35]
	v_mfma_f32_16x16x32_bf16 v[40:43], v[162:165], v[194:197], v[40:43]
	v_mfma_f32_16x16x32_bf16 v[48:51], v[162:165], v[178:181], v[48:51]
	v_mfma_f32_16x16x32_bf16 v[56:59], v[162:165], v[170:173], v[56:59]
	v_mfma_f32_16x16x32_bf16 v[60:63], v[158:161], v[174:177], v[60:63]
	v_mfma_f32_16x16x32_bf16 v[52:55], v[158:161], v[182:185], v[52:55]
	v_mfma_f32_16x16x32_bf16 v[44:47], v[158:161], v[206:209], v[44:47]
	v_mfma_f32_16x16x32_bf16 v[36:39], v[158:161], v[214:217], v[36:39]
	v_mfma_f32_16x16x32_bf16 v[32:35], v[166:169], v[214:217], v[32:35]
	v_mfma_f32_16x16x32_bf16 v[40:43], v[166:169], v[206:209], v[40:43]
	v_mfma_f32_16x16x32_bf16 v[48:51], v[166:169], v[182:185], v[48:51]
	v_mfma_f32_16x16x32_bf16 v[56:59], v[166:169], v[174:177], v[56:59]
	v_mfma_f32_16x16x32_bf16 v[28:31], v[218:221], v[170:173], v[28:31]
	v_mfma_f32_16x16x32_bf16 v[20:23], v[218:221], v[178:181], v[20:23]
	v_mfma_f32_16x16x32_bf16 v[12:15], v[218:221], v[194:197], v[12:15]
	v_mfma_f32_16x16x32_bf16 v[4:7], v[218:221], v[210:213], v[4:7]
	v_mfma_f32_16x16x32_bf16 v[0:3], v[226:229], v[210:213], v[0:3]
	v_mfma_f32_16x16x32_bf16 v[8:11], v[226:229], v[194:197], v[8:11]
	v_mfma_f32_16x16x32_bf16 v[16:19], v[226:229], v[178:181], v[16:19]
	v_mfma_f32_16x16x32_bf16 v[24:27], v[226:229], v[170:173], v[24:27]
	v_mfma_f32_16x16x32_bf16 v[28:31], v[222:225], v[174:177], v[28:31]
	v_mfma_f32_16x16x32_bf16 v[20:23], v[222:225], v[182:185], v[20:23]
	v_mfma_f32_16x16x32_bf16 v[12:15], v[222:225], v[206:209], v[12:15]
	v_mfma_f32_16x16x32_bf16 v[4:7], v[222:225], v[214:217], v[4:7]
	v_mfma_f32_16x16x32_bf16 v[0:3], v[230:233], v[214:217], v[0:3]
	v_mfma_f32_16x16x32_bf16 v[8:11], v[230:233], v[206:209], v[8:11]
	v_mfma_f32_16x16x32_bf16 v[16:19], v[230:233], v[182:185], v[16:19]
	v_mfma_f32_16x16x32_bf16 v[24:27], v[230:233], v[174:177], v[24:27]
	s_add_i32 s75, s75, 2
	s_add_u32 s48, s48, 0x100
	s_addc_u32 s49, s49, 0
	s_cmp_gt_u32 s75, 13
	s_barrier
.LBB0_315:
	s_add_u32 s6, s4, s48
	s_addc_u32 s19, s5, s49
	s_add_u32 s6, s6, 0x100
	s_addc_u32 s19, s19, 0
	s_add_u32 s23, s11, s48
	s_addc_u32 s50, s12, s49
	s_add_i32 s80, 0, 0x10000
	v_add_u32_e32 v157, s80, v154
	ds_read_b128 v[146:149], v157
	ds_read_b128 v[158:161], v157 offset:1024
	ds_read_b128 v[162:165], v157 offset:2048
	ds_read_b128 v[166:169], v157 offset:3072
	s_cmpk_eq_i32 s48, 0x700
	s_cselect_b32 s53, s29, s19
	s_cselect_b32 s52, s31, s6
	s_cselect_b32 s51, s35, s50
	s_cselect_b32 s50, s74, s23
	v_lshl_add_u64 v[218:219], v[150:151], 0, s[48:49]
	s_add_i32 m0, s58, 0xc000
	ds_read_b128 v[170:173], v156
	ds_read_b128 v[174:177], v156 offset:1024
	ds_read_b128 v[178:181], v156 offset:2048
	ds_read_b128 v[182:185], v156 offset:3072
	ds_read_b128 v[194:197], v156 offset:4096
	ds_read_b128 v[206:209], v156 offset:5120
	ds_read_b128 v[210:213], v156 offset:6144
	ds_read_b128 v[214:217], v156 offset:7168
	global_load_lds_dwordx4 v[218:219], off
	v_lshl_add_u64 v[218:219], v[152:153], 0, s[48:49]
	s_add_i32 m0, s58, 0xe000
	s_nop 0
	global_load_lds_dwordx4 v[218:219], off
	s_add_i32 s6, 0, 0x14000
	v_add_u32_e32 v157, s6, v154
	ds_read_b128 v[218:221], v157
	ds_read_b128 v[222:225], v157 offset:1024
	ds_read_b128 v[226:229], v157 offset:2048
	ds_read_b128 v[230:233], v157 offset:3072
	s_waitcnt vmcnt(8)
	s_waitcnt lgkmcnt(0)
	s_barrier
	v_mfma_f32_16x16x32_bf16 v[124:127], v[146:149], v[170:173], v[124:127]
	v_mfma_f32_16x16x32_bf16 v[116:119], v[146:149], v[178:181], v[116:119]
	v_mfma_f32_16x16x32_bf16 v[108:111], v[146:149], v[194:197], v[108:111]
	v_mfma_f32_16x16x32_bf16 v[100:103], v[146:149], v[210:213], v[100:103]
	v_mfma_f32_16x16x32_bf16 v[96:99], v[162:165], v[210:213], v[96:99]
	v_mfma_f32_16x16x32_bf16 v[104:107], v[162:165], v[194:197], v[104:107]
	v_mfma_f32_16x16x32_bf16 v[112:115], v[162:165], v[178:181], v[112:115]
	v_mfma_f32_16x16x32_bf16 v[120:123], v[162:165], v[170:173], v[120:123]
	v_mfma_f32_16x16x32_bf16 v[124:127], v[158:161], v[174:177], v[124:127]
	v_mfma_f32_16x16x32_bf16 v[116:119], v[158:161], v[182:185], v[116:119]
	v_mfma_f32_16x16x32_bf16 v[108:111], v[158:161], v[206:209], v[108:111]
	v_mfma_f32_16x16x32_bf16 v[100:103], v[158:161], v[214:217], v[100:103]
	v_mfma_f32_16x16x32_bf16 v[96:99], v[166:169], v[214:217], v[96:99]
	v_mfma_f32_16x16x32_bf16 v[104:107], v[166:169], v[206:209], v[104:107]
	v_mfma_f32_16x16x32_bf16 v[112:115], v[166:169], v[182:185], v[112:115]
	v_mfma_f32_16x16x32_bf16 v[120:123], v[166:169], v[174:177], v[120:123]
	v_mfma_f32_16x16x32_bf16 v[92:95], v[218:221], v[170:173], v[92:95]
	v_mfma_f32_16x16x32_bf16 v[84:87], v[218:221], v[178:181], v[84:87]
	v_mfma_f32_16x16x32_bf16 v[76:79], v[218:221], v[194:197], v[76:79]
	v_mfma_f32_16x16x32_bf16 v[68:71], v[218:221], v[210:213], v[68:71]
	v_mfma_f32_16x16x32_bf16 v[64:67], v[226:229], v[210:213], v[64:67]
	v_mfma_f32_16x16x32_bf16 v[72:75], v[226:229], v[194:197], v[72:75]
	v_mfma_f32_16x16x32_bf16 v[80:83], v[226:229], v[178:181], v[80:83]
	v_mfma_f32_16x16x32_bf16 v[88:91], v[226:229], v[170:173], v[88:91]
	v_mfma_f32_16x16x32_bf16 v[92:95], v[222:225], v[174:177], v[92:95]
	v_mfma_f32_16x16x32_bf16 v[84:87], v[222:225], v[182:185], v[84:87]
	v_mfma_f32_16x16x32_bf16 v[76:79], v[222:225], v[206:209], v[76:79]
	v_mfma_f32_16x16x32_bf16 v[68:71], v[222:225], v[214:217], v[68:71]
	v_mfma_f32_16x16x32_bf16 v[64:67], v[230:233], v[214:217], v[64:67]
	v_mfma_f32_16x16x32_bf16 v[72:75], v[230:233], v[206:209], v[72:75]
	v_mfma_f32_16x16x32_bf16 v[80:83], v[230:233], v[182:185], v[80:83]
	v_mfma_f32_16x16x32_bf16 v[88:91], v[230:233], v[174:177], v[88:91]
	s_barrier
	s_add_i32 s19, s80, s57
	v_lshl_add_u64 v[234:235], s[50:51], 0, v[140:141]
	s_mov_b32 m0, s19
	s_nop 0
	global_load_lds_dwordx4 v[234:235], off
	v_lshl_add_u64 v[236:237], s[50:51], 0, v[132:133]
	s_add_i32 m0, s19, 0x2000
	s_nop 0
	global_load_lds_dwordx4 v[236:237], off
	s_mov_b32 m0, s58
	v_lshl_add_u64 v[238:239], s[52:53], 0, v[128:129]
	ds_read_b128 v[170:173], v156 offset:16384
	ds_read_b128 v[174:177], v156 offset:17408
	ds_read_b128 v[178:181], v156 offset:18432
	ds_read_b128 v[182:185], v156 offset:19456
	ds_read_b128 v[194:197], v156 offset:20480
	ds_read_b128 v[206:209], v156 offset:21504
	ds_read_b128 v[210:213], v156 offset:22528
	ds_read_b128 v[214:217], v156 offset:23552
	global_load_lds_dwordx4 v[238:239], off
	v_lshl_add_u64 v[240:241], s[52:53], 0, v[130:131]
	s_mov_b32 m0, s59
	s_nop 0
	global_load_lds_dwordx4 v[240:241], off
	s_add_u32 s80, s50, 0x40000
	s_addc_u32 s81, s51, 0
	s_add_i32 s6, s6, s57
	v_lshl_add_u64 v[250:251], s[80:81], 0, v[140:141]
	s_mov_b32 m0, s6
	s_nop 0
	global_load_lds_dwordx4 v[250:251], off
	v_lshl_add_u64 v[250:251], s[80:81], 0, v[132:133]
	s_add_i32 m0, s6, 0x2000
	s_nop 0
	global_load_lds_dwordx4 v[250:251], off
	s_waitcnt vmcnt(8)
	s_waitcnt lgkmcnt(0)
	s_barrier
	v_mfma_f32_16x16x32_bf16 v[60:63], v[146:149], v[170:173], v[60:63]
	v_mfma_f32_16x16x32_bf16 v[52:55], v[146:149], v[178:181], v[52:55]
	v_mfma_f32_16x16x32_bf16 v[44:47], v[146:149], v[194:197], v[44:47]
	v_mfma_f32_16x16x32_bf16 v[36:39], v[146:149], v[210:213], v[36:39]
	v_mfma_f32_16x16x32_bf16 v[32:35], v[162:165], v[210:213], v[32:35]
	v_mfma_f32_16x16x32_bf16 v[40:43], v[162:165], v[194:197], v[40:43]
	v_mfma_f32_16x16x32_bf16 v[48:51], v[162:165], v[178:181], v[48:51]
	v_mfma_f32_16x16x32_bf16 v[56:59], v[162:165], v[170:173], v[56:59]
	v_mfma_f32_16x16x32_bf16 v[60:63], v[158:161], v[174:177], v[60:63]
	v_mfma_f32_16x16x32_bf16 v[52:55], v[158:161], v[182:185], v[52:55]
	v_mfma_f32_16x16x32_bf16 v[44:47], v[158:161], v[206:209], v[44:47]
	v_mfma_f32_16x16x32_bf16 v[36:39], v[158:161], v[214:217], v[36:39]
	v_mfma_f32_16x16x32_bf16 v[32:35], v[166:169], v[214:217], v[32:35]
	v_mfma_f32_16x16x32_bf16 v[40:43], v[166:169], v[206:209], v[40:43]
	v_mfma_f32_16x16x32_bf16 v[48:51], v[166:169], v[182:185], v[48:51]
	v_mfma_f32_16x16x32_bf16 v[56:59], v[166:169], v[174:177], v[56:59]
	v_mfma_f32_16x16x32_bf16 v[28:31], v[218:221], v[170:173], v[28:31]
	v_mfma_f32_16x16x32_bf16 v[20:23], v[218:221], v[178:181], v[20:23]
	v_mfma_f32_16x16x32_bf16 v[12:15], v[218:221], v[194:197], v[12:15]
	v_mfma_f32_16x16x32_bf16 v[4:7], v[218:221], v[210:213], v[4:7]
	v_mfma_f32_16x16x32_bf16 v[0:3], v[226:229], v[210:213], v[0:3]
	v_mfma_f32_16x16x32_bf16 v[8:11], v[226:229], v[194:197], v[8:11]
	v_mfma_f32_16x16x32_bf16 v[16:19], v[226:229], v[178:181], v[16:19]
	v_mfma_f32_16x16x32_bf16 v[24:27], v[226:229], v[170:173], v[24:27]
	v_mfma_f32_16x16x32_bf16 v[28:31], v[222:225], v[174:177], v[28:31]
	v_mfma_f32_16x16x32_bf16 v[20:23], v[222:225], v[182:185], v[20:23]
	v_mfma_f32_16x16x32_bf16 v[12:15], v[222:225], v[206:209], v[12:15]
	v_mfma_f32_16x16x32_bf16 v[4:7], v[222:225], v[214:217], v[4:7]
	v_mfma_f32_16x16x32_bf16 v[0:3], v[230:233], v[214:217], v[0:3]
	v_mfma_f32_16x16x32_bf16 v[8:11], v[230:233], v[206:209], v[8:11]
	v_mfma_f32_16x16x32_bf16 v[16:19], v[230:233], v[182:185], v[16:19]
	v_mfma_f32_16x16x32_bf16 v[24:27], v[230:233], v[174:177], v[24:27]
	s_barrier
	s_add_i32 s6, 0, 0x18000
	v_add_u32_e32 v157, s6, v154
	ds_read_b128 v[146:149], v157
	ds_read_b128 v[158:161], v157 offset:1024
	ds_read_b128 v[162:165], v157 offset:2048
	ds_read_b128 v[166:169], v157 offset:3072
	s_add_u32 s52, s52, 0x40000
	s_addc_u32 s53, s53, 0
	s_mov_b32 m0, s68
	v_lshl_add_u64 v[218:219], s[52:53], 0, v[128:129]
	ds_read_b128 v[170:173], v156 offset:32768
	ds_read_b128 v[174:177], v156 offset:33792
	ds_read_b128 v[178:181], v156 offset:34816
	ds_read_b128 v[182:185], v156 offset:35840
	ds_read_b128 v[194:197], v156 offset:36864
	ds_read_b128 v[206:209], v156 offset:37888
	ds_read_b128 v[210:213], v156 offset:38912
	ds_read_b128 v[214:217], v156 offset:39936
	global_load_lds_dwordx4 v[218:219], off
	v_lshl_add_u64 v[218:219], s[52:53], 0, v[130:131]
	s_mov_b32 m0, s69
	s_nop 0
	global_load_lds_dwordx4 v[218:219], off
	s_add_i32 s19, 0, 0x1c000
	v_add_u32_e32 v157, s19, v154
	ds_read_b128 v[218:221], v157
	ds_read_b128 v[222:225], v157 offset:1024
	ds_read_b128 v[226:229], v157 offset:2048
	ds_read_b128 v[230:233], v157 offset:3072
	s_waitcnt vmcnt(8)
	s_waitcnt lgkmcnt(0)
	s_barrier
	v_mfma_f32_16x16x32_bf16 v[124:127], v[146:149], v[170:173], v[124:127]
	v_mfma_f32_16x16x32_bf16 v[116:119], v[146:149], v[178:181], v[116:119]
	v_mfma_f32_16x16x32_bf16 v[108:111], v[146:149], v[194:197], v[108:111]
	v_mfma_f32_16x16x32_bf16 v[100:103], v[146:149], v[210:213], v[100:103]
	v_mfma_f32_16x16x32_bf16 v[96:99], v[162:165], v[210:213], v[96:99]
	v_mfma_f32_16x16x32_bf16 v[104:107], v[162:165], v[194:197], v[104:107]
	v_mfma_f32_16x16x32_bf16 v[112:115], v[162:165], v[178:181], v[112:115]
	v_mfma_f32_16x16x32_bf16 v[120:123], v[162:165], v[170:173], v[120:123]
	v_mfma_f32_16x16x32_bf16 v[124:127], v[158:161], v[174:177], v[124:127]
	v_mfma_f32_16x16x32_bf16 v[116:119], v[158:161], v[182:185], v[116:119]
	v_mfma_f32_16x16x32_bf16 v[108:111], v[158:161], v[206:209], v[108:111]
	v_mfma_f32_16x16x32_bf16 v[100:103], v[158:161], v[214:217], v[100:103]
	v_mfma_f32_16x16x32_bf16 v[96:99], v[166:169], v[214:217], v[96:99]
	v_mfma_f32_16x16x32_bf16 v[104:107], v[166:169], v[206:209], v[104:107]
	v_mfma_f32_16x16x32_bf16 v[112:115], v[166:169], v[182:185], v[112:115]
	v_mfma_f32_16x16x32_bf16 v[120:123], v[166:169], v[174:177], v[120:123]
	v_mfma_f32_16x16x32_bf16 v[92:95], v[218:221], v[170:173], v[92:95]
	v_mfma_f32_16x16x32_bf16 v[84:87], v[218:221], v[178:181], v[84:87]
	v_mfma_f32_16x16x32_bf16 v[76:79], v[218:221], v[194:197], v[76:79]
	v_mfma_f32_16x16x32_bf16 v[68:71], v[218:221], v[210:213], v[68:71]
	v_mfma_f32_16x16x32_bf16 v[64:67], v[226:229], v[210:213], v[64:67]
	v_mfma_f32_16x16x32_bf16 v[72:75], v[226:229], v[194:197], v[72:75]
	v_mfma_f32_16x16x32_bf16 v[80:83], v[226:229], v[178:181], v[80:83]
	v_mfma_f32_16x16x32_bf16 v[88:91], v[226:229], v[170:173], v[88:91]
	v_mfma_f32_16x16x32_bf16 v[92:95], v[222:225], v[174:177], v[92:95]
	v_mfma_f32_16x16x32_bf16 v[84:87], v[222:225], v[182:185], v[84:87]
	v_mfma_f32_16x16x32_bf16 v[76:79], v[222:225], v[206:209], v[76:79]
	v_mfma_f32_16x16x32_bf16 v[68:71], v[222:225], v[214:217], v[68:71]
	v_mfma_f32_16x16x32_bf16 v[64:67], v[230:233], v[214:217], v[64:67]
	v_mfma_f32_16x16x32_bf16 v[72:75], v[230:233], v[206:209], v[72:75]
	v_mfma_f32_16x16x32_bf16 v[80:83], v[230:233], v[182:185], v[80:83]
	v_mfma_f32_16x16x32_bf16 v[88:91], v[230:233], v[174:177], v[88:91]
	s_barrier
	s_add_i32 s6, s6, s57
	v_lshl_add_u64 v[234:235], v[234:235], 0, s[36:37]
	s_mov_b32 m0, s6
	s_nop 0
	global_load_lds_dwordx4 v[234:235], off
	v_lshl_add_u64 v[234:235], v[236:237], 0, s[36:37]
	s_add_i32 m0, s6, 0x2000
	s_nop 0
	global_load_lds_dwordx4 v[234:235], off
	s_mov_b32 m0, s71
	v_lshl_add_u64 v[234:235], v[238:239], 0, s[36:37]
	ds_read_b128 v[170:173], v156 offset:49152
	ds_read_b128 v[174:177], v156 offset:50176
	ds_read_b128 v[178:181], v156 offset:51200
	ds_read_b128 v[182:185], v156 offset:52224
	ds_read_b128 v[194:197], v156 offset:53248
	ds_read_b128 v[206:209], v156 offset:54272
	ds_read_b128 v[210:213], v156 offset:55296
	ds_read_b128 v[214:217], v156 offset:56320
	global_load_lds_dwordx4 v[234:235], off
	v_lshl_add_u64 v[234:235], v[240:241], 0, s[36:37]
	s_mov_b32 m0, s72
	s_nop 0
	global_load_lds_dwordx4 v[234:235], off
	s_add_u32 s50, s50, 0x40080
	s_addc_u32 s51, s51, 0
	s_add_i32 s6, s19, s57
	v_lshl_add_u64 v[250:251], s[50:51], 0, v[140:141]
	s_mov_b32 m0, s6
	s_nop 0
	global_load_lds_dwordx4 v[250:251], off
	v_lshl_add_u64 v[250:251], s[50:51], 0, v[132:133]
	s_add_i32 m0, s6, 0x2000
	s_nop 0
	global_load_lds_dwordx4 v[250:251], off
	s_waitcnt vmcnt(8)
	s_waitcnt lgkmcnt(0)
	s_barrier
	v_mfma_f32_16x16x32_bf16 v[60:63], v[146:149], v[170:173], v[60:63]
	v_mfma_f32_16x16x32_bf16 v[52:55], v[146:149], v[178:181], v[52:55]
	v_mfma_f32_16x16x32_bf16 v[44:47], v[146:149], v[194:197], v[44:47]
	v_mfma_f32_16x16x32_bf16 v[36:39], v[146:149], v[210:213], v[36:39]
	v_mfma_f32_16x16x32_bf16 v[32:35], v[162:165], v[210:213], v[32:35]
	v_mfma_f32_16x16x32_bf16 v[40:43], v[162:165], v[194:197], v[40:43]
	v_mfma_f32_16x16x32_bf16 v[48:51], v[162:165], v[178:181], v[48:51]
	v_mfma_f32_16x16x32_bf16 v[56:59], v[162:165], v[170:173], v[56:59]
	v_mfma_f32_16x16x32_bf16 v[60:63], v[158:161], v[174:177], v[60:63]
	v_mfma_f32_16x16x32_bf16 v[52:55], v[158:161], v[182:185], v[52:55]
	v_mfma_f32_16x16x32_bf16 v[44:47], v[158:161], v[206:209], v[44:47]
	v_mfma_f32_16x16x32_bf16 v[36:39], v[158:161], v[214:217], v[36:39]
	v_mfma_f32_16x16x32_bf16 v[32:35], v[166:169], v[214:217], v[32:35]
	v_mfma_f32_16x16x32_bf16 v[40:43], v[166:169], v[206:209], v[40:43]
	v_mfma_f32_16x16x32_bf16 v[48:51], v[166:169], v[182:185], v[48:51]
	v_mfma_f32_16x16x32_bf16 v[56:59], v[166:169], v[174:177], v[56:59]
	v_mfma_f32_16x16x32_bf16 v[28:31], v[218:221], v[170:173], v[28:31]
	v_mfma_f32_16x16x32_bf16 v[20:23], v[218:221], v[178:181], v[20:23]
	v_mfma_f32_16x16x32_bf16 v[12:15], v[218:221], v[194:197], v[12:15]
	v_mfma_f32_16x16x32_bf16 v[4:7], v[218:221], v[210:213], v[4:7]
	v_mfma_f32_16x16x32_bf16 v[0:3], v[226:229], v[210:213], v[0:3]
	v_mfma_f32_16x16x32_bf16 v[8:11], v[226:229], v[194:197], v[8:11]
	v_mfma_f32_16x16x32_bf16 v[16:19], v[226:229], v[178:181], v[16:19]
	v_mfma_f32_16x16x32_bf16 v[24:27], v[226:229], v[170:173], v[24:27]
	v_mfma_f32_16x16x32_bf16 v[28:31], v[222:225], v[174:177], v[28:31]
	v_mfma_f32_16x16x32_bf16 v[20:23], v[222:225], v[182:185], v[20:23]
	v_mfma_f32_16x16x32_bf16 v[12:15], v[222:225], v[206:209], v[12:15]
	v_mfma_f32_16x16x32_bf16 v[4:7], v[222:225], v[214:217], v[4:7]
	v_mfma_f32_16x16x32_bf16 v[0:3], v[230:233], v[214:217], v[0:3]
	v_mfma_f32_16x16x32_bf16 v[8:11], v[230:233], v[206:209], v[8:11]
	v_mfma_f32_16x16x32_bf16 v[16:19], v[230:233], v[182:185], v[16:19]
	v_mfma_f32_16x16x32_bf16 v[24:27], v[230:233], v[174:177], v[24:27]
	s_add_i32 s75, s75, 2
	s_add_u32 s48, s48, 0x100
	s_addc_u32 s49, s49, 0
	s_cmp_gt_u32 s75, 13
	s_barrier
	s_cbranch_scc0 .LBB0_315
	s_mov_b32 s100, 1
	s_add_u32 s48, s11, 0xffffff00
	v_lshl_or_b32 v146, s70, 8, v155
	s_addc_u32 s49, s12, -1
	s_ashr_i32 s29, s28, 31
	v_ashrrev_i32_e32 v147, 31, v146
	v_lshl_add_u64 v[146:147], v[146:147], 1, s[26:27]
	s_lshl_b64 s[50:51], s[28:29], 20
	v_lshl_add_u64 v[146:147], v[146:147], 0, s[50:51]
	v_lshl_add_u64 v[150:151], v[146:147], 0, v[134:135]
	v_cvt_pk_bf16_f32 v146, v124, v125
	v_cvt_pk_bf16_f32 v147, v126, v127
	v_cvt_pk_bf16_f32 v148, v120, v121
	v_cvt_pk_bf16_f32 v149, v122, v123
	global_store_dwordx4 v[150:151], v[146:149], off
	v_add_co_u32_e32 v152, vcc, s66, v150
	s_nop 0
	v_cvt_pk_bf16_f32 v146, v92, v93
	v_cvt_pk_bf16_f32 v147, v94, v95
	v_cvt_pk_bf16_f32 v148, v88, v89
	v_cvt_pk_bf16_f32 v149, v90, v91
	global_store_dwordx4 v[150:151], v[146:149], off offset:256
	v_addc_co_u32_e32 v153, vcc, 0, v151, vcc
	s_nop 0
	v_cvt_pk_bf16_f32 v146, v116, v117
	v_cvt_pk_bf16_f32 v147, v118, v119
	v_cvt_pk_bf16_f32 v148, v112, v113
	v_cvt_pk_bf16_f32 v149, v114, v115
	global_store_dwordx4 v[152:153], v[146:149], off
	s_mov_b32 s6, 0x20000
	s_nop 0
	v_cvt_pk_bf16_f32 v146, v84, v85
	v_cvt_pk_bf16_f32 v147, v86, v87
	v_cvt_pk_bf16_f32 v148, v80, v81
	v_cvt_pk_bf16_f32 v149, v82, v83
	global_store_dwordx4 v[152:153], v[146:149], off offset:256
	v_add_co_u32_e32 v152, vcc, s6, v150
	s_nop 0
	v_cvt_pk_bf16_f32 v146, v108, v109
	v_cvt_pk_bf16_f32 v147, v110, v111
	v_cvt_pk_bf16_f32 v148, v104, v105
	v_cvt_pk_bf16_f32 v149, v106, v107
	v_addc_co_u32_e32 v153, vcc, 0, v151, vcc
	global_store_dwordx4 v[152:153], v[146:149], off
	s_mov_b32 s6, 0x30000
	s_nop 0
	v_cvt_pk_bf16_f32 v146, v76, v77
	v_cvt_pk_bf16_f32 v147, v78, v79
	v_cvt_pk_bf16_f32 v148, v72, v73
	v_cvt_pk_bf16_f32 v149, v74, v75
	global_store_dwordx4 v[152:153], v[146:149], off offset:256
	v_add_co_u32_e32 v152, vcc, s6, v150
	s_nop 0
	v_cvt_pk_bf16_f32 v146, v100, v101
	v_cvt_pk_bf16_f32 v147, v102, v103
	v_cvt_pk_bf16_f32 v148, v96, v97
	v_cvt_pk_bf16_f32 v149, v98, v99
	v_addc_co_u32_e32 v153, vcc, 0, v151, vcc
	global_store_dwordx4 v[152:153], v[146:149], off
	s_mov_b32 s6, 0x80000
	s_nop 0
	v_cvt_pk_bf16_f32 v146, v68, v69
	v_cvt_pk_bf16_f32 v147, v70, v71
	v_cvt_pk_bf16_f32 v148, v64, v65
	v_cvt_pk_bf16_f32 v149, v66, v67
	global_store_dwordx4 v[152:153], v[146:149], off offset:256
	v_add_co_u32_e32 v152, vcc, s6, v150
	s_nop 0
	v_cvt_pk_bf16_f32 v146, v60, v61
	v_cvt_pk_bf16_f32 v147, v62, v63
	v_cvt_pk_bf16_f32 v148, v56, v57
	v_cvt_pk_bf16_f32 v149, v58, v59
	v_addc_co_u32_e32 v153, vcc, 0, v151, vcc
	global_store_dwordx4 v[152:153], v[146:149], off
	s_mov_b32 s6, 0x90000
	s_nop 0
	v_cvt_pk_bf16_f32 v146, v28, v29
	v_cvt_pk_bf16_f32 v147, v30, v31
	v_cvt_pk_bf16_f32 v148, v24, v25
	v_cvt_pk_bf16_f32 v149, v26, v27
	global_store_dwordx4 v[152:153], v[146:149], off offset:256
	v_add_co_u32_e32 v152, vcc, s6, v150
	s_nop 0
	v_cvt_pk_bf16_f32 v146, v52, v53
	v_cvt_pk_bf16_f32 v147, v54, v55
	v_cvt_pk_bf16_f32 v148, v48, v49
	v_cvt_pk_bf16_f32 v149, v50, v51
	v_addc_co_u32_e32 v153, vcc, 0, v151, vcc
	global_store_dwordx4 v[152:153], v[146:149], off
	s_mov_b32 s6, 0xa0000
	s_nop 0
	v_cvt_pk_bf16_f32 v146, v20, v21
	v_cvt_pk_bf16_f32 v147, v22, v23
	v_cvt_pk_bf16_f32 v148, v16, v17
	v_cvt_pk_bf16_f32 v149, v18, v19
	global_store_dwordx4 v[152:153], v[146:149], off offset:256
	v_add_co_u32_e32 v152, vcc, s6, v150
	s_nop 0
	v_cvt_pk_bf16_f32 v146, v44, v45
	v_cvt_pk_bf16_f32 v147, v46, v47
	v_cvt_pk_bf16_f32 v148, v40, v41
	v_cvt_pk_bf16_f32 v149, v42, v43
	v_addc_co_u32_e32 v153, vcc, 0, v151, vcc
	s_mov_b32 s6, 0xb0000
	global_store_dwordx4 v[152:153], v[146:149], off
	v_add_co_u32_e32 v150, vcc, s6, v150
	s_nop 0
	v_cvt_pk_bf16_f32 v146, v12, v13
	v_cvt_pk_bf16_f32 v147, v14, v15
	v_cvt_pk_bf16_f32 v148, v8, v9
	v_cvt_pk_bf16_f32 v149, v10, v11
	global_store_dwordx4 v[152:153], v[146:149], off offset:256
	v_addc_co_u32_e32 v151, vcc, 0, v151, vcc
	s_nop 0
	v_cvt_pk_bf16_f32 v146, v36, v37
	v_cvt_pk_bf16_f32 v147, v38, v39
	v_cvt_pk_bf16_f32 v148, v32, v33
	v_cvt_pk_bf16_f32 v149, v34, v35
	global_store_dwordx4 v[150:151], v[146:149], off
	s_andn2_b64 vcc, exec, s[44:45]
	s_nop 0
	v_cvt_pk_bf16_f32 v146, v4, v5
	v_cvt_pk_bf16_f32 v147, v6, v7
	v_cvt_pk_bf16_f32 v148, v0, v1
	v_cvt_pk_bf16_f32 v149, v2, v3
	global_store_dwordx4 v[150:151], v[146:149], off offset:256
	s_cbranch_vccz .LBB0_307
	s_mov_b64 s[42:43], s[48:49]
	s_andn2_b64 vcc, exec, s[38:39]
	s_mov_b64 s[48:49], s[42:43]
	s_cbranch_vccnz .LBB0_308

.Lm4ap_341:
	s_waitcnt lgkmcnt(0)
	s_barrier
	v_mfma_f32_16x16x32_bf16 v[124:127], v[128:131], v[162:165], 0
	v_mfma_f32_16x16x32_bf16 v[108:111], v[128:131], v[170:173], 0
	v_mfma_f32_16x16x32_bf16 v[96:99], v[128:131], v[178:181], 0
	v_mfma_f32_16x16x32_bf16 v[84:87], v[128:131], v[194:197], 0
	v_mfma_f32_16x16x32_bf16 v[80:83], v[136:139], v[194:197], 0
	v_mfma_f32_16x16x32_bf16 v[88:91], v[136:139], v[178:181], 0
	v_mfma_f32_16x16x32_bf16 v[104:107], v[136:139], v[170:173], 0
	v_mfma_f32_16x16x32_bf16 v[120:123], v[136:139], v[162:165], 0
	v_mfma_f32_16x16x32_bf16 v[124:127], v[132:135], v[166:169], v[124:127]
	v_mfma_f32_16x16x32_bf16 v[108:111], v[132:135], v[174:177], v[108:111]
	v_mfma_f32_16x16x32_bf16 v[96:99], v[132:135], v[182:185], v[96:99]
	v_mfma_f32_16x16x32_bf16 v[84:87], v[132:135], v[210:213], v[84:87]
	v_mfma_f32_16x16x32_bf16 v[80:83], v[146:149], v[210:213], v[80:83]
	v_mfma_f32_16x16x32_bf16 v[88:91], v[146:149], v[182:185], v[88:91]
	v_mfma_f32_16x16x32_bf16 v[104:107], v[146:149], v[174:177], v[104:107]
	v_mfma_f32_16x16x32_bf16 v[120:123], v[146:149], v[166:169], v[120:123]
	v_mfma_f32_16x16x32_bf16 v[116:119], v[214:217], v[162:165], 0
	v_mfma_f32_16x16x32_bf16 v[100:103], v[214:217], v[170:173], 0
	v_mfma_f32_16x16x32_bf16 v[76:79], v[214:217], v[178:181], 0
	v_mfma_f32_16x16x32_bf16 v[68:71], v[214:217], v[194:197], 0
	v_mfma_f32_16x16x32_bf16 v[64:67], v[222:225], v[194:197], 0
	v_mfma_f32_16x16x32_bf16 v[72:75], v[222:225], v[178:181], 0
	v_mfma_f32_16x16x32_bf16 v[92:95], v[222:225], v[170:173], 0
	v_mfma_f32_16x16x32_bf16 v[112:115], v[222:225], v[162:165], 0
	v_mfma_f32_16x16x32_bf16 v[116:119], v[218:221], v[166:169], v[116:119]
	v_mfma_f32_16x16x32_bf16 v[100:103], v[218:221], v[174:177], v[100:103]
	v_mfma_f32_16x16x32_bf16 v[76:79], v[218:221], v[182:185], v[76:79]
	v_mfma_f32_16x16x32_bf16 v[68:71], v[218:221], v[210:213], v[68:71]
	v_mfma_f32_16x16x32_bf16 v[64:67], v[226:229], v[210:213], v[64:67]
	v_mfma_f32_16x16x32_bf16 v[72:75], v[226:229], v[182:185], v[72:75]
	v_mfma_f32_16x16x32_bf16 v[92:95], v[226:229], v[174:177], v[92:95]
	v_mfma_f32_16x16x32_bf16 v[112:115], v[226:229], v[166:169], v[112:115]
	s_barrier
	s_add_i32 s6, s6, s57
	v_lshl_add_u64 v[230:231], s[48:49], 0, v[140:141]
	s_mov_b32 m0, s6
	s_nop 0
	global_load_lds_dwordx4 v[230:231], off
	v_lshl_add_u64 v[232:233], s[48:49], 0, v[150:151]
	s_add_i32 m0, s6, 0x2000
	s_nop 0
	global_load_lds_dwordx4 v[232:233], off
	s_mov_b32 m0, s58
	v_lshl_add_u64 v[234:235], s[52:53], 0, v[154:155]
	ds_read_b128 v[162:165], v208 offset:16384
	ds_read_b128 v[166:169], v208 offset:17408
	ds_read_b128 v[170:173], v208 offset:18432
	ds_read_b128 v[174:177], v208 offset:19456
	ds_read_b128 v[178:181], v208 offset:20480
	ds_read_b128 v[182:185], v208 offset:21504
	ds_read_b128 v[194:197], v208 offset:22528
	ds_read_b128 v[210:213], v208 offset:23552
	global_load_lds_dwordx4 v[234:235], off
	v_lshl_add_u64 v[236:237], s[52:53], 0, v[152:153]
	s_mov_b32 m0, s59
	s_nop 0
	global_load_lds_dwordx4 v[236:237], off
	s_add_u32 s50, s48, 0xb0000
	s_addc_u32 s51, s49, 0
	s_add_i32 s6, s19, s57
	v_lshl_add_u64 v[250:251], s[50:51], 0, v[140:141]
	s_mov_b32 m0, s6
	s_nop 0
	global_load_lds_dwordx4 v[250:251], off
	v_lshl_add_u64 v[250:251], s[50:51], 0, v[150:151]
	s_add_i32 m0, s6, 0x2000
	s_nop 0
	global_load_lds_dwordx4 v[250:251], off
	s_waitcnt vmcnt(40)
	s_cmp_lg_u32 s100, 0
	s_cbranch_scc1 .Lm4bp_341
	s_waitcnt vmcnt(8)

.LBB0_341:
	s_add_u32 s46, s50, 0x100
	s_addc_u32 s47, s51, 0
	s_add_i32 s6, 0, 0x10000
	v_add_u32_e32 v146, s6, v206
	ds_read_b128 v[128:131], v146
	ds_read_b128 v[132:135], v146 offset:1024
	ds_read_b128 v[136:139], v146 offset:2048
	ds_read_b128 v[146:149], v146 offset:3072
	s_cmp_eq_u32 s12, 40
	s_cselect_b32 s53, s31, s47
	s_cselect_b32 s52, s30, s46
	s_cselect_b32 s49, s35, s11
	s_cselect_b32 s48, s34, s10
	v_lshl_add_u64 v[214:215], s[50:51], 0, v[158:159]
	s_add_i32 m0, s58, 0xc000
	ds_read_b128 v[162:165], v208
	ds_read_b128 v[166:169], v208 offset:1024
	ds_read_b128 v[170:173], v208 offset:2048
	ds_read_b128 v[174:177], v208 offset:3072
	ds_read_b128 v[178:181], v208 offset:4096
	ds_read_b128 v[182:185], v208 offset:5120
	ds_read_b128 v[194:197], v208 offset:6144
	ds_read_b128 v[210:213], v208 offset:7168
	global_load_lds_dwordx4 v[214:215], off
	v_lshl_add_u64 v[214:215], s[50:51], 0, v[160:161]
	s_add_i32 m0, s58, 0xe000
	s_nop 0
	global_load_lds_dwordx4 v[214:215], off
	s_add_i32 s19, 0, 0x14000
	v_add_u32_e32 v192, s19, v206
	ds_read_b128 v[214:217], v192
	ds_read_b128 v[218:221], v192 offset:1024
	ds_read_b128 v[222:225], v192 offset:2048
	ds_read_b128 v[226:229], v192 offset:3072
	s_nop 0
	s_waitcnt vmcnt(8)
	s_waitcnt lgkmcnt(0)
	s_barrier
	v_mfma_f32_16x16x32_bf16 v[124:127], v[128:131], v[162:165], v[124:127]
	v_mfma_f32_16x16x32_bf16 v[108:111], v[128:131], v[170:173], v[108:111]
	v_mfma_f32_16x16x32_bf16 v[96:99], v[128:131], v[178:181], v[96:99]
	v_mfma_f32_16x16x32_bf16 v[84:87], v[128:131], v[194:197], v[84:87]
	v_mfma_f32_16x16x32_bf16 v[80:83], v[136:139], v[194:197], v[80:83]
	v_mfma_f32_16x16x32_bf16 v[88:91], v[136:139], v[178:181], v[88:91]
	v_mfma_f32_16x16x32_bf16 v[104:107], v[136:139], v[170:173], v[104:107]
	v_mfma_f32_16x16x32_bf16 v[120:123], v[136:139], v[162:165], v[120:123]
	v_mfma_f32_16x16x32_bf16 v[124:127], v[132:135], v[166:169], v[124:127]
	v_mfma_f32_16x16x32_bf16 v[108:111], v[132:135], v[174:177], v[108:111]
	v_mfma_f32_16x16x32_bf16 v[96:99], v[132:135], v[182:185], v[96:99]
	v_mfma_f32_16x16x32_bf16 v[84:87], v[132:135], v[210:213], v[84:87]
	v_mfma_f32_16x16x32_bf16 v[80:83], v[146:149], v[210:213], v[80:83]
	v_mfma_f32_16x16x32_bf16 v[88:91], v[146:149], v[182:185], v[88:91]
	v_mfma_f32_16x16x32_bf16 v[104:107], v[146:149], v[174:177], v[104:107]
	v_mfma_f32_16x16x32_bf16 v[120:123], v[146:149], v[166:169], v[120:123]
	v_mfma_f32_16x16x32_bf16 v[116:119], v[214:217], v[162:165], v[116:119]
	v_mfma_f32_16x16x32_bf16 v[100:103], v[214:217], v[170:173], v[100:103]
	v_mfma_f32_16x16x32_bf16 v[76:79], v[214:217], v[178:181], v[76:79]
	v_mfma_f32_16x16x32_bf16 v[68:71], v[214:217], v[194:197], v[68:71]
	v_mfma_f32_16x16x32_bf16 v[64:67], v[222:225], v[194:197], v[64:67]
	v_mfma_f32_16x16x32_bf16 v[72:75], v[222:225], v[178:181], v[72:75]
	v_mfma_f32_16x16x32_bf16 v[92:95], v[222:225], v[170:173], v[92:95]
	v_mfma_f32_16x16x32_bf16 v[112:115], v[222:225], v[162:165], v[112:115]
	v_mfma_f32_16x16x32_bf16 v[116:119], v[218:221], v[166:169], v[116:119]
	v_mfma_f32_16x16x32_bf16 v[100:103], v[218:221], v[174:177], v[100:103]
	v_mfma_f32_16x16x32_bf16 v[76:79], v[218:221], v[182:185], v[76:79]
	v_mfma_f32_16x16x32_bf16 v[68:71], v[218:221], v[210:213], v[68:71]
	v_mfma_f32_16x16x32_bf16 v[64:67], v[226:229], v[210:213], v[64:67]
	v_mfma_f32_16x16x32_bf16 v[72:75], v[226:229], v[182:185], v[72:75]
	v_mfma_f32_16x16x32_bf16 v[92:95], v[226:229], v[174:177], v[92:95]
	v_mfma_f32_16x16x32_bf16 v[112:115], v[226:229], v[166:169], v[112:115]
	s_barrier
	s_add_i32 s6, s6, s57
	v_lshl_add_u64 v[230:231], s[48:49], 0, v[140:141]
	s_mov_b32 m0, s6
	s_nop 0
	global_load_lds_dwordx4 v[230:231], off
	v_lshl_add_u64 v[232:233], s[48:49], 0, v[150:151]
	s_add_i32 m0, s6, 0x2000
	s_nop 0
	global_load_lds_dwordx4 v[232:233], off
	s_mov_b32 m0, s58
	v_lshl_add_u64 v[234:235], s[52:53], 0, v[154:155]
	ds_read_b128 v[162:165], v208 offset:16384
	ds_read_b128 v[166:169], v208 offset:17408
	ds_read_b128 v[170:173], v208 offset:18432
	ds_read_b128 v[174:177], v208 offset:19456
	ds_read_b128 v[178:181], v208 offset:20480
	ds_read_b128 v[182:185], v208 offset:21504
	ds_read_b128 v[194:197], v208 offset:22528
	ds_read_b128 v[210:213], v208 offset:23552
	global_load_lds_dwordx4 v[234:235], off
	v_lshl_add_u64 v[236:237], s[52:53], 0, v[152:153]
	s_mov_b32 m0, s59
	s_nop 0
	global_load_lds_dwordx4 v[236:237], off
	s_add_u32 s50, s48, 0xb0000
	s_addc_u32 s51, s49, 0
	s_add_i32 s6, s19, s57
	v_lshl_add_u64 v[250:251], s[50:51], 0, v[140:141]
	s_mov_b32 m0, s6
	s_nop 0
	global_load_lds_dwordx4 v[250:251], off
	v_lshl_add_u64 v[250:251], s[50:51], 0, v[150:151]
	s_add_i32 m0, s6, 0x2000
	s_nop 0
	global_load_lds_dwordx4 v[250:251], off
	s_waitcnt vmcnt(8)
	s_waitcnt lgkmcnt(0)
	s_barrier
	v_mfma_f32_16x16x32_bf16 v[60:63], v[128:131], v[162:165], v[60:63]
	v_mfma_f32_16x16x32_bf16 v[48:51], v[128:131], v[170:173], v[48:51]
	v_mfma_f32_16x16x32_bf16 v[32:35], v[128:131], v[178:181], v[32:35]
	v_mfma_f32_16x16x32_bf16 v[16:19], v[128:131], v[194:197], v[16:19]
	v_mfma_f32_16x16x32_bf16 v[8:11], v[136:139], v[194:197], v[8:11]
	v_mfma_f32_16x16x32_bf16 v[24:27], v[136:139], v[178:181], v[24:27]
	v_mfma_f32_16x16x32_bf16 v[40:43], v[136:139], v[170:173], v[40:43]
	v_mfma_f32_16x16x32_bf16 v[56:59], v[136:139], v[162:165], v[56:59]
	v_mfma_f32_16x16x32_bf16 v[60:63], v[132:135], v[166:169], v[60:63]
	v_mfma_f32_16x16x32_bf16 v[48:51], v[132:135], v[174:177], v[48:51]
	v_mfma_f32_16x16x32_bf16 v[32:35], v[132:135], v[182:185], v[32:35]
	v_mfma_f32_16x16x32_bf16 v[16:19], v[132:135], v[210:213], v[16:19]
	v_mfma_f32_16x16x32_bf16 v[8:11], v[146:149], v[210:213], v[8:11]
	v_mfma_f32_16x16x32_bf16 v[24:27], v[146:149], v[182:185], v[24:27]
	v_mfma_f32_16x16x32_bf16 v[40:43], v[146:149], v[174:177], v[40:43]
	v_mfma_f32_16x16x32_bf16 v[56:59], v[146:149], v[166:169], v[56:59]
	v_mfma_f32_16x16x32_bf16 v[52:55], v[214:217], v[162:165], v[52:55]
	v_mfma_f32_16x16x32_bf16 v[36:39], v[214:217], v[170:173], v[36:39]
	v_mfma_f32_16x16x32_bf16 v[20:23], v[214:217], v[178:181], v[20:23]
	v_mfma_f32_16x16x32_bf16 v[4:7], v[214:217], v[194:197], v[4:7]
	v_mfma_f32_16x16x32_bf16 v[0:3], v[222:225], v[194:197], v[0:3]
	v_mfma_f32_16x16x32_bf16 v[12:15], v[222:225], v[178:181], v[12:15]
	v_mfma_f32_16x16x32_bf16 v[28:31], v[222:225], v[170:173], v[28:31]
	v_mfma_f32_16x16x32_bf16 v[44:47], v[222:225], v[162:165], v[44:47]
	v_mfma_f32_16x16x32_bf16 v[52:55], v[218:221], v[166:169], v[52:55]
	v_mfma_f32_16x16x32_bf16 v[36:39], v[218:221], v[174:177], v[36:39]
	v_mfma_f32_16x16x32_bf16 v[20:23], v[218:221], v[182:185], v[20:23]
	v_mfma_f32_16x16x32_bf16 v[4:7], v[218:221], v[210:213], v[4:7]
	v_mfma_f32_16x16x32_bf16 v[0:3], v[226:229], v[210:213], v[0:3]
	v_mfma_f32_16x16x32_bf16 v[12:15], v[226:229], v[182:185], v[12:15]
	v_mfma_f32_16x16x32_bf16 v[28:31], v[226:229], v[174:177], v[28:31]
	v_mfma_f32_16x16x32_bf16 v[44:47], v[226:229], v[166:169], v[44:47]
	s_barrier
	s_add_i32 s6, 0, 0x18000
	v_add_u32_e32 v146, s6, v206
	ds_read_b128 v[128:131], v146
	ds_read_b128 v[132:135], v146 offset:1024
	ds_read_b128 v[136:139], v146 offset:2048
	ds_read_b128 v[146:149], v146 offset:3072
	s_add_u32 s50, s52, 0xb0000
	s_addc_u32 s51, s53, 0
	s_mov_b32 m0, s68
	v_lshl_add_u64 v[214:215], s[50:51], 0, v[154:155]
	ds_read_b128 v[162:165], v208 offset:32768
	ds_read_b128 v[166:169], v208 offset:33792
	ds_read_b128 v[170:173], v208 offset:34816
	ds_read_b128 v[174:177], v208 offset:35840
	ds_read_b128 v[178:181], v208 offset:36864
	ds_read_b128 v[182:185], v208 offset:37888
	ds_read_b128 v[194:197], v208 offset:38912
	ds_read_b128 v[210:213], v208 offset:39936
	global_load_lds_dwordx4 v[214:215], off
	v_lshl_add_u64 v[214:215], s[50:51], 0, v[152:153]
	s_mov_b32 m0, s69
	s_nop 0
	global_load_lds_dwordx4 v[214:215], off
	s_add_i32 s19, 0, 0x1c000
	v_add_u32_e32 v192, s19, v206
	ds_read_b128 v[214:217], v192
	ds_read_b128 v[218:221], v192 offset:1024
	ds_read_b128 v[222:225], v192 offset:2048
	ds_read_b128 v[226:229], v192 offset:3072
	s_waitcnt vmcnt(8)
	s_waitcnt lgkmcnt(0)
	s_barrier
	v_mfma_f32_16x16x32_bf16 v[124:127], v[128:131], v[162:165], v[124:127]
	v_mfma_f32_16x16x32_bf16 v[108:111], v[128:131], v[170:173], v[108:111]
	v_mfma_f32_16x16x32_bf16 v[96:99], v[128:131], v[178:181], v[96:99]
	v_mfma_f32_16x16x32_bf16 v[84:87], v[128:131], v[194:197], v[84:87]
	v_mfma_f32_16x16x32_bf16 v[80:83], v[136:139], v[194:197], v[80:83]
	v_mfma_f32_16x16x32_bf16 v[88:91], v[136:139], v[178:181], v[88:91]
	v_mfma_f32_16x16x32_bf16 v[104:107], v[136:139], v[170:173], v[104:107]
	v_mfma_f32_16x16x32_bf16 v[120:123], v[136:139], v[162:165], v[120:123]
	v_mfma_f32_16x16x32_bf16 v[124:127], v[132:135], v[166:169], v[124:127]
	v_mfma_f32_16x16x32_bf16 v[108:111], v[132:135], v[174:177], v[108:111]
	v_mfma_f32_16x16x32_bf16 v[96:99], v[132:135], v[182:185], v[96:99]
	v_mfma_f32_16x16x32_bf16 v[84:87], v[132:135], v[210:213], v[84:87]
	v_mfma_f32_16x16x32_bf16 v[80:83], v[146:149], v[210:213], v[80:83]
	v_mfma_f32_16x16x32_bf16 v[88:91], v[146:149], v[182:185], v[88:91]
	v_mfma_f32_16x16x32_bf16 v[104:107], v[146:149], v[174:177], v[104:107]
	v_mfma_f32_16x16x32_bf16 v[120:123], v[146:149], v[166:169], v[120:123]
	v_mfma_f32_16x16x32_bf16 v[116:119], v[214:217], v[162:165], v[116:119]
	v_mfma_f32_16x16x32_bf16 v[100:103], v[214:217], v[170:173], v[100:103]
	v_mfma_f32_16x16x32_bf16 v[76:79], v[214:217], v[178:181], v[76:79]
	v_mfma_f32_16x16x32_bf16 v[68:71], v[214:217], v[194:197], v[68:71]
	v_mfma_f32_16x16x32_bf16 v[64:67], v[222:225], v[194:197], v[64:67]
	v_mfma_f32_16x16x32_bf16 v[72:75], v[222:225], v[178:181], v[72:75]
	v_mfma_f32_16x16x32_bf16 v[92:95], v[222:225], v[170:173], v[92:95]
	v_mfma_f32_16x16x32_bf16 v[112:115], v[222:225], v[162:165], v[112:115]
	v_mfma_f32_16x16x32_bf16 v[116:119], v[218:221], v[166:169], v[116:119]
	v_mfma_f32_16x16x32_bf16 v[100:103], v[218:221], v[174:177], v[100:103]
	v_mfma_f32_16x16x32_bf16 v[76:79], v[218:221], v[182:185], v[76:79]
	v_mfma_f32_16x16x32_bf16 v[68:71], v[218:221], v[210:213], v[68:71]
	v_mfma_f32_16x16x32_bf16 v[64:67], v[226:229], v[210:213], v[64:67]
	v_mfma_f32_16x16x32_bf16 v[72:75], v[226:229], v[182:185], v[72:75]
	v_mfma_f32_16x16x32_bf16 v[92:95], v[226:229], v[174:177], v[92:95]
	v_mfma_f32_16x16x32_bf16 v[112:115], v[226:229], v[166:169], v[112:115]
	s_barrier
	s_add_i32 s6, s6, s57
	v_lshl_add_u64 v[230:231], v[230:231], 0, s[36:37]
	s_mov_b32 m0, s6
	s_nop 0
	global_load_lds_dwordx4 v[230:231], off
	v_lshl_add_u64 v[230:231], v[232:233], 0, s[36:37]
	s_add_i32 m0, s6, 0x2000
	s_nop 0
	global_load_lds_dwordx4 v[230:231], off
	s_mov_b32 m0, s70
	v_lshl_add_u64 v[230:231], v[234:235], 0, s[36:37]
	ds_read_b128 v[162:165], v208 offset:49152
	ds_read_b128 v[166:169], v208 offset:50176
	ds_read_b128 v[170:173], v208 offset:51200
	ds_read_b128 v[174:177], v208 offset:52224
	ds_read_b128 v[178:181], v208 offset:53248
	ds_read_b128 v[182:185], v208 offset:54272
	ds_read_b128 v[194:197], v208 offset:55296
	ds_read_b128 v[210:213], v208 offset:56320
	global_load_lds_dwordx4 v[230:231], off
	v_lshl_add_u64 v[230:231], v[236:237], 0, s[36:37]
	s_mov_b32 m0, s71
	s_nop 0
	global_load_lds_dwordx4 v[230:231], off
	s_add_u32 s48, s48, 0xb0080
	s_addc_u32 s49, s49, 0
	s_add_i32 s6, s19, s57
	v_lshl_add_u64 v[250:251], s[48:49], 0, v[140:141]
	s_mov_b32 m0, s6
	s_nop 0
	global_load_lds_dwordx4 v[250:251], off
	v_lshl_add_u64 v[250:251], s[48:49], 0, v[150:151]
	s_add_i32 m0, s6, 0x2000
	s_nop 0
	global_load_lds_dwordx4 v[250:251], off
	s_waitcnt vmcnt(8)
	s_waitcnt lgkmcnt(0)
	s_barrier
	v_mfma_f32_16x16x32_bf16 v[60:63], v[128:131], v[162:165], v[60:63]
	v_mfma_f32_16x16x32_bf16 v[48:51], v[128:131], v[170:173], v[48:51]
	v_mfma_f32_16x16x32_bf16 v[32:35], v[128:131], v[178:181], v[32:35]
	v_mfma_f32_16x16x32_bf16 v[16:19], v[128:131], v[194:197], v[16:19]
	v_mfma_f32_16x16x32_bf16 v[8:11], v[136:139], v[194:197], v[8:11]
	v_mfma_f32_16x16x32_bf16 v[24:27], v[136:139], v[178:181], v[24:27]
	v_mfma_f32_16x16x32_bf16 v[40:43], v[136:139], v[170:173], v[40:43]
	v_mfma_f32_16x16x32_bf16 v[56:59], v[136:139], v[162:165], v[56:59]
	v_mfma_f32_16x16x32_bf16 v[60:63], v[132:135], v[166:169], v[60:63]
	v_mfma_f32_16x16x32_bf16 v[48:51], v[132:135], v[174:177], v[48:51]
	v_mfma_f32_16x16x32_bf16 v[32:35], v[132:135], v[182:185], v[32:35]
	v_mfma_f32_16x16x32_bf16 v[16:19], v[132:135], v[210:213], v[16:19]
	v_mfma_f32_16x16x32_bf16 v[8:11], v[146:149], v[210:213], v[8:11]
	v_mfma_f32_16x16x32_bf16 v[24:27], v[146:149], v[182:185], v[24:27]
	v_mfma_f32_16x16x32_bf16 v[40:43], v[146:149], v[174:177], v[40:43]
	v_mfma_f32_16x16x32_bf16 v[56:59], v[146:149], v[166:169], v[56:59]
	v_mfma_f32_16x16x32_bf16 v[52:55], v[214:217], v[162:165], v[52:55]
	v_mfma_f32_16x16x32_bf16 v[36:39], v[214:217], v[170:173], v[36:39]
	v_mfma_f32_16x16x32_bf16 v[20:23], v[214:217], v[178:181], v[20:23]
	v_mfma_f32_16x16x32_bf16 v[4:7], v[214:217], v[194:197], v[4:7]
	v_mfma_f32_16x16x32_bf16 v[0:3], v[222:225], v[194:197], v[0:3]
	v_mfma_f32_16x16x32_bf16 v[12:15], v[222:225], v[178:181], v[12:15]
	v_mfma_f32_16x16x32_bf16 v[28:31], v[222:225], v[170:173], v[28:31]
	v_mfma_f32_16x16x32_bf16 v[44:47], v[222:225], v[162:165], v[44:47]
	v_mfma_f32_16x16x32_bf16 v[52:55], v[218:221], v[166:169], v[52:55]
	v_mfma_f32_16x16x32_bf16 v[36:39], v[218:221], v[174:177], v[36:39]
	v_mfma_f32_16x16x32_bf16 v[20:23], v[218:221], v[182:185], v[20:23]
	v_mfma_f32_16x16x32_bf16 v[4:7], v[218:221], v[210:213], v[4:7]
	v_mfma_f32_16x16x32_bf16 v[0:3], v[226:229], v[210:213], v[0:3]
	v_mfma_f32_16x16x32_bf16 v[12:15], v[226:229], v[182:185], v[12:15]
	v_mfma_f32_16x16x32_bf16 v[28:31], v[226:229], v[174:177], v[28:31]
	v_mfma_f32_16x16x32_bf16 v[44:47], v[226:229], v[166:169], v[44:47]
	s_add_i32 s12, s12, 2
	s_add_u32 s10, s10, 0x100
	s_addc_u32 s11, s11, 0
	s_cmp_gt_u32 s12, 41
	s_mov_b64 s[50:51], s[46:47]
	s_barrier
	s_cbranch_scc0 .LBB0_341
	s_mov_b32 s100, 1
	s_ashr_i32 s39, s38, 31
	v_lshl_or_b32 v128, s81, 8, v207
	s_lshl_b64 s[10:11], s[38:39], 8
	v_ashrrev_i32_e32 v129, 31, v128
	v_lshl_add_u64 v[168:169], s[10:11], 0, v[156:157]
	v_lshlrev_b64 v[170:171], 1, v[128:129]
	v_lshl_add_u64 v[174:175], s[26:27], 0, v[170:171]
	v_lshlrev_b64 v[172:173], 11, v[168:169]
	v_lshl_add_u64 v[128:129], v[174:175], 0, v[172:173]
	global_load_dwordx4 v[182:185], v[128:129], off
	global_load_dwordx4 v[210:213], v[128:129], off offset:256
	v_or_b32_e32 v166, 16, v168
	v_mov_b32_e32 v167, v169
	v_lshlrev_b64 v[176:177], 11, v[166:167]
	v_lshl_add_u64 v[128:129], v[174:175], 0, v[176:177]
	global_load_dwordx4 v[214:217], v[128:129], off
	global_load_dwordx4 v[218:221], v[128:129], off offset:256
	v_or_b32_e32 v164, 32, v168
	v_mov_b32_e32 v165, v169
	v_or_b32_e32 v162, 48, v168
	v_mov_b32_e32 v163, v169
	v_lshlrev_b64 v[180:181], 11, v[164:165]
	v_lshlrev_b64 v[178:179], 11, v[162:163]
	v_lshl_add_u64 v[128:129], v[174:175], 0, v[180:181]
	v_lshl_add_u64 v[130:131], v[174:175], 0, v[178:179]
	global_load_dwordx4 v[222:225], v[128:129], off
	global_load_dwordx4 v[136:139], v[128:129], off offset:256
	global_load_dwordx4 v[132:135], v[130:131], off
	s_nop 0
	global_load_dwordx4 v[128:131], v[130:131], off offset:256
	s_mov_b64 s[10:11], 0x90
	v_lshl_add_u64 v[172:173], s[28:29], 0, v[172:173]
	v_lshl_add_u64 v[172:173], v[172:173], 0, v[170:171]
	s_waitcnt vmcnt(0)
	v_lshlrev_b32_e32 v146, 16, v182
	v_and_b32_e32 v147, 0xffff0000, v182
	v_lshlrev_b32_e32 v148, 16, v184
	v_and_b32_e32 v149, 0xffff0000, v184
	v_lshlrev_b32_e32 v182, 16, v183
	v_and_b32_e32 v183, 0xffff0000, v183
	v_lshlrev_b32_e32 v194, 16, v210
	v_and_b32_e32 v195, 0xffff0000, v210
	v_lshlrev_b32_e32 v196, 16, v212
	v_and_b32_e32 v197, 0xffff0000, v212
	v_lshlrev_b32_e32 v210, 16, v211
	v_and_b32_e32 v211, 0xffff0000, v211
	v_lshlrev_b32_e32 v212, 16, v213
	v_and_b32_e32 v213, 0xffff0000, v213
	v_pk_fma_f32 v[124:125], v[124:125], 0.5, v[146:147] op_sel_hi:[1,0,1]
	v_pk_fma_f32 v[120:121], v[120:121], 0.5, v[148:149] op_sel_hi:[1,0,1]
	v_pk_fma_f32 v[126:127], v[126:127], 0.5, v[182:183] op_sel_hi:[1,0,1]
	v_pk_fma_f32 v[116:117], v[116:117], 0.5, v[194:195] op_sel_hi:[1,0,1]
	v_pk_fma_f32 v[146:147], v[112:113], 0.5, v[196:197] op_sel_hi:[1,0,1]
	v_pk_fma_f32 v[118:119], v[118:119], 0.5, v[210:211] op_sel_hi:[1,0,1]
	v_pk_fma_f32 v[148:149], v[114:115], 0.5, v[212:213] op_sel_hi:[1,0,1]
	v_pk_mul_f32 v[212:213], v[124:125], v[124:125]
	v_lshlrev_b32_e32 v182, 16, v214
	v_and_b32_e32 v183, 0xffff0000, v214
	v_lshlrev_b32_e32 v194, 16, v215
	v_and_b32_e32 v195, 0xffff0000, v215
	v_pk_mul_f32 v[214:215], v[126:127], v[126:127]
	v_cvt_pk_bf16_f32 v112, v124, v125
	v_cvt_pk_bf16_f32 v113, v126, v127
	v_pk_mul_f32 v[124:125], v[116:117], v[116:117]
	v_pk_mul_f32 v[126:127], v[118:119], v[118:119]
	v_pk_mul_f32 v[228:229], v[146:147], v[146:147]
	v_cvt_pk_bf16_f32 v116, v116, v117
	v_cvt_pk_bf16_f32 v117, v118, v119
	v_cvt_pk_bf16_f32 v118, v146, v147
	v_add_f32_e32 v146, v212, v213
	v_lshlrev_b32_e32 v184, 16, v185
	v_and_b32_e32 v185, 0xffff0000, v185
	v_add_f32_e32 v146, v214, v146
	v_pk_fma_f32 v[122:123], v[122:123], 0.5, v[184:185] op_sel_hi:[1,0,1]
	v_lshlrev_b32_e32 v184, 16, v216
	v_and_b32_e32 v185, 0xffff0000, v216
	v_lshlrev_b32_e32 v196, 16, v217
	v_and_b32_e32 v197, 0xffff0000, v217
	v_pk_mul_f32 v[216:217], v[120:121], v[120:121]
	v_add_f32_e32 v146, v215, v146
	v_add_f32_e32 v146, v216, v146
	v_pk_mul_f32 v[226:227], v[122:123], v[122:123]
	v_add_f32_e32 v146, v217, v146
	v_add_f32_e32 v146, v226, v146
	v_add_f32_e32 v146, v227, v146
	v_add_f32_e32 v124, v124, v146
	v_add_f32_e32 v124, v125, v124
	v_add_f32_e32 v124, v126, v124
	v_add_f32_e32 v124, v127, v124
	v_add_f32_e32 v124, v228, v124
	v_pk_mul_f32 v[230:231], v[148:149], v[148:149]
	v_add_f32_e32 v124, v229, v124
	v_add_f32_e32 v124, v230, v124
	v_add_f32_e32 v209, v231, v124
	v_lshlrev_b32_e32 v124, 16, v220
	v_and_b32_e32 v125, 0xffff0000, v220
	v_pk_fma_f32 v[124:125], v[92:93], 0.5, v[124:125] op_sel_hi:[1,0,1]
	v_lshlrev_b32_e32 v92, 16, v219
	v_and_b32_e32 v93, 0xffff0000, v219
	v_pk_fma_f32 v[102:103], v[102:103], 0.5, v[92:93] op_sel_hi:[1,0,1]
	v_lshlrev_b32_e32 v92, 16, v221
	v_and_b32_e32 v93, 0xffff0000, v221
	v_pk_fma_f32 v[126:127], v[94:95], 0.5, v[92:93] op_sel_hi:[1,0,1]
	v_lshlrev_b32_e32 v92, 16, v222
	v_and_b32_e32 v93, 0xffff0000, v222
	v_pk_fma_f32 v[92:93], v[96:97], 0.5, v[92:93] op_sel_hi:[1,0,1]
	v_lshlrev_b32_e32 v96, 16, v225
	v_and_b32_e32 v97, 0xffff0000, v225
	v_lshlrev_b32_e32 v94, 16, v224
	v_and_b32_e32 v95, 0xffff0000, v224
	v_pk_fma_f32 v[90:91], v[90:91], 0.5, v[96:97] op_sel_hi:[1,0,1]
	v_lshlrev_b32_e32 v96, 16, v136
	v_and_b32_e32 v97, 0xffff0000, v136
	v_pk_fma_f32 v[88:89], v[88:89], 0.5, v[94:95] op_sel_hi:[1,0,1]
	v_lshlrev_b32_e32 v94, 16, v223
	v_and_b32_e32 v95, 0xffff0000, v223
	v_pk_fma_f32 v[96:97], v[76:77], 0.5, v[96:97] op_sel_hi:[1,0,1]
	v_lshl_add_u64 v[76:77], v[168:169], 0, s[36:37]
	v_cvt_pk_bf16_f32 v114, v120, v121
	v_pk_fma_f32 v[120:121], v[108:109], 0.5, v[182:183] op_sel_hi:[1,0,1]
	v_pk_fma_f32 v[94:95], v[98:99], 0.5, v[94:95] op_sel_hi:[1,0,1]
	v_lshlrev_b64 v[182:183], 11, v[76:77]
	v_lshlrev_b32_e32 v98, 16, v138
	v_and_b32_e32 v99, 0xffff0000, v138
	v_lshl_add_u64 v[146:147], v[174:175], 0, v[182:183]
	v_pk_fma_f32 v[98:99], v[72:73], 0.5, v[98:99] op_sel_hi:[1,0,1]
	v_lshlrev_b32_e32 v72, 16, v137
	v_and_b32_e32 v73, 0xffff0000, v137
	v_lshlrev_b32_e32 v210, 16, v218
	v_and_b32_e32 v211, 0xffff0000, v218
	global_load_dwordx4 v[218:221], v[146:147], off
	global_load_dwordx4 v[226:229], v[146:147], off offset:256
	v_pk_fma_f32 v[136:137], v[78:79], 0.5, v[72:73] op_sel_hi:[1,0,1]
	v_lshlrev_b32_e32 v72, 16, v139
	v_and_b32_e32 v73, 0xffff0000, v139
	v_pk_fma_f32 v[138:139], v[74:75], 0.5, v[72:73] op_sel_hi:[1,0,1]
	v_lshlrev_b32_e32 v72, 16, v132
	v_and_b32_e32 v73, 0xffff0000, v132
	v_pk_fma_f32 v[74:75], v[84:85], 0.5, v[72:73] op_sel_hi:[1,0,1]
	v_lshlrev_b32_e32 v72, 16, v134
	v_and_b32_e32 v73, 0xffff0000, v134
	v_pk_fma_f32 v[78:79], v[80:81], 0.5, v[72:73] op_sel_hi:[1,0,1]
	v_lshlrev_b32_e32 v72, 16, v133
	v_and_b32_e32 v73, 0xffff0000, v133
	v_pk_fma_f32 v[80:81], v[86:87], 0.5, v[72:73] op_sel_hi:[1,0,1]
	v_lshlrev_b32_e32 v72, 16, v135
	v_and_b32_e32 v73, 0xffff0000, v135
	v_pk_fma_f32 v[82:83], v[82:83], 0.5, v[72:73] op_sel_hi:[1,0,1]
	v_lshl_add_u64 v[72:73], v[168:169], 0, s[10:11]
	v_lshlrev_b64 v[132:133], 11, v[72:73]
	v_lshl_add_u64 v[134:135], v[174:175], 0, v[132:133]
	global_load_dwordx4 v[234:237], v[134:135], off
	global_load_dwordx4 v[242:245], v[134:135], off offset:256
	v_lshlrev_b32_e32 v84, 16, v128
	v_and_b32_e32 v85, 0xffff0000, v128
	v_pk_fma_f32 v[84:85], v[68:69], 0.5, v[84:85] op_sel_hi:[1,0,1]
	v_lshlrev_b32_e32 v68, 16, v130
	v_and_b32_e32 v69, 0xffff0000, v130
	v_pk_fma_f32 v[86:87], v[64:65], 0.5, v[68:69] op_sel_hi:[1,0,1]
	v_lshlrev_b32_e32 v64, 16, v129
	v_and_b32_e32 v65, 0xffff0000, v129
	s_mov_b64 s[10:11], 0xa0
	v_pk_fma_f32 v[128:129], v[70:71], 0.5, v[64:65] op_sel_hi:[1,0,1]
	v_lshl_add_u64 v[70:71], v[168:169], 0, s[10:11]
	v_lshlrev_b32_e32 v64, 16, v131
	v_and_b32_e32 v65, 0xffff0000, v131
	v_lshlrev_b64 v[134:135], 11, v[70:71]
	v_pk_fma_f32 v[130:131], v[66:67], 0.5, v[64:65] op_sel_hi:[1,0,1]
	v_lshl_add_u64 v[64:65], v[174:175], 0, v[134:135]
	v_cvt_pk_bf16_f32 v115, v122, v123
	v_pk_fma_f32 v[122:123], v[110:111], 0.5, v[194:195] op_sel_hi:[1,0,1]
	v_pk_fma_f32 v[110:111], v[106:107], 0.5, v[196:197] op_sel_hi:[1,0,1]
	global_load_dwordx4 v[246:249], v[64:65], off
	global_load_dwordx4 v[194:197], v[64:65], off offset:256
	s_mov_b64 s[10:11], 0xb0
	v_lshl_add_u64 v[68:69], v[168:169], 0, s[10:11]
	v_pk_fma_f32 v[108:109], v[104:105], 0.5, v[184:185] op_sel_hi:[1,0,1]
	v_lshlrev_b64 v[184:185], 11, v[68:69]
	v_lshl_add_u64 v[64:65], v[174:175], 0, v[184:185]
	v_cvt_pk_bf16_f32 v119, v148, v149
	global_load_dwordx4 v[146:149], v[64:65], off
	s_nop 0
	global_load_dwordx4 v[64:67], v[64:65], off offset:256
	global_store_dwordx4 v[172:173], v[112:115], off
	global_store_dwordx4 v[172:173], v[116:119], off offset:256
	v_cvt_pk_bf16_f32 v104, v120, v121
	v_lshl_add_u64 v[112:113], s[28:29], 0, v[176:177]
	v_cvt_pk_bf16_f32 v105, v122, v123
	v_cvt_pk_bf16_f32 v106, v108, v109
	v_cvt_pk_bf16_f32 v107, v110, v111
	v_pk_fma_f32 v[100:101], v[100:101], 0.5, v[210:211] op_sel_hi:[1,0,1]
	v_lshl_add_u64 v[112:113], v[112:113], 0, v[170:171]
	v_cvt_pk_bf16_f32 v210, v100, v101
	v_cvt_pk_bf16_f32 v211, v102, v103
	v_cvt_pk_bf16_f32 v212, v124, v125
	v_cvt_pk_bf16_f32 v213, v126, v127
	global_store_dwordx4 v[112:113], v[104:107], off
	global_store_dwordx4 v[112:113], v[210:213], off offset:256
	v_cvt_pk_bf16_f32 v214, v92, v93
	v_lshl_add_u64 v[104:105], s[28:29], 0, v[180:181]
	v_cvt_pk_bf16_f32 v215, v94, v95
	v_cvt_pk_bf16_f32 v216, v88, v89
	v_cvt_pk_bf16_f32 v217, v90, v91
	v_lshl_add_u64 v[104:105], v[104:105], 0, v[170:171]
	v_cvt_pk_bf16_f32 v222, v96, v97
	v_cvt_pk_bf16_f32 v223, v136, v137
	v_cvt_pk_bf16_f32 v224, v98, v99
	v_cvt_pk_bf16_f32 v225, v138, v139
	global_store_dwordx4 v[104:105], v[214:217], off
	global_store_dwordx4 v[104:105], v[222:225], off offset:256
	v_lshl_add_u64 v[104:105], s[28:29], 0, v[178:179]
	v_cvt_pk_bf16_f32 v230, v74, v75
	v_cvt_pk_bf16_f32 v231, v80, v81
	v_cvt_pk_bf16_f32 v232, v78, v79
	v_cvt_pk_bf16_f32 v233, v82, v83
	v_lshl_add_u64 v[104:105], v[104:105], 0, v[170:171]
	v_cvt_pk_bf16_f32 v238, v84, v85
	v_cvt_pk_bf16_f32 v239, v128, v129
	v_cvt_pk_bf16_f32 v240, v86, v87
	v_cvt_pk_bf16_f32 v241, v130, v131
	global_store_dwordx4 v[104:105], v[230:233], off
	global_store_dwordx4 v[104:105], v[238:241], off offset:256
	s_waitcnt vmcnt(0)
	v_lshlrev_b32_e32 v104, 16, v218
	v_and_b32_e32 v105, 0xffff0000, v218
	v_pk_fma_f32 v[60:61], v[60:61], 0.5, v[104:105] op_sel_hi:[1,0,1]
	v_lshlrev_b32_e32 v104, 16, v220
	v_and_b32_e32 v105, 0xffff0000, v220
	v_pk_fma_f32 v[56:57], v[56:57], 0.5, v[104:105] op_sel_hi:[1,0,1]
	v_lshlrev_b32_e32 v104, 16, v219
	v_and_b32_e32 v105, 0xffff0000, v219
	v_pk_fma_f32 v[62:63], v[62:63], 0.5, v[104:105] op_sel_hi:[1,0,1]
	v_lshlrev_b32_e32 v104, 16, v221
	v_and_b32_e32 v105, 0xffff0000, v221
	v_pk_fma_f32 v[58:59], v[58:59], 0.5, v[104:105] op_sel_hi:[1,0,1]
	v_lshlrev_b32_e32 v104, 16, v226
	v_and_b32_e32 v105, 0xffff0000, v226
	v_pk_fma_f32 v[52:53], v[52:53], 0.5, v[104:105] op_sel_hi:[1,0,1]
	v_lshlrev_b32_e32 v104, 16, v228
	v_and_b32_e32 v105, 0xffff0000, v228
	v_pk_fma_f32 v[104:105], v[44:45], 0.5, v[104:105] op_sel_hi:[1,0,1]
	v_lshlrev_b32_e32 v44, 16, v227
	v_and_b32_e32 v45, 0xffff0000, v227
	v_pk_fma_f32 v[54:55], v[54:55], 0.5, v[44:45] op_sel_hi:[1,0,1]
	v_lshlrev_b32_e32 v44, 16, v229
	v_and_b32_e32 v45, 0xffff0000, v229
	v_pk_fma_f32 v[106:107], v[46:47], 0.5, v[44:45] op_sel_hi:[1,0,1]
	v_lshlrev_b32_e32 v44, 16, v234
	v_and_b32_e32 v45, 0xffff0000, v234
	v_pk_fma_f32 v[44:45], v[48:49], 0.5, v[44:45] op_sel_hi:[1,0,1]
	v_lshlrev_b32_e32 v48, 16, v237
	v_and_b32_e32 v49, 0xffff0000, v237
	v_pk_fma_f32 v[42:43], v[42:43], 0.5, v[48:49] op_sel_hi:[1,0,1]
	v_lshlrev_b32_e32 v48, 16, v242
	v_and_b32_e32 v49, 0xffff0000, v242
	v_pk_fma_f32 v[36:37], v[36:37], 0.5, v[48:49] op_sel_hi:[1,0,1]
	v_lshlrev_b32_e32 v48, 16, v244
	v_and_b32_e32 v49, 0xffff0000, v244
	v_lshlrev_b32_e32 v46, 16, v236
	v_and_b32_e32 v47, 0xffff0000, v236
	v_pk_fma_f32 v[48:49], v[28:29], 0.5, v[48:49] op_sel_hi:[1,0,1]
	v_lshlrev_b32_e32 v28, 16, v243
	v_and_b32_e32 v29, 0xffff0000, v243
	v_pk_fma_f32 v[40:41], v[40:41], 0.5, v[46:47] op_sel_hi:[1,0,1]
	v_lshlrev_b32_e32 v46, 16, v235
	v_and_b32_e32 v47, 0xffff0000, v235
	v_pk_fma_f32 v[38:39], v[38:39], 0.5, v[28:29] op_sel_hi:[1,0,1]
	v_lshlrev_b32_e32 v28, 16, v245
	v_and_b32_e32 v29, 0xffff0000, v245
	v_pk_fma_f32 v[46:47], v[50:51], 0.5, v[46:47] op_sel_hi:[1,0,1]
	v_pk_fma_f32 v[50:51], v[30:31], 0.5, v[28:29] op_sel_hi:[1,0,1]
	v_lshlrev_b32_e32 v28, 16, v246
	v_and_b32_e32 v29, 0xffff0000, v246
	v_pk_fma_f32 v[28:29], v[32:33], 0.5, v[28:29] op_sel_hi:[1,0,1]
	v_lshlrev_b32_e32 v32, 16, v249
	v_and_b32_e32 v33, 0xffff0000, v249
	v_pk_fma_f32 v[26:27], v[26:27], 0.5, v[32:33] op_sel_hi:[1,0,1]
	v_lshlrev_b32_e32 v32, 16, v194
	v_and_b32_e32 v33, 0xffff0000, v194
	v_pk_fma_f32 v[20:21], v[20:21], 0.5, v[32:33] op_sel_hi:[1,0,1]
	v_lshlrev_b32_e32 v32, 16, v196
	v_and_b32_e32 v33, 0xffff0000, v196
	v_lshlrev_b32_e32 v30, 16, v248
	v_and_b32_e32 v31, 0xffff0000, v248
	v_pk_fma_f32 v[32:33], v[12:13], 0.5, v[32:33] op_sel_hi:[1,0,1]
	v_lshlrev_b32_e32 v12, 16, v195
	v_and_b32_e32 v13, 0xffff0000, v195
	v_pk_fma_f32 v[24:25], v[24:25], 0.5, v[30:31] op_sel_hi:[1,0,1]
	v_lshlrev_b32_e32 v30, 16, v247
	v_and_b32_e32 v31, 0xffff0000, v247
	v_pk_fma_f32 v[22:23], v[22:23], 0.5, v[12:13] op_sel_hi:[1,0,1]
	v_lshlrev_b32_e32 v12, 16, v197
	v_and_b32_e32 v13, 0xffff0000, v197
	v_pk_fma_f32 v[30:31], v[34:35], 0.5, v[30:31] op_sel_hi:[1,0,1]
	v_pk_fma_f32 v[34:35], v[14:15], 0.5, v[12:13] op_sel_hi:[1,0,1]
	v_lshlrev_b32_e32 v14, 16, v148
	v_and_b32_e32 v15, 0xffff0000, v148
	v_lshlrev_b32_e32 v12, 16, v146
	v_and_b32_e32 v13, 0xffff0000, v146
	v_pk_fma_f32 v[8:9], v[8:9], 0.5, v[14:15] op_sel_hi:[1,0,1]
	v_lshlrev_b32_e32 v14, 16, v147
	v_and_b32_e32 v15, 0xffff0000, v147
	v_lshlrev_b32_e32 v146, 16, v64
	v_and_b32_e32 v147, 0xffff0000, v64
	v_pk_fma_f32 v[4:5], v[4:5], 0.5, v[146:147] op_sel_hi:[1,0,1]
	v_lshlrev_b32_e32 v146, 16, v66
	v_and_b32_e32 v147, 0xffff0000, v66
	v_pk_fma_f32 v[0:1], v[0:1], 0.5, v[146:147] op_sel_hi:[1,0,1]
	v_lshl_add_u64 v[146:147], s[28:29], 0, v[182:183]
	v_cvt_pk_bf16_f32 v112, v60, v61
	v_cvt_pk_bf16_f32 v113, v62, v63
	v_cvt_pk_bf16_f32 v114, v56, v57
	v_cvt_pk_bf16_f32 v115, v58, v59
	v_lshl_add_u64 v[146:147], v[146:147], 0, v[170:171]
	v_cvt_pk_bf16_f32 v116, v52, v53
	v_cvt_pk_bf16_f32 v117, v54, v55
	v_cvt_pk_bf16_f32 v118, v104, v105
	v_cvt_pk_bf16_f32 v119, v106, v107
	global_store_dwordx4 v[146:147], v[112:115], off
	global_store_dwordx4 v[146:147], v[116:119], off offset:256
	v_cvt_pk_bf16_f32 v172, v44, v45
	v_lshl_add_u64 v[112:113], s[28:29], 0, v[132:133]
	v_cvt_pk_bf16_f32 v173, v46, v47
	v_cvt_pk_bf16_f32 v174, v40, v41
	v_cvt_pk_bf16_f32 v175, v42, v43
	v_lshl_add_u64 v[112:113], v[112:113], 0, v[170:171]
	v_cvt_pk_bf16_f32 v176, v36, v37
	v_cvt_pk_bf16_f32 v177, v38, v39
	v_cvt_pk_bf16_f32 v178, v48, v49
	v_cvt_pk_bf16_f32 v179, v50, v51
	global_store_dwordx4 v[112:113], v[172:175], off
	global_store_dwordx4 v[112:113], v[176:179], off offset:256
	v_lshl_add_u64 v[112:113], s[28:29], 0, v[134:135]
	v_cvt_pk_bf16_f32 v210, v28, v29
	v_cvt_pk_bf16_f32 v211, v30, v31
	v_cvt_pk_bf16_f32 v212, v24, v25
	v_cvt_pk_bf16_f32 v213, v26, v27
	v_pk_fma_f32 v[12:13], v[16:17], 0.5, v[12:13] op_sel_hi:[1,0,1]
	v_lshlrev_b32_e32 v16, 16, v149
	v_and_b32_e32 v17, 0xffff0000, v149
	v_lshlrev_b32_e32 v64, 16, v65
	v_and_b32_e32 v65, 0xffff0000, v65
	v_lshl_add_u64 v[112:113], v[112:113], 0, v[170:171]
	v_cvt_pk_bf16_f32 v194, v20, v21
	v_cvt_pk_bf16_f32 v195, v22, v23
	v_cvt_pk_bf16_f32 v196, v32, v33
	v_cvt_pk_bf16_f32 v197, v34, v35
	v_pk_fma_f32 v[14:15], v[18:19], 0.5, v[14:15] op_sel_hi:[1,0,1]
	v_pk_fma_f32 v[10:11], v[10:11], 0.5, v[16:17] op_sel_hi:[1,0,1]
	v_pk_fma_f32 v[6:7], v[6:7], 0.5, v[64:65] op_sel_hi:[1,0,1]
	v_lshlrev_b32_e32 v64, 16, v67
	v_and_b32_e32 v65, 0xffff0000, v67
	global_store_dwordx4 v[112:113], v[210:213], off
	global_store_dwordx4 v[112:113], v[194:197], off offset:256
	v_lshl_add_u64 v[112:113], s[28:29], 0, v[184:185]
	v_cvt_pk_bf16_f32 v16, v12, v13
	v_cvt_pk_bf16_f32 v17, v14, v15
	v_cvt_pk_bf16_f32 v18, v8, v9
	v_cvt_pk_bf16_f32 v19, v10, v11
	v_pk_fma_f32 v[2:3], v[2:3], 0.5, v[64:65] op_sel_hi:[1,0,1]
	v_lshl_add_u64 v[112:113], v[112:113], 0, v[170:171]
	v_cvt_pk_bf16_f32 v64, v4, v5
	v_cvt_pk_bf16_f32 v65, v6, v7
	v_cvt_pk_bf16_f32 v66, v0, v1
	v_cvt_pk_bf16_f32 v67, v2, v3
	global_store_dwordx4 v[112:113], v[16:19], off
	global_store_dwordx4 v[112:113], v[64:67], off offset:256
	s_lshl_b32 s10, s81, 2
	v_and_b32_e32 v17, 64, v188
	v_xor_b32_e32 v16, 16, v188
	v_add_u32_e32 v17, 64, v17
	v_cmp_lt_i32_e32 vcc, v16, v17
	v_xor_b32_e32 v18, 32, v188
	s_ashr_i32 s11, s10, 31
	v_cndmask_b32_e32 v16, v188, v16, vcc
	v_lshlrev_b32_e32 v16, 2, v16
	ds_bpermute_b32 v19, v16, v209
	v_cmp_lt_i32_e32 vcc, v18, v17
	s_lshl_b64 s[10:11], s[10:11], 2
	s_add_u32 s38, s73, s10
	v_cndmask_b32_e32 v17, v188, v18, vcc
	v_lshlrev_b32_e32 v17, 2, v17
	s_waitcnt lgkmcnt(0)
	v_add_f32_e32 v18, v209, v19
	ds_bpermute_b32 v19, v17, v18
	s_addc_u32 s39, s74, s11
	s_and_saveexec_b64 s[46:47], s[42:43]
	s_cbranch_execz .LBB0_344
	s_waitcnt lgkmcnt(0)
	v_add_f32_e32 v64, v18, v19
	v_lshlrev_b64 v[18:19], 6, v[168:169]
	v_lshl_add_u64 v[18:19], s[38:39], 0, v[18:19]
	global_store_dword v[18:19], v64, off

.Lm4ap_386:
	s_waitcnt lgkmcnt(0)
	s_barrier
	s_nop 0
	v_mfma_f32_16x16x32_bf16 v[124:127], v[158:161], v[174:177], 0
	v_mfma_f32_16x16x32_bf16 v[116:119], v[158:161], v[182:185], 0
	v_mfma_f32_16x16x32_bf16 v[108:111], v[158:161], v[210:213], 0
	v_mfma_f32_16x16x32_bf16 v[100:103], v[158:161], v[218:221], 0
	v_mfma_f32_16x16x32_bf16 v[96:99], v[166:169], v[218:221], 0
	v_mfma_f32_16x16x32_bf16 v[104:107], v[166:169], v[210:213], 0
	v_mfma_f32_16x16x32_bf16 v[112:115], v[166:169], v[182:185], 0
	v_mfma_f32_16x16x32_bf16 v[120:123], v[166:169], v[174:177], 0
	v_mfma_f32_16x16x32_bf16 v[124:127], v[162:165], v[178:181], v[124:127]
	v_mfma_f32_16x16x32_bf16 v[116:119], v[162:165], v[206:209], v[116:119]
	v_mfma_f32_16x16x32_bf16 v[108:111], v[162:165], v[214:217], v[108:111]
	v_mfma_f32_16x16x32_bf16 v[100:103], v[162:165], v[222:225], v[100:103]
	v_mfma_f32_16x16x32_bf16 v[96:99], v[170:173], v[222:225], v[96:99]
	v_mfma_f32_16x16x32_bf16 v[104:107], v[170:173], v[214:217], v[104:107]
	v_mfma_f32_16x16x32_bf16 v[112:115], v[170:173], v[206:209], v[112:115]
	v_mfma_f32_16x16x32_bf16 v[120:123], v[170:173], v[178:181], v[120:123]
	v_mfma_f32_16x16x32_bf16 v[92:95], v[226:229], v[174:177], 0
	v_mfma_f32_16x16x32_bf16 v[84:87], v[226:229], v[182:185], 0
	v_mfma_f32_16x16x32_bf16 v[76:79], v[226:229], v[210:213], 0
	v_mfma_f32_16x16x32_bf16 v[68:71], v[226:229], v[218:221], 0
	v_mfma_f32_16x16x32_bf16 v[64:67], v[234:237], v[218:221], 0
	v_mfma_f32_16x16x32_bf16 v[72:75], v[234:237], v[210:213], 0
	v_mfma_f32_16x16x32_bf16 v[80:83], v[234:237], v[182:185], 0
	v_mfma_f32_16x16x32_bf16 v[88:91], v[234:237], v[174:177], 0
	v_mfma_f32_16x16x32_bf16 v[92:95], v[230:233], v[178:181], v[92:95]
	v_mfma_f32_16x16x32_bf16 v[84:87], v[230:233], v[206:209], v[84:87]
	v_mfma_f32_16x16x32_bf16 v[76:79], v[230:233], v[214:217], v[76:79]
	v_mfma_f32_16x16x32_bf16 v[68:71], v[230:233], v[222:225], v[68:71]
	v_mfma_f32_16x16x32_bf16 v[64:67], v[238:241], v[222:225], v[64:67]
	v_mfma_f32_16x16x32_bf16 v[72:75], v[238:241], v[214:217], v[72:75]
	v_mfma_f32_16x16x32_bf16 v[80:83], v[238:241], v[206:209], v[80:83]
	v_mfma_f32_16x16x32_bf16 v[88:91], v[238:241], v[178:181], v[88:91]
	s_barrier
	s_add_i32 s19, s82, s57
	v_lshl_add_u64 v[146:147], s[54:55], 0, v[140:141]
	s_mov_b32 m0, s19
	v_lshl_add_u64 v[148:149], s[54:55], 0, v[132:133]
	global_load_lds_dwordx4 v[146:147], off
	s_add_i32 m0, s19, 0x2000
	s_nop 0
	global_load_lds_dwordx4 v[148:149], off
	s_mov_b32 m0, s68
	v_lshl_add_u64 v[194:195], s[58:59], 0, v[128:129]
	ds_read_b128 v[174:177], v157 offset:16384
	ds_read_b128 v[178:181], v157 offset:17408
	ds_read_b128 v[182:185], v157 offset:18432
	ds_read_b128 v[206:209], v157 offset:19456
	ds_read_b128 v[210:213], v157 offset:20480
	ds_read_b128 v[214:217], v157 offset:21504
	ds_read_b128 v[218:221], v157 offset:22528
	ds_read_b128 v[222:225], v157 offset:23552
	global_load_lds_dwordx4 v[194:195], off
	v_lshl_add_u64 v[196:197], s[58:59], 0, v[130:131]
	s_mov_b32 m0, s69
	s_nop 0
	global_load_lds_dwordx4 v[196:197], off
	s_add_u32 s82, s54, 0x40000
	s_addc_u32 s83, s55, 0
	s_add_i32 s6, s6, s57
	v_lshl_add_u64 v[250:251], s[82:83], 0, v[140:141]
	s_mov_b32 m0, s6
	s_nop 0
	global_load_lds_dwordx4 v[250:251], off
	v_lshl_add_u64 v[250:251], s[82:83], 0, v[132:133]
	s_add_i32 m0, s6, 0x2000
	s_nop 0
	global_load_lds_dwordx4 v[250:251], off
	s_waitcnt vmcnt(16)
	s_cmp_lg_u32 s100, 0
	s_cbranch_scc1 .Lm4bp_386
	s_waitcnt vmcnt(8)
.Lm4bp_386:
	s_waitcnt lgkmcnt(0)
	s_mov_b32 s100, 0
	s_barrier
	s_nop 0
	v_mfma_f32_16x16x32_bf16 v[60:63], v[158:161], v[174:177], 0
	v_mfma_f32_16x16x32_bf16 v[52:55], v[158:161], v[182:185], 0
	v_mfma_f32_16x16x32_bf16 v[44:47], v[158:161], v[210:213], 0
	v_mfma_f32_16x16x32_bf16 v[36:39], v[158:161], v[218:221], 0
	v_mfma_f32_16x16x32_bf16 v[32:35], v[166:169], v[218:221], 0
	v_mfma_f32_16x16x32_bf16 v[40:43], v[166:169], v[210:213], 0
	v_mfma_f32_16x16x32_bf16 v[48:51], v[166:169], v[182:185], 0
	v_mfma_f32_16x16x32_bf16 v[56:59], v[166:169], v[174:177], 0
	v_mfma_f32_16x16x32_bf16 v[60:63], v[162:165], v[178:181], v[60:63]
	v_mfma_f32_16x16x32_bf16 v[52:55], v[162:165], v[206:209], v[52:55]
	v_mfma_f32_16x16x32_bf16 v[44:47], v[162:165], v[214:217], v[44:47]
	v_mfma_f32_16x16x32_bf16 v[36:39], v[162:165], v[222:225], v[36:39]
	v_mfma_f32_16x16x32_bf16 v[32:35], v[170:173], v[222:225], v[32:35]
	v_mfma_f32_16x16x32_bf16 v[40:43], v[170:173], v[214:217], v[40:43]
	v_mfma_f32_16x16x32_bf16 v[48:51], v[170:173], v[206:209], v[48:51]
	v_mfma_f32_16x16x32_bf16 v[56:59], v[170:173], v[178:181], v[56:59]
	v_mfma_f32_16x16x32_bf16 v[28:31], v[226:229], v[174:177], 0
	v_mfma_f32_16x16x32_bf16 v[20:23], v[226:229], v[182:185], 0
	v_mfma_f32_16x16x32_bf16 v[12:15], v[226:229], v[210:213], 0
	v_mfma_f32_16x16x32_bf16 v[4:7], v[226:229], v[218:221], 0
	v_mfma_f32_16x16x32_bf16 v[0:3], v[234:237], v[218:221], 0
	v_mfma_f32_16x16x32_bf16 v[8:11], v[234:237], v[210:213], 0
	v_mfma_f32_16x16x32_bf16 v[16:19], v[234:237], v[182:185], 0
	v_mfma_f32_16x16x32_bf16 v[24:27], v[234:237], v[174:177], 0
	v_mfma_f32_16x16x32_bf16 v[28:31], v[230:233], v[178:181], v[28:31]
	v_mfma_f32_16x16x32_bf16 v[20:23], v[230:233], v[206:209], v[20:23]
	v_mfma_f32_16x16x32_bf16 v[12:15], v[230:233], v[214:217], v[12:15]
	v_mfma_f32_16x16x32_bf16 v[4:7], v[230:233], v[222:225], v[4:7]
	v_mfma_f32_16x16x32_bf16 v[0:3], v[238:241], v[222:225], v[0:3]
	v_mfma_f32_16x16x32_bf16 v[8:11], v[238:241], v[214:217], v[8:11]
	v_mfma_f32_16x16x32_bf16 v[16:19], v[238:241], v[206:209], v[16:19]
	v_mfma_f32_16x16x32_bf16 v[24:27], v[238:241], v[178:181], v[24:27]
	s_barrier
	s_add_i32 s6, 0, 0x18000
	v_add_u32_e32 v170, s6, v154
	ds_read_b128 v[158:161], v170
	ds_read_b128 v[162:165], v170 offset:1024
	ds_read_b128 v[166:169], v170 offset:2048
	ds_read_b128 v[170:173], v170 offset:3072
	s_add_u32 s58, s58, 0x40000
	s_addc_u32 s59, s59, 0
	s_mov_b32 m0, s70
	v_lshl_add_u64 v[226:227], s[58:59], 0, v[128:129]
	ds_read_b128 v[174:177], v157 offset:32768
	ds_read_b128 v[178:181], v157 offset:33792
	ds_read_b128 v[182:185], v157 offset:34816
	ds_read_b128 v[206:209], v157 offset:35840
	ds_read_b128 v[210:213], v157 offset:36864
	ds_read_b128 v[214:217], v157 offset:37888
	ds_read_b128 v[218:221], v157 offset:38912
	ds_read_b128 v[222:225], v157 offset:39936
	global_load_lds_dwordx4 v[226:227], off
	v_lshl_add_u64 v[226:227], s[58:59], 0, v[130:131]
	s_mov_b32 m0, s71
	s_nop 0
	global_load_lds_dwordx4 v[226:227], off
	s_add_i32 s19, 0, 0x1c000
	v_add_u32_e32 v192, s19, v154
	ds_read_b128 v[226:229], v192
	ds_read_b128 v[230:233], v192 offset:1024
	ds_read_b128 v[234:237], v192 offset:2048
	ds_read_b128 v[238:241], v192 offset:3072
	s_waitcnt vmcnt(8)
	s_waitcnt lgkmcnt(0)
	s_barrier
	v_mfma_f32_16x16x32_bf16 v[124:127], v[158:161], v[174:177], v[124:127]
	v_mfma_f32_16x16x32_bf16 v[116:119], v[158:161], v[182:185], v[116:119]
	v_mfma_f32_16x16x32_bf16 v[108:111], v[158:161], v[210:213], v[108:111]
	v_mfma_f32_16x16x32_bf16 v[100:103], v[158:161], v[218:221], v[100:103]
	v_mfma_f32_16x16x32_bf16 v[96:99], v[166:169], v[218:221], v[96:99]
	v_mfma_f32_16x16x32_bf16 v[104:107], v[166:169], v[210:213], v[104:107]
	v_mfma_f32_16x16x32_bf16 v[112:115], v[166:169], v[182:185], v[112:115]
	v_mfma_f32_16x16x32_bf16 v[120:123], v[166:169], v[174:177], v[120:123]
	v_mfma_f32_16x16x32_bf16 v[124:127], v[162:165], v[178:181], v[124:127]
	v_mfma_f32_16x16x32_bf16 v[116:119], v[162:165], v[206:209], v[116:119]
	v_mfma_f32_16x16x32_bf16 v[108:111], v[162:165], v[214:217], v[108:111]
	v_mfma_f32_16x16x32_bf16 v[100:103], v[162:165], v[222:225], v[100:103]
	v_mfma_f32_16x16x32_bf16 v[96:99], v[170:173], v[222:225], v[96:99]
	v_mfma_f32_16x16x32_bf16 v[104:107], v[170:173], v[214:217], v[104:107]
	v_mfma_f32_16x16x32_bf16 v[112:115], v[170:173], v[206:209], v[112:115]
	v_mfma_f32_16x16x32_bf16 v[120:123], v[170:173], v[178:181], v[120:123]
	v_mfma_f32_16x16x32_bf16 v[92:95], v[226:229], v[174:177], v[92:95]
	v_mfma_f32_16x16x32_bf16 v[84:87], v[226:229], v[182:185], v[84:87]
	v_mfma_f32_16x16x32_bf16 v[76:79], v[226:229], v[210:213], v[76:79]
	v_mfma_f32_16x16x32_bf16 v[68:71], v[226:229], v[218:221], v[68:71]
	v_mfma_f32_16x16x32_bf16 v[64:67], v[234:237], v[218:221], v[64:67]
	v_mfma_f32_16x16x32_bf16 v[72:75], v[234:237], v[210:213], v[72:75]
	v_mfma_f32_16x16x32_bf16 v[80:83], v[234:237], v[182:185], v[80:83]
	v_mfma_f32_16x16x32_bf16 v[88:91], v[234:237], v[174:177], v[88:91]
	v_mfma_f32_16x16x32_bf16 v[92:95], v[230:233], v[178:181], v[92:95]
	v_mfma_f32_16x16x32_bf16 v[84:87], v[230:233], v[206:209], v[84:87]
	v_mfma_f32_16x16x32_bf16 v[76:79], v[230:233], v[214:217], v[76:79]
	v_mfma_f32_16x16x32_bf16 v[68:71], v[230:233], v[222:225], v[68:71]
	v_mfma_f32_16x16x32_bf16 v[64:67], v[238:241], v[222:225], v[64:67]
	v_mfma_f32_16x16x32_bf16 v[72:75], v[238:241], v[214:217], v[72:75]
	v_mfma_f32_16x16x32_bf16 v[80:83], v[238:241], v[206:209], v[80:83]
	v_mfma_f32_16x16x32_bf16 v[88:91], v[238:241], v[178:181], v[88:91]
	s_barrier
	s_add_i32 s6, s6, s57
	v_lshl_add_u64 v[146:147], v[146:147], 0, s[36:37]
	s_mov_b32 m0, s6
	s_nop 0
	global_load_lds_dwordx4 v[146:147], off
	v_lshl_add_u64 v[146:147], v[148:149], 0, s[36:37]
	s_add_i32 m0, s6, 0x2000
	s_nop 0
	global_load_lds_dwordx4 v[146:147], off
	s_mov_b32 m0, s72
	v_lshl_add_u64 v[146:147], v[194:195], 0, s[36:37]
	ds_read_b128 v[174:177], v157 offset:49152
	ds_read_b128 v[178:181], v157 offset:50176
	ds_read_b128 v[182:185], v157 offset:51200
	ds_read_b128 v[206:209], v157 offset:52224
	ds_read_b128 v[210:213], v157 offset:53248
	ds_read_b128 v[214:217], v157 offset:54272
	ds_read_b128 v[218:221], v157 offset:55296
	ds_read_b128 v[222:225], v157 offset:56320
	global_load_lds_dwordx4 v[146:147], off
	v_lshl_add_u64 v[146:147], v[196:197], 0, s[36:37]
	s_mov_b32 m0, s73
	s_nop 0
	global_load_lds_dwordx4 v[146:147], off
	s_add_u32 s54, s54, 0x40080
	s_addc_u32 s55, s55, 0
	s_add_i32 s6, s19, s57
	v_lshl_add_u64 v[146:147], s[54:55], 0, v[140:141]
	s_mov_b32 m0, s6
	s_nop 0
	global_load_lds_dwordx4 v[146:147], off
	v_lshl_add_u64 v[146:147], s[54:55], 0, v[132:133]
	s_add_i32 m0, s6, 0x2000
	s_nop 0
	global_load_lds_dwordx4 v[146:147], off
	s_waitcnt vmcnt(8)
	s_waitcnt lgkmcnt(0)
	s_barrier
	v_mfma_f32_16x16x32_bf16 v[60:63], v[158:161], v[174:177], v[60:63]
	v_mfma_f32_16x16x32_bf16 v[52:55], v[158:161], v[182:185], v[52:55]
	v_mfma_f32_16x16x32_bf16 v[44:47], v[158:161], v[210:213], v[44:47]
	v_mfma_f32_16x16x32_bf16 v[36:39], v[158:161], v[218:221], v[36:39]
	v_mfma_f32_16x16x32_bf16 v[32:35], v[166:169], v[218:221], v[32:35]
	v_mfma_f32_16x16x32_bf16 v[40:43], v[166:169], v[210:213], v[40:43]
	v_mfma_f32_16x16x32_bf16 v[48:51], v[166:169], v[182:185], v[48:51]
	v_mfma_f32_16x16x32_bf16 v[56:59], v[166:169], v[174:177], v[56:59]
	v_mfma_f32_16x16x32_bf16 v[60:63], v[162:165], v[178:181], v[60:63]
	v_mfma_f32_16x16x32_bf16 v[52:55], v[162:165], v[206:209], v[52:55]
	v_mfma_f32_16x16x32_bf16 v[44:47], v[162:165], v[214:217], v[44:47]
	v_mfma_f32_16x16x32_bf16 v[36:39], v[162:165], v[222:225], v[36:39]
	v_mfma_f32_16x16x32_bf16 v[32:35], v[170:173], v[222:225], v[32:35]
	v_mfma_f32_16x16x32_bf16 v[40:43], v[170:173], v[214:217], v[40:43]
	v_mfma_f32_16x16x32_bf16 v[48:51], v[170:173], v[206:209], v[48:51]
	v_mfma_f32_16x16x32_bf16 v[56:59], v[170:173], v[178:181], v[56:59]
	v_mfma_f32_16x16x32_bf16 v[28:31], v[226:229], v[174:177], v[28:31]
	v_mfma_f32_16x16x32_bf16 v[20:23], v[226:229], v[182:185], v[20:23]
	v_mfma_f32_16x16x32_bf16 v[12:15], v[226:229], v[210:213], v[12:15]
	v_mfma_f32_16x16x32_bf16 v[4:7], v[226:229], v[218:221], v[4:7]
	v_mfma_f32_16x16x32_bf16 v[0:3], v[234:237], v[218:221], v[0:3]
	v_mfma_f32_16x16x32_bf16 v[8:11], v[234:237], v[210:213], v[8:11]
	v_mfma_f32_16x16x32_bf16 v[16:19], v[234:237], v[182:185], v[16:19]
	v_mfma_f32_16x16x32_bf16 v[24:27], v[234:237], v[174:177], v[24:27]
	v_mfma_f32_16x16x32_bf16 v[28:31], v[230:233], v[178:181], v[28:31]
	v_mfma_f32_16x16x32_bf16 v[20:23], v[230:233], v[206:209], v[20:23]
	v_mfma_f32_16x16x32_bf16 v[12:15], v[230:233], v[214:217], v[12:15]
	v_mfma_f32_16x16x32_bf16 v[4:7], v[230:233], v[222:225], v[4:7]
	v_mfma_f32_16x16x32_bf16 v[0:3], v[238:241], v[222:225], v[0:3]
	v_mfma_f32_16x16x32_bf16 v[8:11], v[238:241], v[214:217], v[8:11]
	v_mfma_f32_16x16x32_bf16 v[16:19], v[238:241], v[206:209], v[16:19]
	v_mfma_f32_16x16x32_bf16 v[24:27], v[238:241], v[178:181], v[24:27]
	s_add_i32 s81, s81, 2
	s_add_u32 s52, s52, 0x100
	s_addc_u32 s53, s53, 0
	s_cmp_gt_u32 s81, 13
	s_barrier
.LBB0_386:
	s_add_u32 s6, s28, s52
	s_addc_u32 s19, s29, s53
	s_add_u32 s6, s6, 0x100
	s_addc_u32 s19, s19, 0
	s_add_u32 s23, s10, s52
	s_addc_u32 s54, s11, s53
	s_add_i32 s82, 0, 0x10000
	v_add_u32_e32 v146, s82, v154
	ds_read_b128 v[158:161], v146
	ds_read_b128 v[162:165], v146 offset:1024
	ds_read_b128 v[166:169], v146 offset:2048
	ds_read_b128 v[170:173], v146 offset:3072
	s_cmpk_eq_i32 s52, 0x700
	s_cselect_b32 s59, s12, s19
	s_cselect_b32 s58, s35, s6
	s_cselect_b32 s55, s39, s54
	s_cselect_b32 s54, s47, s23
	v_lshl_add_u64 v[146:147], v[150:151], 0, s[52:53]
	s_add_i32 m0, s68, 0xc000
	ds_read_b128 v[174:177], v157
	ds_read_b128 v[178:181], v157 offset:1024
	ds_read_b128 v[182:185], v157 offset:2048
	ds_read_b128 v[206:209], v157 offset:3072
	ds_read_b128 v[210:213], v157 offset:4096
	ds_read_b128 v[214:217], v157 offset:5120
	ds_read_b128 v[218:221], v157 offset:6144
	ds_read_b128 v[222:225], v157 offset:7168
	global_load_lds_dwordx4 v[146:147], off
	v_lshl_add_u64 v[146:147], v[152:153], 0, s[52:53]
	s_add_i32 m0, s68, 0xe000
	s_nop 0
	global_load_lds_dwordx4 v[146:147], off
	s_add_i32 s6, 0, 0x14000
	v_add_u32_e32 v146, s6, v154
	ds_read_b128 v[226:229], v146
	ds_read_b128 v[230:233], v146 offset:1024
	ds_read_b128 v[234:237], v146 offset:2048
	ds_read_b128 v[238:241], v146 offset:3072
	s_waitcnt vmcnt(8)
	s_waitcnt lgkmcnt(0)
	s_barrier
	v_mfma_f32_16x16x32_bf16 v[124:127], v[158:161], v[174:177], v[124:127]
	v_mfma_f32_16x16x32_bf16 v[116:119], v[158:161], v[182:185], v[116:119]
	v_mfma_f32_16x16x32_bf16 v[108:111], v[158:161], v[210:213], v[108:111]
	v_mfma_f32_16x16x32_bf16 v[100:103], v[158:161], v[218:221], v[100:103]
	v_mfma_f32_16x16x32_bf16 v[96:99], v[166:169], v[218:221], v[96:99]
	v_mfma_f32_16x16x32_bf16 v[104:107], v[166:169], v[210:213], v[104:107]
	v_mfma_f32_16x16x32_bf16 v[112:115], v[166:169], v[182:185], v[112:115]
	v_mfma_f32_16x16x32_bf16 v[120:123], v[166:169], v[174:177], v[120:123]
	v_mfma_f32_16x16x32_bf16 v[124:127], v[162:165], v[178:181], v[124:127]
	v_mfma_f32_16x16x32_bf16 v[116:119], v[162:165], v[206:209], v[116:119]
	v_mfma_f32_16x16x32_bf16 v[108:111], v[162:165], v[214:217], v[108:111]
	v_mfma_f32_16x16x32_bf16 v[100:103], v[162:165], v[222:225], v[100:103]
	v_mfma_f32_16x16x32_bf16 v[96:99], v[170:173], v[222:225], v[96:99]
	v_mfma_f32_16x16x32_bf16 v[104:107], v[170:173], v[214:217], v[104:107]
	v_mfma_f32_16x16x32_bf16 v[112:115], v[170:173], v[206:209], v[112:115]
	v_mfma_f32_16x16x32_bf16 v[120:123], v[170:173], v[178:181], v[120:123]
	v_mfma_f32_16x16x32_bf16 v[92:95], v[226:229], v[174:177], v[92:95]
	v_mfma_f32_16x16x32_bf16 v[84:87], v[226:229], v[182:185], v[84:87]
	v_mfma_f32_16x16x32_bf16 v[76:79], v[226:229], v[210:213], v[76:79]
	v_mfma_f32_16x16x32_bf16 v[68:71], v[226:229], v[218:221], v[68:71]
	v_mfma_f32_16x16x32_bf16 v[64:67], v[234:237], v[218:221], v[64:67]
	v_mfma_f32_16x16x32_bf16 v[72:75], v[234:237], v[210:213], v[72:75]
	v_mfma_f32_16x16x32_bf16 v[80:83], v[234:237], v[182:185], v[80:83]
	v_mfma_f32_16x16x32_bf16 v[88:91], v[234:237], v[174:177], v[88:91]
	v_mfma_f32_16x16x32_bf16 v[92:95], v[230:233], v[178:181], v[92:95]
	v_mfma_f32_16x16x32_bf16 v[84:87], v[230:233], v[206:209], v[84:87]
	v_mfma_f32_16x16x32_bf16 v[76:79], v[230:233], v[214:217], v[76:79]
	v_mfma_f32_16x16x32_bf16 v[68:71], v[230:233], v[222:225], v[68:71]
	v_mfma_f32_16x16x32_bf16 v[64:67], v[238:241], v[222:225], v[64:67]
	v_mfma_f32_16x16x32_bf16 v[72:75], v[238:241], v[214:217], v[72:75]
	v_mfma_f32_16x16x32_bf16 v[80:83], v[238:241], v[206:209], v[80:83]
	v_mfma_f32_16x16x32_bf16 v[88:91], v[238:241], v[178:181], v[88:91]
	s_barrier
	s_add_i32 s19, s82, s57
	v_lshl_add_u64 v[146:147], s[54:55], 0, v[140:141]
	s_mov_b32 m0, s19
	v_lshl_add_u64 v[148:149], s[54:55], 0, v[132:133]
	global_load_lds_dwordx4 v[146:147], off
	s_add_i32 m0, s19, 0x2000
	s_nop 0
	global_load_lds_dwordx4 v[148:149], off
	s_mov_b32 m0, s68
	v_lshl_add_u64 v[194:195], s[58:59], 0, v[128:129]
	ds_read_b128 v[174:177], v157 offset:16384
	ds_read_b128 v[178:181], v157 offset:17408
	ds_read_b128 v[182:185], v157 offset:18432
	ds_read_b128 v[206:209], v157 offset:19456
	ds_read_b128 v[210:213], v157 offset:20480
	ds_read_b128 v[214:217], v157 offset:21504
	ds_read_b128 v[218:221], v157 offset:22528
	ds_read_b128 v[222:225], v157 offset:23552
	global_load_lds_dwordx4 v[194:195], off
	v_lshl_add_u64 v[196:197], s[58:59], 0, v[130:131]
	s_mov_b32 m0, s69
	s_nop 0
	global_load_lds_dwordx4 v[196:197], off
	s_add_u32 s82, s54, 0x40000
	s_addc_u32 s83, s55, 0
	s_add_i32 s6, s6, s57
	v_lshl_add_u64 v[250:251], s[82:83], 0, v[140:141]
	s_mov_b32 m0, s6
	s_nop 0
	global_load_lds_dwordx4 v[250:251], off
	v_lshl_add_u64 v[250:251], s[82:83], 0, v[132:133]
	s_add_i32 m0, s6, 0x2000
	s_nop 0
	global_load_lds_dwordx4 v[250:251], off
	s_nop 0
	s_waitcnt vmcnt(8)
	s_waitcnt lgkmcnt(0)
	s_barrier
	v_mfma_f32_16x16x32_bf16 v[60:63], v[158:161], v[174:177], v[60:63]
	v_mfma_f32_16x16x32_bf16 v[52:55], v[158:161], v[182:185], v[52:55]
	v_mfma_f32_16x16x32_bf16 v[44:47], v[158:161], v[210:213], v[44:47]
	v_mfma_f32_16x16x32_bf16 v[36:39], v[158:161], v[218:221], v[36:39]
	v_mfma_f32_16x16x32_bf16 v[32:35], v[166:169], v[218:221], v[32:35]
	v_mfma_f32_16x16x32_bf16 v[40:43], v[166:169], v[210:213], v[40:43]
	v_mfma_f32_16x16x32_bf16 v[48:51], v[166:169], v[182:185], v[48:51]
	v_mfma_f32_16x16x32_bf16 v[56:59], v[166:169], v[174:177], v[56:59]
	v_mfma_f32_16x16x32_bf16 v[60:63], v[162:165], v[178:181], v[60:63]
	v_mfma_f32_16x16x32_bf16 v[52:55], v[162:165], v[206:209], v[52:55]
	v_mfma_f32_16x16x32_bf16 v[44:47], v[162:165], v[214:217], v[44:47]
	v_mfma_f32_16x16x32_bf16 v[36:39], v[162:165], v[222:225], v[36:39]
	v_mfma_f32_16x16x32_bf16 v[32:35], v[170:173], v[222:225], v[32:35]
	v_mfma_f32_16x16x32_bf16 v[40:43], v[170:173], v[214:217], v[40:43]
	v_mfma_f32_16x16x32_bf16 v[48:51], v[170:173], v[206:209], v[48:51]
	v_mfma_f32_16x16x32_bf16 v[56:59], v[170:173], v[178:181], v[56:59]
	v_mfma_f32_16x16x32_bf16 v[28:31], v[226:229], v[174:177], v[28:31]
	v_mfma_f32_16x16x32_bf16 v[20:23], v[226:229], v[182:185], v[20:23]
	v_mfma_f32_16x16x32_bf16 v[12:15], v[226:229], v[210:213], v[12:15]
	v_mfma_f32_16x16x32_bf16 v[4:7], v[226:229], v[218:221], v[4:7]
	v_mfma_f32_16x16x32_bf16 v[0:3], v[234:237], v[218:221], v[0:3]
	v_mfma_f32_16x16x32_bf16 v[8:11], v[234:237], v[210:213], v[8:11]
	v_mfma_f32_16x16x32_bf16 v[16:19], v[234:237], v[182:185], v[16:19]
	v_mfma_f32_16x16x32_bf16 v[24:27], v[234:237], v[174:177], v[24:27]
	v_mfma_f32_16x16x32_bf16 v[28:31], v[230:233], v[178:181], v[28:31]
	v_mfma_f32_16x16x32_bf16 v[20:23], v[230:233], v[206:209], v[20:23]
	v_mfma_f32_16x16x32_bf16 v[12:15], v[230:233], v[214:217], v[12:15]
	v_mfma_f32_16x16x32_bf16 v[4:7], v[230:233], v[222:225], v[4:7]
	v_mfma_f32_16x16x32_bf16 v[0:3], v[238:241], v[222:225], v[0:3]
	v_mfma_f32_16x16x32_bf16 v[8:11], v[238:241], v[214:217], v[8:11]
	v_mfma_f32_16x16x32_bf16 v[16:19], v[238:241], v[206:209], v[16:19]
	v_mfma_f32_16x16x32_bf16 v[24:27], v[238:241], v[178:181], v[24:27]
	s_barrier
	s_add_i32 s6, 0, 0x18000
	v_add_u32_e32 v170, s6, v154
	ds_read_b128 v[158:161], v170
	ds_read_b128 v[162:165], v170 offset:1024
	ds_read_b128 v[166:169], v170 offset:2048
	ds_read_b128 v[170:173], v170 offset:3072
	s_add_u32 s58, s58, 0x40000
	s_addc_u32 s59, s59, 0
	s_mov_b32 m0, s70
	v_lshl_add_u64 v[226:227], s[58:59], 0, v[128:129]
	ds_read_b128 v[174:177], v157 offset:32768
	ds_read_b128 v[178:181], v157 offset:33792
	ds_read_b128 v[182:185], v157 offset:34816
	ds_read_b128 v[206:209], v157 offset:35840
	ds_read_b128 v[210:213], v157 offset:36864
	ds_read_b128 v[214:217], v157 offset:37888
	ds_read_b128 v[218:221], v157 offset:38912
	ds_read_b128 v[222:225], v157 offset:39936
	global_load_lds_dwordx4 v[226:227], off
	v_lshl_add_u64 v[226:227], s[58:59], 0, v[130:131]
	s_mov_b32 m0, s71
	s_nop 0
	global_load_lds_dwordx4 v[226:227], off
	s_add_i32 s19, 0, 0x1c000
	v_add_u32_e32 v192, s19, v154
	ds_read_b128 v[226:229], v192
	ds_read_b128 v[230:233], v192 offset:1024
	ds_read_b128 v[234:237], v192 offset:2048
	ds_read_b128 v[238:241], v192 offset:3072
	s_waitcnt vmcnt(8)
	s_waitcnt lgkmcnt(0)
	s_barrier
	v_mfma_f32_16x16x32_bf16 v[124:127], v[158:161], v[174:177], v[124:127]
	v_mfma_f32_16x16x32_bf16 v[116:119], v[158:161], v[182:185], v[116:119]
	v_mfma_f32_16x16x32_bf16 v[108:111], v[158:161], v[210:213], v[108:111]
	v_mfma_f32_16x16x32_bf16 v[100:103], v[158:161], v[218:221], v[100:103]
	v_mfma_f32_16x16x32_bf16 v[96:99], v[166:169], v[218:221], v[96:99]
	v_mfma_f32_16x16x32_bf16 v[104:107], v[166:169], v[210:213], v[104:107]
	v_mfma_f32_16x16x32_bf16 v[112:115], v[166:169], v[182:185], v[112:115]
	v_mfma_f32_16x16x32_bf16 v[120:123], v[166:169], v[174:177], v[120:123]
	v_mfma_f32_16x16x32_bf16 v[124:127], v[162:165], v[178:181], v[124:127]
	v_mfma_f32_16x16x32_bf16 v[116:119], v[162:165], v[206:209], v[116:119]
	v_mfma_f32_16x16x32_bf16 v[108:111], v[162:165], v[214:217], v[108:111]
	v_mfma_f32_16x16x32_bf16 v[100:103], v[162:165], v[222:225], v[100:103]
	v_mfma_f32_16x16x32_bf16 v[96:99], v[170:173], v[222:225], v[96:99]
	v_mfma_f32_16x16x32_bf16 v[104:107], v[170:173], v[214:217], v[104:107]
	v_mfma_f32_16x16x32_bf16 v[112:115], v[170:173], v[206:209], v[112:115]
	v_mfma_f32_16x16x32_bf16 v[120:123], v[170:173], v[178:181], v[120:123]
	v_mfma_f32_16x16x32_bf16 v[92:95], v[226:229], v[174:177], v[92:95]
	v_mfma_f32_16x16x32_bf16 v[84:87], v[226:229], v[182:185], v[84:87]
	v_mfma_f32_16x16x32_bf16 v[76:79], v[226:229], v[210:213], v[76:79]
	v_mfma_f32_16x16x32_bf16 v[68:71], v[226:229], v[218:221], v[68:71]
	v_mfma_f32_16x16x32_bf16 v[64:67], v[234:237], v[218:221], v[64:67]
	v_mfma_f32_16x16x32_bf16 v[72:75], v[234:237], v[210:213], v[72:75]
	v_mfma_f32_16x16x32_bf16 v[80:83], v[234:237], v[182:185], v[80:83]
	v_mfma_f32_16x16x32_bf16 v[88:91], v[234:237], v[174:177], v[88:91]
	v_mfma_f32_16x16x32_bf16 v[92:95], v[230:233], v[178:181], v[92:95]
	v_mfma_f32_16x16x32_bf16 v[84:87], v[230:233], v[206:209], v[84:87]
	v_mfma_f32_16x16x32_bf16 v[76:79], v[230:233], v[214:217], v[76:79]
	v_mfma_f32_16x16x32_bf16 v[68:71], v[230:233], v[222:225], v[68:71]
	v_mfma_f32_16x16x32_bf16 v[64:67], v[238:241], v[222:225], v[64:67]
	v_mfma_f32_16x16x32_bf16 v[72:75], v[238:241], v[214:217], v[72:75]
	v_mfma_f32_16x16x32_bf16 v[80:83], v[238:241], v[206:209], v[80:83]
	v_mfma_f32_16x16x32_bf16 v[88:91], v[238:241], v[178:181], v[88:91]
	s_barrier
	s_add_i32 s6, s6, s57
	v_lshl_add_u64 v[146:147], v[146:147], 0, s[36:37]
	s_mov_b32 m0, s6
	s_nop 0
	global_load_lds_dwordx4 v[146:147], off
	v_lshl_add_u64 v[146:147], v[148:149], 0, s[36:37]
	s_add_i32 m0, s6, 0x2000
	s_nop 0
	global_load_lds_dwordx4 v[146:147], off
	s_mov_b32 m0, s72
	v_lshl_add_u64 v[146:147], v[194:195], 0, s[36:37]
	ds_read_b128 v[174:177], v157 offset:49152
	ds_read_b128 v[178:181], v157 offset:50176
	ds_read_b128 v[182:185], v157 offset:51200
	ds_read_b128 v[206:209], v157 offset:52224
	ds_read_b128 v[210:213], v157 offset:53248
	ds_read_b128 v[214:217], v157 offset:54272
	ds_read_b128 v[218:221], v157 offset:55296
	ds_read_b128 v[222:225], v157 offset:56320
	global_load_lds_dwordx4 v[146:147], off
	v_lshl_add_u64 v[146:147], v[196:197], 0, s[36:37]
	s_mov_b32 m0, s73
	s_nop 0
	global_load_lds_dwordx4 v[146:147], off
	s_add_u32 s54, s54, 0x40080
	s_addc_u32 s55, s55, 0
	s_add_i32 s6, s19, s57
	v_lshl_add_u64 v[146:147], s[54:55], 0, v[140:141]
	s_mov_b32 m0, s6
	s_nop 0
	global_load_lds_dwordx4 v[146:147], off
	v_lshl_add_u64 v[146:147], s[54:55], 0, v[132:133]
	s_add_i32 m0, s6, 0x2000
	s_nop 0
	global_load_lds_dwordx4 v[146:147], off
	s_waitcnt vmcnt(8)
	s_waitcnt lgkmcnt(0)
	s_barrier
	v_mfma_f32_16x16x32_bf16 v[60:63], v[158:161], v[174:177], v[60:63]
	v_mfma_f32_16x16x32_bf16 v[52:55], v[158:161], v[182:185], v[52:55]
	v_mfma_f32_16x16x32_bf16 v[44:47], v[158:161], v[210:213], v[44:47]
	v_mfma_f32_16x16x32_bf16 v[36:39], v[158:161], v[218:221], v[36:39]
	v_mfma_f32_16x16x32_bf16 v[32:35], v[166:169], v[218:221], v[32:35]
	v_mfma_f32_16x16x32_bf16 v[40:43], v[166:169], v[210:213], v[40:43]
	v_mfma_f32_16x16x32_bf16 v[48:51], v[166:169], v[182:185], v[48:51]
	v_mfma_f32_16x16x32_bf16 v[56:59], v[166:169], v[174:177], v[56:59]
	v_mfma_f32_16x16x32_bf16 v[60:63], v[162:165], v[178:181], v[60:63]
	v_mfma_f32_16x16x32_bf16 v[52:55], v[162:165], v[206:209], v[52:55]
	v_mfma_f32_16x16x32_bf16 v[44:47], v[162:165], v[214:217], v[44:47]
	v_mfma_f32_16x16x32_bf16 v[36:39], v[162:165], v[222:225], v[36:39]
	v_mfma_f32_16x16x32_bf16 v[32:35], v[170:173], v[222:225], v[32:35]
	v_mfma_f32_16x16x32_bf16 v[40:43], v[170:173], v[214:217], v[40:43]
	v_mfma_f32_16x16x32_bf16 v[48:51], v[170:173], v[206:209], v[48:51]
	v_mfma_f32_16x16x32_bf16 v[56:59], v[170:173], v[178:181], v[56:59]
	v_mfma_f32_16x16x32_bf16 v[28:31], v[226:229], v[174:177], v[28:31]
	v_mfma_f32_16x16x32_bf16 v[20:23], v[226:229], v[182:185], v[20:23]
	v_mfma_f32_16x16x32_bf16 v[12:15], v[226:229], v[210:213], v[12:15]
	v_mfma_f32_16x16x32_bf16 v[4:7], v[226:229], v[218:221], v[4:7]
	v_mfma_f32_16x16x32_bf16 v[0:3], v[234:237], v[218:221], v[0:3]
	v_mfma_f32_16x16x32_bf16 v[8:11], v[234:237], v[210:213], v[8:11]
	v_mfma_f32_16x16x32_bf16 v[16:19], v[234:237], v[182:185], v[16:19]
	v_mfma_f32_16x16x32_bf16 v[24:27], v[234:237], v[174:177], v[24:27]
	v_mfma_f32_16x16x32_bf16 v[28:31], v[230:233], v[178:181], v[28:31]
	v_mfma_f32_16x16x32_bf16 v[20:23], v[230:233], v[206:209], v[20:23]
	v_mfma_f32_16x16x32_bf16 v[12:15], v[230:233], v[214:217], v[12:15]
	v_mfma_f32_16x16x32_bf16 v[4:7], v[230:233], v[222:225], v[4:7]
	v_mfma_f32_16x16x32_bf16 v[0:3], v[238:241], v[222:225], v[0:3]
	v_mfma_f32_16x16x32_bf16 v[8:11], v[238:241], v[214:217], v[8:11]
	v_mfma_f32_16x16x32_bf16 v[16:19], v[238:241], v[206:209], v[16:19]
	v_mfma_f32_16x16x32_bf16 v[24:27], v[238:241], v[178:181], v[24:27]
	s_add_i32 s81, s81, 2
	s_add_u32 s52, s52, 0x100
	s_addc_u32 s53, s53, 0
	s_cmp_gt_u32 s81, 13
	s_barrier
	s_cbranch_scc0 .LBB0_386
	s_mov_b32 s100, 1
	v_lshl_add_u32 v158, s75, 10, v155
	ds_read2_b32 v[146:147], v158 offset1:16
	s_add_u32 s52, s10, 0xffffff00
	s_addc_u32 s53, s11, -1
	s_ashr_i32 s35, s34, 31
	s_lshl_b64 s[10:11], s[34:35], 8
	s_waitcnt lgkmcnt(0)
	v_mul_f32_e32 v184, 0xbfb8aa3b, v146
	v_mul_f32_e32 v206, v146, v146
	v_pk_mul_f32 v[168:169], v[124:125], v[184:185] op_sel_hi:[1,0]
	v_pk_mul_f32 v[170:171], v[126:127], v[184:185] op_sel_hi:[1,0]
	v_pk_mul_f32 v[172:173], v[120:121], v[184:185] op_sel_hi:[1,0]
	v_pk_mul_f32 v[174:175], v[122:123], v[184:185] op_sel_hi:[1,0]
	v_exp_f32_e32 v168, v168
	v_exp_f32_e32 v169, v169
	v_exp_f32_e32 v170, v170
	v_exp_f32_e32 v171, v171
	v_exp_f32_e32 v172, v172
	v_exp_f32_e32 v173, v173
	v_exp_f32_e32 v174, v174
	v_exp_f32_e32 v175, v175
	v_pk_mul_f32 v[176:177], v[124:125], v[92:93]
	v_pk_mul_f32 v[178:179], v[126:127], v[94:95]
	v_pk_mul_f32 v[180:181], v[120:121], v[88:89]
	v_pk_mul_f32 v[182:183], v[122:123], v[90:91]
	v_pk_add_f32 v[168:169], v[168:169], 1.0 op_sel_hi:[1,0]
	v_pk_add_f32 v[170:171], v[170:171], 1.0 op_sel_hi:[1,0]
	v_pk_add_f32 v[172:173], v[172:173], 1.0 op_sel_hi:[1,0]
	v_pk_add_f32 v[174:175], v[174:175], 1.0 op_sel_hi:[1,0]
	v_rcp_f32_e32 v168, v168
	v_rcp_f32_e32 v169, v169
	v_rcp_f32_e32 v170, v170
	v_rcp_f32_e32 v171, v171
	v_rcp_f32_e32 v172, v172
	v_rcp_f32_e32 v173, v173
	v_rcp_f32_e32 v174, v174
	v_rcp_f32_e32 v175, v175
	v_pk_mul_f32 v[176:177], v[176:177], v[206:207] op_sel_hi:[1,0]
	v_pk_mul_f32 v[178:179], v[178:179], v[206:207] op_sel_hi:[1,0]
	v_pk_mul_f32 v[180:181], v[180:181], v[206:207] op_sel_hi:[1,0]
	v_pk_mul_f32 v[182:183], v[182:183], v[206:207] op_sel_hi:[1,0]
	v_pk_mul_f32 v[176:177], v[176:177], v[168:169]
	v_pk_mul_f32 v[178:179], v[178:179], v[170:171]
	v_pk_mul_f32 v[180:181], v[180:181], v[172:173]
	v_pk_mul_f32 v[182:183], v[182:183], v[174:175]
	v_cvt_pk_bf16_f32 v160, v176, v177
	v_cvt_pk_bf16_f32 v161, v178, v179
	v_cvt_pk_bf16_f32 v162, v180, v181
	v_cvt_pk_bf16_f32 v163, v182, v183
	v_lshl_add_u64 v[152:153], v[134:135], 0, s[10:11]
	s_movk_i32 s6, 0x1600
	v_lshl_or_b32 v150, s74, 7, v156
	v_ashrrev_i32_e32 v151, 31, v150
	s_nop 1
	v_mov_b64_e32 v[148:149], s[30:31]
	v_mad_u64_u32 v[148:149], s[10:11], v152, s6, v[148:149]
	v_mov_b32_e32 v146, v149
	v_mad_u64_u32 v[152:153], s[10:11], v153, s6, v[146:147]
	v_mov_b32_e32 v149, v152
	v_mov_b32_e32 v146, v147
	v_lshl_add_u64 v[150:151], v[150:151], 1, v[148:149]
	global_store_dwordx4 v[150:151], v[160:163], off
	v_mul_f32_e32 v184, 0xbfb8aa3b, v146
	v_mul_f32_e32 v206, v146, v146
	v_pk_mul_f32 v[168:169], v[116:117], v[184:185] op_sel_hi:[1,0]
	v_pk_mul_f32 v[170:171], v[118:119], v[184:185] op_sel_hi:[1,0]
	v_pk_mul_f32 v[172:173], v[112:113], v[184:185] op_sel_hi:[1,0]
	v_pk_mul_f32 v[174:175], v[114:115], v[184:185] op_sel_hi:[1,0]
	v_exp_f32_e32 v168, v168
	v_exp_f32_e32 v169, v169
	v_exp_f32_e32 v170, v170
	v_exp_f32_e32 v171, v171
	v_exp_f32_e32 v172, v172
	v_exp_f32_e32 v173, v173
	v_exp_f32_e32 v174, v174
	v_exp_f32_e32 v175, v175
	v_pk_mul_f32 v[176:177], v[116:117], v[84:85]
	v_pk_mul_f32 v[178:179], v[118:119], v[86:87]
	v_pk_mul_f32 v[180:181], v[112:113], v[80:81]
	v_pk_mul_f32 v[182:183], v[114:115], v[82:83]
	v_pk_add_f32 v[168:169], v[168:169], 1.0 op_sel_hi:[1,0]
	v_pk_add_f32 v[170:171], v[170:171], 1.0 op_sel_hi:[1,0]
	v_pk_add_f32 v[172:173], v[172:173], 1.0 op_sel_hi:[1,0]
	v_pk_add_f32 v[174:175], v[174:175], 1.0 op_sel_hi:[1,0]
	v_rcp_f32_e32 v168, v168
	v_rcp_f32_e32 v169, v169
	v_rcp_f32_e32 v170, v170
	v_rcp_f32_e32 v171, v171
	v_rcp_f32_e32 v172, v172
	v_rcp_f32_e32 v173, v173
	v_rcp_f32_e32 v174, v174
	v_rcp_f32_e32 v175, v175
	v_pk_mul_f32 v[176:177], v[176:177], v[206:207] op_sel_hi:[1,0]
	v_pk_mul_f32 v[178:179], v[178:179], v[206:207] op_sel_hi:[1,0]
	v_pk_mul_f32 v[180:181], v[180:181], v[206:207] op_sel_hi:[1,0]
	v_pk_mul_f32 v[182:183], v[182:183], v[206:207] op_sel_hi:[1,0]
	v_pk_mul_f32 v[176:177], v[176:177], v[168:169]
	v_pk_mul_f32 v[178:179], v[178:179], v[170:171]
	v_pk_mul_f32 v[180:181], v[180:181], v[172:173]
	v_pk_mul_f32 v[182:183], v[182:183], v[174:175]
	v_cvt_pk_bf16_f32 v160, v176, v177
	v_cvt_pk_bf16_f32 v161, v178, v179
	v_cvt_pk_bf16_f32 v162, v180, v181
	v_cvt_pk_bf16_f32 v163, v182, v183
	s_mov_b32 s6, 0x16000
	s_nop 1
	v_add_co_u32_e32 v146, vcc, s6, v150
	s_nop 0
	v_addc_co_u32_e32 v147, vcc, 0, v151, vcc
	global_store_dwordx4 v[146:147], v[160:163], off
	ds_read2_b32 v[146:147], v158 offset0:32 offset1:48
	s_mov_b32 s6, 0x2c000
	s_waitcnt lgkmcnt(0)
	v_mul_f32_e32 v184, 0xbfb8aa3b, v146
	v_mul_f32_e32 v206, v146, v146
	v_pk_mul_f32 v[168:169], v[108:109], v[184:185] op_sel_hi:[1,0]
	v_pk_mul_f32 v[170:171], v[110:111], v[184:185] op_sel_hi:[1,0]
	v_pk_mul_f32 v[172:173], v[104:105], v[184:185] op_sel_hi:[1,0]
	v_pk_mul_f32 v[174:175], v[106:107], v[184:185] op_sel_hi:[1,0]
	v_exp_f32_e32 v168, v168
	v_exp_f32_e32 v169, v169
	v_exp_f32_e32 v170, v170
	v_exp_f32_e32 v171, v171
	v_exp_f32_e32 v172, v172
	v_exp_f32_e32 v173, v173
	v_exp_f32_e32 v174, v174
	v_exp_f32_e32 v175, v175
	v_pk_mul_f32 v[176:177], v[108:109], v[76:77]
	v_pk_mul_f32 v[178:179], v[110:111], v[78:79]
	v_pk_mul_f32 v[180:181], v[104:105], v[72:73]
	v_pk_mul_f32 v[182:183], v[106:107], v[74:75]
	v_pk_add_f32 v[168:169], v[168:169], 1.0 op_sel_hi:[1,0]
	v_pk_add_f32 v[170:171], v[170:171], 1.0 op_sel_hi:[1,0]
	v_pk_add_f32 v[172:173], v[172:173], 1.0 op_sel_hi:[1,0]
	v_pk_add_f32 v[174:175], v[174:175], 1.0 op_sel_hi:[1,0]
	v_rcp_f32_e32 v168, v168
	v_rcp_f32_e32 v169, v169
	v_rcp_f32_e32 v170, v170
	v_rcp_f32_e32 v171, v171
	v_rcp_f32_e32 v172, v172
	v_rcp_f32_e32 v173, v173
	v_rcp_f32_e32 v174, v174
	v_rcp_f32_e32 v175, v175
	v_pk_mul_f32 v[176:177], v[176:177], v[206:207] op_sel_hi:[1,0]
	v_pk_mul_f32 v[178:179], v[178:179], v[206:207] op_sel_hi:[1,0]
	v_pk_mul_f32 v[180:181], v[180:181], v[206:207] op_sel_hi:[1,0]
	v_pk_mul_f32 v[182:183], v[182:183], v[206:207] op_sel_hi:[1,0]
	v_pk_mul_f32 v[176:177], v[176:177], v[168:169]
	v_pk_mul_f32 v[178:179], v[178:179], v[170:171]
	v_pk_mul_f32 v[180:181], v[180:181], v[172:173]
	v_pk_mul_f32 v[182:183], v[182:183], v[174:175]
	v_cvt_pk_bf16_f32 v160, v176, v177
	v_cvt_pk_bf16_f32 v161, v178, v179
	v_cvt_pk_bf16_f32 v162, v180, v181
	v_cvt_pk_bf16_f32 v163, v182, v183
	s_nop 1
	v_mov_b32_e32 v146, v147
	v_add_co_u32_e32 v148, vcc, s6, v150
	v_addc_co_u32_e32 v149, vcc, 0, v151, vcc
	global_store_dwordx4 v[148:149], v[160:163], off
	v_mul_f32_e32 v184, 0xbfb8aa3b, v146
	v_mul_f32_e32 v206, v146, v146
	v_pk_mul_f32 v[168:169], v[100:101], v[184:185] op_sel_hi:[1,0]
	v_pk_mul_f32 v[170:171], v[102:103], v[184:185] op_sel_hi:[1,0]
	v_pk_mul_f32 v[172:173], v[96:97], v[184:185] op_sel_hi:[1,0]
	v_pk_mul_f32 v[174:175], v[98:99], v[184:185] op_sel_hi:[1,0]
	v_exp_f32_e32 v168, v168
	v_exp_f32_e32 v169, v169
	v_exp_f32_e32 v170, v170
	v_exp_f32_e32 v171, v171
	v_exp_f32_e32 v172, v172
	v_exp_f32_e32 v173, v173
	v_exp_f32_e32 v174, v174
	v_exp_f32_e32 v175, v175
	v_pk_mul_f32 v[176:177], v[100:101], v[68:69]
	v_pk_mul_f32 v[178:179], v[102:103], v[70:71]
	v_pk_mul_f32 v[180:181], v[96:97], v[64:65]
	v_pk_mul_f32 v[182:183], v[98:99], v[66:67]
	v_pk_add_f32 v[168:169], v[168:169], 1.0 op_sel_hi:[1,0]
	v_pk_add_f32 v[170:171], v[170:171], 1.0 op_sel_hi:[1,0]
	v_pk_add_f32 v[172:173], v[172:173], 1.0 op_sel_hi:[1,0]
	v_pk_add_f32 v[174:175], v[174:175], 1.0 op_sel_hi:[1,0]
	v_rcp_f32_e32 v168, v168
	v_rcp_f32_e32 v169, v169
	v_rcp_f32_e32 v170, v170
	v_rcp_f32_e32 v171, v171
	v_rcp_f32_e32 v172, v172
	v_rcp_f32_e32 v173, v173
	v_rcp_f32_e32 v174, v174
	v_rcp_f32_e32 v175, v175
	v_pk_mul_f32 v[176:177], v[176:177], v[206:207] op_sel_hi:[1,0]
	v_pk_mul_f32 v[178:179], v[178:179], v[206:207] op_sel_hi:[1,0]
	v_pk_mul_f32 v[180:181], v[180:181], v[206:207] op_sel_hi:[1,0]
	v_pk_mul_f32 v[182:183], v[182:183], v[206:207] op_sel_hi:[1,0]
	v_pk_mul_f32 v[176:177], v[176:177], v[168:169]
	v_pk_mul_f32 v[178:179], v[178:179], v[170:171]
	v_pk_mul_f32 v[180:181], v[180:181], v[172:173]
	v_pk_mul_f32 v[182:183], v[182:183], v[174:175]
	v_cvt_pk_bf16_f32 v160, v176, v177
	v_cvt_pk_bf16_f32 v161, v178, v179
	v_cvt_pk_bf16_f32 v162, v180, v181
	v_cvt_pk_bf16_f32 v163, v182, v183
	s_mov_b32 s6, 0x42000
	s_nop 1
	v_add_co_u32_e32 v146, vcc, s6, v150
	s_nop 0
	v_addc_co_u32_e32 v147, vcc, 0, v151, vcc
	global_store_dwordx4 v[146:147], v[160:163], off
	ds_read2_b32 v[146:147], v158 offset0:128 offset1:144
	s_mov_b32 s6, 0xb0000
	s_waitcnt lgkmcnt(0)
	v_mul_f32_e32 v184, 0xbfb8aa3b, v146
	v_mul_f32_e32 v206, v146, v146
	v_pk_mul_f32 v[168:169], v[60:61], v[184:185] op_sel_hi:[1,0]
	v_pk_mul_f32 v[170:171], v[62:63], v[184:185] op_sel_hi:[1,0]
	v_pk_mul_f32 v[172:173], v[56:57], v[184:185] op_sel_hi:[1,0]
	v_pk_mul_f32 v[174:175], v[58:59], v[184:185] op_sel_hi:[1,0]
	v_exp_f32_e32 v168, v168
	v_exp_f32_e32 v169, v169
	v_exp_f32_e32 v170, v170
	v_exp_f32_e32 v171, v171
	v_exp_f32_e32 v172, v172
	v_exp_f32_e32 v173, v173
	v_exp_f32_e32 v174, v174
	v_exp_f32_e32 v175, v175
	v_pk_mul_f32 v[176:177], v[60:61], v[28:29]
	v_pk_mul_f32 v[178:179], v[62:63], v[30:31]
	v_pk_mul_f32 v[180:181], v[56:57], v[24:25]
	v_pk_mul_f32 v[182:183], v[58:59], v[26:27]
	v_pk_add_f32 v[168:169], v[168:169], 1.0 op_sel_hi:[1,0]
	v_pk_add_f32 v[170:171], v[170:171], 1.0 op_sel_hi:[1,0]
	v_pk_add_f32 v[172:173], v[172:173], 1.0 op_sel_hi:[1,0]
	v_pk_add_f32 v[174:175], v[174:175], 1.0 op_sel_hi:[1,0]
	v_rcp_f32_e32 v168, v168
	v_rcp_f32_e32 v169, v169
	v_rcp_f32_e32 v170, v170
	v_rcp_f32_e32 v171, v171
	v_rcp_f32_e32 v172, v172
	v_rcp_f32_e32 v173, v173
	v_rcp_f32_e32 v174, v174
	v_rcp_f32_e32 v175, v175
	v_pk_mul_f32 v[176:177], v[176:177], v[206:207] op_sel_hi:[1,0]
	v_pk_mul_f32 v[178:179], v[178:179], v[206:207] op_sel_hi:[1,0]
	v_pk_mul_f32 v[180:181], v[180:181], v[206:207] op_sel_hi:[1,0]
	v_pk_mul_f32 v[182:183], v[182:183], v[206:207] op_sel_hi:[1,0]
	v_pk_mul_f32 v[176:177], v[176:177], v[168:169]
	v_pk_mul_f32 v[178:179], v[178:179], v[170:171]
	v_pk_mul_f32 v[180:181], v[180:181], v[172:173]
	v_pk_mul_f32 v[182:183], v[182:183], v[174:175]
	v_cvt_pk_bf16_f32 v160, v176, v177
	v_cvt_pk_bf16_f32 v161, v178, v179
	v_cvt_pk_bf16_f32 v162, v180, v181
	v_cvt_pk_bf16_f32 v163, v182, v183
	s_nop 1
	v_mov_b32_e32 v146, v147
	v_add_co_u32_e32 v148, vcc, s6, v150
	v_addc_co_u32_e32 v149, vcc, 0, v151, vcc
	global_store_dwordx4 v[148:149], v[160:163], off
	v_mul_f32_e32 v184, 0xbfb8aa3b, v146
	v_mul_f32_e32 v206, v146, v146
	v_pk_mul_f32 v[168:169], v[52:53], v[184:185] op_sel_hi:[1,0]
	v_pk_mul_f32 v[170:171], v[54:55], v[184:185] op_sel_hi:[1,0]
	v_pk_mul_f32 v[172:173], v[48:49], v[184:185] op_sel_hi:[1,0]
	v_pk_mul_f32 v[174:175], v[50:51], v[184:185] op_sel_hi:[1,0]
	v_exp_f32_e32 v168, v168
	v_exp_f32_e32 v169, v169
	v_exp_f32_e32 v170, v170
	v_exp_f32_e32 v171, v171
	v_exp_f32_e32 v172, v172
	v_exp_f32_e32 v173, v173
	v_exp_f32_e32 v174, v174
	v_exp_f32_e32 v175, v175
	v_pk_mul_f32 v[176:177], v[52:53], v[20:21]
	v_pk_mul_f32 v[178:179], v[54:55], v[22:23]
	v_pk_mul_f32 v[180:181], v[48:49], v[16:17]
	v_pk_mul_f32 v[182:183], v[50:51], v[18:19]
	v_pk_add_f32 v[168:169], v[168:169], 1.0 op_sel_hi:[1,0]
	v_pk_add_f32 v[170:171], v[170:171], 1.0 op_sel_hi:[1,0]
	v_pk_add_f32 v[172:173], v[172:173], 1.0 op_sel_hi:[1,0]
	v_pk_add_f32 v[174:175], v[174:175], 1.0 op_sel_hi:[1,0]
	v_rcp_f32_e32 v168, v168
	v_rcp_f32_e32 v169, v169
	v_rcp_f32_e32 v170, v170
	v_rcp_f32_e32 v171, v171
	v_rcp_f32_e32 v172, v172
	v_rcp_f32_e32 v173, v173
	v_rcp_f32_e32 v174, v174
	v_rcp_f32_e32 v175, v175
	v_pk_mul_f32 v[176:177], v[176:177], v[206:207] op_sel_hi:[1,0]
	v_pk_mul_f32 v[178:179], v[178:179], v[206:207] op_sel_hi:[1,0]
	v_pk_mul_f32 v[180:181], v[180:181], v[206:207] op_sel_hi:[1,0]
	v_pk_mul_f32 v[182:183], v[182:183], v[206:207] op_sel_hi:[1,0]
	v_pk_mul_f32 v[176:177], v[176:177], v[168:169]
	v_pk_mul_f32 v[178:179], v[178:179], v[170:171]
	v_pk_mul_f32 v[180:181], v[180:181], v[172:173]
	v_pk_mul_f32 v[182:183], v[182:183], v[174:175]
	v_cvt_pk_bf16_f32 v160, v176, v177
	v_cvt_pk_bf16_f32 v161, v178, v179
	v_cvt_pk_bf16_f32 v162, v180, v181
	v_cvt_pk_bf16_f32 v163, v182, v183
	s_mov_b32 s6, 0xc6000
	s_nop 1
	v_add_co_u32_e32 v146, vcc, s6, v150
	s_nop 0
	v_addc_co_u32_e32 v147, vcc, 0, v151, vcc
	global_store_dwordx4 v[146:147], v[160:163], off
	ds_read2_b32 v[146:147], v158 offset0:160 offset1:176
	s_mov_b32 s6, 0xdc000
	s_waitcnt lgkmcnt(0)
	v_mul_f32_e32 v184, 0xbfb8aa3b, v146
	v_mul_f32_e32 v206, v146, v146
	v_pk_mul_f32 v[168:169], v[44:45], v[184:185] op_sel_hi:[1,0]
	v_pk_mul_f32 v[170:171], v[46:47], v[184:185] op_sel_hi:[1,0]
	v_pk_mul_f32 v[172:173], v[40:41], v[184:185] op_sel_hi:[1,0]
	v_pk_mul_f32 v[174:175], v[42:43], v[184:185] op_sel_hi:[1,0]
	v_exp_f32_e32 v168, v168
	v_exp_f32_e32 v169, v169
	v_exp_f32_e32 v170, v170
	v_exp_f32_e32 v171, v171
	v_exp_f32_e32 v172, v172
	v_exp_f32_e32 v173, v173
	v_exp_f32_e32 v174, v174
	v_exp_f32_e32 v175, v175
	v_pk_mul_f32 v[176:177], v[44:45], v[12:13]
	v_pk_mul_f32 v[178:179], v[46:47], v[14:15]
	v_pk_mul_f32 v[180:181], v[40:41], v[8:9]
	v_pk_mul_f32 v[182:183], v[42:43], v[10:11]
	v_pk_add_f32 v[168:169], v[168:169], 1.0 op_sel_hi:[1,0]
	v_pk_add_f32 v[170:171], v[170:171], 1.0 op_sel_hi:[1,0]
	v_pk_add_f32 v[172:173], v[172:173], 1.0 op_sel_hi:[1,0]
	v_pk_add_f32 v[174:175], v[174:175], 1.0 op_sel_hi:[1,0]
	v_rcp_f32_e32 v168, v168
	v_rcp_f32_e32 v169, v169
	v_rcp_f32_e32 v170, v170
	v_rcp_f32_e32 v171, v171
	v_rcp_f32_e32 v172, v172
	v_rcp_f32_e32 v173, v173
	v_rcp_f32_e32 v174, v174
	v_rcp_f32_e32 v175, v175
	v_pk_mul_f32 v[176:177], v[176:177], v[206:207] op_sel_hi:[1,0]
	v_pk_mul_f32 v[178:179], v[178:179], v[206:207] op_sel_hi:[1,0]
	v_pk_mul_f32 v[180:181], v[180:181], v[206:207] op_sel_hi:[1,0]
	v_pk_mul_f32 v[182:183], v[182:183], v[206:207] op_sel_hi:[1,0]
	v_pk_mul_f32 v[176:177], v[176:177], v[168:169]
	v_pk_mul_f32 v[178:179], v[178:179], v[170:171]
	v_pk_mul_f32 v[180:181], v[180:181], v[172:173]
	v_pk_mul_f32 v[182:183], v[182:183], v[174:175]
	v_cvt_pk_bf16_f32 v158, v176, v177
	v_cvt_pk_bf16_f32 v159, v178, v179
	v_cvt_pk_bf16_f32 v160, v180, v181
	v_cvt_pk_bf16_f32 v161, v182, v183
	s_nop 1
	v_mov_b32_e32 v146, v147
	v_add_co_u32_e32 v148, vcc, s6, v150
	v_addc_co_u32_e32 v149, vcc, 0, v151, vcc
	global_store_dwordx4 v[148:149], v[158:161], off
	v_mul_f32_e32 v184, 0xbfb8aa3b, v146
	v_mul_f32_e32 v206, v146, v146
	v_pk_mul_f32 v[168:169], v[36:37], v[184:185] op_sel_hi:[1,0]
	v_pk_mul_f32 v[170:171], v[38:39], v[184:185] op_sel_hi:[1,0]
	v_pk_mul_f32 v[172:173], v[32:33], v[184:185] op_sel_hi:[1,0]
	v_pk_mul_f32 v[174:175], v[34:35], v[184:185] op_sel_hi:[1,0]
	v_exp_f32_e32 v168, v168
	v_exp_f32_e32 v169, v169
	v_exp_f32_e32 v170, v170
	v_exp_f32_e32 v171, v171
	v_exp_f32_e32 v172, v172
	v_exp_f32_e32 v173, v173
	v_exp_f32_e32 v174, v174
	v_exp_f32_e32 v175, v175
	v_pk_mul_f32 v[176:177], v[36:37], v[4:5]
	v_pk_mul_f32 v[178:179], v[38:39], v[6:7]
	v_pk_mul_f32 v[180:181], v[32:33], v[0:1]
	v_pk_mul_f32 v[182:183], v[34:35], v[2:3]
	v_pk_add_f32 v[168:169], v[168:169], 1.0 op_sel_hi:[1,0]
	v_pk_add_f32 v[170:171], v[170:171], 1.0 op_sel_hi:[1,0]
	v_pk_add_f32 v[172:173], v[172:173], 1.0 op_sel_hi:[1,0]
	v_pk_add_f32 v[174:175], v[174:175], 1.0 op_sel_hi:[1,0]
	v_rcp_f32_e32 v168, v168
	v_rcp_f32_e32 v169, v169
	v_rcp_f32_e32 v170, v170
	v_rcp_f32_e32 v171, v171
	v_rcp_f32_e32 v172, v172
	v_rcp_f32_e32 v173, v173
	v_rcp_f32_e32 v174, v174
	v_rcp_f32_e32 v175, v175
	v_pk_mul_f32 v[176:177], v[176:177], v[206:207] op_sel_hi:[1,0]
	v_pk_mul_f32 v[178:179], v[178:179], v[206:207] op_sel_hi:[1,0]
	v_pk_mul_f32 v[180:181], v[180:181], v[206:207] op_sel_hi:[1,0]
	v_pk_mul_f32 v[182:183], v[182:183], v[206:207] op_sel_hi:[1,0]
	v_pk_mul_f32 v[176:177], v[176:177], v[168:169]
	v_pk_mul_f32 v[178:179], v[178:179], v[170:171]
	v_pk_mul_f32 v[180:181], v[180:181], v[172:173]
	v_pk_mul_f32 v[182:183], v[182:183], v[174:175]
	v_cvt_pk_bf16_f32 v158, v176, v177
	v_cvt_pk_bf16_f32 v159, v178, v179
	v_cvt_pk_bf16_f32 v160, v180, v181
	v_cvt_pk_bf16_f32 v161, v182, v183
	s_nop 1
	v_add_co_u32_e32 v146, vcc, 0xf2000, v150
	s_nop 0
	v_addc_co_u32_e32 v147, vcc, 0, v151, vcc
	s_andn2_b64 vcc, exec, s[44:45]
	global_store_dwordx4 v[146:147], v[158:161], off
	s_cbranch_vccz .LBB0_382
	s_mov_b64 s[48:49], s[52:53]
	s_andn2_b64 vcc, exec, s[42:43]
	s_mov_b64 s[52:53], s[48:49]
	s_cbranch_vccnz .LBB0_383

.LBB0_773:
	s_add_u32 s12, s26, s6
	s_addc_u32 s19, s27, 0
	s_add_u32 s23, s12, 0x100
	s_addc_u32 s29, s19, 0
	s_and_b64 s[10:11], s[46:47], exec
	s_cselect_b32 s53, s35, s29
	s_cselect_b32 s52, s34, s23
	s_add_u32 s6, s4, s6
	s_addc_u32 s10, s5, 0
	s_add_u32 s6, s6, 0x100
	s_addc_u32 s23, s10, 0
	s_add_i32 s84, 0, 0x10000
	s_and_b64 s[10:11], s[46:47], exec
	s_cselect_b32 s55, s39, s23
	s_cselect_b32 s54, s38, s6
	s_add_u32 s58, s12, 0x80080
	s_addc_u32 s59, s19, 0
	s_add_i32 s88, s84, s68
	s_add_i32 m0, s69, 0xc000
	s_add_i32 s23, s69, 0xe000
	s_add_i32 s87, 0, 0x14000
	s_add_i32 s86, s88, 0x2000
	s_add_u32 s50, s54, 0x40000
	v_add_u32_e32 v136, s84, v138
	s_addc_u32 s51, s55, 0
	s_add_i32 s29, s87, s68
	ds_read_b128 v[146:149], v136
	ds_read_b128 v[152:155], v136 offset:1024
	ds_read_b128 v[156:159], v136 offset:2048
	ds_read_b128 v[160:163], v136 offset:3072
	s_add_i32 s19, s29, 0x2000
	s_add_i32 s12, 0, 0x18000
	s_add_u32 s48, s52, 0x80000
	s_addc_u32 s49, s53, 0
	s_add_i32 s11, s12, s68
	s_add_i32 s10, 0, 0x1c000
	s_add_i32 s6, s11, 0x2000
	s_add_u32 s46, s54, 0x40080
	s_addc_u32 s47, s55, 0
	s_add_i32 s85, s10, s68
	s_add_i32 s84, s85, 0x2000
	v_lshl_add_u64 v[136:137], s[58:59], 0, v[132:133]
	ds_read_b128 v[164:167], v150
	ds_read_b128 v[168:171], v150 offset:1024
	ds_read_b128 v[172:175], v150 offset:2048
	ds_read_b128 v[176:179], v150 offset:3072
	ds_read_b128 v[180:183], v150 offset:4096
	ds_read_b128 v[194:197], v150 offset:5120
	ds_read_b128 v[206:209], v150 offset:6144
	ds_read_b128 v[210:213], v150 offset:7168
	global_load_lds_dwordx4 v[136:137], off
	v_lshl_add_u64 v[136:137], s[58:59], 0, v[130:131]
	s_mov_b32 m0, s23
	s_nop 0
	global_load_lds_dwordx4 v[136:137], off
	s_waitcnt lgkmcnt(8)
	s_barrier
	s_setprio 1
	s_waitcnt lgkmcnt(7)
	v_mfma_f32_16x16x32_bf16 v[124:127], v[146:149], v[164:167], v[124:127]
	v_mfma_f32_16x16x32_bf16 v[120:123], v[156:159], v[164:167], v[120:123]
	s_waitcnt lgkmcnt(5)
	v_mfma_f32_16x16x32_bf16 v[116:119], v[146:149], v[172:175], v[116:119]
	v_mfma_f32_16x16x32_bf16 v[112:115], v[156:159], v[172:175], v[112:115]
	s_waitcnt lgkmcnt(3)
	v_mfma_f32_16x16x32_bf16 v[108:111], v[146:149], v[180:183], v[108:111]
	v_mfma_f32_16x16x32_bf16 v[104:107], v[156:159], v[180:183], v[104:107]
	s_waitcnt lgkmcnt(1)
	v_mfma_f32_16x16x32_bf16 v[100:103], v[146:149], v[206:209], v[100:103]
	v_mfma_f32_16x16x32_bf16 v[96:99], v[156:159], v[206:209], v[96:99]
	v_mfma_f32_16x16x32_bf16 v[124:127], v[152:155], v[168:171], v[124:127]
	v_mfma_f32_16x16x32_bf16 v[120:123], v[160:163], v[168:171], v[120:123]
	v_mfma_f32_16x16x32_bf16 v[116:119], v[152:155], v[176:179], v[116:119]
	v_mfma_f32_16x16x32_bf16 v[112:115], v[160:163], v[176:179], v[112:115]
	v_mfma_f32_16x16x32_bf16 v[108:111], v[152:155], v[194:197], v[108:111]
	v_mfma_f32_16x16x32_bf16 v[104:107], v[160:163], v[194:197], v[104:107]
	s_waitcnt lgkmcnt(0)
	v_mfma_f32_16x16x32_bf16 v[100:103], v[152:155], v[210:213], v[100:103]
	v_mfma_f32_16x16x32_bf16 v[96:99], v[160:163], v[210:213], v[96:99]
	s_setprio 0
	s_barrier
	v_add_u32_e32 v136, s87, v138
	s_mov_b32 m0, s88
	ds_read_b128 v[214:217], v136
	ds_read_b128 v[218:221], v136 offset:1024
	ds_read_b128 v[222:225], v136 offset:2048
	ds_read_b128 v[226:229], v136 offset:3072
	v_lshl_add_u64 v[136:137], s[54:55], 0, v[140:141]
	global_load_lds_dwordx4 v[136:137], off
	v_lshl_add_u64 v[184:185], s[54:55], 0, v[128:129]
	s_mov_b32 m0, s86
	s_nop 0
	global_load_lds_dwordx4 v[184:185], off
	s_barrier
	s_setprio 1
	s_waitcnt lgkmcnt(3)
	v_mfma_f32_16x16x32_bf16 v[92:95], v[214:217], v[164:167], v[92:95]
	s_waitcnt lgkmcnt(1)
	v_mfma_f32_16x16x32_bf16 v[88:91], v[222:225], v[164:167], v[88:91]
	v_mfma_f32_16x16x32_bf16 v[84:87], v[214:217], v[172:175], v[84:87]
	v_mfma_f32_16x16x32_bf16 v[80:83], v[222:225], v[172:175], v[80:83]
	v_mfma_f32_16x16x32_bf16 v[76:79], v[214:217], v[180:183], v[76:79]
	v_mfma_f32_16x16x32_bf16 v[72:75], v[222:225], v[180:183], v[72:75]
	v_mfma_f32_16x16x32_bf16 v[68:71], v[214:217], v[206:209], v[68:71]
	v_mfma_f32_16x16x32_bf16 v[64:67], v[222:225], v[206:209], v[64:67]
	v_mfma_f32_16x16x32_bf16 v[92:95], v[218:221], v[168:171], v[92:95]
	s_waitcnt lgkmcnt(0)
	v_mfma_f32_16x16x32_bf16 v[88:91], v[226:229], v[168:171], v[88:91]
	v_mfma_f32_16x16x32_bf16 v[84:87], v[218:221], v[176:179], v[84:87]
	v_mfma_f32_16x16x32_bf16 v[80:83], v[226:229], v[176:179], v[80:83]
	v_mfma_f32_16x16x32_bf16 v[76:79], v[218:221], v[194:197], v[76:79]
	v_mfma_f32_16x16x32_bf16 v[72:75], v[226:229], v[194:197], v[72:75]
	v_mfma_f32_16x16x32_bf16 v[68:71], v[218:221], v[210:213], v[68:71]
	v_mfma_f32_16x16x32_bf16 v[64:67], v[226:229], v[210:213], v[64:67]
	s_setprio 0
	s_mov_b32 m0, s69
	v_lshl_add_u64 v[192:193], s[52:53], 0, v[132:133]
	s_barrier
	ds_read_b128 v[164:167], v150 offset:16384
	ds_read_b128 v[168:171], v150 offset:17408
	ds_read_b128 v[172:175], v150 offset:18432
	ds_read_b128 v[176:179], v150 offset:19456
	ds_read_b128 v[180:183], v150 offset:20480
	ds_read_b128 v[194:197], v150 offset:21504
	ds_read_b128 v[206:209], v150 offset:22528
	ds_read_b128 v[210:213], v150 offset:23552
	global_load_lds_dwordx4 v[192:193], off
	v_lshl_add_u64 v[230:231], s[52:53], 0, v[130:131]
	s_mov_b32 m0, s70
	s_nop 0
	global_load_lds_dwordx4 v[230:231], off
	s_barrier
	s_setprio 1
	s_waitcnt lgkmcnt(7)
	v_mfma_f32_16x16x32_bf16 v[60:63], v[146:149], v[164:167], v[60:63]
	v_mfma_f32_16x16x32_bf16 v[56:59], v[156:159], v[164:167], v[56:59]
	s_waitcnt lgkmcnt(5)
	v_mfma_f32_16x16x32_bf16 v[52:55], v[146:149], v[172:175], v[52:55]
	v_mfma_f32_16x16x32_bf16 v[48:51], v[156:159], v[172:175], v[48:51]
	s_waitcnt lgkmcnt(3)
	v_mfma_f32_16x16x32_bf16 v[44:47], v[146:149], v[180:183], v[44:47]
	v_mfma_f32_16x16x32_bf16 v[40:43], v[156:159], v[180:183], v[40:43]
	s_waitcnt lgkmcnt(1)
	v_mfma_f32_16x16x32_bf16 v[36:39], v[146:149], v[206:209], v[36:39]
	v_mfma_f32_16x16x32_bf16 v[32:35], v[156:159], v[206:209], v[32:35]
	v_mfma_f32_16x16x32_bf16 v[60:63], v[152:155], v[168:171], v[60:63]
	v_mfma_f32_16x16x32_bf16 v[56:59], v[160:163], v[168:171], v[56:59]
	v_mfma_f32_16x16x32_bf16 v[52:55], v[152:155], v[176:179], v[52:55]
	v_mfma_f32_16x16x32_bf16 v[48:51], v[160:163], v[176:179], v[48:51]
	v_mfma_f32_16x16x32_bf16 v[44:47], v[152:155], v[194:197], v[44:47]
	v_mfma_f32_16x16x32_bf16 v[40:43], v[160:163], v[194:197], v[40:43]
	s_waitcnt lgkmcnt(0)
	v_mfma_f32_16x16x32_bf16 v[36:39], v[152:155], v[210:213], v[36:39]
	v_mfma_f32_16x16x32_bf16 v[32:35], v[160:163], v[210:213], v[32:35]
	s_setprio 0
	s_barrier
	s_mov_b32 m0, s29
	v_lshl_add_u64 v[146:147], s[50:51], 0, v[140:141]
	global_load_lds_dwordx4 v[146:147], off
	v_lshl_add_u64 v[146:147], s[50:51], 0, v[128:129]
	s_mov_b32 m0, s19
	s_nop 0
	global_load_lds_dwordx4 v[146:147], off
	s_waitcnt vmcnt(6)
	s_barrier
	s_setprio 1
	v_mfma_f32_16x16x32_bf16 v[28:31], v[214:217], v[164:167], v[28:31]
	v_mfma_f32_16x16x32_bf16 v[20:23], v[214:217], v[172:175], v[20:23]
	v_mfma_f32_16x16x32_bf16 v[12:15], v[214:217], v[180:183], v[12:15]
	v_mfma_f32_16x16x32_bf16 v[4:7], v[214:217], v[206:209], v[4:7]
	v_mfma_f32_16x16x32_bf16 v[0:3], v[222:225], v[206:209], v[0:3]
	v_mfma_f32_16x16x32_bf16 v[8:11], v[222:225], v[180:183], v[8:11]
	v_mfma_f32_16x16x32_bf16 v[16:19], v[222:225], v[172:175], v[16:19]
	v_mfma_f32_16x16x32_bf16 v[24:27], v[222:225], v[164:167], v[24:27]
	v_mfma_f32_16x16x32_bf16 v[28:31], v[218:221], v[168:171], v[28:31]
	v_mfma_f32_16x16x32_bf16 v[20:23], v[218:221], v[176:179], v[20:23]
	v_mfma_f32_16x16x32_bf16 v[12:15], v[218:221], v[194:197], v[12:15]
	v_mfma_f32_16x16x32_bf16 v[4:7], v[218:221], v[210:213], v[4:7]
	v_mfma_f32_16x16x32_bf16 v[0:3], v[226:229], v[210:213], v[0:3]
	v_mfma_f32_16x16x32_bf16 v[8:11], v[226:229], v[194:197], v[8:11]
	v_mfma_f32_16x16x32_bf16 v[16:19], v[226:229], v[176:179], v[16:19]
	v_mfma_f32_16x16x32_bf16 v[24:27], v[226:229], v[168:171], v[24:27]
	s_setprio 0
	v_add_u32_e32 v151, s12, v138
	s_barrier
	ds_read_b128 v[146:149], v151
	ds_read_b128 v[152:155], v151 offset:1024
	ds_read_b128 v[156:159], v151 offset:2048
	ds_read_b128 v[160:163], v151 offset:3072
	s_mov_b32 m0, s71
	v_lshl_add_u64 v[214:215], s[48:49], 0, v[132:133]
	ds_read_b128 v[164:167], v150 offset:32768
	ds_read_b128 v[168:171], v150 offset:33792
	ds_read_b128 v[172:175], v150 offset:34816
	ds_read_b128 v[176:179], v150 offset:35840
	ds_read_b128 v[180:183], v150 offset:36864
	ds_read_b128 v[194:197], v150 offset:37888
	ds_read_b128 v[206:209], v150 offset:38912
	ds_read_b128 v[210:213], v150 offset:39936
	global_load_lds_dwordx4 v[214:215], off
	v_lshl_add_u64 v[214:215], s[48:49], 0, v[130:131]
	s_mov_b32 m0, s72
	s_nop 0
	global_load_lds_dwordx4 v[214:215], off
	s_waitcnt lgkmcnt(8)
	s_barrier
	s_setprio 1
	s_waitcnt lgkmcnt(7)
	v_mfma_f32_16x16x32_bf16 v[124:127], v[146:149], v[164:167], v[124:127]
	v_mfma_f32_16x16x32_bf16 v[120:123], v[156:159], v[164:167], v[120:123]
	s_waitcnt lgkmcnt(5)
	v_mfma_f32_16x16x32_bf16 v[116:119], v[146:149], v[172:175], v[116:119]
	v_mfma_f32_16x16x32_bf16 v[112:115], v[156:159], v[172:175], v[112:115]
	s_waitcnt lgkmcnt(3)
	v_mfma_f32_16x16x32_bf16 v[108:111], v[146:149], v[180:183], v[108:111]
	v_mfma_f32_16x16x32_bf16 v[104:107], v[156:159], v[180:183], v[104:107]
	s_waitcnt lgkmcnt(1)
	v_mfma_f32_16x16x32_bf16 v[100:103], v[146:149], v[206:209], v[100:103]
	v_mfma_f32_16x16x32_bf16 v[96:99], v[156:159], v[206:209], v[96:99]
	v_mfma_f32_16x16x32_bf16 v[124:127], v[152:155], v[168:171], v[124:127]
	v_mfma_f32_16x16x32_bf16 v[120:123], v[160:163], v[168:171], v[120:123]
	v_mfma_f32_16x16x32_bf16 v[116:119], v[152:155], v[176:179], v[116:119]
	v_mfma_f32_16x16x32_bf16 v[112:115], v[160:163], v[176:179], v[112:115]
	v_mfma_f32_16x16x32_bf16 v[108:111], v[152:155], v[194:197], v[108:111]
	v_mfma_f32_16x16x32_bf16 v[104:107], v[160:163], v[194:197], v[104:107]
	s_waitcnt lgkmcnt(0)
	v_mfma_f32_16x16x32_bf16 v[100:103], v[152:155], v[210:213], v[100:103]
	v_mfma_f32_16x16x32_bf16 v[96:99], v[160:163], v[210:213], v[96:99]
	s_setprio 0
	s_barrier
	s_mov_b32 m0, s11
	v_add_u32_e32 v151, s10, v138
	v_lshl_add_u64 v[136:137], v[136:137], 0, s[36:37]
	ds_read_b128 v[214:217], v151
	ds_read_b128 v[218:221], v151 offset:1024
	ds_read_b128 v[222:225], v151 offset:2048
	ds_read_b128 v[226:229], v151 offset:3072
	global_load_lds_dwordx4 v[136:137], off
	v_lshl_add_u64 v[136:137], v[184:185], 0, s[36:37]
	s_mov_b32 m0, s6
	s_nop 0
	global_load_lds_dwordx4 v[136:137], off
	s_barrier
	s_setprio 1
	s_waitcnt lgkmcnt(3)
	v_mfma_f32_16x16x32_bf16 v[92:95], v[214:217], v[164:167], v[92:95]
	s_waitcnt lgkmcnt(1)
	v_mfma_f32_16x16x32_bf16 v[88:91], v[222:225], v[164:167], v[88:91]
	v_mfma_f32_16x16x32_bf16 v[84:87], v[214:217], v[172:175], v[84:87]
	v_mfma_f32_16x16x32_bf16 v[80:83], v[222:225], v[172:175], v[80:83]
	v_mfma_f32_16x16x32_bf16 v[76:79], v[214:217], v[180:183], v[76:79]
	v_mfma_f32_16x16x32_bf16 v[72:75], v[222:225], v[180:183], v[72:75]
	v_mfma_f32_16x16x32_bf16 v[68:71], v[214:217], v[206:209], v[68:71]
	v_mfma_f32_16x16x32_bf16 v[64:67], v[222:225], v[206:209], v[64:67]
	v_mfma_f32_16x16x32_bf16 v[92:95], v[218:221], v[168:171], v[92:95]
	s_waitcnt lgkmcnt(0)
	v_mfma_f32_16x16x32_bf16 v[88:91], v[226:229], v[168:171], v[88:91]
	v_mfma_f32_16x16x32_bf16 v[84:87], v[218:221], v[176:179], v[84:87]
	v_mfma_f32_16x16x32_bf16 v[80:83], v[226:229], v[176:179], v[80:83]
	v_mfma_f32_16x16x32_bf16 v[76:79], v[218:221], v[194:197], v[76:79]
	v_mfma_f32_16x16x32_bf16 v[72:75], v[226:229], v[194:197], v[72:75]
	v_mfma_f32_16x16x32_bf16 v[68:71], v[218:221], v[210:213], v[68:71]
	v_mfma_f32_16x16x32_bf16 v[64:67], v[226:229], v[210:213], v[64:67]
	s_setprio 0
	s_mov_b32 m0, s75
	v_lshl_add_u64 v[136:137], v[192:193], 0, s[36:37]
	s_barrier
	ds_read_b128 v[164:167], v150 offset:49152
	ds_read_b128 v[168:171], v150 offset:50176
	ds_read_b128 v[172:175], v150 offset:51200
	ds_read_b128 v[176:179], v150 offset:52224
	ds_read_b128 v[180:183], v150 offset:53248
	ds_read_b128 v[194:197], v150 offset:54272
	ds_read_b128 v[206:209], v150 offset:55296
	ds_read_b128 v[210:213], v150 offset:56320
	global_load_lds_dwordx4 v[136:137], off
	v_lshl_add_u64 v[136:137], v[230:231], 0, s[36:37]
	s_mov_b32 m0, s76
	s_nop 0
	global_load_lds_dwordx4 v[136:137], off
	s_barrier
	s_setprio 1
	s_waitcnt lgkmcnt(7)
	v_mfma_f32_16x16x32_bf16 v[60:63], v[146:149], v[164:167], v[60:63]
	v_mfma_f32_16x16x32_bf16 v[56:59], v[156:159], v[164:167], v[56:59]
	s_waitcnt lgkmcnt(5)
	v_mfma_f32_16x16x32_bf16 v[52:55], v[146:149], v[172:175], v[52:55]
	v_mfma_f32_16x16x32_bf16 v[48:51], v[156:159], v[172:175], v[48:51]
	s_waitcnt lgkmcnt(3)
	v_mfma_f32_16x16x32_bf16 v[44:47], v[146:149], v[180:183], v[44:47]
	v_mfma_f32_16x16x32_bf16 v[40:43], v[156:159], v[180:183], v[40:43]
	s_waitcnt lgkmcnt(1)
	v_mfma_f32_16x16x32_bf16 v[36:39], v[146:149], v[206:209], v[36:39]
	v_mfma_f32_16x16x32_bf16 v[32:35], v[156:159], v[206:209], v[32:35]
	v_mfma_f32_16x16x32_bf16 v[60:63], v[152:155], v[168:171], v[60:63]
	v_mfma_f32_16x16x32_bf16 v[56:59], v[160:163], v[168:171], v[56:59]
	v_mfma_f32_16x16x32_bf16 v[52:55], v[152:155], v[176:179], v[52:55]
	v_mfma_f32_16x16x32_bf16 v[48:51], v[160:163], v[176:179], v[48:51]
	v_mfma_f32_16x16x32_bf16 v[44:47], v[152:155], v[194:197], v[44:47]
	v_mfma_f32_16x16x32_bf16 v[40:43], v[160:163], v[194:197], v[40:43]
	s_waitcnt lgkmcnt(0)
	v_mfma_f32_16x16x32_bf16 v[36:39], v[152:155], v[210:213], v[36:39]
	v_mfma_f32_16x16x32_bf16 v[32:35], v[160:163], v[210:213], v[32:35]
	s_setprio 0
	s_barrier
	s_mov_b32 m0, s85
	v_lshl_add_u64 v[136:137], s[46:47], 0, v[140:141]
	global_load_lds_dwordx4 v[136:137], off
	v_lshl_add_u64 v[136:137], s[46:47], 0, v[128:129]
	s_mov_b32 m0, s84
	s_nop 0
	global_load_lds_dwordx4 v[136:137], off
	s_nop 0
	s_waitcnt vmcnt(6)
	s_barrier
	s_setprio 1
	v_mfma_f32_16x16x32_bf16 v[28:31], v[214:217], v[164:167], v[28:31]
	v_mfma_f32_16x16x32_bf16 v[20:23], v[214:217], v[172:175], v[20:23]
	v_mfma_f32_16x16x32_bf16 v[12:15], v[214:217], v[180:183], v[12:15]
	v_mfma_f32_16x16x32_bf16 v[4:7], v[214:217], v[206:209], v[4:7]
	v_mfma_f32_16x16x32_bf16 v[0:3], v[222:225], v[206:209], v[0:3]
	v_mfma_f32_16x16x32_bf16 v[8:11], v[222:225], v[180:183], v[8:11]
	v_mfma_f32_16x16x32_bf16 v[16:19], v[222:225], v[172:175], v[16:19]
	v_mfma_f32_16x16x32_bf16 v[24:27], v[222:225], v[164:167], v[24:27]
	v_mfma_f32_16x16x32_bf16 v[28:31], v[218:221], v[168:171], v[28:31]
	v_mfma_f32_16x16x32_bf16 v[20:23], v[218:221], v[176:179], v[20:23]
	v_mfma_f32_16x16x32_bf16 v[12:15], v[218:221], v[194:197], v[12:15]
	v_mfma_f32_16x16x32_bf16 v[4:7], v[218:221], v[210:213], v[4:7]
	v_mfma_f32_16x16x32_bf16 v[0:3], v[226:229], v[210:213], v[0:3]
	v_mfma_f32_16x16x32_bf16 v[8:11], v[226:229], v[194:197], v[8:11]
	v_mfma_f32_16x16x32_bf16 v[16:19], v[226:229], v[176:179], v[16:19]
	v_mfma_f32_16x16x32_bf16 v[24:27], v[226:229], v[168:171], v[24:27]
	s_setprio 0
	s_movk_i32 s6, 0x100
	s_andn2_b64 vcc, exec, s[44:45]
	s_mov_b64 s[46:47], -1
	s_mov_b64 s[44:45], 0
	s_barrier
	s_cbranch_vccz .LBB0_773
	s_ashr_i32 s10, s81, 2
	s_ashr_i32 s11, s10, 31
	s_lshl_b64 s[10:11], s[10:11], 21
	s_add_u32 s6, s73, s10
	s_addc_u32 s11, s74, s11
	s_lshl_b32 s10, s81, 19
	s_and_b32 s10, s10, 0x180000
	s_add_u32 s10, s6, s10
	v_lshl_or_b32 v136, s77, 8, v139
	s_addc_u32 s11, s11, 0
	v_ashrrev_i32_e32 v137, 31, v136
	v_lshl_add_u64 v[136:137], v[136:137], 1, s[10:11]
	v_pk_mul_f32 v[148:149], v[126:127], s[40:41] op_sel_hi:[1,0]
	v_pk_mul_f32 v[146:147], v[124:125], s[40:41] op_sel_hi:[1,0]
	v_pk_mul_f32 v[152:153], v[122:123], s[40:41] op_sel_hi:[1,0]
	v_pk_mul_f32 v[154:155], v[120:121], s[40:41] op_sel_hi:[1,0]
	v_lshl_add_u64 v[136:137], v[136:137], 0, v[134:135]
	v_cvt_pk_bf16_f32 v146, v146, v147
	v_cvt_pk_bf16_f32 v147, v148, v149
	v_cvt_pk_bf16_f32 v148, v154, v155
	v_cvt_pk_bf16_f32 v149, v152, v153
	global_store_dwordx4 v[136:137], v[146:149], off
	v_pk_mul_f32 v[152:153], v[90:91], s[40:41] op_sel_hi:[1,0]
	v_pk_mul_f32 v[154:155], v[88:89], s[40:41] op_sel_hi:[1,0]
	v_pk_mul_f32 v[148:149], v[94:95], s[40:41] op_sel_hi:[1,0]
	v_pk_mul_f32 v[146:147], v[92:93], s[40:41] op_sel_hi:[1,0]
	v_pk_mul_f32 v[156:157], v[80:81], s[40:41] op_sel_hi:[1,0]
	v_cvt_pk_bf16_f32 v146, v146, v147
	v_cvt_pk_bf16_f32 v147, v148, v149
	v_cvt_pk_bf16_f32 v148, v154, v155
	v_cvt_pk_bf16_f32 v149, v152, v153
	global_store_dwordx4 v[136:137], v[146:149], off offset:256
	v_pk_mul_f32 v[152:153], v[114:115], s[40:41] op_sel_hi:[1,0]
	v_pk_mul_f32 v[154:155], v[112:113], s[40:41] op_sel_hi:[1,0]
	v_pk_mul_f32 v[148:149], v[118:119], s[40:41] op_sel_hi:[1,0]
	v_pk_mul_f32 v[146:147], v[116:117], s[40:41] op_sel_hi:[1,0]
	s_mov_b32 s6, 0x40000
	v_cvt_pk_bf16_f32 v146, v146, v147
	v_cvt_pk_bf16_f32 v147, v148, v149
	v_cvt_pk_bf16_f32 v149, v152, v153
	v_add_co_u32_e32 v152, vcc, s65, v136
	v_cvt_pk_bf16_f32 v148, v154, v155
	s_nop 0
	v_addc_co_u32_e32 v153, vcc, 0, v137, vcc
	global_store_dwordx4 v[152:153], v[146:149], off
	v_pk_mul_f32 v[154:155], v[82:83], s[40:41] op_sel_hi:[1,0]
	s_nop 0
	v_pk_mul_f32 v[148:149], v[86:87], s[40:41] op_sel_hi:[1,0]
	v_pk_mul_f32 v[146:147], v[84:85], s[40:41] op_sel_hi:[1,0]
	s_nop 0
	v_cvt_pk_bf16_f32 v146, v146, v147
	v_cvt_pk_bf16_f32 v147, v148, v149
	v_cvt_pk_bf16_f32 v148, v156, v157
	v_cvt_pk_bf16_f32 v149, v154, v155
	global_store_dwordx4 v[152:153], v[146:149], off offset:256
	v_pk_mul_f32 v[152:153], v[106:107], s[40:41] op_sel_hi:[1,0]
	v_pk_mul_f32 v[154:155], v[104:105], s[40:41] op_sel_hi:[1,0]
	v_pk_mul_f32 v[148:149], v[110:111], s[40:41] op_sel_hi:[1,0]
	v_pk_mul_f32 v[146:147], v[108:109], s[40:41] op_sel_hi:[1,0]
	v_pk_mul_f32 v[156:157], v[72:73], s[40:41] op_sel_hi:[1,0]
	v_cvt_pk_bf16_f32 v146, v146, v147
	v_cvt_pk_bf16_f32 v147, v148, v149
	v_cvt_pk_bf16_f32 v149, v152, v153
	v_add_co_u32_e32 v152, vcc, s66, v136
	v_cvt_pk_bf16_f32 v148, v154, v155
	s_nop 0
	v_addc_co_u32_e32 v153, vcc, 0, v137, vcc
	global_store_dwordx4 v[152:153], v[146:149], off
	v_pk_mul_f32 v[154:155], v[74:75], s[40:41] op_sel_hi:[1,0]
	s_nop 0
	v_pk_mul_f32 v[148:149], v[78:79], s[40:41] op_sel_hi:[1,0]
	v_pk_mul_f32 v[146:147], v[76:77], s[40:41] op_sel_hi:[1,0]
	s_nop 0
	v_cvt_pk_bf16_f32 v146, v146, v147
	v_cvt_pk_bf16_f32 v147, v148, v149
	v_cvt_pk_bf16_f32 v148, v156, v157
	v_cvt_pk_bf16_f32 v149, v154, v155
	global_store_dwordx4 v[152:153], v[146:149], off offset:256
	v_pk_mul_f32 v[152:153], v[98:99], s[40:41] op_sel_hi:[1,0]
	v_pk_mul_f32 v[154:155], v[96:97], s[40:41] op_sel_hi:[1,0]
	v_pk_mul_f32 v[148:149], v[102:103], s[40:41] op_sel_hi:[1,0]
	v_pk_mul_f32 v[146:147], v[100:101], s[40:41] op_sel_hi:[1,0]
	v_pk_mul_f32 v[156:157], v[64:65], s[40:41] op_sel_hi:[1,0]
	v_cvt_pk_bf16_f32 v146, v146, v147
	v_cvt_pk_bf16_f32 v147, v148, v149
	v_cvt_pk_bf16_f32 v149, v152, v153
	v_add_co_u32_e32 v152, vcc, s64, v136
	v_cvt_pk_bf16_f32 v148, v154, v155
	s_nop 0
	v_addc_co_u32_e32 v153, vcc, 0, v137, vcc
	global_store_dwordx4 v[152:153], v[146:149], off
	v_pk_mul_f32 v[154:155], v[66:67], s[40:41] op_sel_hi:[1,0]
	s_nop 0
	v_pk_mul_f32 v[148:149], v[70:71], s[40:41] op_sel_hi:[1,0]
	v_pk_mul_f32 v[146:147], v[68:69], s[40:41] op_sel_hi:[1,0]
	s_nop 0
	v_cvt_pk_bf16_f32 v146, v146, v147
	v_cvt_pk_bf16_f32 v147, v148, v149
	v_cvt_pk_bf16_f32 v148, v156, v157
	v_cvt_pk_bf16_f32 v149, v154, v155
	global_store_dwordx4 v[152:153], v[146:149], off offset:256
	v_pk_mul_f32 v[152:153], v[58:59], s[40:41] op_sel_hi:[1,0]
	v_pk_mul_f32 v[154:155], v[56:57], s[40:41] op_sel_hi:[1,0]
	v_pk_mul_f32 v[148:149], v[62:63], s[40:41] op_sel_hi:[1,0]
	v_pk_mul_f32 v[146:147], v[60:61], s[40:41] op_sel_hi:[1,0]
	v_pk_mul_f32 v[156:157], v[24:25], s[40:41] op_sel_hi:[1,0]
	v_cvt_pk_bf16_f32 v146, v146, v147
	v_cvt_pk_bf16_f32 v147, v148, v149
	v_cvt_pk_bf16_f32 v149, v152, v153
	v_add_co_u32_e32 v152, vcc, s6, v136
	v_cvt_pk_bf16_f32 v148, v154, v155
	s_nop 0
	v_addc_co_u32_e32 v153, vcc, 0, v137, vcc
	global_store_dwordx4 v[152:153], v[146:149], off
	v_pk_mul_f32 v[154:155], v[26:27], s[40:41] op_sel_hi:[1,0]
	s_mov_b32 s6, 0x48000
	v_pk_mul_f32 v[148:149], v[30:31], s[40:41] op_sel_hi:[1,0]
	v_pk_mul_f32 v[146:147], v[28:29], s[40:41] op_sel_hi:[1,0]
	s_nop 0
	v_cvt_pk_bf16_f32 v146, v146, v147
	v_cvt_pk_bf16_f32 v147, v148, v149
	v_cvt_pk_bf16_f32 v148, v156, v157
	v_cvt_pk_bf16_f32 v149, v154, v155
	global_store_dwordx4 v[152:153], v[146:149], off offset:256
	v_pk_mul_f32 v[152:153], v[50:51], s[40:41] op_sel_hi:[1,0]
	v_pk_mul_f32 v[154:155], v[48:49], s[40:41] op_sel_hi:[1,0]
	v_pk_mul_f32 v[148:149], v[54:55], s[40:41] op_sel_hi:[1,0]
	v_pk_mul_f32 v[146:147], v[52:53], s[40:41] op_sel_hi:[1,0]
	v_pk_mul_f32 v[156:157], v[16:17], s[40:41] op_sel_hi:[1,0]
	v_cvt_pk_bf16_f32 v146, v146, v147
	v_cvt_pk_bf16_f32 v147, v148, v149
	v_cvt_pk_bf16_f32 v149, v152, v153
	v_add_co_u32_e32 v152, vcc, s6, v136
	v_cvt_pk_bf16_f32 v148, v154, v155
	s_nop 0
	v_addc_co_u32_e32 v153, vcc, 0, v137, vcc
	global_store_dwordx4 v[152:153], v[146:149], off
	v_pk_mul_f32 v[154:155], v[18:19], s[40:41] op_sel_hi:[1,0]
	s_mov_b32 s6, 0x50000
	v_pk_mul_f32 v[148:149], v[22:23], s[40:41] op_sel_hi:[1,0]
	v_pk_mul_f32 v[146:147], v[20:21], s[40:41] op_sel_hi:[1,0]
	s_nop 0
	v_cvt_pk_bf16_f32 v146, v146, v147
	v_cvt_pk_bf16_f32 v147, v148, v149
	v_cvt_pk_bf16_f32 v148, v156, v157
	v_cvt_pk_bf16_f32 v149, v154, v155
	global_store_dwordx4 v[152:153], v[146:149], off offset:256
	v_pk_mul_f32 v[152:153], v[42:43], s[40:41] op_sel_hi:[1,0]
	v_pk_mul_f32 v[154:155], v[40:41], s[40:41] op_sel_hi:[1,0]
	v_pk_mul_f32 v[148:149], v[46:47], s[40:41] op_sel_hi:[1,0]
	v_pk_mul_f32 v[146:147], v[44:45], s[40:41] op_sel_hi:[1,0]
	v_pk_mul_f32 v[156:157], v[8:9], s[40:41] op_sel_hi:[1,0]
	v_cvt_pk_bf16_f32 v146, v146, v147
	v_cvt_pk_bf16_f32 v147, v148, v149
	v_cvt_pk_bf16_f32 v149, v152, v153
	v_add_co_u32_e32 v152, vcc, s6, v136
	v_cvt_pk_bf16_f32 v148, v154, v155
	s_nop 0
	v_addc_co_u32_e32 v153, vcc, 0, v137, vcc
	global_store_dwordx4 v[152:153], v[146:149], off
	v_pk_mul_f32 v[154:155], v[10:11], s[40:41] op_sel_hi:[1,0]
	s_mov_b32 s6, 0x58000
	v_pk_mul_f32 v[148:149], v[14:15], s[40:41] op_sel_hi:[1,0]
	v_pk_mul_f32 v[146:147], v[12:13], s[40:41] op_sel_hi:[1,0]
	v_add_co_u32_e32 v136, vcc, s6, v136
	v_cvt_pk_bf16_f32 v146, v146, v147
	v_cvt_pk_bf16_f32 v147, v148, v149
	v_cvt_pk_bf16_f32 v148, v156, v157
	v_cvt_pk_bf16_f32 v149, v154, v155
	global_store_dwordx4 v[152:153], v[146:149], off offset:256
	v_pk_mul_f32 v[152:153], v[34:35], s[40:41] op_sel_hi:[1,0]
	v_pk_mul_f32 v[154:155], v[32:33], s[40:41] op_sel_hi:[1,0]
	v_pk_mul_f32 v[148:149], v[38:39], s[40:41] op_sel_hi:[1,0]
	v_pk_mul_f32 v[146:147], v[36:37], s[40:41] op_sel_hi:[1,0]
	v_addc_co_u32_e32 v137, vcc, 0, v137, vcc
	v_cvt_pk_bf16_f32 v146, v146, v147
	v_cvt_pk_bf16_f32 v147, v148, v149
	v_cvt_pk_bf16_f32 v148, v154, v155
	v_cvt_pk_bf16_f32 v149, v152, v153
	global_store_dwordx4 v[136:137], v[146:149], off
	v_pk_mul_f32 v[152:153], v[2:3], s[40:41] op_sel_hi:[1,0]
	v_pk_mul_f32 v[154:155], v[0:1], s[40:41] op_sel_hi:[1,0]
	v_pk_mul_f32 v[148:149], v[6:7], s[40:41] op_sel_hi:[1,0]
	v_pk_mul_f32 v[146:147], v[4:5], s[40:41] op_sel_hi:[1,0]
	s_and_b64 vcc, exec, s[42:43]
	v_cvt_pk_bf16_f32 v146, v146, v147
	v_cvt_pk_bf16_f32 v147, v148, v149
	v_cvt_pk_bf16_f32 v148, v154, v155
	v_cvt_pk_bf16_f32 v149, v152, v153
	global_store_dwordx4 v[136:137], v[146:149], off offset:256
	s_cbranch_vccnz .LBB0_761
	v_mov_b32_e32 v0, 0
	s_mov_b32 s77, s28
	s_mov_b32 s81, s82
	s_mov_b64 s[4:5], s[38:39]
	s_mov_b64 s[26:27], s[34:35]
	s_mov_b32 s80, s83
	v_mov_b32_e32 v1, v0
	v_mov_b32_e32 v2, v0
	v_mov_b32_e32 v3, v0
	v_mov_b32_e32 v4, v0
	v_mov_b32_e32 v5, v0
	v_mov_b32_e32 v6, v0
	v_mov_b32_e32 v7, v0
	v_mov_b32_e32 v8, v0
	v_mov_b32_e32 v9, v0
	v_mov_b32_e32 v10, v0
	v_mov_b32_e32 v11, v0
	v_mov_b32_e32 v12, v0
	v_mov_b32_e32 v13, v0
	v_mov_b32_e32 v14, v0
	v_mov_b32_e32 v15, v0
	v_mov_b32_e32 v16, v0
	v_mov_b32_e32 v17, v0
	v_mov_b32_e32 v18, v0
	v_mov_b32_e32 v19, v0
	v_mov_b32_e32 v20, v0
	v_mov_b32_e32 v21, v0
	v_mov_b32_e32 v22, v0
	v_mov_b32_e32 v23, v0
	v_mov_b32_e32 v24, v0
	v_mov_b32_e32 v25, v0
	v_mov_b32_e32 v26, v0
	v_mov_b32_e32 v27, v0
	v_mov_b32_e32 v28, v0
	v_mov_b32_e32 v29, v0
	v_mov_b32_e32 v30, v0
	v_mov_b32_e32 v31, v0
	v_mov_b32_e32 v32, v0
	v_mov_b32_e32 v33, v0
	v_mov_b32_e32 v34, v0
	v_mov_b32_e32 v35, v0
	v_mov_b32_e32 v36, v0
	v_mov_b32_e32 v37, v0
	v_mov_b32_e32 v38, v0
	v_mov_b32_e32 v39, v0
	v_mov_b32_e32 v40, v0
	v_mov_b32_e32 v41, v0
	v_mov_b32_e32 v42, v0
	v_mov_b32_e32 v43, v0
	v_mov_b32_e32 v44, v0
	v_mov_b32_e32 v45, v0
	v_mov_b32_e32 v46, v0
	v_mov_b32_e32 v47, v0
	v_mov_b32_e32 v48, v0
	v_mov_b32_e32 v49, v0
	v_mov_b32_e32 v50, v0
	v_mov_b32_e32 v51, v0
	v_mov_b32_e32 v52, v0
	v_mov_b32_e32 v53, v0
	v_mov_b32_e32 v54, v0
	v_mov_b32_e32 v55, v0
	v_mov_b32_e32 v56, v0
	v_mov_b32_e32 v57, v0
	v_mov_b32_e32 v58, v0
	v_mov_b32_e32 v59, v0
	v_mov_b32_e32 v60, v0
	v_mov_b32_e32 v61, v0
	v_mov_b32_e32 v62, v0
	v_mov_b32_e32 v63, v0
	v_mov_b32_e32 v64, v0
	v_mov_b32_e32 v65, v0
	v_mov_b32_e32 v66, v0
	v_mov_b32_e32 v67, v0
	v_mov_b32_e32 v68, v0
	v_mov_b32_e32 v69, v0
	v_mov_b32_e32 v70, v0
	v_mov_b32_e32 v71, v0
	v_mov_b32_e32 v72, v0
	v_mov_b32_e32 v73, v0
	v_mov_b32_e32 v74, v0
	v_mov_b32_e32 v75, v0
	v_mov_b32_e32 v76, v0
	v_mov_b32_e32 v77, v0
	v_mov_b32_e32 v78, v0
	v_mov_b32_e32 v79, v0
	v_mov_b32_e32 v80, v0
	v_mov_b32_e32 v81, v0
	v_mov_b32_e32 v82, v0
	v_mov_b32_e32 v83, v0
	v_mov_b32_e32 v84, v0
	v_mov_b32_e32 v85, v0
	v_mov_b32_e32 v86, v0
	v_mov_b32_e32 v87, v0
	v_mov_b32_e32 v88, v0
	v_mov_b32_e32 v89, v0
	v_mov_b32_e32 v90, v0
	v_mov_b32_e32 v91, v0
	v_mov_b32_e32 v92, v0
	v_mov_b32_e32 v93, v0
	v_mov_b32_e32 v94, v0
	v_mov_b32_e32 v95, v0
	v_mov_b32_e32 v96, v0
	v_mov_b32_e32 v97, v0
	v_mov_b32_e32 v98, v0
	v_mov_b32_e32 v99, v0
	v_mov_b32_e32 v100, v0
	v_mov_b32_e32 v101, v0
	v_mov_b32_e32 v102, v0
	v_mov_b32_e32 v103, v0
	v_mov_b32_e32 v104, v0
	v_mov_b32_e32 v105, v0
	v_mov_b32_e32 v106, v0
	v_mov_b32_e32 v107, v0
	v_mov_b32_e32 v108, v0
	v_mov_b32_e32 v109, v0
	v_mov_b32_e32 v110, v0
	v_mov_b32_e32 v111, v0
	v_mov_b32_e32 v112, v0
	v_mov_b32_e32 v113, v0
	v_mov_b32_e32 v114, v0
	v_mov_b32_e32 v115, v0
	v_mov_b32_e32 v116, v0
	v_mov_b32_e32 v117, v0
	v_mov_b32_e32 v118, v0
	v_mov_b32_e32 v119, v0
	v_mov_b32_e32 v120, v0
	v_mov_b32_e32 v121, v0
	v_mov_b32_e32 v122, v0
	v_mov_b32_e32 v123, v0
	v_mov_b32_e32 v124, v0
	v_mov_b32_e32 v125, v0
	v_mov_b32_e32 v126, v0
	v_mov_b32_e32 v127, v0
	s_branch .LBB0_761

.LBB0_797:
	s_add_u32 s6, s28, s5
	s_addc_u32 s12, s29, 0
	s_add_u32 s19, s6, 0x100
	s_addc_u32 s23, s12, 0
	s_and_b64 s[10:11], s[48:49], exec
	s_cselect_b32 s55, s39, s23
	s_cselect_b32 s54, s38, s19
	s_add_u32 s5, s26, s5
	s_addc_u32 s10, s27, 0
	s_add_u32 s5, s5, 0x100
	s_addc_u32 s19, s10, 0
	s_add_i32 s23, 0, 0x10000
	s_and_b64 s[10:11], s[48:49], exec
	s_cselect_b32 s59, s45, s19
	s_cselect_b32 s58, s44, s5
	s_add_u32 s68, s6, 0x40080
	s_addc_u32 s69, s12, 0
	s_add_i32 s88, s23, s70
	s_add_i32 m0, s72, 0xc000
	s_add_i32 s89, s72, 0xe000
	s_add_i32 s87, 0, 0x14000
	s_add_i32 s86, s88, 0x2000
	s_add_u32 s52, s58, 0x80000
	v_add_u32_e32 v158, s23, v138
	s_addc_u32 s53, s59, 0
	s_add_i32 s19, s87, s70
	ds_read_b128 v[146:149], v158
	ds_read_b128 v[150:153], v158 offset:1024
	ds_read_b128 v[154:157], v158 offset:2048
	ds_read_b128 v[158:161], v158 offset:3072
	s_add_i32 s12, s19, 0x2000
	s_add_i32 s11, 0, 0x18000
	s_add_u32 s50, s54, 0x40000
	s_addc_u32 s51, s55, 0
	s_add_i32 s10, s11, s70
	s_add_i32 s6, 0, 0x1c000
	s_add_i32 s5, s10, 0x2000
	s_add_u32 s48, s58, 0x80080
	s_addc_u32 s49, s59, 0
	s_add_i32 s85, s6, s70
	s_add_i32 s31, s85, 0x2000
	v_lshl_add_u64 v[192:193], s[68:69], 0, v[128:129]
	ds_read_b128 v[162:165], v139
	ds_read_b128 v[166:169], v139 offset:1024
	ds_read_b128 v[170:173], v139 offset:2048
	ds_read_b128 v[174:177], v139 offset:3072
	ds_read_b128 v[178:181], v139 offset:4096
	ds_read_b128 v[182:185], v139 offset:5120
	ds_read_b128 v[194:197], v139 offset:6144
	ds_read_b128 v[206:209], v139 offset:7168
	global_load_lds_dwordx4 v[192:193], off
	v_lshl_add_u64 v[192:193], s[68:69], 0, v[132:133]
	s_mov_b32 m0, s89
	s_nop 0
	global_load_lds_dwordx4 v[192:193], off
	s_waitcnt lgkmcnt(8)
	s_barrier
	s_setprio 1
	s_waitcnt lgkmcnt(7)
	v_mfma_f32_16x16x32_bf16 v[124:127], v[146:149], v[162:165], v[124:127]
	v_mfma_f32_16x16x32_bf16 v[120:123], v[154:157], v[162:165], v[120:123]
	s_waitcnt lgkmcnt(5)
	v_mfma_f32_16x16x32_bf16 v[116:119], v[146:149], v[170:173], v[116:119]
	v_mfma_f32_16x16x32_bf16 v[112:115], v[154:157], v[170:173], v[112:115]
	s_waitcnt lgkmcnt(3)
	v_mfma_f32_16x16x32_bf16 v[108:111], v[146:149], v[178:181], v[108:111]
	v_mfma_f32_16x16x32_bf16 v[104:107], v[154:157], v[178:181], v[104:107]
	s_waitcnt lgkmcnt(1)
	v_mfma_f32_16x16x32_bf16 v[100:103], v[146:149], v[194:197], v[100:103]
	v_mfma_f32_16x16x32_bf16 v[96:99], v[154:157], v[194:197], v[96:99]
	v_mfma_f32_16x16x32_bf16 v[124:127], v[150:153], v[166:169], v[124:127]
	v_mfma_f32_16x16x32_bf16 v[120:123], v[158:161], v[166:169], v[120:123]
	v_mfma_f32_16x16x32_bf16 v[116:119], v[150:153], v[174:177], v[116:119]
	v_mfma_f32_16x16x32_bf16 v[112:115], v[158:161], v[174:177], v[112:115]
	v_mfma_f32_16x16x32_bf16 v[108:111], v[150:153], v[182:185], v[108:111]
	v_mfma_f32_16x16x32_bf16 v[104:107], v[158:161], v[182:185], v[104:107]
	s_waitcnt lgkmcnt(0)
	v_mfma_f32_16x16x32_bf16 v[100:103], v[150:153], v[206:209], v[100:103]
	v_mfma_f32_16x16x32_bf16 v[96:99], v[158:161], v[206:209], v[96:99]
	s_setprio 0
	s_barrier
	v_add_u32_e32 v192, s87, v138
	s_mov_b32 m0, s88
	ds_read_b128 v[210:213], v192
	ds_read_b128 v[214:217], v192 offset:1024
	ds_read_b128 v[218:221], v192 offset:2048
	ds_read_b128 v[222:225], v192 offset:3072
	v_lshl_add_u64 v[192:193], s[58:59], 0, v[130:131]
	global_load_lds_dwordx4 v[192:193], off
	v_lshl_add_u64 v[226:227], s[58:59], 0, v[134:135]
	s_mov_b32 m0, s86
	s_nop 0
	global_load_lds_dwordx4 v[226:227], off
	s_barrier
	s_setprio 1
	s_waitcnt lgkmcnt(3)
	v_mfma_f32_16x16x32_bf16 v[92:95], v[210:213], v[162:165], v[92:95]
	s_waitcnt lgkmcnt(1)
	v_mfma_f32_16x16x32_bf16 v[88:91], v[218:221], v[162:165], v[88:91]
	v_mfma_f32_16x16x32_bf16 v[84:87], v[210:213], v[170:173], v[84:87]
	v_mfma_f32_16x16x32_bf16 v[80:83], v[218:221], v[170:173], v[80:83]
	v_mfma_f32_16x16x32_bf16 v[76:79], v[210:213], v[178:181], v[76:79]
	v_mfma_f32_16x16x32_bf16 v[72:75], v[218:221], v[178:181], v[72:75]
	v_mfma_f32_16x16x32_bf16 v[68:71], v[210:213], v[194:197], v[68:71]
	v_mfma_f32_16x16x32_bf16 v[64:67], v[218:221], v[194:197], v[64:67]
	v_mfma_f32_16x16x32_bf16 v[92:95], v[214:217], v[166:169], v[92:95]
	s_waitcnt lgkmcnt(0)
	v_mfma_f32_16x16x32_bf16 v[88:91], v[222:225], v[166:169], v[88:91]
	v_mfma_f32_16x16x32_bf16 v[84:87], v[214:217], v[174:177], v[84:87]
	v_mfma_f32_16x16x32_bf16 v[80:83], v[222:225], v[174:177], v[80:83]
	v_mfma_f32_16x16x32_bf16 v[76:79], v[214:217], v[182:185], v[76:79]
	v_mfma_f32_16x16x32_bf16 v[72:75], v[222:225], v[182:185], v[72:75]
	v_mfma_f32_16x16x32_bf16 v[68:71], v[214:217], v[206:209], v[68:71]
	v_mfma_f32_16x16x32_bf16 v[64:67], v[222:225], v[206:209], v[64:67]
	s_setprio 0
	s_mov_b32 m0, s72
	v_lshl_add_u64 v[228:229], s[54:55], 0, v[128:129]
	s_barrier
	ds_read_b128 v[162:165], v139 offset:16384
	ds_read_b128 v[166:169], v139 offset:17408
	ds_read_b128 v[170:173], v139 offset:18432
	ds_read_b128 v[174:177], v139 offset:19456
	ds_read_b128 v[178:181], v139 offset:20480
	ds_read_b128 v[182:185], v139 offset:21504
	ds_read_b128 v[194:197], v139 offset:22528
	ds_read_b128 v[206:209], v139 offset:23552
	global_load_lds_dwordx4 v[228:229], off
	v_lshl_add_u64 v[230:231], s[54:55], 0, v[132:133]
	s_mov_b32 m0, s73
	s_nop 0
	global_load_lds_dwordx4 v[230:231], off
	s_barrier
	s_setprio 1
	s_waitcnt lgkmcnt(7)
	v_mfma_f32_16x16x32_bf16 v[60:63], v[146:149], v[162:165], v[60:63]
	v_mfma_f32_16x16x32_bf16 v[56:59], v[154:157], v[162:165], v[56:59]
	s_waitcnt lgkmcnt(5)
	v_mfma_f32_16x16x32_bf16 v[52:55], v[146:149], v[170:173], v[52:55]
	v_mfma_f32_16x16x32_bf16 v[48:51], v[154:157], v[170:173], v[48:51]
	s_waitcnt lgkmcnt(3)
	v_mfma_f32_16x16x32_bf16 v[44:47], v[146:149], v[178:181], v[44:47]
	v_mfma_f32_16x16x32_bf16 v[40:43], v[154:157], v[178:181], v[40:43]
	s_waitcnt lgkmcnt(1)
	v_mfma_f32_16x16x32_bf16 v[36:39], v[146:149], v[194:197], v[36:39]
	v_mfma_f32_16x16x32_bf16 v[32:35], v[154:157], v[194:197], v[32:35]
	v_mfma_f32_16x16x32_bf16 v[60:63], v[150:153], v[166:169], v[60:63]
	v_mfma_f32_16x16x32_bf16 v[56:59], v[158:161], v[166:169], v[56:59]
	v_mfma_f32_16x16x32_bf16 v[52:55], v[150:153], v[174:177], v[52:55]
	v_mfma_f32_16x16x32_bf16 v[48:51], v[158:161], v[174:177], v[48:51]
	v_mfma_f32_16x16x32_bf16 v[44:47], v[150:153], v[182:185], v[44:47]
	v_mfma_f32_16x16x32_bf16 v[40:43], v[158:161], v[182:185], v[40:43]
	s_waitcnt lgkmcnt(0)
	v_mfma_f32_16x16x32_bf16 v[36:39], v[150:153], v[206:209], v[36:39]
	v_mfma_f32_16x16x32_bf16 v[32:35], v[158:161], v[206:209], v[32:35]
	s_setprio 0
	s_barrier
	s_mov_b32 m0, s19
	v_lshl_add_u64 v[146:147], s[52:53], 0, v[130:131]
	global_load_lds_dwordx4 v[146:147], off
	v_lshl_add_u64 v[146:147], s[52:53], 0, v[134:135]
	s_mov_b32 m0, s12
	s_nop 0
	global_load_lds_dwordx4 v[146:147], off
	s_nop 0
	s_waitcnt vmcnt(6)
	s_barrier
	s_setprio 1
	v_mfma_f32_16x16x32_bf16 v[28:31], v[210:213], v[162:165], v[28:31]
	v_mfma_f32_16x16x32_bf16 v[20:23], v[210:213], v[170:173], v[20:23]
	v_mfma_f32_16x16x32_bf16 v[12:15], v[210:213], v[178:181], v[12:15]
	v_mfma_f32_16x16x32_bf16 v[4:7], v[210:213], v[194:197], v[4:7]
	v_mfma_f32_16x16x32_bf16 v[0:3], v[218:221], v[194:197], v[0:3]
	v_mfma_f32_16x16x32_bf16 v[8:11], v[218:221], v[178:181], v[8:11]
	v_mfma_f32_16x16x32_bf16 v[16:19], v[218:221], v[170:173], v[16:19]
	v_mfma_f32_16x16x32_bf16 v[24:27], v[218:221], v[162:165], v[24:27]
	v_mfma_f32_16x16x32_bf16 v[28:31], v[214:217], v[166:169], v[28:31]
	v_mfma_f32_16x16x32_bf16 v[20:23], v[214:217], v[174:177], v[20:23]
	v_mfma_f32_16x16x32_bf16 v[12:15], v[214:217], v[182:185], v[12:15]
	v_mfma_f32_16x16x32_bf16 v[4:7], v[214:217], v[206:209], v[4:7]
	v_mfma_f32_16x16x32_bf16 v[0:3], v[222:225], v[206:209], v[0:3]
	v_mfma_f32_16x16x32_bf16 v[8:11], v[222:225], v[182:185], v[8:11]
	v_mfma_f32_16x16x32_bf16 v[16:19], v[222:225], v[174:177], v[16:19]
	v_mfma_f32_16x16x32_bf16 v[24:27], v[222:225], v[166:169], v[24:27]
	s_setprio 0
	v_add_u32_e32 v158, s11, v138
	s_barrier
	ds_read_b128 v[146:149], v158
	ds_read_b128 v[150:153], v158 offset:1024
	ds_read_b128 v[154:157], v158 offset:2048
	ds_read_b128 v[158:161], v158 offset:3072
	s_mov_b32 m0, s74
	v_lshl_add_u64 v[210:211], s[50:51], 0, v[128:129]
	ds_read_b128 v[162:165], v139 offset:32768
	ds_read_b128 v[166:169], v139 offset:33792
	ds_read_b128 v[170:173], v139 offset:34816
	ds_read_b128 v[174:177], v139 offset:35840
	ds_read_b128 v[178:181], v139 offset:36864
	ds_read_b128 v[182:185], v139 offset:37888
	ds_read_b128 v[194:197], v139 offset:38912
	ds_read_b128 v[206:209], v139 offset:39936
	global_load_lds_dwordx4 v[210:211], off
	v_lshl_add_u64 v[210:211], s[50:51], 0, v[132:133]
	s_mov_b32 m0, s75
	s_nop 0
	global_load_lds_dwordx4 v[210:211], off
	s_waitcnt lgkmcnt(8)
	s_barrier
	s_setprio 1
	s_waitcnt lgkmcnt(7)
	v_mfma_f32_16x16x32_bf16 v[124:127], v[146:149], v[162:165], v[124:127]
	v_mfma_f32_16x16x32_bf16 v[120:123], v[154:157], v[162:165], v[120:123]
	s_waitcnt lgkmcnt(5)
	v_mfma_f32_16x16x32_bf16 v[116:119], v[146:149], v[170:173], v[116:119]
	v_mfma_f32_16x16x32_bf16 v[112:115], v[154:157], v[170:173], v[112:115]
	s_waitcnt lgkmcnt(3)
	v_mfma_f32_16x16x32_bf16 v[108:111], v[146:149], v[178:181], v[108:111]
	v_mfma_f32_16x16x32_bf16 v[104:107], v[154:157], v[178:181], v[104:107]
	s_waitcnt lgkmcnt(1)
	v_mfma_f32_16x16x32_bf16 v[100:103], v[146:149], v[194:197], v[100:103]
	v_mfma_f32_16x16x32_bf16 v[96:99], v[154:157], v[194:197], v[96:99]
	v_mfma_f32_16x16x32_bf16 v[124:127], v[150:153], v[166:169], v[124:127]
	v_mfma_f32_16x16x32_bf16 v[120:123], v[158:161], v[166:169], v[120:123]
	v_mfma_f32_16x16x32_bf16 v[116:119], v[150:153], v[174:177], v[116:119]
	v_mfma_f32_16x16x32_bf16 v[112:115], v[158:161], v[174:177], v[112:115]
	v_mfma_f32_16x16x32_bf16 v[108:111], v[150:153], v[182:185], v[108:111]
	v_mfma_f32_16x16x32_bf16 v[104:107], v[158:161], v[182:185], v[104:107]
	s_waitcnt lgkmcnt(0)
	v_mfma_f32_16x16x32_bf16 v[100:103], v[150:153], v[206:209], v[100:103]
	v_mfma_f32_16x16x32_bf16 v[96:99], v[158:161], v[206:209], v[96:99]
	s_setprio 0
	s_barrier
	s_mov_b32 m0, s10
	v_add_u32_e32 v222, s6, v138
	v_lshl_add_u64 v[192:193], v[192:193], 0, s[36:37]
	ds_read_b128 v[210:213], v222
	ds_read_b128 v[214:217], v222 offset:1024
	ds_read_b128 v[218:221], v222 offset:2048
	ds_read_b128 v[222:225], v222 offset:3072
	global_load_lds_dwordx4 v[192:193], off
	v_lshl_add_u64 v[192:193], v[226:227], 0, s[36:37]
	s_mov_b32 m0, s5
	s_nop 0
	global_load_lds_dwordx4 v[192:193], off
	s_barrier
	s_setprio 1
	s_waitcnt lgkmcnt(3)
	v_mfma_f32_16x16x32_bf16 v[92:95], v[210:213], v[162:165], v[92:95]
	s_waitcnt lgkmcnt(1)
	v_mfma_f32_16x16x32_bf16 v[88:91], v[218:221], v[162:165], v[88:91]
	v_mfma_f32_16x16x32_bf16 v[84:87], v[210:213], v[170:173], v[84:87]
	v_mfma_f32_16x16x32_bf16 v[80:83], v[218:221], v[170:173], v[80:83]
	v_mfma_f32_16x16x32_bf16 v[76:79], v[210:213], v[178:181], v[76:79]
	v_mfma_f32_16x16x32_bf16 v[72:75], v[218:221], v[178:181], v[72:75]
	v_mfma_f32_16x16x32_bf16 v[68:71], v[210:213], v[194:197], v[68:71]
	v_mfma_f32_16x16x32_bf16 v[64:67], v[218:221], v[194:197], v[64:67]
	v_mfma_f32_16x16x32_bf16 v[92:95], v[214:217], v[166:169], v[92:95]
	s_waitcnt lgkmcnt(0)
	v_mfma_f32_16x16x32_bf16 v[88:91], v[222:225], v[166:169], v[88:91]
	v_mfma_f32_16x16x32_bf16 v[84:87], v[214:217], v[174:177], v[84:87]
	v_mfma_f32_16x16x32_bf16 v[80:83], v[222:225], v[174:177], v[80:83]
	v_mfma_f32_16x16x32_bf16 v[76:79], v[214:217], v[182:185], v[76:79]
	v_mfma_f32_16x16x32_bf16 v[72:75], v[222:225], v[182:185], v[72:75]
	v_mfma_f32_16x16x32_bf16 v[68:71], v[214:217], v[206:209], v[68:71]
	v_mfma_f32_16x16x32_bf16 v[64:67], v[222:225], v[206:209], v[64:67]
	s_setprio 0
	s_mov_b32 m0, s80
	v_lshl_add_u64 v[192:193], v[228:229], 0, s[36:37]
	s_barrier
	ds_read_b128 v[162:165], v139 offset:49152
	ds_read_b128 v[166:169], v139 offset:50176
	ds_read_b128 v[170:173], v139 offset:51200
	ds_read_b128 v[174:177], v139 offset:52224
	ds_read_b128 v[178:181], v139 offset:53248
	ds_read_b128 v[182:185], v139 offset:54272
	ds_read_b128 v[194:197], v139 offset:55296
	ds_read_b128 v[206:209], v139 offset:56320
	global_load_lds_dwordx4 v[192:193], off
	v_lshl_add_u64 v[192:193], v[230:231], 0, s[36:37]
	s_mov_b32 m0, s81
	s_nop 0
	global_load_lds_dwordx4 v[192:193], off
	s_barrier
	s_setprio 1
	s_waitcnt lgkmcnt(7)
	v_mfma_f32_16x16x32_bf16 v[60:63], v[146:149], v[162:165], v[60:63]
	v_mfma_f32_16x16x32_bf16 v[56:59], v[154:157], v[162:165], v[56:59]
	s_waitcnt lgkmcnt(5)
	v_mfma_f32_16x16x32_bf16 v[52:55], v[146:149], v[170:173], v[52:55]
	v_mfma_f32_16x16x32_bf16 v[48:51], v[154:157], v[170:173], v[48:51]
	s_waitcnt lgkmcnt(3)
	v_mfma_f32_16x16x32_bf16 v[44:47], v[146:149], v[178:181], v[44:47]
	v_mfma_f32_16x16x32_bf16 v[40:43], v[154:157], v[178:181], v[40:43]
	s_waitcnt lgkmcnt(1)
	v_mfma_f32_16x16x32_bf16 v[36:39], v[146:149], v[194:197], v[36:39]
	v_mfma_f32_16x16x32_bf16 v[32:35], v[154:157], v[194:197], v[32:35]
	v_mfma_f32_16x16x32_bf16 v[60:63], v[150:153], v[166:169], v[60:63]
	v_mfma_f32_16x16x32_bf16 v[56:59], v[158:161], v[166:169], v[56:59]
	v_mfma_f32_16x16x32_bf16 v[52:55], v[150:153], v[174:177], v[52:55]
	v_mfma_f32_16x16x32_bf16 v[48:51], v[158:161], v[174:177], v[48:51]
	v_mfma_f32_16x16x32_bf16 v[44:47], v[150:153], v[182:185], v[44:47]
	v_mfma_f32_16x16x32_bf16 v[40:43], v[158:161], v[182:185], v[40:43]
	s_waitcnt lgkmcnt(0)
	v_mfma_f32_16x16x32_bf16 v[36:39], v[150:153], v[206:209], v[36:39]
	v_mfma_f32_16x16x32_bf16 v[32:35], v[158:161], v[206:209], v[32:35]
	s_setprio 0
	s_barrier
	s_mov_b32 m0, s85
	v_lshl_add_u64 v[146:147], s[48:49], 0, v[130:131]
	global_load_lds_dwordx4 v[146:147], off
	v_lshl_add_u64 v[146:147], s[48:49], 0, v[134:135]
	s_mov_b32 m0, s31
	s_nop 0
	global_load_lds_dwordx4 v[146:147], off
	s_nop 0
	s_waitcnt vmcnt(6)
	s_barrier
	s_setprio 1
	v_mfma_f32_16x16x32_bf16 v[28:31], v[210:213], v[162:165], v[28:31]
	v_mfma_f32_16x16x32_bf16 v[20:23], v[210:213], v[170:173], v[20:23]
	v_mfma_f32_16x16x32_bf16 v[12:15], v[210:213], v[178:181], v[12:15]
	v_mfma_f32_16x16x32_bf16 v[4:7], v[210:213], v[194:197], v[4:7]
	v_mfma_f32_16x16x32_bf16 v[0:3], v[218:221], v[194:197], v[0:3]
	v_mfma_f32_16x16x32_bf16 v[8:11], v[218:221], v[178:181], v[8:11]
	v_mfma_f32_16x16x32_bf16 v[16:19], v[218:221], v[170:173], v[16:19]
	v_mfma_f32_16x16x32_bf16 v[24:27], v[218:221], v[162:165], v[24:27]
	v_mfma_f32_16x16x32_bf16 v[28:31], v[214:217], v[166:169], v[28:31]
	v_mfma_f32_16x16x32_bf16 v[20:23], v[214:217], v[174:177], v[20:23]
	v_mfma_f32_16x16x32_bf16 v[12:15], v[214:217], v[182:185], v[12:15]
	v_mfma_f32_16x16x32_bf16 v[4:7], v[214:217], v[206:209], v[4:7]
	v_mfma_f32_16x16x32_bf16 v[0:3], v[222:225], v[206:209], v[0:3]
	v_mfma_f32_16x16x32_bf16 v[8:11], v[222:225], v[182:185], v[8:11]
	v_mfma_f32_16x16x32_bf16 v[16:19], v[222:225], v[174:177], v[16:19]
	v_mfma_f32_16x16x32_bf16 v[24:27], v[222:225], v[166:169], v[24:27]
	s_setprio 0
	s_movk_i32 s5, 0x100
	s_andn2_b64 vcc, exec, s[46:47]
	s_mov_b64 s[48:49], -1
	s_mov_b64 s[46:47], 0
	s_barrier
	s_cbranch_vccz .LBB0_797
	s_ashr_i32 s10, s71, 2
	s_ashr_i32 s11, s10, 31
	s_lshl_b64 s[10:11], s[10:11], 21
	s_add_u32 s5, s76, s10
	s_addc_u32 s6, s77, s11
	s_lshl_b32 s10, s71, 9
	s_and_b32 s10, s10, 0x600
	s_add_u32 s10, s5, s10
	s_addc_u32 s11, s6, 0
	s_ashr_i32 s5, s4, 31
	v_lshl_add_u64 v[146:147], s[10:11], 0, v[140:141]
	s_lshl_b64 s[10:11], s[4:5], 19
	v_lshl_add_u64 v[146:147], v[146:147], 0, s[10:11]
	v_lshl_add_u64 v[150:151], v[146:147], 0, v[136:137]
	v_cvt_pk_bf16_f32 v146, v124, v125
	v_cvt_pk_bf16_f32 v147, v126, v127
	v_cvt_pk_bf16_f32 v148, v120, v121
	v_cvt_pk_bf16_f32 v149, v122, v123
	global_store_dwordx4 v[150:151], v[146:149], off
	v_add_co_u32_e32 v152, vcc, s65, v150
	s_nop 0
	v_cvt_pk_bf16_f32 v146, v92, v93
	v_cvt_pk_bf16_f32 v147, v94, v95
	v_cvt_pk_bf16_f32 v148, v88, v89
	v_cvt_pk_bf16_f32 v149, v90, v91
	global_store_dwordx4 v[150:151], v[146:149], off offset:256
	v_addc_co_u32_e32 v153, vcc, 0, v151, vcc
	s_nop 0
	v_cvt_pk_bf16_f32 v146, v116, v117
	v_cvt_pk_bf16_f32 v147, v118, v119
	v_cvt_pk_bf16_f32 v148, v112, v113
	v_cvt_pk_bf16_f32 v149, v114, v115
	global_store_dwordx4 v[152:153], v[146:149], off
	s_mov_b32 s5, 0x40000
	s_nop 0
	v_cvt_pk_bf16_f32 v146, v84, v85
	v_cvt_pk_bf16_f32 v147, v86, v87
	v_cvt_pk_bf16_f32 v148, v80, v81
	v_cvt_pk_bf16_f32 v149, v82, v83
	global_store_dwordx4 v[152:153], v[146:149], off offset:256
	v_add_co_u32_e32 v152, vcc, s66, v150
	s_nop 0
	v_cvt_pk_bf16_f32 v146, v108, v109
	v_cvt_pk_bf16_f32 v147, v110, v111
	v_cvt_pk_bf16_f32 v148, v104, v105
	v_cvt_pk_bf16_f32 v149, v106, v107
	v_addc_co_u32_e32 v153, vcc, 0, v151, vcc
	global_store_dwordx4 v[152:153], v[146:149], off
	s_nop 1
	v_cvt_pk_bf16_f32 v146, v76, v77
	v_cvt_pk_bf16_f32 v147, v78, v79
	v_cvt_pk_bf16_f32 v148, v72, v73
	v_cvt_pk_bf16_f32 v149, v74, v75
	global_store_dwordx4 v[152:153], v[146:149], off offset:256
	v_add_co_u32_e32 v152, vcc, s64, v150
	s_nop 0
	v_cvt_pk_bf16_f32 v146, v100, v101
	v_cvt_pk_bf16_f32 v147, v102, v103
	v_cvt_pk_bf16_f32 v148, v96, v97
	v_cvt_pk_bf16_f32 v149, v98, v99
	v_addc_co_u32_e32 v153, vcc, 0, v151, vcc
	global_store_dwordx4 v[152:153], v[146:149], off
	s_nop 1
	v_cvt_pk_bf16_f32 v146, v68, v69
	v_cvt_pk_bf16_f32 v147, v70, v71
	v_cvt_pk_bf16_f32 v148, v64, v65
	v_cvt_pk_bf16_f32 v149, v66, v67
	global_store_dwordx4 v[152:153], v[146:149], off offset:256
	v_add_co_u32_e32 v152, vcc, s5, v150
	s_nop 0
	v_cvt_pk_bf16_f32 v146, v60, v61
	v_cvt_pk_bf16_f32 v147, v62, v63
	v_cvt_pk_bf16_f32 v148, v56, v57
	v_cvt_pk_bf16_f32 v149, v58, v59
	v_addc_co_u32_e32 v153, vcc, 0, v151, vcc
	global_store_dwordx4 v[152:153], v[146:149], off
	s_mov_b32 s5, 0x48000
	s_nop 0
	v_cvt_pk_bf16_f32 v146, v28, v29
	v_cvt_pk_bf16_f32 v147, v30, v31
	v_cvt_pk_bf16_f32 v148, v24, v25
	v_cvt_pk_bf16_f32 v149, v26, v27
	global_store_dwordx4 v[152:153], v[146:149], off offset:256
	v_add_co_u32_e32 v152, vcc, s5, v150
	s_nop 0
	v_cvt_pk_bf16_f32 v146, v52, v53
	v_cvt_pk_bf16_f32 v147, v54, v55
	v_cvt_pk_bf16_f32 v148, v48, v49
	v_cvt_pk_bf16_f32 v149, v50, v51
	v_addc_co_u32_e32 v153, vcc, 0, v151, vcc
	global_store_dwordx4 v[152:153], v[146:149], off
	s_mov_b32 s5, 0x50000
	s_nop 0
	v_cvt_pk_bf16_f32 v146, v20, v21
	v_cvt_pk_bf16_f32 v147, v22, v23
	v_cvt_pk_bf16_f32 v148, v16, v17
	v_cvt_pk_bf16_f32 v149, v18, v19
	global_store_dwordx4 v[152:153], v[146:149], off offset:256
	v_add_co_u32_e32 v152, vcc, s5, v150
	s_nop 0
	v_cvt_pk_bf16_f32 v146, v44, v45
	v_cvt_pk_bf16_f32 v147, v46, v47
	v_cvt_pk_bf16_f32 v148, v40, v41
	v_cvt_pk_bf16_f32 v149, v42, v43
	v_addc_co_u32_e32 v153, vcc, 0, v151, vcc
	s_mov_b32 s5, 0x58000
	global_store_dwordx4 v[152:153], v[146:149], off
	v_add_co_u32_e32 v150, vcc, s5, v150
	s_nop 0
	v_cvt_pk_bf16_f32 v146, v12, v13
	v_cvt_pk_bf16_f32 v147, v14, v15
	v_cvt_pk_bf16_f32 v148, v8, v9
	v_cvt_pk_bf16_f32 v149, v10, v11
	global_store_dwordx4 v[152:153], v[146:149], off offset:256
	v_addc_co_u32_e32 v151, vcc, 0, v151, vcc
	s_nop 0
	v_cvt_pk_bf16_f32 v146, v36, v37
	v_cvt_pk_bf16_f32 v147, v38, v39
	v_cvt_pk_bf16_f32 v148, v32, v33
	v_cvt_pk_bf16_f32 v149, v34, v35
	global_store_dwordx4 v[150:151], v[146:149], off
	s_and_b64 vcc, exec, s[42:43]
	s_nop 0
	v_cvt_pk_bf16_f32 v146, v4, v5
	v_cvt_pk_bf16_f32 v147, v6, v7
	v_cvt_pk_bf16_f32 v148, v0, v1
	v_cvt_pk_bf16_f32 v149, v2, v3
	global_store_dwordx4 v[150:151], v[146:149], off offset:256
	s_cbranch_vccnz .LBB0_785
	v_mov_b32_e32 v0, 0
	s_mov_b32 s4, s30
	s_mov_b32 s71, s83
	s_mov_b64 s[26:27], s[44:45]
	s_mov_b64 s[28:29], s[38:39]
	s_mov_b32 s82, s84
	v_mov_b32_e32 v1, v0
	v_mov_b32_e32 v2, v0
	v_mov_b32_e32 v3, v0
	v_mov_b32_e32 v4, v0
	v_mov_b32_e32 v5, v0
	v_mov_b32_e32 v6, v0
	v_mov_b32_e32 v7, v0
	v_mov_b32_e32 v8, v0
	v_mov_b32_e32 v9, v0
	v_mov_b32_e32 v10, v0
	v_mov_b32_e32 v11, v0
	v_mov_b32_e32 v12, v0
	v_mov_b32_e32 v13, v0
	v_mov_b32_e32 v14, v0
	v_mov_b32_e32 v15, v0
	v_mov_b32_e32 v16, v0
	v_mov_b32_e32 v17, v0
	v_mov_b32_e32 v18, v0
	v_mov_b32_e32 v19, v0
	v_mov_b32_e32 v20, v0
	v_mov_b32_e32 v21, v0
	v_mov_b32_e32 v22, v0
	v_mov_b32_e32 v23, v0
	v_mov_b32_e32 v24, v0
	v_mov_b32_e32 v25, v0
	v_mov_b32_e32 v26, v0
	v_mov_b32_e32 v27, v0
	v_mov_b32_e32 v28, v0
	v_mov_b32_e32 v29, v0
	v_mov_b32_e32 v30, v0
	v_mov_b32_e32 v31, v0
	v_mov_b32_e32 v32, v0
	v_mov_b32_e32 v33, v0
	v_mov_b32_e32 v34, v0
	v_mov_b32_e32 v35, v0
	v_mov_b32_e32 v36, v0
	v_mov_b32_e32 v37, v0
	v_mov_b32_e32 v38, v0
	v_mov_b32_e32 v39, v0
	v_mov_b32_e32 v40, v0
	v_mov_b32_e32 v41, v0
	v_mov_b32_e32 v42, v0
	v_mov_b32_e32 v43, v0
	v_mov_b32_e32 v44, v0
	v_mov_b32_e32 v45, v0
	v_mov_b32_e32 v46, v0
	v_mov_b32_e32 v47, v0
	v_mov_b32_e32 v48, v0
	v_mov_b32_e32 v49, v0
	v_mov_b32_e32 v50, v0
	v_mov_b32_e32 v51, v0
	v_mov_b32_e32 v52, v0
	v_mov_b32_e32 v53, v0
	v_mov_b32_e32 v54, v0
	v_mov_b32_e32 v55, v0
	v_mov_b32_e32 v56, v0
	v_mov_b32_e32 v57, v0
	v_mov_b32_e32 v58, v0
	v_mov_b32_e32 v59, v0
	v_mov_b32_e32 v60, v0
	v_mov_b32_e32 v61, v0
	v_mov_b32_e32 v62, v0
	v_mov_b32_e32 v63, v0
	v_mov_b32_e32 v64, v0
	v_mov_b32_e32 v65, v0
	v_mov_b32_e32 v66, v0
	v_mov_b32_e32 v67, v0
	v_mov_b32_e32 v68, v0
	v_mov_b32_e32 v69, v0
	v_mov_b32_e32 v70, v0
	v_mov_b32_e32 v71, v0
	v_mov_b32_e32 v72, v0
	v_mov_b32_e32 v73, v0
	v_mov_b32_e32 v74, v0
	v_mov_b32_e32 v75, v0
	v_mov_b32_e32 v76, v0
	v_mov_b32_e32 v77, v0
	v_mov_b32_e32 v78, v0
	v_mov_b32_e32 v79, v0
	v_mov_b32_e32 v80, v0
	v_mov_b32_e32 v81, v0
	v_mov_b32_e32 v82, v0
	v_mov_b32_e32 v83, v0
	v_mov_b32_e32 v84, v0
	v_mov_b32_e32 v85, v0
	v_mov_b32_e32 v86, v0
	v_mov_b32_e32 v87, v0
	v_mov_b32_e32 v88, v0
	v_mov_b32_e32 v89, v0
	v_mov_b32_e32 v90, v0
	v_mov_b32_e32 v91, v0
	v_mov_b32_e32 v92, v0
	v_mov_b32_e32 v93, v0
	v_mov_b32_e32 v94, v0
	v_mov_b32_e32 v95, v0
	v_mov_b32_e32 v96, v0
	v_mov_b32_e32 v97, v0
	v_mov_b32_e32 v98, v0
	v_mov_b32_e32 v99, v0
	v_mov_b32_e32 v100, v0
	v_mov_b32_e32 v101, v0
	v_mov_b32_e32 v102, v0
	v_mov_b32_e32 v103, v0
	v_mov_b32_e32 v104, v0
	v_mov_b32_e32 v105, v0
	v_mov_b32_e32 v106, v0
	v_mov_b32_e32 v107, v0
	v_mov_b32_e32 v108, v0
	v_mov_b32_e32 v109, v0
	v_mov_b32_e32 v110, v0
	v_mov_b32_e32 v111, v0
	v_mov_b32_e32 v112, v0
	v_mov_b32_e32 v113, v0
	v_mov_b32_e32 v114, v0
	v_mov_b32_e32 v115, v0
	v_mov_b32_e32 v116, v0
	v_mov_b32_e32 v117, v0
	v_mov_b32_e32 v118, v0
	v_mov_b32_e32 v119, v0
	v_mov_b32_e32 v120, v0
	v_mov_b32_e32 v121, v0
	v_mov_b32_e32 v122, v0
	v_mov_b32_e32 v123, v0
	v_mov_b32_e32 v124, v0
	v_mov_b32_e32 v125, v0
	v_mov_b32_e32 v126, v0
	v_mov_b32_e32 v127, v0
	s_branch .LBB0_785
